# 16-byte stores of phases P1-P7 made write-through (sc1) so the barrier L2 write-back has less to flush
# speedup vs baseline: 1.0150x; 1.0047x over previous
; __device__ __forceinline__ unsigned cvt_pk_bf16(float lo, float hi) { unsigned r; asm volatile("v_cvt_pk_bf16_f32 %0, %1, %2" : "=v"(r) : "v"(lo), "v"(hi)); return r; }
;     __device__ __forceinline__ void operator()(f32x4 (&acc)[2][2][4][2], const Unit& u, int wr, int wc, int fr, int fq) const {
;         const int row0 = u.pm * BM + wr * 64 + fr, col0 = u.pn * HALF + wc * 32 + 8 * fq;
;         bf16_t* Ob = O + ((size_t)(u.pm * ldc + (col0 >> 6)) * BM) * 64;
;         float sq[2][4];
; #pragma unroll
;         for (int ai = 0; ai < 2; ++ai)
; #pragma unroll
;             for (int m = 0; m < 4; ++m) sq[ai][m] = ssq[row0 + ai * HALF + m * 16];
; #pragma unroll
;         for (int ai = 0; ai < 2; ++ai)
; #pragma unroll
;             for (int m = 0; m < 4; ++m) { const float ms = sq[ai][m] * (1.0f / 1024.0f) + 1e-6f, nrl = -__builtin_amdgcn_rsqf(ms) * LOG2E;
;                 float o[8];
; #pragma unroll
;                 for (int n = 0; n < 2; ++n)
; #pragma unroll
;                     for (int e = 0; e < 4; ++e) { const float a = acc[ai][0][m][n][e], bb = acc[ai][1][m][n][e];
;                         o[4 * n + e] = (a * bb) * __builtin_amdgcn_rcpf(__builtin_fmaf(__builtin_amdgcn_exp2f(a * nrl), ms, ms)); }
;                 u32x4 w; w.x = cvt_pk_bf16(o[0], o[1]); w.y = cvt_pk_bf16(o[2], o[3]); w.z = cvt_pk_bf16(o[4], o[5]); w.w = cvt_pk_bf16(o[6], o[7]);
;                 *(u32x4*)((char*)Ob + ai * HTB + lds_byte(wr * 64 + m * 16 + fr, (col0 & 63))) = w; }
.LBB0_144:
	v_lshl_add_u32 v150, s68, 8, v142
	v_ashrrev_i32_e32 v151, 31, v150
	v_lshl_add_u64 v[150:151], v[150:151], 2, s[22:23]
	global_load_dword v149, v[150:151], off
	global_load_dword v152, v[150:151], off offset:64
	v_mul_f32_e32 v155, v108, v104
	global_load_dword v156, v[150:151], off offset:128
	global_load_dword v157, v[150:151], off offset:192
	global_load_dword v158, v[150:151], off offset:512
	global_load_dword v159, v[150:151], off offset:576
	global_load_dword v160, v[150:151], off offset:640
	global_load_dword v104, v[150:151], off offset:704
	v_mul_f32_e32 v105, v109, v105
	v_mul_f32_e32 v106, v110, v106
	v_mul_f32_e32 v96, v100, v96
	v_mul_f32_e32 v124, v116, v124
	v_mul_f32_e32 v125, v117, v125
	v_mul_f32_e32 v126, v118, v126
	v_mul_f32_e32 v127, v119, v127
	v_mul_f32_e32 v153, v112, v120
	v_mul_f32_e32 v154, v113, v121
	v_mul_f32_e32 v122, v114, v122
	v_mul_f32_e32 v123, v115, v123
	s_lshl_b32 s8, s69, 7
	s_or_b32 s8, s8, s79
	s_mul_i32 s9, s68, 44
	s_ashr_i32 s8, s8, 6
	s_add_i32 s8, s8, s9
	v_mul_f32_e32 v98, v102, v98
	s_ashr_i32 s9, s8, 31
	s_lshl_b64 s[8:9], s[8:9], 15
	s_add_u32 s68, s28, s8
	s_addc_u32 s69, s29, s9
	v_lshl_add_u64 v[120:121], s[68:69], 0, v[130:131]
	v_mul_f32_e32 v107, v111, v107
	v_mul_f32_e32 v88, v92, v88
	v_mul_f32_e32 v89, v93, v89
	v_mul_f32_e32 v90, v94, v90
	v_mul_f32_e32 v91, v95, v91
	v_mul_f32_e32 v80, v84, v80
	v_mul_f32_e32 v82, v86, v82
	v_mul_f32_e32 v72, v76, v72
	v_mul_f32_e32 v73, v77, v73
	v_mul_f32_e32 v74, v78, v74
	v_mul_f32_e32 v75, v79, v75
	v_mul_f32_e32 v64, v68, v64
	v_mul_f32_e32 v66, v70, v66
	v_mul_f32_e32 v56, v60, v56
	v_mul_f32_e32 v57, v61, v57
	v_mul_f32_e32 v58, v62, v58
	v_mul_f32_e32 v59, v63, v59
	v_mul_f32_e32 v48, v52, v48
	v_mul_f32_e32 v50, v54, v50
	v_mul_f32_e32 v40, v44, v40
	v_mul_f32_e32 v41, v45, v41
	v_mul_f32_e32 v42, v46, v42
	v_mul_f32_e32 v43, v47, v43
	v_mul_f32_e32 v32, v36, v32
	v_mul_f32_e32 v34, v38, v34
	v_mul_f32_e32 v24, v28, v24
	v_mul_f32_e32 v25, v29, v25
	v_mul_f32_e32 v26, v30, v26
	v_mul_f32_e32 v27, v31, v27
	v_mul_f32_e32 v16, v20, v16
	v_mul_f32_e32 v18, v22, v18
	v_mul_f32_e32 v8, v12, v8
	v_mul_f32_e32 v9, v13, v9
	v_mul_f32_e32 v10, v14, v10
	v_mul_f32_e32 v11, v15, v11
	v_mul_f32_e32 v0, v4, v0
	v_mul_f32_e32 v2, v6, v2
	s_waitcnt vmcnt(0)
	v_fmamk_f32 v149, v149, 0x3a800000, v148
	v_fmamk_f32 v150, v152, 0x3a800000, v148
	v_rsq_f32_e32 v152, v150
	v_rsq_f32_e32 v151, v149
	v_mul_f32_e32 v152, 0xbfb8aa3b, v152
	v_mul_f32_e32 v109, v109, v152
	v_exp_f32_e32 v109, v109
	v_mul_f32_e32 v110, v110, v152
	v_exp_f32_e32 v110, v110
	v_mul_f32_e32 v161, v100, v152
	v_fma_f32 v109, v109, v150, v150
	v_rcp_f32_e32 v109, v109
	v_fma_f32 v110, v110, v150, v150
	v_rcp_f32_e32 v110, v110
	v_mul_f32_e32 v151, 0xbfb8aa3b, v151
	v_mul_f32_e32 v105, v105, v109
	v_exp_f32_e32 v109, v161
	v_mul_f32_e32 v106, v106, v110
	v_mul_f32_e32 v110, v101, v152
	v_exp_f32_e32 v110, v110
	v_fma_f32 v109, v109, v150, v150
	v_rcp_f32_e32 v109, v109
	v_mul_f32_e32 v116, v116, v151
	v_mul_f32_e32 v117, v117, v151
	v_mul_f32_e32 v118, v118, v151
	v_mul_f32_e32 v100, v96, v109
	v_mul_f32_e32 v96, v101, v97
	v_fma_f32 v97, v110, v150, v150
	v_mul_f32_e32 v101, v102, v152
	v_rcp_f32_e32 v97, v97
	v_exp_f32_e32 v101, v101
	v_mul_f32_e32 v119, v119, v151
	v_mul_f32_e32 v112, v112, v151
	v_mul_f32_e32 v113, v113, v151
	v_mul_f32_e32 v114, v114, v151
	v_mul_f32_e32 v115, v115, v151
	v_mul_f32_e32 v108, v108, v152
	v_mul_f32_e32 v151, v111, v152
	v_exp_f32_e32 v116, v116
	v_mul_f32_e32 v109, v103, v152
	v_mul_f32_e32 v110, v96, v97
	v_fma_f32 v96, v101, v150, v150
	v_exp_f32_e32 v117, v117
	v_exp_f32_e32 v118, v118
	v_exp_f32_e32 v119, v119
	v_exp_f32_e32 v112, v112
	v_exp_f32_e32 v113, v113
	v_exp_f32_e32 v114, v114
	v_exp_f32_e32 v115, v115
	v_exp_f32_e32 v108, v108
	v_exp_f32_e32 v151, v151
	v_exp_f32_e32 v109, v109
	v_rcp_f32_e32 v96, v96
	v_fma_f32 v116, v116, v149, v149
	v_fmamk_f32 v102, v156, 0x3a800000, v148
	v_fma_f32 v117, v117, v149, v149
	v_fma_f32 v118, v118, v149, v149
	v_fma_f32 v119, v119, v149, v149
	v_fma_f32 v112, v112, v149, v149
	v_fma_f32 v113, v113, v149, v149
	v_fma_f32 v114, v114, v149, v149
	v_fmac_f32_e32 v149, v115, v149
	v_fma_f32 v108, v108, v150, v150
	v_fma_f32 v115, v151, v150, v150
	v_rcp_f32_e32 v116, v116
	v_fmac_f32_e32 v150, v109, v150
	v_mul_f32_e32 v101, v98, v96
	v_mul_f32_e32 v96, v103, v99
	v_rsq_f32_e32 v103, v102
	v_rcp_f32_e32 v117, v117
	v_rcp_f32_e32 v118, v118
	v_rcp_f32_e32 v119, v119
	v_rcp_f32_e32 v112, v112
	v_rcp_f32_e32 v113, v113
	v_rcp_f32_e32 v114, v114
	v_rcp_f32_e32 v149, v149
	v_rcp_f32_e32 v108, v108
	v_rcp_f32_e32 v151, v115
	v_rcp_f32_e32 v97, v150
	v_mul_f32_e32 v115, v124, v116
	v_mul_f32_e32 v103, 0xbfb8aa3b, v103
	v_mul_f32_e32 v116, v125, v117
	v_mul_f32_e32 v117, v126, v118
	v_mul_f32_e32 v118, v127, v119
	v_mul_f32_e32 v119, v153, v112
	v_mul_f32_e32 v124, v154, v113
	v_mul_f32_e32 v122, v122, v114
	v_mul_f32_e32 v123, v123, v149
	v_mul_f32_e32 v108, v155, v108
	v_cvt_pk_bf16_f32 v112, v115, v116
	v_cvt_pk_bf16_f32 v113, v117, v118
	v_cvt_pk_bf16_f32 v114, v119, v124
	v_cvt_pk_bf16_f32 v115, v122, v123
	global_store_dwordx4 v[120:121], v[112:115], off sc1
	v_mul_f32_e32 v107, v107, v151
	v_mul_f32_e32 v99, v96, v97
	v_cvt_pk_bf16_f32 v96, v108, v105
	v_cvt_pk_bf16_f32 v97, v106, v107
	v_mul_f32_e32 v105, v92, v103
	v_mul_f32_e32 v106, v93, v103
	v_mul_f32_e32 v92, v94, v103
	v_mul_f32_e32 v93, v95, v103
	v_exp_f32_e32 v92, v92
	v_exp_f32_e32 v93, v93
	v_mul_f32_e32 v94, v84, v103
	v_exp_f32_e32 v94, v94
	v_fma_f32 v92, v92, v102, v102
	v_fma_f32 v93, v93, v102, v102
	v_rcp_f32_e32 v92, v92
; __device__ __forceinline__ unsigned cvt_pk_bf16(float lo, float hi) { unsigned r; asm volatile("v_cvt_pk_bf16_f32 %0, %1, %2" : "=v"(r) : "v"(lo), "v"(hi)); return r; }
;     __device__ __forceinline__ void operator()(f32x4 (&acc)[2][2][4][2], const Unit& u, int wr, int wc, int fr, int fq) const {
;     ...
;             for (int m = 0; m < 4; ++m) { const float ms = sq[ai][m] * (1.0f / 1024.0f) + 1e-6f, nrl = -__builtin_amdgcn_rsqf(ms) * LOG2E;
;                 float o[8];
; #pragma unroll
;                 for (int n = 0; n < 2; ++n)
; #pragma unroll
;                     for (int e = 0; e < 4; ++e) { const float a = acc[ai][0][m][n][e], bb = acc[ai][1][m][n][e];
;                         o[4 * n + e] = (a * bb) * __builtin_amdgcn_rcpf(__builtin_fmaf(__builtin_amdgcn_exp2f(a * nrl), ms, ms)); }
;                 u32x4 w; w.x = cvt_pk_bf16(o[0], o[1]); w.y = cvt_pk_bf16(o[2], o[3]); w.z = cvt_pk_bf16(o[4], o[5]); w.w = cvt_pk_bf16(o[6], o[7]);
;                 *(u32x4*)((char*)Ob + ai * HTB + lds_byte(wr * 64 + m * 16 + fr, (col0 & 63))) = w; }
	v_rcp_f32_e32 v93, v93
	v_exp_f32_e32 v105, v105
	v_exp_f32_e32 v106, v106
	v_mul_f32_e32 v90, v90, v92
	v_mul_f32_e32 v91, v91, v93
	v_fma_f32 v92, v94, v102, v102
	v_mul_f32_e32 v93, v85, v103
	v_rcp_f32_e32 v92, v92
	v_exp_f32_e32 v93, v93
	v_cvt_pk_bf16_f32 v98, v100, v110
	v_cvt_pk_bf16_f32 v99, v101, v99
	v_mul_f32_e32 v84, v80, v92
	v_mul_f32_e32 v80, v85, v81
	v_fma_f32 v81, v93, v102, v102
	v_mul_f32_e32 v85, v86, v103
	v_rcp_f32_e32 v81, v81
	v_exp_f32_e32 v85, v85
	v_mul_f32_e32 v92, v87, v103
	v_exp_f32_e32 v92, v92
	v_mul_f32_e32 v93, v80, v81
	v_fma_f32 v80, v85, v102, v102
	v_rcp_f32_e32 v80, v80
	v_lshl_add_u64 v[100:101], s[68:69], 0, v[132:133]
	global_store_dwordx4 v[100:101], v[96:99], off sc1
	v_fmamk_f32 v86, v157, 0x3a800000, v148
	v_mul_f32_e32 v85, v82, v80
	v_fma_f32 v96, v105, v102, v102
	v_fma_f32 v97, v106, v102, v102
	v_rcp_f32_e32 v96, v96
	v_rcp_f32_e32 v97, v97
	v_fmac_f32_e32 v102, v92, v102
	v_mul_f32_e32 v80, v87, v83
	v_rsq_f32_e32 v87, v86
	v_rcp_f32_e32 v81, v102
	v_mul_f32_e32 v88, v88, v96
	v_mul_f32_e32 v89, v89, v97
	v_mul_f32_e32 v87, 0xbfb8aa3b, v87
	v_mul_f32_e32 v83, v80, v81
	v_cvt_pk_bf16_f32 v80, v88, v89
	v_mul_f32_e32 v88, v76, v87
	v_mul_f32_e32 v89, v77, v87
	v_mul_f32_e32 v76, v78, v87
	v_mul_f32_e32 v77, v79, v87
	v_exp_f32_e32 v76, v76
	v_exp_f32_e32 v77, v77
	v_mul_f32_e32 v78, v68, v87
	v_exp_f32_e32 v78, v78
	v_fma_f32 v76, v76, v86, v86
	v_fma_f32 v77, v77, v86, v86
	v_rcp_f32_e32 v76, v76
	v_rcp_f32_e32 v77, v77
	v_exp_f32_e32 v88, v88
	v_exp_f32_e32 v89, v89
	v_mul_f32_e32 v74, v74, v76
	v_mul_f32_e32 v75, v75, v77
	v_fma_f32 v76, v78, v86, v86
	v_mul_f32_e32 v77, v69, v87
	v_rcp_f32_e32 v76, v76
	v_exp_f32_e32 v77, v77
	v_cvt_pk_bf16_f32 v81, v90, v91
	v_cvt_pk_bf16_f32 v82, v84, v93
	v_mul_f32_e32 v68, v64, v76
	v_mul_f32_e32 v64, v69, v65
	v_fma_f32 v65, v77, v86, v86
	v_mul_f32_e32 v69, v70, v87
	v_rcp_f32_e32 v65, v65
	v_exp_f32_e32 v69, v69
	v_mul_f32_e32 v76, v71, v87
	v_exp_f32_e32 v76, v76
	v_mul_f32_e32 v77, v64, v65
	v_fma_f32 v64, v69, v86, v86
	v_cvt_pk_bf16_f32 v83, v85, v83
	v_lshl_add_u64 v[84:85], s[68:69], 0, v[134:135]
	v_rcp_f32_e32 v64, v64
	global_store_dwordx4 v[84:85], v[80:83], off sc1
	v_fmamk_f32 v70, v158, 0x3a800000, v148
	v_mul_f32_e32 v69, v66, v64
	v_fma_f32 v80, v88, v86, v86
	v_fma_f32 v81, v89, v86, v86
	v_fmac_f32_e32 v86, v76, v86
	v_rcp_f32_e32 v65, v86
	v_rcp_f32_e32 v80, v80
	v_rcp_f32_e32 v81, v81
	v_mul_f32_e32 v64, v71, v67
	v_rsq_f32_e32 v71, v70
	v_mul_f32_e32 v67, v64, v65
	v_mul_f32_e32 v72, v72, v80
	v_mul_f32_e32 v73, v73, v81
	v_cvt_pk_bf16_f32 v64, v72, v73
	v_cvt_pk_bf16_f32 v65, v74, v75
	v_cvt_pk_bf16_f32 v66, v68, v77
	v_cvt_pk_bf16_f32 v67, v69, v67
	v_lshl_add_u64 v[68:69], s[68:69], 0, v[136:137]
	global_store_dwordx4 v[68:69], v[64:67], off sc1
	s_add_u32 s68, s68, 0x4000
	s_addc_u32 s69, s69, 0
	v_mul_f32_e32 v64, 0xbfb8aa3b, v71
	v_mul_f32_e32 v65, v60, v64
	v_mul_f32_e32 v66, v61, v64
	v_mul_f32_e32 v60, v62, v64
	v_mul_f32_e32 v61, v63, v64
	v_exp_f32_e32 v60, v60
	v_exp_f32_e32 v61, v61
	v_mul_f32_e32 v62, v52, v64
	v_exp_f32_e32 v62, v62
	v_fma_f32 v60, v60, v70, v70
	v_fma_f32 v61, v61, v70, v70
	v_rcp_f32_e32 v60, v60
	v_rcp_f32_e32 v61, v61
	v_exp_f32_e32 v65, v65
	v_exp_f32_e32 v66, v66
	v_mul_f32_e32 v58, v58, v60
	v_mul_f32_e32 v59, v59, v61
	v_fma_f32 v60, v62, v70, v70
	v_mul_f32_e32 v61, v53, v64
	v_rcp_f32_e32 v60, v60
	v_exp_f32_e32 v61, v61
	v_fma_f32 v65, v65, v70, v70
	v_fma_f32 v66, v66, v70, v70
	v_mul_f32_e32 v52, v48, v60
	v_mul_f32_e32 v48, v53, v49
	v_fma_f32 v49, v61, v70, v70
	v_mul_f32_e32 v53, v54, v64
	v_rcp_f32_e32 v49, v49
	v_exp_f32_e32 v53, v53
	v_mul_f32_e32 v60, v55, v64
	v_exp_f32_e32 v60, v60
	v_mul_f32_e32 v61, v48, v49
	v_fma_f32 v48, v53, v70, v70
	v_rcp_f32_e32 v48, v48
	v_fmamk_f32 v54, v159, 0x3a800000, v148
	v_rcp_f32_e32 v65, v65
	v_rcp_f32_e32 v66, v66
	v_fmac_f32_e32 v70, v60, v70
	v_mul_f32_e32 v53, v50, v48
	v_mul_f32_e32 v48, v55, v51
	v_rsq_f32_e32 v55, v54
	v_rcp_f32_e32 v49, v70
	v_mul_f32_e32 v56, v56, v65
	v_mul_f32_e32 v57, v57, v66
	v_mul_f32_e32 v55, 0xbfb8aa3b, v55
	v_mul_f32_e32 v51, v48, v49
	v_cvt_pk_bf16_f32 v48, v56, v57
	v_mul_f32_e32 v56, v44, v55
	v_mul_f32_e32 v57, v45, v55
	v_mul_f32_e32 v44, v46, v55
	v_mul_f32_e32 v45, v47, v55
	v_exp_f32_e32 v44, v44
	v_exp_f32_e32 v45, v45
	v_mul_f32_e32 v46, v36, v55
	v_exp_f32_e32 v46, v46
	v_fma_f32 v44, v44, v54, v54
; __device__ __forceinline__ unsigned cvt_pk_bf16(float lo, float hi) { unsigned r; asm volatile("v_cvt_pk_bf16_f32 %0, %1, %2" : "=v"(r) : "v"(lo), "v"(hi)); return r; }
;     __device__ __forceinline__ void operator()(f32x4 (&acc)[2][2][4][2], const Unit& u, int wr, int wc, int fr, int fq) const {
;     ...
;             for (int m = 0; m < 4; ++m) { const float ms = sq[ai][m] * (1.0f / 1024.0f) + 1e-6f, nrl = -__builtin_amdgcn_rsqf(ms) * LOG2E;
;                 float o[8];
; #pragma unroll
;                 for (int n = 0; n < 2; ++n)
; #pragma unroll
;                     for (int e = 0; e < 4; ++e) { const float a = acc[ai][0][m][n][e], bb = acc[ai][1][m][n][e];
;                         o[4 * n + e] = (a * bb) * __builtin_amdgcn_rcpf(__builtin_fmaf(__builtin_amdgcn_exp2f(a * nrl), ms, ms)); }
;                 u32x4 w; w.x = cvt_pk_bf16(o[0], o[1]); w.y = cvt_pk_bf16(o[2], o[3]); w.z = cvt_pk_bf16(o[4], o[5]); w.w = cvt_pk_bf16(o[6], o[7]);
;                 *(u32x4*)((char*)Ob + ai * HTB + lds_byte(wr * 64 + m * 16 + fr, (col0 & 63))) = w; }
	v_fma_f32 v45, v45, v54, v54
	v_rcp_f32_e32 v44, v44
	v_rcp_f32_e32 v45, v45
	v_exp_f32_e32 v56, v56
	v_exp_f32_e32 v57, v57
	v_mul_f32_e32 v42, v42, v44
	v_mul_f32_e32 v43, v43, v45
	v_fma_f32 v44, v46, v54, v54
	v_mul_f32_e32 v45, v37, v55
	v_rcp_f32_e32 v44, v44
	v_exp_f32_e32 v45, v45
	v_cvt_pk_bf16_f32 v49, v58, v59
	v_cvt_pk_bf16_f32 v50, v52, v61
	v_mul_f32_e32 v36, v32, v44
	v_mul_f32_e32 v32, v37, v33
	v_fma_f32 v33, v45, v54, v54
	v_mul_f32_e32 v37, v38, v55
	v_rcp_f32_e32 v33, v33
	v_exp_f32_e32 v37, v37
	v_mul_f32_e32 v44, v39, v55
	v_exp_f32_e32 v44, v44
	v_mul_f32_e32 v45, v32, v33
	v_fma_f32 v32, v37, v54, v54
	v_rcp_f32_e32 v32, v32
	v_cvt_pk_bf16_f32 v51, v53, v51
	v_lshl_add_u64 v[52:53], s[68:69], 0, v[130:131]
	global_store_dwordx4 v[52:53], v[48:51], off sc1
	v_fmamk_f32 v38, v160, 0x3a800000, v148
	v_mul_f32_e32 v37, v34, v32
	v_fma_f32 v48, v56, v54, v54
	v_fma_f32 v49, v57, v54, v54
	v_rcp_f32_e32 v48, v48
	v_rcp_f32_e32 v49, v49
	v_fmac_f32_e32 v54, v44, v54
	v_mul_f32_e32 v32, v39, v35
	v_rsq_f32_e32 v39, v38
	v_rcp_f32_e32 v33, v54
	v_mul_f32_e32 v40, v40, v48
	v_mul_f32_e32 v41, v41, v49
	v_mul_f32_e32 v39, 0xbfb8aa3b, v39
	v_mul_f32_e32 v35, v32, v33
	v_cvt_pk_bf16_f32 v32, v40, v41
	v_mul_f32_e32 v40, v28, v39
	v_mul_f32_e32 v41, v29, v39
	v_mul_f32_e32 v28, v30, v39
	v_mul_f32_e32 v29, v31, v39
	v_exp_f32_e32 v28, v28
	v_exp_f32_e32 v29, v29
	v_mul_f32_e32 v30, v20, v39
	v_exp_f32_e32 v30, v30
	v_fma_f32 v28, v28, v38, v38
	v_fma_f32 v29, v29, v38, v38
	v_rcp_f32_e32 v28, v28
	v_rcp_f32_e32 v29, v29
	v_exp_f32_e32 v40, v40
	v_exp_f32_e32 v41, v41
	v_mul_f32_e32 v26, v26, v28
	v_mul_f32_e32 v27, v27, v29
	v_fma_f32 v28, v30, v38, v38
	v_mul_f32_e32 v29, v21, v39
	v_rcp_f32_e32 v28, v28
	v_exp_f32_e32 v29, v29
	v_cvt_pk_bf16_f32 v33, v42, v43
	v_cvt_pk_bf16_f32 v34, v36, v45
	v_mul_f32_e32 v20, v16, v28
	v_mul_f32_e32 v16, v21, v17
	v_fma_f32 v17, v29, v38, v38
	v_mul_f32_e32 v21, v22, v39
	v_rcp_f32_e32 v17, v17
	v_exp_f32_e32 v21, v21
	v_mul_f32_e32 v28, v23, v39
	v_exp_f32_e32 v28, v28
	v_mul_f32_e32 v29, v16, v17
	v_fma_f32 v16, v21, v38, v38
	v_rcp_f32_e32 v16, v16
	v_cvt_pk_bf16_f32 v35, v37, v35
	v_lshl_add_u64 v[36:37], s[68:69], 0, v[132:133]
	global_store_dwordx4 v[36:37], v[32:35], off sc1
	v_fmamk_f32 v22, v104, 0x3a800000, v148
	v_mul_f32_e32 v21, v18, v16
	v_fma_f32 v32, v40, v38, v38
	v_fma_f32 v33, v41, v38, v38
	v_rcp_f32_e32 v32, v32
	v_rcp_f32_e32 v33, v33
	v_fmac_f32_e32 v38, v28, v38
	v_mul_f32_e32 v16, v23, v19
	v_rsq_f32_e32 v23, v22
	v_rcp_f32_e32 v17, v38
	v_mul_f32_e32 v24, v24, v32
	v_mul_f32_e32 v25, v25, v33
	v_mul_f32_e32 v23, 0xbfb8aa3b, v23
	v_mul_f32_e32 v19, v16, v17
	v_cvt_pk_bf16_f32 v16, v24, v25
	v_mul_f32_e32 v24, v12, v23
	v_mul_f32_e32 v25, v13, v23
	v_mul_f32_e32 v12, v14, v23
	v_mul_f32_e32 v13, v15, v23
	v_exp_f32_e32 v12, v12
	v_exp_f32_e32 v13, v13
	v_mul_f32_e32 v14, v4, v23
	v_exp_f32_e32 v14, v14
	v_fma_f32 v12, v12, v22, v22
	v_fma_f32 v13, v13, v22, v22
	v_rcp_f32_e32 v12, v12
	v_rcp_f32_e32 v13, v13
	v_exp_f32_e32 v24, v24
	v_exp_f32_e32 v25, v25
	v_mul_f32_e32 v10, v10, v12
	v_mul_f32_e32 v11, v11, v13
	v_fma_f32 v12, v14, v22, v22
	v_mul_f32_e32 v13, v5, v23
	v_rcp_f32_e32 v12, v12
	v_exp_f32_e32 v13, v13
	v_cvt_pk_bf16_f32 v17, v26, v27
	v_cvt_pk_bf16_f32 v18, v20, v29
	v_mul_f32_e32 v4, v0, v12
	v_mul_f32_e32 v0, v5, v1
	v_fma_f32 v1, v13, v22, v22
	v_mul_f32_e32 v5, v6, v23
	v_rcp_f32_e32 v1, v1
	v_exp_f32_e32 v5, v5
	v_mul_f32_e32 v12, v7, v23
	v_exp_f32_e32 v12, v12
	v_cvt_pk_bf16_f32 v19, v21, v19
	v_lshl_add_u64 v[20:21], s[68:69], 0, v[134:135]
	v_mul_f32_e32 v13, v0, v1
	v_fma_f32 v0, v5, v22, v22
	global_store_dwordx4 v[20:21], v[16:19], off sc1
	v_rcp_f32_e32 v0, v0
	s_andn2_b64 vcc, exec, s[2:3]
	v_fma_f32 v16, v24, v22, v22
	v_fma_f32 v17, v25, v22, v22
	v_fmac_f32_e32 v22, v12, v22
	v_rcp_f32_e32 v1, v22
	v_rcp_f32_e32 v16, v16
	v_rcp_f32_e32 v17, v17
	v_mul_f32_e32 v5, v2, v0
	v_mul_f32_e32 v0, v7, v3
	v_mul_f32_e32 v3, v0, v1
	v_mul_f32_e32 v8, v8, v16
	v_mul_f32_e32 v9, v9, v17
	v_cvt_pk_bf16_f32 v0, v8, v9
	v_cvt_pk_bf16_f32 v1, v10, v11
	v_cvt_pk_bf16_f32 v2, v4, v13
	v_cvt_pk_bf16_f32 v3, v5, v3
	v_lshl_add_u64 v[4:5], s[68:69], 0, v[136:137]
	s_mov_b64 s[2:3], -1
	global_store_dwordx4 v[4:5], v[0:3], off sc1
	s_cbranch_vccnz .LBB0_137
	s_andn2_b64 vcc, exec, s[52:53]
	s_cbranch_vccnz .LBB0_136
	s_barrier
	s_branch .LBB0_136

; __device__ __forceinline__ unsigned cvt_pk_bf16(float lo, float hi) { unsigned r; asm volatile("v_cvt_pk_bf16_f32 %0, %1, %2" : "=v"(r) : "v"(lo), "v"(hi)); return r; }
;     __device__ __forceinline__ char* hb_at(const Unit& u, int ai, int m, int bj, int wr, int wc, int fr, int fq) const {
;         return (char*)hb + ((size_t)((u.pm * 16 + u.pn * 4 + bj * 2 + (wc >> 1)) * 2 + ai) * HTB) + lds_byte(wr * 64 + m * 16 + fr, (wc & 1) * 32 + 8 * fq); }
;     __device__ __forceinline__ void operator()(f32x4 (&acc)[2][2][4][2], const Unit& u, int wr, int wc, int fr, int fq) const {
;         const int row0 = u.pm * BM + wr * 64 + fr, col0 = u.pn * BM + wc * 32 + 8 * fq;
;         u32x4 pre[2][4][2];
; #pragma unroll
;         for (int ai = 0; ai < 2; ++ai)
; #pragma unroll
;             for (int m = 0; m < 4; ++m)
; #pragma unroll
;                 for (int bj = 0; bj < 2; ++bj) pre[ai][m][bj] = *(const u32x4*)hb_at(u, ai, m, bj, wr, wc, fr, fq);
; #pragma unroll
;         for (int ai = 0; ai < 2; ++ai)
; #pragma unroll
;             for (int m = 0; m < 4; ++m) { const int row = row0 + ai * HALF + m * 16; float s = 0.f;
; #pragma unroll
;                 for (int bj = 0; bj < 2; ++bj) { const size_t o2 = (size_t)row * 1024 + col0 + bj * HALF; const u32x4 p = pre[ai][m][bj]; const f32x4 a0 = acc[ai][bj][m][0], a1 = acc[ai][bj][m][1];
;                     f32x4 o0, o1; o0[0] = bf_lo(p.x) + a0[0] * alpha; o0[1] = bf_hi(p.x) + a0[1] * alpha; o0[2] = bf_lo(p.y) + a0[2] * alpha; o0[3] = bf_hi(p.y) + a0[3] * alpha;
;                     o1[0] = bf_lo(p.z) + a1[0] * alpha; o1[1] = bf_hi(p.z) + a1[1] * alpha; o1[2] = bf_lo(p.w) + a1[2] * alpha; o1[3] = bf_hi(p.w) + a1[3] * alpha;
;                     s += ((o0[0] * o0[0] + o0[1] * o0[1]) + (o0[2] * o0[2] + o0[3] * o0[3])) + ((o1[0] * o1[0] + o1[1] * o1[1]) + (o1[2] * o1[2] + o1[3] * o1[3]));
;                     u32x4 w; w.x = cvt_pk_bf16(o0[0], o0[1]); w.y = cvt_pk_bf16(o0[2], o0[3]); w.z = cvt_pk_bf16(o1[0], o1[1]); w.w = cvt_pk_bf16(o1[2], o1[3]);
;                     *(u32x4*)hb_at(u, ai, m, bj, wr, wc, fr, fq) = w;
;                     if (out) { *(f32x4*)(out + o2) = o0; *(f32x4*)(out + o2 + 4) = o1; } }
;                 s += __shfl_xor(s, 16); s += __shfl_xor(s, 32);
;                 if (ssq && fq == 0) atomicAdd(ssq + row, s); }
.LBB0_229:
	s_lshl_b32 s8, s72, 3
	s_lshl_b32 s9, s76, 5
	s_add_i32 s9, s9, s8
	s_or_b32 s8, s9, s81
	s_ashr_i32 s9, s8, 31
	s_or_b32 s68, s8, 4
	s_lshl_b64 s[72:73], s[8:9], 14
	s_ashr_i32 s69, s68, 31
	v_lshl_add_u64 v[112:113], v[198:199], 0, s[72:73]
	s_lshl_b64 s[74:75], s[68:69], 14
	global_load_dwordx4 v[220:223], v[112:113], off
	v_lshl_add_u64 v[112:113], v[198:199], 0, s[74:75]
	global_load_dwordx4 v[224:227], v[112:113], off
	s_or_b32 s68, s8, 1
	s_or_b32 s8, s8, 5
	s_ashr_i32 s69, s68, 31
	s_ashr_i32 s9, s8, 31
	s_lshl_b64 s[70:71], s[68:69], 14
	s_lshl_b64 s[68:69], s[8:9], 14
	v_lshl_add_u64 v[112:113], v[200:201], 0, s[72:73]
	v_lshl_add_u64 v[114:115], v[202:203], 0, s[72:73]
	v_lshl_add_u64 v[124:125], v[196:197], 0, s[72:73]
	v_lshl_add_u64 v[126:127], v[200:201], 0, s[74:75]
	v_lshl_add_u64 v[136:137], v[202:203], 0, s[74:75]
	v_lshl_add_u64 v[138:139], v[196:197], 0, s[74:75]
	v_lshl_add_u64 v[140:141], v[198:199], 0, s[70:71]
	v_lshl_add_u64 v[142:143], v[198:199], 0, s[68:69]
	v_lshl_add_u64 v[144:145], v[200:201], 0, s[70:71]
	v_lshl_add_u64 v[146:147], v[200:201], 0, s[68:69]
	v_lshl_add_u64 v[216:217], v[202:203], 0, s[70:71]
	v_lshl_add_u64 v[228:229], v[202:203], 0, s[68:69]
	v_lshl_add_u64 v[230:231], v[196:197], 0, s[70:71]
	v_lshl_add_u64 v[232:233], v[196:197], 0, s[68:69]
	global_load_dwordx4 v[180:183], v[112:113], off
	global_load_dwordx4 v[176:179], v[126:127], off
	global_load_dwordx4 v[172:175], v[114:115], off
	global_load_dwordx4 v[168:171], v[136:137], off
	global_load_dwordx4 v[164:167], v[124:125], off
	global_load_dwordx4 v[160:163], v[138:139], off
	global_load_dwordx4 v[156:159], v[140:141], off
	global_load_dwordx4 v[152:155], v[142:143], off
	global_load_dwordx4 v[148:151], v[144:145], off
	s_nop 0
	global_load_dwordx4 v[144:147], v[146:147], off
	s_nop 0
	global_load_dwordx4 v[140:143], v[216:217], off
	global_load_dwordx4 v[136:139], v[228:229], off
	global_load_dwordx4 v[124:127], v[230:231], off
	global_load_dwordx4 v[112:115], v[232:233], off
	s_add_u32 s72, s12, s72
	s_addc_u32 s73, s13, s73
	v_lshl_add_u64 v[216:217], s[72:73], 0, v[190:191]
	s_add_u32 s74, s12, s74
	v_lshl_add_u32 v208, s76, 8, v189
	s_addc_u32 s75, s13, s75
	s_waitcnt vmcnt(0)
	v_lshlrev_b32_e32 v209, 16, v220
	v_and_b32_e32 v219, 0xffff0000, v220
	v_lshlrev_b32_e32 v220, 16, v221
	v_fmac_f32_e32 v220, 0.5, v134
	v_lshlrev_b32_e32 v134, 16, v225
	v_and_b32_e32 v221, 0xffff0000, v221
	v_lshlrev_b32_e32 v228, 16, v222
	v_and_b32_e32 v222, 0xffff0000, v222
	v_lshlrev_b32_e32 v229, 16, v223
	v_and_b32_e32 v223, 0xffff0000, v223
	v_fmac_f32_e32 v134, 0.5, v122
	v_and_b32_e32 v122, 0xffff0000, v226
	v_fmac_f32_e32 v219, 0.5, v133
	v_fmac_f32_e32 v221, 0.5, v135
	v_fmac_f32_e32 v222, 0.5, v129
	v_fmac_f32_e32 v223, 0.5, v131
	v_and_b32_e32 v133, 0xffff0000, v224
	v_and_b32_e32 v135, 0xffff0000, v225
	v_fmac_f32_e32 v122, 0.5, v117
	v_lshlrev_b32_e32 v117, 16, v227
	v_fmac_f32_e32 v209, 0.5, v132
	v_fmac_f32_e32 v228, 0.5, v128
	v_fmac_f32_e32 v229, 0.5, v130
	v_lshlrev_b32_e32 v132, 16, v224
	v_lshlrev_b32_e32 v224, 16, v226
	v_mul_f32_e32 v225, v219, v219
	v_mul_f32_e32 v230, v221, v221
	v_mul_f32_e32 v231, v222, v222
	v_mul_f32_e32 v232, v223, v223
	v_fmac_f32_e32 v133, 0.5, v121
	v_fmac_f32_e32 v135, 0.5, v123
	v_fmac_f32_e32 v117, 0.5, v118
	v_and_b32_e32 v118, 0xffff0000, v227
	v_fmac_f32_e32 v132, 0.5, v120
	v_fmac_f32_e32 v225, v209, v209
	v_fmac_f32_e32 v230, v220, v220
	v_fmac_f32_e32 v231, v228, v228
	v_fmac_f32_e32 v232, v229, v229
	v_fmac_f32_e32 v224, 0.5, v116
	v_fmac_f32_e32 v118, 0.5, v119
	v_mul_f32_e32 v116, v133, v133
	v_mul_f32_e32 v119, v135, v135
	v_add_f32_e32 v120, v225, v230
	v_add_f32_e32 v121, v231, v232
	v_fmac_f32_e32 v116, v132, v132
	v_fmac_f32_e32 v119, v134, v134
	v_add_f32_e32 v120, v120, v121
	v_add_f32_e32 v116, v116, v119
	v_mul_f32_e32 v119, v122, v122
	v_mul_f32_e32 v121, v118, v118
	v_fmac_f32_e32 v119, v224, v224
	v_fmac_f32_e32 v121, v117, v117
	v_add_f32_e32 v119, v119, v121
	v_cvt_pk_bf16_f32 v128, v209, v219
	v_add_f32_e32 v116, v116, v119
	v_and_b32_e32 v121, 64, v215
	v_cvt_pk_bf16_f32 v129, v220, v221
	v_cvt_pk_bf16_f32 v130, v228, v222
	v_cvt_pk_bf16_f32 v131, v229, v223
	global_store_dwordx4 v[216:217], v[128:131], off sc1
	v_add_f32_e32 v119, v120, v116
	v_xor_b32_e32 v116, 16, v215
	v_add_u32_e32 v128, 64, v121
	v_cmp_lt_i32_e32 vcc, v116, v128
	v_cvt_pk_bf16_f32 v120, v132, v133
	v_cvt_pk_bf16_f32 v121, v134, v135
	v_cvt_pk_bf16_f32 v122, v224, v122
	v_cvt_pk_bf16_f32 v123, v117, v118
	v_xor_b32_e32 v117, 32, v215
	s_nop 0
	v_cndmask_b32_e32 v116, v215, v116, vcc
	v_lshlrev_b32_e32 v116, 2, v116
	ds_bpermute_b32 v129, v116, v119
	v_cmp_lt_i32_e32 vcc, v117, v128
	v_ashrrev_i32_e32 v209, 31, v208
	s_waitcnt lgkmcnt(0)
	v_add_f32_e32 v118, v119, v129
	v_cndmask_b32_e32 v117, v215, v117, vcc
	v_lshlrev_b32_e32 v117, 2, v117
	ds_bpermute_b32 v119, v117, v118
	v_lshl_add_u64 v[128:129], s[74:75], 0, v[190:191]
	global_store_dwordx4 v[128:129], v[120:123], off sc1
	s_and_saveexec_b64 s[76:77], s[2:3]
	s_cbranch_execz .LBB0_231
	v_lshl_add_u64 v[120:121], v[208:209], 2, s[10:11]
	s_waitcnt lgkmcnt(0)
	v_add_f32_e32 v118, v118, v119
	global_atomic_add_f32 v[120:121], v118, off
; __device__ __forceinline__ unsigned cvt_pk_bf16(float lo, float hi) { unsigned r; asm volatile("v_cvt_pk_bf16_f32 %0, %1, %2" : "=v"(r) : "v"(lo), "v"(hi)); return r; }
; __device__ __forceinline__ float bf_lo(unsigned w) { return __uint_as_float(w << 16); }
; __device__ __forceinline__ float bf_hi(unsigned w) { return __uint_as_float(w & 0xffff0000u); }
;     __device__ __forceinline__ void operator()(f32x4 (&acc)[2][2][4][2], const Unit& u, int wr, int wc, int fr, int fq) const {
;     ...
;             for (int m = 0; m < 4; ++m) { const int row = row0 + ai * HALF + m * 16; float s = 0.f;
; #pragma unroll
;                 for (int bj = 0; bj < 2; ++bj) { const size_t o2 = (size_t)row * 1024 + col0 + bj * HALF; const u32x4 p = pre[ai][m][bj]; const f32x4 a0 = acc[ai][bj][m][0], a1 = acc[ai][bj][m][1];
;                     f32x4 o0, o1; o0[0] = bf_lo(p.x) + a0[0] * alpha; o0[1] = bf_hi(p.x) + a0[1] * alpha; o0[2] = bf_lo(p.y) + a0[2] * alpha; o0[3] = bf_hi(p.y) + a0[3] * alpha;
;                     o1[0] = bf_lo(p.z) + a1[0] * alpha; o1[1] = bf_hi(p.z) + a1[1] * alpha; o1[2] = bf_lo(p.w) + a1[2] * alpha; o1[3] = bf_hi(p.w) + a1[3] * alpha;
;                     s += ((o0[0] * o0[0] + o0[1] * o0[1]) + (o0[2] * o0[2] + o0[3] * o0[3])) + ((o1[0] * o1[0] + o1[1] * o1[1]) + (o1[2] * o1[2] + o1[3] * o1[3]));
;                     u32x4 w; w.x = cvt_pk_bf16(o0[0], o0[1]); w.y = cvt_pk_bf16(o0[2], o0[3]); w.z = cvt_pk_bf16(o1[0], o1[1]); w.w = cvt_pk_bf16(o1[2], o1[3]);
;                     *(u32x4*)hb_at(u, ai, m, bj, wr, wc, fr, fq) = w;
;                     if (out) { *(f32x4*)(out + o2) = o0; *(f32x4*)(out + o2 + 4) = o1; } }
;                 s += __shfl_xor(s, 16); s += __shfl_xor(s, 32);
;                 if (ssq && fq == 0) atomicAdd(ssq + row, s); }
.LBB0_231:
	s_or_b64 exec, exec, s[76:77]
	v_lshlrev_b32_e32 v118, 16, v180
	v_fmac_f32_e32 v118, 0.5, v108
	v_and_b32_e32 v108, 0xffff0000, v180
	v_fmac_f32_e32 v108, 0.5, v109
	v_lshlrev_b32_e32 v109, 16, v181
	v_fmac_f32_e32 v109, 0.5, v110
	v_and_b32_e32 v110, 0xffff0000, v181
	v_fmac_f32_e32 v110, 0.5, v111
	v_lshlrev_b32_e32 v111, 16, v182
	s_waitcnt lgkmcnt(0)
	v_and_b32_e32 v119, 0xffff0000, v182
	v_fmac_f32_e32 v111, 0.5, v104
	v_fmac_f32_e32 v119, 0.5, v105
	v_and_b32_e32 v121, 0xffff0000, v183
	v_mul_f32_e32 v104, v108, v108
	v_mul_f32_e32 v105, v110, v110
	v_lshlrev_b32_e32 v120, 16, v183
	v_fmac_f32_e32 v121, 0.5, v107
	v_fmac_f32_e32 v104, v118, v118
	v_fmac_f32_e32 v105, v109, v109
	v_fmac_f32_e32 v120, 0.5, v106
	v_add_f32_e32 v104, v104, v105
	v_mul_f32_e32 v105, v119, v119
	v_mul_f32_e32 v106, v121, v121
	v_fmac_f32_e32 v105, v111, v111
	v_fmac_f32_e32 v106, v120, v120
	v_add_f32_e32 v105, v105, v106
	v_add_f32_e32 v122, v104, v105
	v_cvt_pk_bf16_f32 v104, v118, v108
	v_lshlrev_b32_e32 v108, 16, v176
	v_fmac_f32_e32 v108, 0.5, v100
	v_and_b32_e32 v100, 0xffff0000, v176
	v_fmac_f32_e32 v100, 0.5, v101
	v_lshlrev_b32_e32 v101, 16, v177
	v_fmac_f32_e32 v101, 0.5, v102
	v_and_b32_e32 v102, 0xffff0000, v177
	v_cvt_pk_bf16_f32 v105, v109, v110
	v_fmac_f32_e32 v102, 0.5, v103
	v_lshlrev_b32_e32 v103, 16, v178
	v_and_b32_e32 v109, 0xffff0000, v178
	v_cvt_pk_bf16_f32 v106, v111, v119
	v_fmac_f32_e32 v103, 0.5, v96
	v_fmac_f32_e32 v109, 0.5, v97
	v_and_b32_e32 v111, 0xffff0000, v179
	v_mul_f32_e32 v96, v100, v100
	v_mul_f32_e32 v97, v102, v102
	v_lshlrev_b32_e32 v110, 16, v179
	v_fmac_f32_e32 v111, 0.5, v99
	v_fmac_f32_e32 v96, v108, v108
	v_fmac_f32_e32 v97, v101, v101
	v_fmac_f32_e32 v110, 0.5, v98
	v_add_f32_e32 v96, v96, v97
	v_mul_f32_e32 v97, v109, v109
	v_mul_f32_e32 v98, v111, v111
	v_fmac_f32_e32 v97, v103, v103
	v_fmac_f32_e32 v98, v110, v110
	v_add_f32_e32 v97, v97, v98
	v_add_f32_e32 v96, v96, v97
	v_add_f32_e32 v118, v122, v96
	ds_bpermute_b32 v119, v116, v118
	v_lshl_add_u64 v[96:97], s[72:73], 0, v[192:193]
	v_cvt_pk_bf16_f32 v107, v120, v121
	global_store_dwordx4 v[96:97], v[104:107], off sc1
	v_cvt_pk_bf16_f32 v98, v108, v100
	s_waitcnt lgkmcnt(0)
	v_add_f32_e32 v96, v118, v119
	ds_bpermute_b32 v97, v117, v96
	v_cvt_pk_bf16_f32 v99, v101, v102
	v_cvt_pk_bf16_f32 v100, v103, v109
	v_lshl_add_u64 v[102:103], s[74:75], 0, v[192:193]
	v_cvt_pk_bf16_f32 v101, v110, v111
	global_store_dwordx4 v[102:103], v[98:101], off sc1
	s_and_saveexec_b64 s[76:77], s[2:3]
	s_cbranch_execz .LBB0_233
	v_lshl_add_u64 v[98:99], v[208:209], 2, s[10:11]
	s_waitcnt lgkmcnt(0)
	v_add_f32_e32 v96, v96, v97
	global_atomic_add_f32 v[98:99], v96, off offset:64
.LBB0_233:
	s_or_b64 exec, exec, s[76:77]
	v_lshlrev_b32_e32 v96, 16, v172
	v_fmac_f32_e32 v96, 0.5, v92
	v_and_b32_e32 v92, 0xffff0000, v172
	v_fmac_f32_e32 v92, 0.5, v93
	v_lshlrev_b32_e32 v93, 16, v173
	v_fmac_f32_e32 v93, 0.5, v94
	v_and_b32_e32 v94, 0xffff0000, v173
	v_fmac_f32_e32 v94, 0.5, v95
	v_lshlrev_b32_e32 v95, 16, v174
	s_waitcnt lgkmcnt(0)
	v_and_b32_e32 v97, 0xffff0000, v174
	v_fmac_f32_e32 v95, 0.5, v88
	v_fmac_f32_e32 v97, 0.5, v89
	v_and_b32_e32 v99, 0xffff0000, v175
	v_mul_f32_e32 v88, v92, v92
	v_mul_f32_e32 v89, v94, v94
	v_lshlrev_b32_e32 v98, 16, v175
	v_fmac_f32_e32 v99, 0.5, v91
	v_fmac_f32_e32 v88, v96, v96
	v_fmac_f32_e32 v89, v93, v93
	v_fmac_f32_e32 v98, 0.5, v90
	v_add_f32_e32 v88, v88, v89
	v_mul_f32_e32 v89, v97, v97
	v_mul_f32_e32 v90, v99, v99
	v_fmac_f32_e32 v89, v95, v95
	v_fmac_f32_e32 v90, v98, v98
	v_add_f32_e32 v89, v89, v90
	v_add_f32_e32 v100, v88, v89
	v_cvt_pk_bf16_f32 v88, v96, v92
	v_lshlrev_b32_e32 v92, 16, v168
	v_fmac_f32_e32 v92, 0.5, v84
	v_and_b32_e32 v84, 0xffff0000, v168
	v_fmac_f32_e32 v84, 0.5, v85
	v_lshlrev_b32_e32 v85, 16, v169
	v_fmac_f32_e32 v85, 0.5, v86
	v_and_b32_e32 v86, 0xffff0000, v169
	v_cvt_pk_bf16_f32 v89, v93, v94
	v_fmac_f32_e32 v86, 0.5, v87
	v_lshlrev_b32_e32 v87, 16, v170
	v_and_b32_e32 v93, 0xffff0000, v170
	v_cvt_pk_bf16_f32 v90, v95, v97
	v_fmac_f32_e32 v87, 0.5, v80
	v_fmac_f32_e32 v93, 0.5, v81
	v_and_b32_e32 v95, 0xffff0000, v171
	v_mul_f32_e32 v80, v84, v84
	v_mul_f32_e32 v81, v86, v86
	v_lshlrev_b32_e32 v94, 16, v171
	v_fmac_f32_e32 v95, 0.5, v83
	v_fmac_f32_e32 v80, v92, v92
	v_fmac_f32_e32 v81, v85, v85
	v_fmac_f32_e32 v94, 0.5, v82
	v_add_f32_e32 v80, v80, v81
	v_mul_f32_e32 v81, v93, v93
	v_mul_f32_e32 v82, v95, v95
	v_fmac_f32_e32 v81, v87, v87
	v_fmac_f32_e32 v82, v94, v94
	v_add_f32_e32 v81, v81, v82
	v_add_f32_e32 v80, v80, v81
	v_add_f32_e32 v96, v100, v80
	ds_bpermute_b32 v97, v116, v96
	v_lshl_add_u64 v[80:81], s[72:73], 0, v[194:195]
	v_cvt_pk_bf16_f32 v91, v98, v99
	global_store_dwordx4 v[80:81], v[88:91], off sc1
	v_cvt_pk_bf16_f32 v82, v92, v84
	s_waitcnt lgkmcnt(0)
	v_add_f32_e32 v80, v96, v97
	ds_bpermute_b32 v81, v117, v80
	v_cvt_pk_bf16_f32 v83, v85, v86
	v_cvt_pk_bf16_f32 v84, v87, v93
	v_lshl_add_u64 v[86:87], s[74:75], 0, v[194:195]
	v_cvt_pk_bf16_f32 v85, v94, v95
	global_store_dwordx4 v[86:87], v[82:85], off sc1
	s_and_saveexec_b64 s[76:77], s[2:3]
	s_cbranch_execz .LBB0_235
	v_lshl_add_u64 v[82:83], v[208:209], 2, s[10:11]
	s_waitcnt lgkmcnt(0)
	v_add_f32_e32 v80, v80, v81
	global_atomic_add_f32 v[82:83], v80, off offset:128
; __device__ __forceinline__ unsigned cvt_pk_bf16(float lo, float hi) { unsigned r; asm volatile("v_cvt_pk_bf16_f32 %0, %1, %2" : "=v"(r) : "v"(lo), "v"(hi)); return r; }
; __device__ __forceinline__ float bf_lo(unsigned w) { return __uint_as_float(w << 16); }
; __device__ __forceinline__ float bf_hi(unsigned w) { return __uint_as_float(w & 0xffff0000u); }
;     __device__ __forceinline__ void operator()(f32x4 (&acc)[2][2][4][2], const Unit& u, int wr, int wc, int fr, int fq) const {
;     ...
;             for (int m = 0; m < 4; ++m) { const int row = row0 + ai * HALF + m * 16; float s = 0.f;
; #pragma unroll
;                 for (int bj = 0; bj < 2; ++bj) { const size_t o2 = (size_t)row * 1024 + col0 + bj * HALF; const u32x4 p = pre[ai][m][bj]; const f32x4 a0 = acc[ai][bj][m][0], a1 = acc[ai][bj][m][1];
;                     f32x4 o0, o1; o0[0] = bf_lo(p.x) + a0[0] * alpha; o0[1] = bf_hi(p.x) + a0[1] * alpha; o0[2] = bf_lo(p.y) + a0[2] * alpha; o0[3] = bf_hi(p.y) + a0[3] * alpha;
;                     o1[0] = bf_lo(p.z) + a1[0] * alpha; o1[1] = bf_hi(p.z) + a1[1] * alpha; o1[2] = bf_lo(p.w) + a1[2] * alpha; o1[3] = bf_hi(p.w) + a1[3] * alpha;
;                     s += ((o0[0] * o0[0] + o0[1] * o0[1]) + (o0[2] * o0[2] + o0[3] * o0[3])) + ((o1[0] * o1[0] + o1[1] * o1[1]) + (o1[2] * o1[2] + o1[3] * o1[3]));
;                     u32x4 w; w.x = cvt_pk_bf16(o0[0], o0[1]); w.y = cvt_pk_bf16(o0[2], o0[3]); w.z = cvt_pk_bf16(o1[0], o1[1]); w.w = cvt_pk_bf16(o1[2], o1[3]);
;                     *(u32x4*)hb_at(u, ai, m, bj, wr, wc, fr, fq) = w;
;                     if (out) { *(f32x4*)(out + o2) = o0; *(f32x4*)(out + o2 + 4) = o1; } }
;                 s += __shfl_xor(s, 16); s += __shfl_xor(s, 32);
;                 if (ssq && fq == 0) atomicAdd(ssq + row, s); }
.LBB0_235:
	s_or_b64 exec, exec, s[76:77]
	v_lshlrev_b32_e32 v80, 16, v164
	v_fmac_f32_e32 v80, 0.5, v76
	v_and_b32_e32 v76, 0xffff0000, v164
	v_fmac_f32_e32 v76, 0.5, v77
	v_lshlrev_b32_e32 v77, 16, v165
	v_fmac_f32_e32 v77, 0.5, v78
	v_and_b32_e32 v78, 0xffff0000, v165
	v_fmac_f32_e32 v78, 0.5, v79
	v_lshlrev_b32_e32 v79, 16, v166
	s_waitcnt lgkmcnt(0)
	v_and_b32_e32 v81, 0xffff0000, v166
	v_fmac_f32_e32 v79, 0.5, v72
	v_fmac_f32_e32 v81, 0.5, v73
	v_and_b32_e32 v83, 0xffff0000, v167
	v_mul_f32_e32 v72, v76, v76
	v_mul_f32_e32 v73, v78, v78
	v_lshlrev_b32_e32 v82, 16, v167
	v_fmac_f32_e32 v83, 0.5, v75
	v_fmac_f32_e32 v72, v80, v80
	v_fmac_f32_e32 v73, v77, v77
	v_fmac_f32_e32 v82, 0.5, v74
	v_add_f32_e32 v72, v72, v73
	v_mul_f32_e32 v73, v81, v81
	v_mul_f32_e32 v74, v83, v83
	v_fmac_f32_e32 v73, v79, v79
	v_fmac_f32_e32 v74, v82, v82
	v_add_f32_e32 v73, v73, v74
	v_add_f32_e32 v84, v72, v73
	v_cvt_pk_bf16_f32 v72, v80, v76
	v_lshlrev_b32_e32 v76, 16, v160
	v_fmac_f32_e32 v76, 0.5, v68
	v_and_b32_e32 v68, 0xffff0000, v160
	v_fmac_f32_e32 v68, 0.5, v69
	v_lshlrev_b32_e32 v69, 16, v161
	v_fmac_f32_e32 v69, 0.5, v70
	v_and_b32_e32 v70, 0xffff0000, v161
	v_cvt_pk_bf16_f32 v73, v77, v78
	v_fmac_f32_e32 v70, 0.5, v71
	v_lshlrev_b32_e32 v71, 16, v162
	v_and_b32_e32 v77, 0xffff0000, v162
	v_cvt_pk_bf16_f32 v74, v79, v81
	v_fmac_f32_e32 v71, 0.5, v64
	v_fmac_f32_e32 v77, 0.5, v65
	v_and_b32_e32 v79, 0xffff0000, v163
	v_mul_f32_e32 v64, v68, v68
	v_mul_f32_e32 v65, v70, v70
	v_lshlrev_b32_e32 v78, 16, v163
	v_fmac_f32_e32 v79, 0.5, v67
	v_fmac_f32_e32 v64, v76, v76
	v_fmac_f32_e32 v65, v69, v69
	v_fmac_f32_e32 v78, 0.5, v66
	v_add_f32_e32 v64, v64, v65
	v_mul_f32_e32 v65, v77, v77
	v_mul_f32_e32 v66, v79, v79
	v_fmac_f32_e32 v65, v71, v71
	v_fmac_f32_e32 v66, v78, v78
	v_add_f32_e32 v65, v65, v66
	v_add_f32_e32 v64, v64, v65
	v_add_f32_e32 v80, v84, v64
	ds_bpermute_b32 v81, v116, v80
	v_lshl_add_u64 v[64:65], s[72:73], 0, v[186:187]
	v_cvt_pk_bf16_f32 v75, v82, v83
	global_store_dwordx4 v[64:65], v[72:75], off sc1
	v_cvt_pk_bf16_f32 v66, v76, v68
	s_waitcnt lgkmcnt(0)
	v_add_f32_e32 v64, v80, v81
	ds_bpermute_b32 v65, v117, v64
	v_cvt_pk_bf16_f32 v67, v69, v70
	v_cvt_pk_bf16_f32 v68, v71, v77
	v_lshl_add_u64 v[70:71], s[74:75], 0, v[186:187]
	v_cvt_pk_bf16_f32 v69, v78, v79
	global_store_dwordx4 v[70:71], v[66:69], off sc1
	s_and_saveexec_b64 s[72:73], s[2:3]
	s_cbranch_execz .LBB0_237
	v_lshl_add_u64 v[66:67], v[208:209], 2, s[10:11]
	s_waitcnt lgkmcnt(0)
	v_add_f32_e32 v64, v64, v65
	global_atomic_add_f32 v[66:67], v64, off offset:192
.LBB0_237:
	s_or_b64 exec, exec, s[72:73]
	v_lshlrev_b32_e32 v64, 16, v156
	v_fmac_f32_e32 v64, 0.5, v60
	v_and_b32_e32 v60, 0xffff0000, v156
	v_fmac_f32_e32 v60, 0.5, v61
	v_lshlrev_b32_e32 v61, 16, v157
	v_fmac_f32_e32 v61, 0.5, v62
	v_and_b32_e32 v62, 0xffff0000, v157
	v_fmac_f32_e32 v62, 0.5, v63
	v_lshlrev_b32_e32 v63, 16, v158
	s_waitcnt lgkmcnt(0)
	v_and_b32_e32 v65, 0xffff0000, v158
	v_fmac_f32_e32 v63, 0.5, v56
	v_fmac_f32_e32 v65, 0.5, v57
	v_and_b32_e32 v67, 0xffff0000, v159
	v_mul_f32_e32 v56, v60, v60
	v_mul_f32_e32 v57, v62, v62
	v_lshlrev_b32_e32 v66, 16, v159
	v_fmac_f32_e32 v67, 0.5, v59
	v_fmac_f32_e32 v56, v64, v64
	v_fmac_f32_e32 v57, v61, v61
	v_fmac_f32_e32 v66, 0.5, v58
	v_add_f32_e32 v56, v56, v57
	v_mul_f32_e32 v57, v65, v65
	v_mul_f32_e32 v58, v67, v67
	v_fmac_f32_e32 v57, v63, v63
	v_fmac_f32_e32 v58, v66, v66
	s_add_u32 s70, s12, s70
	v_add_f32_e32 v57, v57, v58
	s_addc_u32 s71, s13, s71
	v_add_f32_e32 v68, v56, v57
	v_cvt_pk_bf16_f32 v56, v64, v60
	v_cvt_pk_bf16_f32 v57, v61, v62
	v_lshl_add_u64 v[60:61], s[70:71], 0, v[190:191]
	v_cvt_pk_bf16_f32 v58, v63, v65
	v_cvt_pk_bf16_f32 v59, v66, v67
	global_store_dwordx4 v[60:61], v[56:59], off sc1
	s_add_u32 s68, s12, s68
	s_addc_u32 s69, s13, s69
	v_lshlrev_b32_e32 v56, 16, v152
	v_fmac_f32_e32 v56, 0.5, v52
	v_and_b32_e32 v52, 0xffff0000, v152
	v_fmac_f32_e32 v52, 0.5, v53
	v_lshlrev_b32_e32 v53, 16, v153
	v_fmac_f32_e32 v53, 0.5, v54
	v_and_b32_e32 v54, 0xffff0000, v153
	v_fmac_f32_e32 v54, 0.5, v55
	v_lshlrev_b32_e32 v55, 16, v154
	v_fmac_f32_e32 v55, 0.5, v48
	v_and_b32_e32 v48, 0xffff0000, v154
	v_fmac_f32_e32 v48, 0.5, v49
	v_lshlrev_b32_e32 v49, 16, v155
	v_and_b32_e32 v57, 0xffff0000, v155
	v_fmac_f32_e32 v49, 0.5, v50
	v_fmac_f32_e32 v57, 0.5, v51
	v_mul_f32_e32 v50, v52, v52
	v_mul_f32_e32 v51, v54, v54
	v_fmac_f32_e32 v50, v56, v56
	v_fmac_f32_e32 v51, v53, v53
	v_add_f32_e32 v50, v50, v51
	v_mul_f32_e32 v51, v48, v48
	v_mul_f32_e32 v58, v57, v57
	v_fmac_f32_e32 v51, v55, v55
	v_fmac_f32_e32 v58, v49, v49
	v_add_f32_e32 v51, v51, v58
	v_add_f32_e32 v50, v50, v51
	v_add_f32_e32 v58, v68, v50
	ds_bpermute_b32 v59, v116, v58
	v_cvt_pk_bf16_f32 v50, v56, v52
	v_cvt_pk_bf16_f32 v51, v53, v54
	v_cvt_pk_bf16_f32 v52, v55, v48
	v_cvt_pk_bf16_f32 v53, v49, v57
	s_waitcnt lgkmcnt(0)
	v_add_f32_e32 v48, v58, v59
	ds_bpermute_b32 v49, v117, v48
	v_lshl_add_u64 v[54:55], s[68:69], 0, v[190:191]
	global_store_dwordx4 v[54:55], v[50:53], off sc1
	s_and_saveexec_b64 s[72:73], s[2:3]
	s_cbranch_execz .LBB0_239
	v_lshl_add_u64 v[50:51], v[208:209], 2, s[10:11]
	s_waitcnt lgkmcnt(0)
	v_add_f32_e32 v48, v48, v49
	global_atomic_add_f32 v[50:51], v48, off offset:512
; __device__ __forceinline__ unsigned cvt_pk_bf16(float lo, float hi) { unsigned r; asm volatile("v_cvt_pk_bf16_f32 %0, %1, %2" : "=v"(r) : "v"(lo), "v"(hi)); return r; }
; __device__ __forceinline__ float bf_lo(unsigned w) { return __uint_as_float(w << 16); }
; __device__ __forceinline__ float bf_hi(unsigned w) { return __uint_as_float(w & 0xffff0000u); }
;     __device__ __forceinline__ void operator()(f32x4 (&acc)[2][2][4][2], const Unit& u, int wr, int wc, int fr, int fq) const {
;     ...
;             for (int m = 0; m < 4; ++m) { const int row = row0 + ai * HALF + m * 16; float s = 0.f;
; #pragma unroll
;                 for (int bj = 0; bj < 2; ++bj) { const size_t o2 = (size_t)row * 1024 + col0 + bj * HALF; const u32x4 p = pre[ai][m][bj]; const f32x4 a0 = acc[ai][bj][m][0], a1 = acc[ai][bj][m][1];
;                     f32x4 o0, o1; o0[0] = bf_lo(p.x) + a0[0] * alpha; o0[1] = bf_hi(p.x) + a0[1] * alpha; o0[2] = bf_lo(p.y) + a0[2] * alpha; o0[3] = bf_hi(p.y) + a0[3] * alpha;
;                     o1[0] = bf_lo(p.z) + a1[0] * alpha; o1[1] = bf_hi(p.z) + a1[1] * alpha; o1[2] = bf_lo(p.w) + a1[2] * alpha; o1[3] = bf_hi(p.w) + a1[3] * alpha;
;                     s += ((o0[0] * o0[0] + o0[1] * o0[1]) + (o0[2] * o0[2] + o0[3] * o0[3])) + ((o1[0] * o1[0] + o1[1] * o1[1]) + (o1[2] * o1[2] + o1[3] * o1[3]));
;                     u32x4 w; w.x = cvt_pk_bf16(o0[0], o0[1]); w.y = cvt_pk_bf16(o0[2], o0[3]); w.z = cvt_pk_bf16(o1[0], o1[1]); w.w = cvt_pk_bf16(o1[2], o1[3]);
;                     *(u32x4*)hb_at(u, ai, m, bj, wr, wc, fr, fq) = w;
;                     if (out) { *(f32x4*)(out + o2) = o0; *(f32x4*)(out + o2 + 4) = o1; } }
;                 s += __shfl_xor(s, 16); s += __shfl_xor(s, 32);
;                 if (ssq && fq == 0) atomicAdd(ssq + row, s); }
.LBB0_239:
	s_or_b64 exec, exec, s[72:73]
	v_lshlrev_b32_e32 v48, 16, v148
	v_fmac_f32_e32 v48, 0.5, v44
	v_and_b32_e32 v44, 0xffff0000, v148
	v_fmac_f32_e32 v44, 0.5, v45
	v_lshlrev_b32_e32 v45, 16, v149
	v_fmac_f32_e32 v45, 0.5, v46
	v_and_b32_e32 v46, 0xffff0000, v149
	v_fmac_f32_e32 v46, 0.5, v47
	v_lshlrev_b32_e32 v47, 16, v150
	s_waitcnt lgkmcnt(0)
	v_and_b32_e32 v49, 0xffff0000, v150
	v_fmac_f32_e32 v47, 0.5, v40
	v_fmac_f32_e32 v49, 0.5, v41
	v_and_b32_e32 v51, 0xffff0000, v151
	v_mul_f32_e32 v40, v44, v44
	v_mul_f32_e32 v41, v46, v46
	v_lshlrev_b32_e32 v50, 16, v151
	v_fmac_f32_e32 v51, 0.5, v43
	v_fmac_f32_e32 v40, v48, v48
	v_fmac_f32_e32 v41, v45, v45
	v_fmac_f32_e32 v50, 0.5, v42
	v_add_f32_e32 v40, v40, v41
	v_mul_f32_e32 v41, v49, v49
	v_mul_f32_e32 v42, v51, v51
	v_fmac_f32_e32 v41, v47, v47
	v_fmac_f32_e32 v42, v50, v50
	v_add_f32_e32 v41, v41, v42
	v_add_f32_e32 v52, v40, v41
	v_cvt_pk_bf16_f32 v40, v48, v44
	v_lshlrev_b32_e32 v44, 16, v144
	v_fmac_f32_e32 v44, 0.5, v36
	v_and_b32_e32 v36, 0xffff0000, v144
	v_fmac_f32_e32 v36, 0.5, v37
	v_lshlrev_b32_e32 v37, 16, v145
	v_fmac_f32_e32 v37, 0.5, v38
	v_and_b32_e32 v38, 0xffff0000, v145
	v_cvt_pk_bf16_f32 v41, v45, v46
	v_fmac_f32_e32 v38, 0.5, v39
	v_lshlrev_b32_e32 v39, 16, v146
	v_and_b32_e32 v45, 0xffff0000, v146
	v_cvt_pk_bf16_f32 v42, v47, v49
	v_fmac_f32_e32 v39, 0.5, v32
	v_fmac_f32_e32 v45, 0.5, v33
	v_and_b32_e32 v47, 0xffff0000, v147
	v_mul_f32_e32 v32, v36, v36
	v_mul_f32_e32 v33, v38, v38
	v_lshlrev_b32_e32 v46, 16, v147
	v_fmac_f32_e32 v47, 0.5, v35
	v_fmac_f32_e32 v32, v44, v44
	v_fmac_f32_e32 v33, v37, v37
	v_fmac_f32_e32 v46, 0.5, v34
	v_add_f32_e32 v32, v32, v33
	v_mul_f32_e32 v33, v45, v45
	v_mul_f32_e32 v34, v47, v47
	v_fmac_f32_e32 v33, v39, v39
	v_fmac_f32_e32 v34, v46, v46
	v_add_f32_e32 v33, v33, v34
	v_add_f32_e32 v32, v32, v33
	v_add_f32_e32 v48, v52, v32
	ds_bpermute_b32 v49, v116, v48
	v_lshl_add_u64 v[32:33], s[70:71], 0, v[192:193]
	v_cvt_pk_bf16_f32 v43, v50, v51
	global_store_dwordx4 v[32:33], v[40:43], off sc1
	v_cvt_pk_bf16_f32 v34, v44, v36
	s_waitcnt lgkmcnt(0)
	v_add_f32_e32 v32, v48, v49
	ds_bpermute_b32 v33, v117, v32
	v_cvt_pk_bf16_f32 v35, v37, v38
	v_cvt_pk_bf16_f32 v36, v39, v45
	v_lshl_add_u64 v[38:39], s[68:69], 0, v[192:193]
	v_cvt_pk_bf16_f32 v37, v46, v47
	global_store_dwordx4 v[38:39], v[34:37], off sc1
	s_and_saveexec_b64 s[72:73], s[2:3]
	s_cbranch_execz .LBB0_241
	v_lshl_add_u64 v[34:35], v[208:209], 2, s[10:11]
	s_waitcnt lgkmcnt(0)
	v_add_f32_e32 v32, v32, v33
	global_atomic_add_f32 v[34:35], v32, off offset:576
; __device__ __forceinline__ unsigned cvt_pk_bf16(float lo, float hi) { unsigned r; asm volatile("v_cvt_pk_bf16_f32 %0, %1, %2" : "=v"(r) : "v"(lo), "v"(hi)); return r; }
; __device__ __forceinline__ float bf_lo(unsigned w) { return __uint_as_float(w << 16); }
; __device__ __forceinline__ float bf_hi(unsigned w) { return __uint_as_float(w & 0xffff0000u); }
;     __device__ __forceinline__ void operator()(f32x4 (&acc)[2][2][4][2], const Unit& u, int wr, int wc, int fr, int fq) const {
;     ...
;             for (int m = 0; m < 4; ++m) { const int row = row0 + ai * HALF + m * 16; float s = 0.f;
; #pragma unroll
;                 for (int bj = 0; bj < 2; ++bj) { const size_t o2 = (size_t)row * 1024 + col0 + bj * HALF; const u32x4 p = pre[ai][m][bj]; const f32x4 a0 = acc[ai][bj][m][0], a1 = acc[ai][bj][m][1];
;                     f32x4 o0, o1; o0[0] = bf_lo(p.x) + a0[0] * alpha; o0[1] = bf_hi(p.x) + a0[1] * alpha; o0[2] = bf_lo(p.y) + a0[2] * alpha; o0[3] = bf_hi(p.y) + a0[3] * alpha;
;                     o1[0] = bf_lo(p.z) + a1[0] * alpha; o1[1] = bf_hi(p.z) + a1[1] * alpha; o1[2] = bf_lo(p.w) + a1[2] * alpha; o1[3] = bf_hi(p.w) + a1[3] * alpha;
;                     s += ((o0[0] * o0[0] + o0[1] * o0[1]) + (o0[2] * o0[2] + o0[3] * o0[3])) + ((o1[0] * o1[0] + o1[1] * o1[1]) + (o1[2] * o1[2] + o1[3] * o1[3]));
;                     u32x4 w; w.x = cvt_pk_bf16(o0[0], o0[1]); w.y = cvt_pk_bf16(o0[2], o0[3]); w.z = cvt_pk_bf16(o1[0], o1[1]); w.w = cvt_pk_bf16(o1[2], o1[3]);
;                     *(u32x4*)hb_at(u, ai, m, bj, wr, wc, fr, fq) = w;
;                     if (out) { *(f32x4*)(out + o2) = o0; *(f32x4*)(out + o2 + 4) = o1; } }
;                 s += __shfl_xor(s, 16); s += __shfl_xor(s, 32);
;                 if (ssq && fq == 0) atomicAdd(ssq + row, s); }
.LBB0_241:
	s_or_b64 exec, exec, s[72:73]
	v_lshlrev_b32_e32 v32, 16, v140
	v_fmac_f32_e32 v32, 0.5, v28
	v_and_b32_e32 v28, 0xffff0000, v140
	v_fmac_f32_e32 v28, 0.5, v29
	v_lshlrev_b32_e32 v29, 16, v141
	v_fmac_f32_e32 v29, 0.5, v30
	v_and_b32_e32 v30, 0xffff0000, v141
	v_fmac_f32_e32 v30, 0.5, v31
	v_lshlrev_b32_e32 v31, 16, v142
	s_waitcnt lgkmcnt(0)
	v_and_b32_e32 v33, 0xffff0000, v142
	v_fmac_f32_e32 v31, 0.5, v24
	v_fmac_f32_e32 v33, 0.5, v25
	v_and_b32_e32 v35, 0xffff0000, v143
	v_mul_f32_e32 v24, v28, v28
	v_mul_f32_e32 v25, v30, v30
	v_lshlrev_b32_e32 v34, 16, v143
	v_fmac_f32_e32 v35, 0.5, v27
	v_fmac_f32_e32 v24, v32, v32
	v_fmac_f32_e32 v25, v29, v29
	v_fmac_f32_e32 v34, 0.5, v26
	v_add_f32_e32 v24, v24, v25
	v_mul_f32_e32 v25, v33, v33
	v_mul_f32_e32 v26, v35, v35
	v_fmac_f32_e32 v25, v31, v31
	v_fmac_f32_e32 v26, v34, v34
	v_add_f32_e32 v25, v25, v26
	v_add_f32_e32 v36, v24, v25
	v_cvt_pk_bf16_f32 v24, v32, v28
	v_lshlrev_b32_e32 v28, 16, v136
	v_fmac_f32_e32 v28, 0.5, v20
	v_and_b32_e32 v20, 0xffff0000, v136
	v_fmac_f32_e32 v20, 0.5, v21
	v_lshlrev_b32_e32 v21, 16, v137
	v_fmac_f32_e32 v21, 0.5, v22
	v_and_b32_e32 v22, 0xffff0000, v137
	v_cvt_pk_bf16_f32 v25, v29, v30
	v_fmac_f32_e32 v22, 0.5, v23
	v_lshlrev_b32_e32 v23, 16, v138
	v_and_b32_e32 v29, 0xffff0000, v138
	v_cvt_pk_bf16_f32 v26, v31, v33
	v_fmac_f32_e32 v23, 0.5, v16
	v_fmac_f32_e32 v29, 0.5, v17
	v_and_b32_e32 v31, 0xffff0000, v139
	v_mul_f32_e32 v16, v20, v20
	v_mul_f32_e32 v17, v22, v22
	v_lshlrev_b32_e32 v30, 16, v139
	v_fmac_f32_e32 v31, 0.5, v19
	v_fmac_f32_e32 v16, v28, v28
	v_fmac_f32_e32 v17, v21, v21
	v_fmac_f32_e32 v30, 0.5, v18
	v_add_f32_e32 v16, v16, v17
	v_mul_f32_e32 v17, v29, v29
	v_mul_f32_e32 v18, v31, v31
	v_fmac_f32_e32 v17, v23, v23
	v_fmac_f32_e32 v18, v30, v30
	v_add_f32_e32 v17, v17, v18
	v_add_f32_e32 v16, v16, v17
	v_add_f32_e32 v32, v36, v16
	ds_bpermute_b32 v33, v116, v32
	v_lshl_add_u64 v[16:17], s[70:71], 0, v[194:195]
	v_cvt_pk_bf16_f32 v27, v34, v35
	global_store_dwordx4 v[16:17], v[24:27], off sc1
	v_cvt_pk_bf16_f32 v18, v28, v20
	s_waitcnt lgkmcnt(0)
	v_add_f32_e32 v16, v32, v33
	ds_bpermute_b32 v17, v117, v16
	v_cvt_pk_bf16_f32 v19, v21, v22
	v_cvt_pk_bf16_f32 v20, v23, v29
	v_lshl_add_u64 v[22:23], s[68:69], 0, v[194:195]
	v_cvt_pk_bf16_f32 v21, v30, v31
	global_store_dwordx4 v[22:23], v[18:21], off sc1
	s_and_saveexec_b64 s[72:73], s[2:3]
	s_cbranch_execz .LBB0_243
	v_lshl_add_u64 v[18:19], v[208:209], 2, s[10:11]
	s_waitcnt lgkmcnt(0)
	v_add_f32_e32 v16, v16, v17
	global_atomic_add_f32 v[18:19], v16, off offset:640
.LBB0_243:
	s_or_b64 exec, exec, s[72:73]
	v_lshlrev_b32_e32 v16, 16, v124
	v_fmac_f32_e32 v16, 0.5, v12
	v_and_b32_e32 v12, 0xffff0000, v124
	v_fmac_f32_e32 v12, 0.5, v13
	v_lshlrev_b32_e32 v13, 16, v125
	v_fmac_f32_e32 v13, 0.5, v14
	v_and_b32_e32 v14, 0xffff0000, v125
	v_fmac_f32_e32 v14, 0.5, v15
	v_lshlrev_b32_e32 v15, 16, v126
	s_waitcnt lgkmcnt(0)
	v_and_b32_e32 v17, 0xffff0000, v126
	v_fmac_f32_e32 v15, 0.5, v8
	v_fmac_f32_e32 v17, 0.5, v9
	v_and_b32_e32 v19, 0xffff0000, v127
	v_mul_f32_e32 v8, v12, v12
	v_mul_f32_e32 v9, v14, v14
	v_lshlrev_b32_e32 v18, 16, v127
	v_fmac_f32_e32 v19, 0.5, v11
	v_fmac_f32_e32 v8, v16, v16
	v_fmac_f32_e32 v9, v13, v13
	v_fmac_f32_e32 v18, 0.5, v10
	v_add_f32_e32 v8, v8, v9
	v_mul_f32_e32 v9, v17, v17
	v_mul_f32_e32 v10, v19, v19
	v_fmac_f32_e32 v9, v15, v15
	v_fmac_f32_e32 v10, v18, v18
	v_add_f32_e32 v9, v9, v10
	v_add_f32_e32 v20, v8, v9
	v_cvt_pk_bf16_f32 v8, v16, v12
	v_lshlrev_b32_e32 v12, 16, v112
	v_fmac_f32_e32 v12, 0.5, v4
	v_and_b32_e32 v4, 0xffff0000, v112
	v_fmac_f32_e32 v4, 0.5, v5
	v_lshlrev_b32_e32 v5, 16, v113
	v_fmac_f32_e32 v5, 0.5, v6
	v_and_b32_e32 v6, 0xffff0000, v113
	v_cvt_pk_bf16_f32 v9, v13, v14
	v_fmac_f32_e32 v6, 0.5, v7
	v_lshlrev_b32_e32 v7, 16, v114
	v_and_b32_e32 v13, 0xffff0000, v114
	v_cvt_pk_bf16_f32 v10, v15, v17
	v_fmac_f32_e32 v7, 0.5, v0
	v_fmac_f32_e32 v13, 0.5, v1
	v_and_b32_e32 v15, 0xffff0000, v115
	v_mul_f32_e32 v0, v4, v4
	v_mul_f32_e32 v1, v6, v6
	v_lshlrev_b32_e32 v14, 16, v115
	v_fmac_f32_e32 v15, 0.5, v3
	v_fmac_f32_e32 v0, v12, v12
	v_fmac_f32_e32 v1, v5, v5
	v_fmac_f32_e32 v14, 0.5, v2
	v_add_f32_e32 v0, v0, v1
	v_mul_f32_e32 v1, v13, v13
	v_mul_f32_e32 v2, v15, v15
	v_fmac_f32_e32 v1, v7, v7
	v_fmac_f32_e32 v2, v14, v14
	v_add_f32_e32 v1, v1, v2
	v_add_f32_e32 v0, v0, v1
	v_add_f32_e32 v16, v20, v0
	ds_bpermute_b32 v17, v116, v16
	v_lshl_add_u64 v[0:1], s[70:71], 0, v[186:187]
	v_cvt_pk_bf16_f32 v11, v18, v19
	global_store_dwordx4 v[0:1], v[8:11], off sc1
	v_cvt_pk_bf16_f32 v2, v12, v4
	s_waitcnt lgkmcnt(0)
	v_add_f32_e32 v0, v16, v17
	ds_bpermute_b32 v1, v117, v0
	v_cvt_pk_bf16_f32 v3, v5, v6
	v_cvt_pk_bf16_f32 v4, v7, v13
	v_lshl_add_u64 v[6:7], s[68:69], 0, v[186:187]
	v_cvt_pk_bf16_f32 v5, v14, v15
	global_store_dwordx4 v[6:7], v[2:5], off sc1
	s_and_saveexec_b64 s[68:69], s[2:3]
	s_cbranch_execz .LBB0_245
	v_lshl_add_u64 v[2:3], v[208:209], 2, s[10:11]
	s_waitcnt lgkmcnt(0)
	v_add_f32_e32 v0, v0, v1
	global_atomic_add_f32 v[2:3], v0, off offset:704

; __device__ __forceinline__ unsigned cvt_pk_bf16(float lo, float hi) { unsigned r; asm volatile("v_cvt_pk_bf16_f32 %0, %1, %2" : "=v"(r) : "v"(lo), "v"(hi)); return r; }
;     __device__ __forceinline__ void operator()(f32x4 (&acc)[2][2][4][2], const Unit& u, int wr, int wc, int fr, int fq) const {
;         const int row0 = u.pm * BM + wr * 64 + fr, col0 = u.pn * BM + wc * 32 + 8 * fq;
;         const bool sig = u.pn >= 7; const float sc = u.pn < 4 ? qscale : 1.f;
;         float sq[2][4];
; #pragma unroll
;         for (int ai = 0; ai < 2; ++ai)
; #pragma unroll
;             for (int m = 0; m < 4; ++m) sq[ai][m] = ssq[row0 + ai * HALF + m * 16];
; #pragma unroll
;         for (int ai = 0; ai < 2; ++ai)
; #pragma unroll
;             for (int m = 0; m < 4; ++m) { const int row = row0 + ai * HALF + m * 16; const float rs = rstd_of(sq[ai][m]) * sc;
;                 u32x4 g8 = {0u, 0u, 0u, 0u};
; #pragma unroll
;                 for (int bj = 0; bj < 2; ++bj) { f32x4 v0 = acc[ai][bj][m][0] * rs, v1 = acc[ai][bj][m][1] * rs;
;                     if (sig) {
; #pragma unroll
;                         for (int e = 0; e < 4; ++e) { v0[e] = sigmoid_f(v0[e]); v1[e] = sigmoid_f(v1[e]); }
;                         unsigned lo = 0u, hi = 0u;
;                         lo = __builtin_amdgcn_cvt_pk_u8_f32(__builtin_rintf(v0[0] * 255.0f), 0, lo); lo = __builtin_amdgcn_cvt_pk_u8_f32(__builtin_rintf(v0[1] * 255.0f), 1, lo);
;                         lo = __builtin_amdgcn_cvt_pk_u8_f32(__builtin_rintf(v0[2] * 255.0f), 2, lo); lo = __builtin_amdgcn_cvt_pk_u8_f32(__builtin_rintf(v0[3] * 255.0f), 3, lo);
;                         hi = __builtin_amdgcn_cvt_pk_u8_f32(__builtin_rintf(v1[0] * 255.0f), 0, hi); hi = __builtin_amdgcn_cvt_pk_u8_f32(__builtin_rintf(v1[1] * 255.0f), 1, hi);
;                         hi = __builtin_amdgcn_cvt_pk_u8_f32(__builtin_rintf(v1[2] * 255.0f), 2, hi); hi = __builtin_amdgcn_cvt_pk_u8_f32(__builtin_rintf(v1[3] * 255.0f), 3, hi);
;                         if (bj == 0) { g8.x = lo; g8.y = hi; } else { g8.z = lo; g8.w = hi; } }
;                     else { u32x4 w; w.x = cvt_pk_bf16(v0[0], v0[1]); w.y = cvt_pk_bf16(v0[2], v0[3]); w.z = cvt_pk_bf16(v1[0], v1[1]); w.w = cvt_pk_bf16(v1[2], v1[3]);
;                         *(u32x4*)(O + (size_t)row * 3840 + col0 + bj * HALF) = w; } }
.LBB0_318:
	v_lshl_add_u32 v140, s72, 8, v157
	v_ashrrev_i32_e32 v141, 31, v140
	v_lshl_add_u64 v[2:3], v[140:141], 2, s[10:11]
	v_or_b32_e32 v148, 16, v140
	global_load_dword v1, v[2:3], off
	v_ashrrev_i32_e32 v149, 31, v148
	v_or_b32_e32 v146, 32, v140
	v_or_b32_e32 v144, 48, v140
	v_lshl_add_u64 v[142:143], v[148:149], 2, s[10:11]
	v_ashrrev_i32_e32 v147, 31, v146
	v_ashrrev_i32_e32 v145, 31, v144
	v_lshl_add_u64 v[150:151], v[146:147], 2, s[10:11]
	v_lshl_add_u64 v[152:153], v[144:145], 2, s[10:11]
	global_load_dword v169, v[142:143], off
	global_load_dword v168, v[150:151], off
	global_load_dword v167, v[152:153], off
	global_load_dword v166, v[2:3], off offset:512
	global_load_dword v149, v[2:3], off offset:576
	global_load_dword v147, v[2:3], off offset:640
	global_load_dword v141, v[2:3], off offset:704
	s_cmp_gt_i32 s6, 6
	s_cselect_b64 s[74:75], -1, 0
	s_cmp_lt_i32 s6, 7
	s_cselect_b64 s[76:77], -1, 0
	s_cmp_lt_i32 s6, 4
	s_cselect_b64 vcc, -1, 0
	v_lshl_or_b32 v142, s6, 8, v158
	v_mad_i64_i32 v[2:3], s[8:9], v140, s81, 0
	v_cndmask_b32_e32 v145, 1.0, v165, vcc
	v_ashrrev_i32_e32 v143, 31, v142
	v_lshl_add_u64 v[2:3], s[28:29], 0, v[2:3]
	s_mov_b64 s[4:5], -1
	s_and_b64 vcc, exec, s[76:77]
	v_lshl_add_u64 v[150:151], v[142:143], 1, v[2:3]
	s_waitcnt vmcnt(0)
	v_fmamk_f32 v1, v1, 0x3a800000, v164
	v_rsq_f32_e32 v1, v1
	s_nop 0
	v_mul_f32_e32 v152, v145, v1
	v_pk_mul_f32 v[130:131], v[130:131], v[152:153] op_sel_hi:[1,0]
	v_pk_mul_f32 v[128:129], v[128:129], v[152:153] op_sel_hi:[1,0]
	v_pk_mul_f32 v[2:3], v[126:127], v[152:153] op_sel_hi:[1,0]
	v_pk_mul_f32 v[124:125], v[124:125], v[152:153] op_sel_hi:[1,0]
	s_cbranch_vccz .LBB0_320
	v_cvt_pk_bf16_f32 v170, v128, v129
	v_cvt_pk_bf16_f32 v171, v130, v131
	v_cvt_pk_bf16_f32 v172, v124, v125
	v_cvt_pk_bf16_f32 v173, v2, v3
	global_store_dwordx4 v[150:151], v[170:173], off sc1
	s_mov_b64 s[4:5], 0

; __device__ __forceinline__ unsigned cvt_pk_bf16(float lo, float hi) { unsigned r; asm volatile("v_cvt_pk_bf16_f32 %0, %1, %2" : "=v"(r) : "v"(lo), "v"(hi)); return r; }
; __device__ __forceinline__ float sigmoid_f(float v) { return __builtin_amdgcn_rcpf(1.0f + __builtin_amdgcn_exp2f(-v * LOG2E)); }
;     __device__ __forceinline__ void operator()(f32x4 (&acc)[2][2][4][2], const Unit& u, int wr, int wc, int fr, int fq) const {
;     ...
;                 for (int bj = 0; bj < 2; ++bj) { f32x4 v0 = acc[ai][bj][m][0] * rs, v1 = acc[ai][bj][m][1] * rs;
;                     if (sig) {
; #pragma unroll
;                         for (int e = 0; e < 4; ++e) { v0[e] = sigmoid_f(v0[e]); v1[e] = sigmoid_f(v1[e]); }
;                         unsigned lo = 0u, hi = 0u;
;                         lo = __builtin_amdgcn_cvt_pk_u8_f32(__builtin_rintf(v0[0] * 255.0f), 0, lo); lo = __builtin_amdgcn_cvt_pk_u8_f32(__builtin_rintf(v0[1] * 255.0f), 1, lo);
;                         lo = __builtin_amdgcn_cvt_pk_u8_f32(__builtin_rintf(v0[2] * 255.0f), 2, lo); lo = __builtin_amdgcn_cvt_pk_u8_f32(__builtin_rintf(v0[3] * 255.0f), 3, lo);
;                         hi = __builtin_amdgcn_cvt_pk_u8_f32(__builtin_rintf(v1[0] * 255.0f), 0, hi); hi = __builtin_amdgcn_cvt_pk_u8_f32(__builtin_rintf(v1[1] * 255.0f), 1, hi);
;                         hi = __builtin_amdgcn_cvt_pk_u8_f32(__builtin_rintf(v1[2] * 255.0f), 2, hi); hi = __builtin_amdgcn_cvt_pk_u8_f32(__builtin_rintf(v1[3] * 255.0f), 3, hi);
;                         if (bj == 0) { g8.x = lo; g8.y = hi; } else { g8.z = lo; g8.w = hi; } }
;                     else { u32x4 w; w.x = cvt_pk_bf16(v0[0], v0[1]); w.y = cvt_pk_bf16(v0[2], v0[3]); w.z = cvt_pk_bf16(v1[0], v1[1]); w.w = cvt_pk_bf16(v1[2], v1[3]);
;                         *(u32x4*)(O + (size_t)row * 3840 + col0 + bj * HALF) = w; } }
.LBB0_323:
	v_mov_b32_e32 v153, v152
	v_mov_b32_e32 v128, v152
	v_mov_b32_e32 v129, v152
	v_cndmask_b32_e64 v1, 0, 1, s[76:77]
	v_pk_mul_f32 v[2:3], v[122:123], v[128:129]
	v_pk_mul_f32 v[120:121], v[120:121], v[152:153]
	v_pk_mul_f32 v[118:119], v[118:119], v[128:129]
	v_pk_mul_f32 v[116:117], v[116:117], v[152:153]
	v_cmp_ne_u32_e64 s[4:5], 1, v1
	s_andn2_b64 vcc, exec, s[76:77]
	s_mov_b64 s[76:77], -1
	s_cbranch_vccnz .LBB0_325
	s_mov_b64 s[76:77], 0
	v_cvt_pk_bf16_f32 v128, v120, v121
	v_cvt_pk_bf16_f32 v129, v2, v3
	v_cvt_pk_bf16_f32 v130, v116, v117
	v_cvt_pk_bf16_f32 v131, v118, v119
	global_store_dwordx4 v[150:151], v[128:131], off offset:256 sc1

; __device__ __forceinline__ unsigned cvt_pk_bf16(float lo, float hi) { unsigned r; asm volatile("v_cvt_pk_bf16_f32 %0, %1, %2" : "=v"(r) : "v"(lo), "v"(hi)); return r; }
; __device__ __forceinline__ float rstd_of(float ssq) { return __builtin_amdgcn_rsqf(ssq * (1.0f / 1024.0f) + 1e-6f); }
; __device__ __forceinline__ float sigmoid_f(float v) { return __builtin_amdgcn_rcpf(1.0f + __builtin_amdgcn_exp2f(-v * LOG2E)); }
;     __device__ __forceinline__ void operator()(f32x4 (&acc)[2][2][4][2], const Unit& u, int wr, int wc, int fr, int fq) const {
;     ...
;             for (int m = 0; m < 4; ++m) { const int row = row0 + ai * HALF + m * 16; const float rs = rstd_of(sq[ai][m]) * sc;
;                 u32x4 g8 = {0u, 0u, 0u, 0u};
; #pragma unroll
;                 for (int bj = 0; bj < 2; ++bj) { f32x4 v0 = acc[ai][bj][m][0] * rs, v1 = acc[ai][bj][m][1] * rs;
;                     if (sig) {
; #pragma unroll
;                         for (int e = 0; e < 4; ++e) { v0[e] = sigmoid_f(v0[e]); v1[e] = sigmoid_f(v1[e]); }
;                         unsigned lo = 0u, hi = 0u;
;                         lo = __builtin_amdgcn_cvt_pk_u8_f32(__builtin_rintf(v0[0] * 255.0f), 0, lo); lo = __builtin_amdgcn_cvt_pk_u8_f32(__builtin_rintf(v0[1] * 255.0f), 1, lo);
;                         lo = __builtin_amdgcn_cvt_pk_u8_f32(__builtin_rintf(v0[2] * 255.0f), 2, lo); lo = __builtin_amdgcn_cvt_pk_u8_f32(__builtin_rintf(v0[3] * 255.0f), 3, lo);
;                         hi = __builtin_amdgcn_cvt_pk_u8_f32(__builtin_rintf(v1[0] * 255.0f), 0, hi); hi = __builtin_amdgcn_cvt_pk_u8_f32(__builtin_rintf(v1[1] * 255.0f), 1, hi);
;                         hi = __builtin_amdgcn_cvt_pk_u8_f32(__builtin_rintf(v1[2] * 255.0f), 2, hi); hi = __builtin_amdgcn_cvt_pk_u8_f32(__builtin_rintf(v1[3] * 255.0f), 3, hi);
;                         if (bj == 0) { g8.x = lo; g8.y = hi; } else { g8.z = lo; g8.w = hi; } }
;                     else { u32x4 w; w.x = cvt_pk_bf16(v0[0], v0[1]); w.y = cvt_pk_bf16(v0[2], v0[3]); w.z = cvt_pk_bf16(v1[0], v1[1]); w.w = cvt_pk_bf16(v1[2], v1[3]);
;                         *(u32x4*)(O + (size_t)row * 3840 + col0 + bj * HALF) = w; } }
;                 if (sig) *(u32x4*)(G8 + ((size_t)(((u.pm * 8 + (u.pn - 7)) * 8 + (wr * 4 + wc)) * 8 + (ai * 4 + m)) * 1024) + (fq * 16 + fr) * 16) = g8; }
.LBB0_327:
	s_lshl_b32 s6, s6, 6
	s_lshl_b32 s8, s72, 9
	s_add_i32 s9, s14, s6
	v_cndmask_b32_e64 v1, 0, 1, s[74:75]
	v_cmp_ne_u32_e64 s[6:7], 1, v1
	s_andn2_b64 vcc, exec, s[74:75]
	s_add_i32 s72, s9, s8
	s_cbranch_vccnz .LBB0_329
	s_ashr_i32 s73, s72, 31
	s_lshl_b64 s[8:9], s[72:73], 10
	v_lshl_add_u64 v[2:3], v[134:135], 0, s[8:9]
	global_store_dwordx4 v[2:3], v[124:127], off sc1
.LBB0_329:
	v_fmamk_f32 v1, v169, 0x3a800000, v164
	v_rsq_f32_e32 v1, v1
	v_mad_i64_i32 v[118:119], s[8:9], v148, s81, 0
	s_mov_b64 s[74:75], -1
	v_mul_f32_e32 v116, v145, v1
	v_pk_mul_f32 v[2:3], v[114:115], v[116:117] op_sel_hi:[1,0]
	v_pk_mul_f32 v[114:115], v[112:113], v[116:117] op_sel_hi:[1,0]
	v_lshl_add_u64 v[112:113], s[28:29], 0, v[118:119]
	v_pk_mul_f32 v[110:111], v[110:111], v[116:117] op_sel_hi:[1,0]
	v_pk_mul_f32 v[108:109], v[108:109], v[116:117] op_sel_hi:[1,0]
	s_and_b64 vcc, exec, s[4:5]
	v_lshl_add_u64 v[112:113], v[142:143], 1, v[112:113]
	s_cbranch_vccnz .LBB0_331
	s_mov_b64 s[74:75], 0
	v_cvt_pk_bf16_f32 v118, v114, v115
	v_cvt_pk_bf16_f32 v119, v2, v3
	v_cvt_pk_bf16_f32 v120, v108, v109
	v_cvt_pk_bf16_f32 v121, v110, v111
	global_store_dwordx4 v[112:113], v[118:121], off sc1

; __device__ __forceinline__ unsigned cvt_pk_bf16(float lo, float hi) { unsigned r; asm volatile("v_cvt_pk_bf16_f32 %0, %1, %2" : "=v"(r) : "v"(lo), "v"(hi)); return r; }
; __device__ __forceinline__ float rstd_of(float ssq) { return __builtin_amdgcn_rsqf(ssq * (1.0f / 1024.0f) + 1e-6f); }
; __device__ __forceinline__ float sigmoid_f(float v) { return __builtin_amdgcn_rcpf(1.0f + __builtin_amdgcn_exp2f(-v * LOG2E)); }
;     __device__ __forceinline__ void operator()(f32x4 (&acc)[2][2][4][2], const Unit& u, int wr, int wc, int fr, int fq) const {
;     ...
;             for (int m = 0; m < 4; ++m) { const int row = row0 + ai * HALF + m * 16; const float rs = rstd_of(sq[ai][m]) * sc;
;                 u32x4 g8 = {0u, 0u, 0u, 0u};
; #pragma unroll
;                 for (int bj = 0; bj < 2; ++bj) { f32x4 v0 = acc[ai][bj][m][0] * rs, v1 = acc[ai][bj][m][1] * rs;
;                     if (sig) {
; #pragma unroll
;                         for (int e = 0; e < 4; ++e) { v0[e] = sigmoid_f(v0[e]); v1[e] = sigmoid_f(v1[e]); }
;                         unsigned lo = 0u, hi = 0u;
;                         lo = __builtin_amdgcn_cvt_pk_u8_f32(__builtin_rintf(v0[0] * 255.0f), 0, lo); lo = __builtin_amdgcn_cvt_pk_u8_f32(__builtin_rintf(v0[1] * 255.0f), 1, lo);
;                         lo = __builtin_amdgcn_cvt_pk_u8_f32(__builtin_rintf(v0[2] * 255.0f), 2, lo); lo = __builtin_amdgcn_cvt_pk_u8_f32(__builtin_rintf(v0[3] * 255.0f), 3, lo);
;                         hi = __builtin_amdgcn_cvt_pk_u8_f32(__builtin_rintf(v1[0] * 255.0f), 0, hi); hi = __builtin_amdgcn_cvt_pk_u8_f32(__builtin_rintf(v1[1] * 255.0f), 1, hi);
;                         hi = __builtin_amdgcn_cvt_pk_u8_f32(__builtin_rintf(v1[2] * 255.0f), 2, hi); hi = __builtin_amdgcn_cvt_pk_u8_f32(__builtin_rintf(v1[3] * 255.0f), 3, hi);
;                         if (bj == 0) { g8.x = lo; g8.y = hi; } else { g8.z = lo; g8.w = hi; } }
;                     else { u32x4 w; w.x = cvt_pk_bf16(v0[0], v0[1]); w.y = cvt_pk_bf16(v0[2], v0[3]); w.z = cvt_pk_bf16(v1[0], v1[1]); w.w = cvt_pk_bf16(v1[2], v1[3]);
;                         *(u32x4*)(O + (size_t)row * 3840 + col0 + bj * HALF) = w; } }
;                 if (sig) *(u32x4*)(G8 + ((size_t)(((u.pm * 8 + (u.pn - 7)) * 8 + (wr * 4 + wc)) * 8 + (ai * 4 + m)) * 1024) + (fq * 16 + fr) * 16) = g8; }
.LBB0_337:
	s_or_b32 s8, s72, 1
	s_ashr_i32 s9, s8, 31
	s_lshl_b64 s[8:9], s[8:9], 10
	v_lshl_add_u64 v[2:3], v[134:135], 0, s[8:9]
	global_store_dwordx4 v[2:3], v[108:111], off sc1
.LBB0_338:
	v_fmamk_f32 v1, v168, 0x3a800000, v164
	v_rsq_f32_e32 v1, v1
	v_mad_i64_i32 v[102:103], s[8:9], v146, s81, 0
	s_mov_b64 s[74:75], -1
	v_mul_f32_e32 v100, v145, v1
	v_pk_mul_f32 v[2:3], v[98:99], v[100:101] op_sel_hi:[1,0]
	v_pk_mul_f32 v[98:99], v[96:97], v[100:101] op_sel_hi:[1,0]
	v_lshl_add_u64 v[96:97], s[28:29], 0, v[102:103]
	v_pk_mul_f32 v[94:95], v[94:95], v[100:101] op_sel_hi:[1,0]
	v_pk_mul_f32 v[92:93], v[92:93], v[100:101] op_sel_hi:[1,0]
	s_and_b64 vcc, exec, s[4:5]
	v_lshl_add_u64 v[96:97], v[142:143], 1, v[96:97]
	s_cbranch_vccnz .LBB0_340
	s_mov_b64 s[74:75], 0
	v_cvt_pk_bf16_f32 v102, v98, v99
	v_cvt_pk_bf16_f32 v103, v2, v3
	v_cvt_pk_bf16_f32 v104, v92, v93
	v_cvt_pk_bf16_f32 v105, v94, v95
	global_store_dwordx4 v[96:97], v[102:105], off sc1

; __device__ __forceinline__ unsigned cvt_pk_bf16(float lo, float hi) { unsigned r; asm volatile("v_cvt_pk_bf16_f32 %0, %1, %2" : "=v"(r) : "v"(lo), "v"(hi)); return r; }
; __device__ __forceinline__ float sigmoid_f(float v) { return __builtin_amdgcn_rcpf(1.0f + __builtin_amdgcn_exp2f(-v * LOG2E)); }
;     __device__ __forceinline__ void operator()(f32x4 (&acc)[2][2][4][2], const Unit& u, int wr, int wc, int fr, int fq) const {
;     ...
;                 for (int bj = 0; bj < 2; ++bj) { f32x4 v0 = acc[ai][bj][m][0] * rs, v1 = acc[ai][bj][m][1] * rs;
;                     if (sig) {
; #pragma unroll
;                         for (int e = 0; e < 4; ++e) { v0[e] = sigmoid_f(v0[e]); v1[e] = sigmoid_f(v1[e]); }
;                         unsigned lo = 0u, hi = 0u;
;                         lo = __builtin_amdgcn_cvt_pk_u8_f32(__builtin_rintf(v0[0] * 255.0f), 0, lo); lo = __builtin_amdgcn_cvt_pk_u8_f32(__builtin_rintf(v0[1] * 255.0f), 1, lo);
;                         lo = __builtin_amdgcn_cvt_pk_u8_f32(__builtin_rintf(v0[2] * 255.0f), 2, lo); lo = __builtin_amdgcn_cvt_pk_u8_f32(__builtin_rintf(v0[3] * 255.0f), 3, lo);
;                         hi = __builtin_amdgcn_cvt_pk_u8_f32(__builtin_rintf(v1[0] * 255.0f), 0, hi); hi = __builtin_amdgcn_cvt_pk_u8_f32(__builtin_rintf(v1[1] * 255.0f), 1, hi);
;                         hi = __builtin_amdgcn_cvt_pk_u8_f32(__builtin_rintf(v1[2] * 255.0f), 2, hi); hi = __builtin_amdgcn_cvt_pk_u8_f32(__builtin_rintf(v1[3] * 255.0f), 3, hi);
;                         if (bj == 0) { g8.x = lo; g8.y = hi; } else { g8.z = lo; g8.w = hi; } }
;                     else { u32x4 w; w.x = cvt_pk_bf16(v0[0], v0[1]); w.y = cvt_pk_bf16(v0[2], v0[3]); w.z = cvt_pk_bf16(v1[0], v1[1]); w.w = cvt_pk_bf16(v1[2], v1[3]);
;                         *(u32x4*)(O + (size_t)row * 3840 + col0 + bj * HALF) = w; } }
.LBB0_342:
	v_cvt_pk_bf16_f32 v114, v104, v105
	v_cvt_pk_bf16_f32 v115, v2, v3
	v_cvt_pk_bf16_f32 v116, v100, v101
	v_cvt_pk_bf16_f32 v117, v102, v103
	global_store_dwordx4 v[112:113], v[114:117], off offset:256 sc1
	s_cbranch_execnz .LBB0_336

; __device__ __forceinline__ unsigned cvt_pk_bf16(float lo, float hi) { unsigned r; asm volatile("v_cvt_pk_bf16_f32 %0, %1, %2" : "=v"(r) : "v"(lo), "v"(hi)); return r; }
; __device__ __forceinline__ float rstd_of(float ssq) { return __builtin_amdgcn_rsqf(ssq * (1.0f / 1024.0f) + 1e-6f); }
; __device__ __forceinline__ float sigmoid_f(float v) { return __builtin_amdgcn_rcpf(1.0f + __builtin_amdgcn_exp2f(-v * LOG2E)); }
;     __device__ __forceinline__ void operator()(f32x4 (&acc)[2][2][4][2], const Unit& u, int wr, int wc, int fr, int fq) const {
;     ...
;             for (int m = 0; m < 4; ++m) { const int row = row0 + ai * HALF + m * 16; const float rs = rstd_of(sq[ai][m]) * sc;
;                 u32x4 g8 = {0u, 0u, 0u, 0u};
; #pragma unroll
;                 for (int bj = 0; bj < 2; ++bj) { f32x4 v0 = acc[ai][bj][m][0] * rs, v1 = acc[ai][bj][m][1] * rs;
;                     if (sig) {
; #pragma unroll
;                         for (int e = 0; e < 4; ++e) { v0[e] = sigmoid_f(v0[e]); v1[e] = sigmoid_f(v1[e]); }
;                         unsigned lo = 0u, hi = 0u;
;                         lo = __builtin_amdgcn_cvt_pk_u8_f32(__builtin_rintf(v0[0] * 255.0f), 0, lo); lo = __builtin_amdgcn_cvt_pk_u8_f32(__builtin_rintf(v0[1] * 255.0f), 1, lo);
;                         lo = __builtin_amdgcn_cvt_pk_u8_f32(__builtin_rintf(v0[2] * 255.0f), 2, lo); lo = __builtin_amdgcn_cvt_pk_u8_f32(__builtin_rintf(v0[3] * 255.0f), 3, lo);
;                         hi = __builtin_amdgcn_cvt_pk_u8_f32(__builtin_rintf(v1[0] * 255.0f), 0, hi); hi = __builtin_amdgcn_cvt_pk_u8_f32(__builtin_rintf(v1[1] * 255.0f), 1, hi);
;                         hi = __builtin_amdgcn_cvt_pk_u8_f32(__builtin_rintf(v1[2] * 255.0f), 2, hi); hi = __builtin_amdgcn_cvt_pk_u8_f32(__builtin_rintf(v1[3] * 255.0f), 3, hi);
;                         if (bj == 0) { g8.x = lo; g8.y = hi; } else { g8.z = lo; g8.w = hi; } }
;                     else { u32x4 w; w.x = cvt_pk_bf16(v0[0], v0[1]); w.y = cvt_pk_bf16(v0[2], v0[3]); w.z = cvt_pk_bf16(v1[0], v1[1]); w.w = cvt_pk_bf16(v1[2], v1[3]);
;                         *(u32x4*)(O + (size_t)row * 3840 + col0 + bj * HALF) = w; } }
;                 if (sig) *(u32x4*)(G8 + ((size_t)(((u.pm * 8 + (u.pn - 7)) * 8 + (wr * 4 + wc)) * 8 + (ai * 4 + m)) * 1024) + (fq * 16 + fr) * 16) = g8; }
.LBB0_348:
	s_or_b32 s8, s72, 2
	s_ashr_i32 s9, s8, 31
	s_lshl_b64 s[8:9], s[8:9], 10
	v_lshl_add_u64 v[2:3], v[134:135], 0, s[8:9]
	global_store_dwordx4 v[2:3], v[92:95], off sc1
.LBB0_349:
	v_fmamk_f32 v1, v167, 0x3a800000, v164
	v_rsq_f32_e32 v1, v1
	v_mad_i64_i32 v[86:87], s[8:9], v144, s81, 0
	s_mov_b64 s[74:75], -1
	v_mul_f32_e32 v84, v145, v1
	v_pk_mul_f32 v[2:3], v[82:83], v[84:85] op_sel_hi:[1,0]
	v_pk_mul_f32 v[82:83], v[80:81], v[84:85] op_sel_hi:[1,0]
	v_lshl_add_u64 v[80:81], s[28:29], 0, v[86:87]
	v_pk_mul_f32 v[78:79], v[78:79], v[84:85] op_sel_hi:[1,0]
	v_pk_mul_f32 v[76:77], v[76:77], v[84:85] op_sel_hi:[1,0]
	s_and_b64 vcc, exec, s[4:5]
	v_lshl_add_u64 v[80:81], v[142:143], 1, v[80:81]
	s_cbranch_vccnz .LBB0_351
	s_mov_b64 s[74:75], 0
	v_cvt_pk_bf16_f32 v86, v82, v83
	v_cvt_pk_bf16_f32 v87, v2, v3
	v_cvt_pk_bf16_f32 v88, v76, v77
	v_cvt_pk_bf16_f32 v89, v78, v79
	global_store_dwordx4 v[80:81], v[86:89], off sc1

; __device__ __forceinline__ unsigned cvt_pk_bf16(float lo, float hi) { unsigned r; asm volatile("v_cvt_pk_bf16_f32 %0, %1, %2" : "=v"(r) : "v"(lo), "v"(hi)); return r; }
; __device__ __forceinline__ float sigmoid_f(float v) { return __builtin_amdgcn_rcpf(1.0f + __builtin_amdgcn_exp2f(-v * LOG2E)); }
;     __device__ __forceinline__ void operator()(f32x4 (&acc)[2][2][4][2], const Unit& u, int wr, int wc, int fr, int fq) const {
;     ...
;                 for (int bj = 0; bj < 2; ++bj) { f32x4 v0 = acc[ai][bj][m][0] * rs, v1 = acc[ai][bj][m][1] * rs;
;                     if (sig) {
; #pragma unroll
;                         for (int e = 0; e < 4; ++e) { v0[e] = sigmoid_f(v0[e]); v1[e] = sigmoid_f(v1[e]); }
;                         unsigned lo = 0u, hi = 0u;
;                         lo = __builtin_amdgcn_cvt_pk_u8_f32(__builtin_rintf(v0[0] * 255.0f), 0, lo); lo = __builtin_amdgcn_cvt_pk_u8_f32(__builtin_rintf(v0[1] * 255.0f), 1, lo);
;                         lo = __builtin_amdgcn_cvt_pk_u8_f32(__builtin_rintf(v0[2] * 255.0f), 2, lo); lo = __builtin_amdgcn_cvt_pk_u8_f32(__builtin_rintf(v0[3] * 255.0f), 3, lo);
;                         hi = __builtin_amdgcn_cvt_pk_u8_f32(__builtin_rintf(v1[0] * 255.0f), 0, hi); hi = __builtin_amdgcn_cvt_pk_u8_f32(__builtin_rintf(v1[1] * 255.0f), 1, hi);
;                         hi = __builtin_amdgcn_cvt_pk_u8_f32(__builtin_rintf(v1[2] * 255.0f), 2, hi); hi = __builtin_amdgcn_cvt_pk_u8_f32(__builtin_rintf(v1[3] * 255.0f), 3, hi);
;                         if (bj == 0) { g8.x = lo; g8.y = hi; } else { g8.z = lo; g8.w = hi; } }
;                     else { u32x4 w; w.x = cvt_pk_bf16(v0[0], v0[1]); w.y = cvt_pk_bf16(v0[2], v0[3]); w.z = cvt_pk_bf16(v1[0], v1[1]); w.w = cvt_pk_bf16(v1[2], v1[3]);
;                         *(u32x4*)(O + (size_t)row * 3840 + col0 + bj * HALF) = w; } }
.LBB0_353:
	v_cvt_pk_bf16_f32 v98, v88, v89
	v_cvt_pk_bf16_f32 v99, v2, v3
	v_cvt_pk_bf16_f32 v100, v84, v85
	v_cvt_pk_bf16_f32 v101, v86, v87
	global_store_dwordx4 v[96:97], v[98:101], off offset:256 sc1
	s_cbranch_execnz .LBB0_347

; __device__ __forceinline__ unsigned cvt_pk_bf16(float lo, float hi) { unsigned r; asm volatile("v_cvt_pk_bf16_f32 %0, %1, %2" : "=v"(r) : "v"(lo), "v"(hi)); return r; }
; __device__ __forceinline__ float rstd_of(float ssq) { return __builtin_amdgcn_rsqf(ssq * (1.0f / 1024.0f) + 1e-6f); }
; __device__ __forceinline__ float sigmoid_f(float v) { return __builtin_amdgcn_rcpf(1.0f + __builtin_amdgcn_exp2f(-v * LOG2E)); }
;     __device__ __forceinline__ void operator()(f32x4 (&acc)[2][2][4][2], const Unit& u, int wr, int wc, int fr, int fq) const {
;     ...
;             for (int m = 0; m < 4; ++m) { const int row = row0 + ai * HALF + m * 16; const float rs = rstd_of(sq[ai][m]) * sc;
;                 u32x4 g8 = {0u, 0u, 0u, 0u};
; #pragma unroll
;                 for (int bj = 0; bj < 2; ++bj) { f32x4 v0 = acc[ai][bj][m][0] * rs, v1 = acc[ai][bj][m][1] * rs;
;                     if (sig) {
; #pragma unroll
;                         for (int e = 0; e < 4; ++e) { v0[e] = sigmoid_f(v0[e]); v1[e] = sigmoid_f(v1[e]); }
;                         unsigned lo = 0u, hi = 0u;
;                         lo = __builtin_amdgcn_cvt_pk_u8_f32(__builtin_rintf(v0[0] * 255.0f), 0, lo); lo = __builtin_amdgcn_cvt_pk_u8_f32(__builtin_rintf(v0[1] * 255.0f), 1, lo);
;                         lo = __builtin_amdgcn_cvt_pk_u8_f32(__builtin_rintf(v0[2] * 255.0f), 2, lo); lo = __builtin_amdgcn_cvt_pk_u8_f32(__builtin_rintf(v0[3] * 255.0f), 3, lo);
;                         hi = __builtin_amdgcn_cvt_pk_u8_f32(__builtin_rintf(v1[0] * 255.0f), 0, hi); hi = __builtin_amdgcn_cvt_pk_u8_f32(__builtin_rintf(v1[1] * 255.0f), 1, hi);
;                         hi = __builtin_amdgcn_cvt_pk_u8_f32(__builtin_rintf(v1[2] * 255.0f), 2, hi); hi = __builtin_amdgcn_cvt_pk_u8_f32(__builtin_rintf(v1[3] * 255.0f), 3, hi);
;                         if (bj == 0) { g8.x = lo; g8.y = hi; } else { g8.z = lo; g8.w = hi; } }
;                     else { u32x4 w; w.x = cvt_pk_bf16(v0[0], v0[1]); w.y = cvt_pk_bf16(v0[2], v0[3]); w.z = cvt_pk_bf16(v1[0], v1[1]); w.w = cvt_pk_bf16(v1[2], v1[3]);
;                         *(u32x4*)(O + (size_t)row * 3840 + col0 + bj * HALF) = w; } }
;                 if (sig) *(u32x4*)(G8 + ((size_t)(((u.pm * 8 + (u.pn - 7)) * 8 + (wr * 4 + wc)) * 8 + (ai * 4 + m)) * 1024) + (fq * 16 + fr) * 16) = g8; }
.LBB0_359:
	s_or_b32 s8, s72, 3
	s_ashr_i32 s9, s8, 31
	s_lshl_b64 s[8:9], s[8:9], 10
	v_lshl_add_u64 v[2:3], v[134:135], 0, s[8:9]
	global_store_dwordx4 v[2:3], v[76:79], off sc1
.LBB0_360:
	v_fmamk_f32 v1, v166, 0x3a800000, v164
	v_rsq_f32_e32 v1, v1
	v_add_u32_e32 v2, 0x80, v140
	v_mad_i64_i32 v[70:71], s[8:9], v2, s81, 0
	v_mul_f32_e32 v68, v145, v1
	v_pk_mul_f32 v[2:3], v[66:67], v[68:69] op_sel_hi:[1,0]
	v_pk_mul_f32 v[66:67], v[64:65], v[68:69] op_sel_hi:[1,0]
	v_lshl_add_u64 v[64:65], s[28:29], 0, v[70:71]
	v_pk_mul_f32 v[62:63], v[62:63], v[68:69] op_sel_hi:[1,0]
	v_pk_mul_f32 v[60:61], v[60:61], v[68:69] op_sel_hi:[1,0]
	s_mov_b64 s[74:75], -1
	s_and_b64 vcc, exec, s[4:5]
	v_lshl_add_u64 v[64:65], v[142:143], 1, v[64:65]
	s_cbranch_vccnz .LBB0_362
	s_mov_b64 s[74:75], 0
	v_cvt_pk_bf16_f32 v70, v66, v67
	v_cvt_pk_bf16_f32 v71, v2, v3
	v_cvt_pk_bf16_f32 v72, v60, v61
	v_cvt_pk_bf16_f32 v73, v62, v63
	global_store_dwordx4 v[64:65], v[70:73], off sc1

; __device__ __forceinline__ unsigned cvt_pk_bf16(float lo, float hi) { unsigned r; asm volatile("v_cvt_pk_bf16_f32 %0, %1, %2" : "=v"(r) : "v"(lo), "v"(hi)); return r; }
; __device__ __forceinline__ float sigmoid_f(float v) { return __builtin_amdgcn_rcpf(1.0f + __builtin_amdgcn_exp2f(-v * LOG2E)); }
;     __device__ __forceinline__ void operator()(f32x4 (&acc)[2][2][4][2], const Unit& u, int wr, int wc, int fr, int fq) const {
;     ...
;                 for (int bj = 0; bj < 2; ++bj) { f32x4 v0 = acc[ai][bj][m][0] * rs, v1 = acc[ai][bj][m][1] * rs;
;                     if (sig) {
; #pragma unroll
;                         for (int e = 0; e < 4; ++e) { v0[e] = sigmoid_f(v0[e]); v1[e] = sigmoid_f(v1[e]); }
;                         unsigned lo = 0u, hi = 0u;
;                         lo = __builtin_amdgcn_cvt_pk_u8_f32(__builtin_rintf(v0[0] * 255.0f), 0, lo); lo = __builtin_amdgcn_cvt_pk_u8_f32(__builtin_rintf(v0[1] * 255.0f), 1, lo);
;                         lo = __builtin_amdgcn_cvt_pk_u8_f32(__builtin_rintf(v0[2] * 255.0f), 2, lo); lo = __builtin_amdgcn_cvt_pk_u8_f32(__builtin_rintf(v0[3] * 255.0f), 3, lo);
;                         hi = __builtin_amdgcn_cvt_pk_u8_f32(__builtin_rintf(v1[0] * 255.0f), 0, hi); hi = __builtin_amdgcn_cvt_pk_u8_f32(__builtin_rintf(v1[1] * 255.0f), 1, hi);
;                         hi = __builtin_amdgcn_cvt_pk_u8_f32(__builtin_rintf(v1[2] * 255.0f), 2, hi); hi = __builtin_amdgcn_cvt_pk_u8_f32(__builtin_rintf(v1[3] * 255.0f), 3, hi);
;                         if (bj == 0) { g8.x = lo; g8.y = hi; } else { g8.z = lo; g8.w = hi; } }
;                     else { u32x4 w; w.x = cvt_pk_bf16(v0[0], v0[1]); w.y = cvt_pk_bf16(v0[2], v0[3]); w.z = cvt_pk_bf16(v1[0], v1[1]); w.w = cvt_pk_bf16(v1[2], v1[3]);
;                         *(u32x4*)(O + (size_t)row * 3840 + col0 + bj * HALF) = w; } }
.LBB0_364:
	v_cvt_pk_bf16_f32 v82, v72, v73
	v_cvt_pk_bf16_f32 v83, v2, v3
	v_cvt_pk_bf16_f32 v84, v68, v69
	v_cvt_pk_bf16_f32 v85, v70, v71
	global_store_dwordx4 v[80:81], v[82:85], off offset:256 sc1
	s_cbranch_execnz .LBB0_358

; __device__ __forceinline__ unsigned cvt_pk_bf16(float lo, float hi) { unsigned r; asm volatile("v_cvt_pk_bf16_f32 %0, %1, %2" : "=v"(r) : "v"(lo), "v"(hi)); return r; }
; __device__ __forceinline__ float rstd_of(float ssq) { return __builtin_amdgcn_rsqf(ssq * (1.0f / 1024.0f) + 1e-6f); }
; __device__ __forceinline__ float sigmoid_f(float v) { return __builtin_amdgcn_rcpf(1.0f + __builtin_amdgcn_exp2f(-v * LOG2E)); }
;     __device__ __forceinline__ void operator()(f32x4 (&acc)[2][2][4][2], const Unit& u, int wr, int wc, int fr, int fq) const {
;     ...
;             for (int m = 0; m < 4; ++m) { const int row = row0 + ai * HALF + m * 16; const float rs = rstd_of(sq[ai][m]) * sc;
;                 u32x4 g8 = {0u, 0u, 0u, 0u};
; #pragma unroll
;                 for (int bj = 0; bj < 2; ++bj) { f32x4 v0 = acc[ai][bj][m][0] * rs, v1 = acc[ai][bj][m][1] * rs;
;                     if (sig) {
; #pragma unroll
;                         for (int e = 0; e < 4; ++e) { v0[e] = sigmoid_f(v0[e]); v1[e] = sigmoid_f(v1[e]); }
;                         unsigned lo = 0u, hi = 0u;
;                         lo = __builtin_amdgcn_cvt_pk_u8_f32(__builtin_rintf(v0[0] * 255.0f), 0, lo); lo = __builtin_amdgcn_cvt_pk_u8_f32(__builtin_rintf(v0[1] * 255.0f), 1, lo);
;                         lo = __builtin_amdgcn_cvt_pk_u8_f32(__builtin_rintf(v0[2] * 255.0f), 2, lo); lo = __builtin_amdgcn_cvt_pk_u8_f32(__builtin_rintf(v0[3] * 255.0f), 3, lo);
;                         hi = __builtin_amdgcn_cvt_pk_u8_f32(__builtin_rintf(v1[0] * 255.0f), 0, hi); hi = __builtin_amdgcn_cvt_pk_u8_f32(__builtin_rintf(v1[1] * 255.0f), 1, hi);
;                         hi = __builtin_amdgcn_cvt_pk_u8_f32(__builtin_rintf(v1[2] * 255.0f), 2, hi); hi = __builtin_amdgcn_cvt_pk_u8_f32(__builtin_rintf(v1[3] * 255.0f), 3, hi);
;                         if (bj == 0) { g8.x = lo; g8.y = hi; } else { g8.z = lo; g8.w = hi; } }
;                     else { u32x4 w; w.x = cvt_pk_bf16(v0[0], v0[1]); w.y = cvt_pk_bf16(v0[2], v0[3]); w.z = cvt_pk_bf16(v1[0], v1[1]); w.w = cvt_pk_bf16(v1[2], v1[3]);
;                         *(u32x4*)(O + (size_t)row * 3840 + col0 + bj * HALF) = w; } }
;                 if (sig) *(u32x4*)(G8 + ((size_t)(((u.pm * 8 + (u.pn - 7)) * 8 + (wr * 4 + wc)) * 8 + (ai * 4 + m)) * 1024) + (fq * 16 + fr) * 16) = g8; }
.LBB0_370:
	s_or_b32 s8, s72, 4
	s_ashr_i32 s9, s8, 31
	s_lshl_b64 s[8:9], s[8:9], 10
	v_lshl_add_u64 v[2:3], v[134:135], 0, s[8:9]
	global_store_dwordx4 v[2:3], v[60:63], off sc1
.LBB0_371:
	v_fmamk_f32 v1, v149, 0x3a800000, v164
	v_rsq_f32_e32 v1, v1
	v_add_u32_e32 v2, 0x90, v140
	v_mad_i64_i32 v[54:55], s[8:9], v2, s81, 0
	v_mul_f32_e32 v52, v145, v1
	v_pk_mul_f32 v[2:3], v[50:51], v[52:53] op_sel_hi:[1,0]
	v_pk_mul_f32 v[50:51], v[48:49], v[52:53] op_sel_hi:[1,0]
	v_lshl_add_u64 v[48:49], s[28:29], 0, v[54:55]
	v_pk_mul_f32 v[46:47], v[46:47], v[52:53] op_sel_hi:[1,0]
	v_pk_mul_f32 v[44:45], v[44:45], v[52:53] op_sel_hi:[1,0]
	s_mov_b64 s[74:75], -1
	s_and_b64 vcc, exec, s[4:5]
	v_lshl_add_u64 v[48:49], v[142:143], 1, v[48:49]
	s_cbranch_vccnz .LBB0_373
	s_mov_b64 s[74:75], 0
	v_cvt_pk_bf16_f32 v54, v50, v51
	v_cvt_pk_bf16_f32 v55, v2, v3
	v_cvt_pk_bf16_f32 v56, v44, v45
	v_cvt_pk_bf16_f32 v57, v46, v47
	global_store_dwordx4 v[48:49], v[54:57], off sc1

; __device__ __forceinline__ unsigned cvt_pk_bf16(float lo, float hi) { unsigned r; asm volatile("v_cvt_pk_bf16_f32 %0, %1, %2" : "=v"(r) : "v"(lo), "v"(hi)); return r; }
; __device__ __forceinline__ float sigmoid_f(float v) { return __builtin_amdgcn_rcpf(1.0f + __builtin_amdgcn_exp2f(-v * LOG2E)); }
;     __device__ __forceinline__ void operator()(f32x4 (&acc)[2][2][4][2], const Unit& u, int wr, int wc, int fr, int fq) const {
;     ...
;                 for (int bj = 0; bj < 2; ++bj) { f32x4 v0 = acc[ai][bj][m][0] * rs, v1 = acc[ai][bj][m][1] * rs;
;                     if (sig) {
; #pragma unroll
;                         for (int e = 0; e < 4; ++e) { v0[e] = sigmoid_f(v0[e]); v1[e] = sigmoid_f(v1[e]); }
;                         unsigned lo = 0u, hi = 0u;
;                         lo = __builtin_amdgcn_cvt_pk_u8_f32(__builtin_rintf(v0[0] * 255.0f), 0, lo); lo = __builtin_amdgcn_cvt_pk_u8_f32(__builtin_rintf(v0[1] * 255.0f), 1, lo);
;                         lo = __builtin_amdgcn_cvt_pk_u8_f32(__builtin_rintf(v0[2] * 255.0f), 2, lo); lo = __builtin_amdgcn_cvt_pk_u8_f32(__builtin_rintf(v0[3] * 255.0f), 3, lo);
;                         hi = __builtin_amdgcn_cvt_pk_u8_f32(__builtin_rintf(v1[0] * 255.0f), 0, hi); hi = __builtin_amdgcn_cvt_pk_u8_f32(__builtin_rintf(v1[1] * 255.0f), 1, hi);
;                         hi = __builtin_amdgcn_cvt_pk_u8_f32(__builtin_rintf(v1[2] * 255.0f), 2, hi); hi = __builtin_amdgcn_cvt_pk_u8_f32(__builtin_rintf(v1[3] * 255.0f), 3, hi);
;                         if (bj == 0) { g8.x = lo; g8.y = hi; } else { g8.z = lo; g8.w = hi; } }
;                     else { u32x4 w; w.x = cvt_pk_bf16(v0[0], v0[1]); w.y = cvt_pk_bf16(v0[2], v0[3]); w.z = cvt_pk_bf16(v1[0], v1[1]); w.w = cvt_pk_bf16(v1[2], v1[3]);
;                         *(u32x4*)(O + (size_t)row * 3840 + col0 + bj * HALF) = w; } }
.LBB0_375:
	v_cvt_pk_bf16_f32 v66, v56, v57
	v_cvt_pk_bf16_f32 v67, v2, v3
	v_cvt_pk_bf16_f32 v68, v52, v53
	v_cvt_pk_bf16_f32 v69, v54, v55
	global_store_dwordx4 v[64:65], v[66:69], off offset:256 sc1
	s_cbranch_execnz .LBB0_369

; __device__ __forceinline__ unsigned cvt_pk_bf16(float lo, float hi) { unsigned r; asm volatile("v_cvt_pk_bf16_f32 %0, %1, %2" : "=v"(r) : "v"(lo), "v"(hi)); return r; }
; __device__ __forceinline__ float rstd_of(float ssq) { return __builtin_amdgcn_rsqf(ssq * (1.0f / 1024.0f) + 1e-6f); }
; __device__ __forceinline__ float sigmoid_f(float v) { return __builtin_amdgcn_rcpf(1.0f + __builtin_amdgcn_exp2f(-v * LOG2E)); }
;     __device__ __forceinline__ void operator()(f32x4 (&acc)[2][2][4][2], const Unit& u, int wr, int wc, int fr, int fq) const {
;     ...
;             for (int m = 0; m < 4; ++m) { const int row = row0 + ai * HALF + m * 16; const float rs = rstd_of(sq[ai][m]) * sc;
;                 u32x4 g8 = {0u, 0u, 0u, 0u};
; #pragma unroll
;                 for (int bj = 0; bj < 2; ++bj) { f32x4 v0 = acc[ai][bj][m][0] * rs, v1 = acc[ai][bj][m][1] * rs;
;                     if (sig) {
; #pragma unroll
;                         for (int e = 0; e < 4; ++e) { v0[e] = sigmoid_f(v0[e]); v1[e] = sigmoid_f(v1[e]); }
;                         unsigned lo = 0u, hi = 0u;
;                         lo = __builtin_amdgcn_cvt_pk_u8_f32(__builtin_rintf(v0[0] * 255.0f), 0, lo); lo = __builtin_amdgcn_cvt_pk_u8_f32(__builtin_rintf(v0[1] * 255.0f), 1, lo);
;                         lo = __builtin_amdgcn_cvt_pk_u8_f32(__builtin_rintf(v0[2] * 255.0f), 2, lo); lo = __builtin_amdgcn_cvt_pk_u8_f32(__builtin_rintf(v0[3] * 255.0f), 3, lo);
;                         hi = __builtin_amdgcn_cvt_pk_u8_f32(__builtin_rintf(v1[0] * 255.0f), 0, hi); hi = __builtin_amdgcn_cvt_pk_u8_f32(__builtin_rintf(v1[1] * 255.0f), 1, hi);
;                         hi = __builtin_amdgcn_cvt_pk_u8_f32(__builtin_rintf(v1[2] * 255.0f), 2, hi); hi = __builtin_amdgcn_cvt_pk_u8_f32(__builtin_rintf(v1[3] * 255.0f), 3, hi);
;                         if (bj == 0) { g8.x = lo; g8.y = hi; } else { g8.z = lo; g8.w = hi; } }
;                     else { u32x4 w; w.x = cvt_pk_bf16(v0[0], v0[1]); w.y = cvt_pk_bf16(v0[2], v0[3]); w.z = cvt_pk_bf16(v1[0], v1[1]); w.w = cvt_pk_bf16(v1[2], v1[3]);
;                         *(u32x4*)(O + (size_t)row * 3840 + col0 + bj * HALF) = w; } }
;                 if (sig) *(u32x4*)(G8 + ((size_t)(((u.pm * 8 + (u.pn - 7)) * 8 + (wr * 4 + wc)) * 8 + (ai * 4 + m)) * 1024) + (fq * 16 + fr) * 16) = g8; }
.LBB0_381:
	s_or_b32 s8, s72, 5
	s_ashr_i32 s9, s8, 31
	s_lshl_b64 s[8:9], s[8:9], 10
	v_lshl_add_u64 v[2:3], v[134:135], 0, s[8:9]
	global_store_dwordx4 v[2:3], v[44:47], off sc1
.LBB0_382:
	v_fmamk_f32 v1, v147, 0x3a800000, v164
	v_rsq_f32_e32 v1, v1
	v_add_u32_e32 v2, 0xa0, v140
	v_mad_i64_i32 v[38:39], s[8:9], v2, s81, 0
	v_mul_f32_e32 v36, v145, v1
	v_pk_mul_f32 v[2:3], v[34:35], v[36:37] op_sel_hi:[1,0]
	v_pk_mul_f32 v[34:35], v[32:33], v[36:37] op_sel_hi:[1,0]
	v_lshl_add_u64 v[32:33], s[28:29], 0, v[38:39]
	v_pk_mul_f32 v[30:31], v[30:31], v[36:37] op_sel_hi:[1,0]
	v_pk_mul_f32 v[28:29], v[28:29], v[36:37] op_sel_hi:[1,0]
	s_mov_b64 s[74:75], -1
	s_and_b64 vcc, exec, s[4:5]
	v_lshl_add_u64 v[32:33], v[142:143], 1, v[32:33]
	s_cbranch_vccnz .LBB0_384
	s_mov_b64 s[74:75], 0
	v_cvt_pk_bf16_f32 v38, v34, v35
	v_cvt_pk_bf16_f32 v39, v2, v3
	v_cvt_pk_bf16_f32 v40, v28, v29
	v_cvt_pk_bf16_f32 v41, v30, v31
	global_store_dwordx4 v[32:33], v[38:41], off sc1

; __device__ __forceinline__ unsigned cvt_pk_bf16(float lo, float hi) { unsigned r; asm volatile("v_cvt_pk_bf16_f32 %0, %1, %2" : "=v"(r) : "v"(lo), "v"(hi)); return r; }
; __device__ __forceinline__ float sigmoid_f(float v) { return __builtin_amdgcn_rcpf(1.0f + __builtin_amdgcn_exp2f(-v * LOG2E)); }
;     __device__ __forceinline__ void operator()(f32x4 (&acc)[2][2][4][2], const Unit& u, int wr, int wc, int fr, int fq) const {
;     ...
;                 for (int bj = 0; bj < 2; ++bj) { f32x4 v0 = acc[ai][bj][m][0] * rs, v1 = acc[ai][bj][m][1] * rs;
;                     if (sig) {
; #pragma unroll
;                         for (int e = 0; e < 4; ++e) { v0[e] = sigmoid_f(v0[e]); v1[e] = sigmoid_f(v1[e]); }
;                         unsigned lo = 0u, hi = 0u;
;                         lo = __builtin_amdgcn_cvt_pk_u8_f32(__builtin_rintf(v0[0] * 255.0f), 0, lo); lo = __builtin_amdgcn_cvt_pk_u8_f32(__builtin_rintf(v0[1] * 255.0f), 1, lo);
;                         lo = __builtin_amdgcn_cvt_pk_u8_f32(__builtin_rintf(v0[2] * 255.0f), 2, lo); lo = __builtin_amdgcn_cvt_pk_u8_f32(__builtin_rintf(v0[3] * 255.0f), 3, lo);
;                         hi = __builtin_amdgcn_cvt_pk_u8_f32(__builtin_rintf(v1[0] * 255.0f), 0, hi); hi = __builtin_amdgcn_cvt_pk_u8_f32(__builtin_rintf(v1[1] * 255.0f), 1, hi);
;                         hi = __builtin_amdgcn_cvt_pk_u8_f32(__builtin_rintf(v1[2] * 255.0f), 2, hi); hi = __builtin_amdgcn_cvt_pk_u8_f32(__builtin_rintf(v1[3] * 255.0f), 3, hi);
;                         if (bj == 0) { g8.x = lo; g8.y = hi; } else { g8.z = lo; g8.w = hi; } }
;                     else { u32x4 w; w.x = cvt_pk_bf16(v0[0], v0[1]); w.y = cvt_pk_bf16(v0[2], v0[3]); w.z = cvt_pk_bf16(v1[0], v1[1]); w.w = cvt_pk_bf16(v1[2], v1[3]);
;                         *(u32x4*)(O + (size_t)row * 3840 + col0 + bj * HALF) = w; } }
.LBB0_386:
	v_cvt_pk_bf16_f32 v50, v40, v41
	v_cvt_pk_bf16_f32 v51, v2, v3
	v_cvt_pk_bf16_f32 v52, v36, v37
	v_cvt_pk_bf16_f32 v53, v38, v39
	global_store_dwordx4 v[48:49], v[50:53], off offset:256 sc1
	s_cbranch_execnz .LBB0_380

; __device__ __forceinline__ unsigned cvt_pk_bf16(float lo, float hi) { unsigned r; asm volatile("v_cvt_pk_bf16_f32 %0, %1, %2" : "=v"(r) : "v"(lo), "v"(hi)); return r; }
; __device__ __forceinline__ float rstd_of(float ssq) { return __builtin_amdgcn_rsqf(ssq * (1.0f / 1024.0f) + 1e-6f); }
; __device__ __forceinline__ float sigmoid_f(float v) { return __builtin_amdgcn_rcpf(1.0f + __builtin_amdgcn_exp2f(-v * LOG2E)); }
;     __device__ __forceinline__ void operator()(f32x4 (&acc)[2][2][4][2], const Unit& u, int wr, int wc, int fr, int fq) const {
;     ...
;             for (int m = 0; m < 4; ++m) { const int row = row0 + ai * HALF + m * 16; const float rs = rstd_of(sq[ai][m]) * sc;
;                 u32x4 g8 = {0u, 0u, 0u, 0u};
; #pragma unroll
;                 for (int bj = 0; bj < 2; ++bj) { f32x4 v0 = acc[ai][bj][m][0] * rs, v1 = acc[ai][bj][m][1] * rs;
;                     if (sig) {
; #pragma unroll
;                         for (int e = 0; e < 4; ++e) { v0[e] = sigmoid_f(v0[e]); v1[e] = sigmoid_f(v1[e]); }
;                         unsigned lo = 0u, hi = 0u;
;                         lo = __builtin_amdgcn_cvt_pk_u8_f32(__builtin_rintf(v0[0] * 255.0f), 0, lo); lo = __builtin_amdgcn_cvt_pk_u8_f32(__builtin_rintf(v0[1] * 255.0f), 1, lo);
;                         lo = __builtin_amdgcn_cvt_pk_u8_f32(__builtin_rintf(v0[2] * 255.0f), 2, lo); lo = __builtin_amdgcn_cvt_pk_u8_f32(__builtin_rintf(v0[3] * 255.0f), 3, lo);
;                         hi = __builtin_amdgcn_cvt_pk_u8_f32(__builtin_rintf(v1[0] * 255.0f), 0, hi); hi = __builtin_amdgcn_cvt_pk_u8_f32(__builtin_rintf(v1[1] * 255.0f), 1, hi);
;                         hi = __builtin_amdgcn_cvt_pk_u8_f32(__builtin_rintf(v1[2] * 255.0f), 2, hi); hi = __builtin_amdgcn_cvt_pk_u8_f32(__builtin_rintf(v1[3] * 255.0f), 3, hi);
;                         if (bj == 0) { g8.x = lo; g8.y = hi; } else { g8.z = lo; g8.w = hi; } }
;                     else { u32x4 w; w.x = cvt_pk_bf16(v0[0], v0[1]); w.y = cvt_pk_bf16(v0[2], v0[3]); w.z = cvt_pk_bf16(v1[0], v1[1]); w.w = cvt_pk_bf16(v1[2], v1[3]);
;                         *(u32x4*)(O + (size_t)row * 3840 + col0 + bj * HALF) = w; } }
;                 if (sig) *(u32x4*)(G8 + ((size_t)(((u.pm * 8 + (u.pn - 7)) * 8 + (wr * 4 + wc)) * 8 + (ai * 4 + m)) * 1024) + (fq * 16 + fr) * 16) = g8; }
.LBB0_392:
	s_or_b32 s8, s72, 6
	s_ashr_i32 s9, s8, 31
	s_lshl_b64 s[8:9], s[8:9], 10
	v_lshl_add_u64 v[2:3], v[134:135], 0, s[8:9]
	global_store_dwordx4 v[2:3], v[28:31], off sc1
.LBB0_393:
	v_fmamk_f32 v1, v141, 0x3a800000, v164
	v_rsq_f32_e32 v1, v1
	v_add_u32_e32 v2, 0xb0, v140
	v_mad_i64_i32 v[22:23], s[8:9], v2, s81, 0
	v_mul_f32_e32 v20, v145, v1
	v_pk_mul_f32 v[2:3], v[18:19], v[20:21] op_sel_hi:[1,0]
	v_pk_mul_f32 v[18:19], v[16:17], v[20:21] op_sel_hi:[1,0]
	v_lshl_add_u64 v[16:17], s[28:29], 0, v[22:23]
	v_pk_mul_f32 v[14:15], v[14:15], v[20:21] op_sel_hi:[1,0]
	v_pk_mul_f32 v[12:13], v[12:13], v[20:21] op_sel_hi:[1,0]
	s_mov_b64 s[74:75], -1
	s_and_b64 vcc, exec, s[4:5]
	v_lshl_add_u64 v[16:17], v[142:143], 1, v[16:17]
	s_cbranch_vccnz .LBB0_395
	s_mov_b64 s[74:75], 0
	v_cvt_pk_bf16_f32 v22, v18, v19
	v_cvt_pk_bf16_f32 v23, v2, v3
	v_cvt_pk_bf16_f32 v24, v12, v13
	v_cvt_pk_bf16_f32 v25, v14, v15
	global_store_dwordx4 v[16:17], v[22:25], off sc1

; __device__ __forceinline__ unsigned cvt_pk_bf16(float lo, float hi) { unsigned r; asm volatile("v_cvt_pk_bf16_f32 %0, %1, %2" : "=v"(r) : "v"(lo), "v"(hi)); return r; }
; __device__ __forceinline__ float sigmoid_f(float v) { return __builtin_amdgcn_rcpf(1.0f + __builtin_amdgcn_exp2f(-v * LOG2E)); }
;     __device__ __forceinline__ void operator()(f32x4 (&acc)[2][2][4][2], const Unit& u, int wr, int wc, int fr, int fq) const {
;     ...
;                 for (int bj = 0; bj < 2; ++bj) { f32x4 v0 = acc[ai][bj][m][0] * rs, v1 = acc[ai][bj][m][1] * rs;
;                     if (sig) {
; #pragma unroll
;                         for (int e = 0; e < 4; ++e) { v0[e] = sigmoid_f(v0[e]); v1[e] = sigmoid_f(v1[e]); }
;                         unsigned lo = 0u, hi = 0u;
;                         lo = __builtin_amdgcn_cvt_pk_u8_f32(__builtin_rintf(v0[0] * 255.0f), 0, lo); lo = __builtin_amdgcn_cvt_pk_u8_f32(__builtin_rintf(v0[1] * 255.0f), 1, lo);
;                         lo = __builtin_amdgcn_cvt_pk_u8_f32(__builtin_rintf(v0[2] * 255.0f), 2, lo); lo = __builtin_amdgcn_cvt_pk_u8_f32(__builtin_rintf(v0[3] * 255.0f), 3, lo);
;                         hi = __builtin_amdgcn_cvt_pk_u8_f32(__builtin_rintf(v1[0] * 255.0f), 0, hi); hi = __builtin_amdgcn_cvt_pk_u8_f32(__builtin_rintf(v1[1] * 255.0f), 1, hi);
;                         hi = __builtin_amdgcn_cvt_pk_u8_f32(__builtin_rintf(v1[2] * 255.0f), 2, hi); hi = __builtin_amdgcn_cvt_pk_u8_f32(__builtin_rintf(v1[3] * 255.0f), 3, hi);
;                         if (bj == 0) { g8.x = lo; g8.y = hi; } else { g8.z = lo; g8.w = hi; } }
;                     else { u32x4 w; w.x = cvt_pk_bf16(v0[0], v0[1]); w.y = cvt_pk_bf16(v0[2], v0[3]); w.z = cvt_pk_bf16(v1[0], v1[1]); w.w = cvt_pk_bf16(v1[2], v1[3]);
;                         *(u32x4*)(O + (size_t)row * 3840 + col0 + bj * HALF) = w; } }
.LBB0_397:
	v_cvt_pk_bf16_f32 v34, v24, v25
	v_cvt_pk_bf16_f32 v35, v2, v3
	v_cvt_pk_bf16_f32 v36, v20, v21
	v_cvt_pk_bf16_f32 v37, v22, v23
	global_store_dwordx4 v[32:33], v[34:37], off offset:256 sc1
	s_cbranch_execnz .LBB0_391

; __device__ __forceinline__ unsigned cvt_pk_bf16(float lo, float hi) { unsigned r; asm volatile("v_cvt_pk_bf16_f32 %0, %1, %2" : "=v"(r) : "v"(lo), "v"(hi)); return r; }
; __device__ __forceinline__ float sigmoid_f(float v) { return __builtin_amdgcn_rcpf(1.0f + __builtin_amdgcn_exp2f(-v * LOG2E)); }
;     __device__ __forceinline__ void operator()(f32x4 (&acc)[2][2][4][2], const Unit& u, int wr, int wc, int fr, int fq) const {
;     ...
;                 for (int bj = 0; bj < 2; ++bj) { f32x4 v0 = acc[ai][bj][m][0] * rs, v1 = acc[ai][bj][m][1] * rs;
;                     if (sig) {
; #pragma unroll
;                         for (int e = 0; e < 4; ++e) { v0[e] = sigmoid_f(v0[e]); v1[e] = sigmoid_f(v1[e]); }
;                         unsigned lo = 0u, hi = 0u;
;                         lo = __builtin_amdgcn_cvt_pk_u8_f32(__builtin_rintf(v0[0] * 255.0f), 0, lo); lo = __builtin_amdgcn_cvt_pk_u8_f32(__builtin_rintf(v0[1] * 255.0f), 1, lo);
;                         lo = __builtin_amdgcn_cvt_pk_u8_f32(__builtin_rintf(v0[2] * 255.0f), 2, lo); lo = __builtin_amdgcn_cvt_pk_u8_f32(__builtin_rintf(v0[3] * 255.0f), 3, lo);
;                         hi = __builtin_amdgcn_cvt_pk_u8_f32(__builtin_rintf(v1[0] * 255.0f), 0, hi); hi = __builtin_amdgcn_cvt_pk_u8_f32(__builtin_rintf(v1[1] * 255.0f), 1, hi);
;                         hi = __builtin_amdgcn_cvt_pk_u8_f32(__builtin_rintf(v1[2] * 255.0f), 2, hi); hi = __builtin_amdgcn_cvt_pk_u8_f32(__builtin_rintf(v1[3] * 255.0f), 3, hi);
;                         if (bj == 0) { g8.x = lo; g8.y = hi; } else { g8.z = lo; g8.w = hi; } }
;                     else { u32x4 w; w.x = cvt_pk_bf16(v0[0], v0[1]); w.y = cvt_pk_bf16(v0[2], v0[3]); w.z = cvt_pk_bf16(v1[0], v1[1]); w.w = cvt_pk_bf16(v1[2], v1[3]);
;                         *(u32x4*)(O + (size_t)row * 3840 + col0 + bj * HALF) = w; } }
.LBB0_404:
	v_cvt_pk_bf16_f32 v18, v8, v9
	v_cvt_pk_bf16_f32 v19, v2, v3
	v_cvt_pk_bf16_f32 v20, v4, v5
	v_cvt_pk_bf16_f32 v21, v6, v7
	global_store_dwordx4 v[16:17], v[18:21], off offset:256 sc1
	s_cbranch_execnz .LBB0_402

;     __device__ __forceinline__ void operator()(f32x4 (&acc)[2][2][4][2], const Unit& u, int wr, int wc, int fr, int fq) const {
;     ...
;                 if (sig) *(u32x4*)(G8 + ((size_t)(((u.pm * 8 + (u.pn - 7)) * 8 + (wr * 4 + wc)) * 8 + (ai * 4 + m)) * 1024) + (fq * 16 + fr) * 16) = g8; }
.LBB0_406:
	s_or_b32 s4, s72, 7
	s_ashr_i32 s5, s4, 31
	s_lshl_b64 s[4:5], s[4:5], 10
	v_lshl_add_u64 v[2:3], v[134:135], 0, s[4:5]
	global_store_dwordx4 v[2:3], v[12:15], off sc1
	s_andn2_b64 vcc, exec, s[2:3]
	s_mov_b64 s[2:3], -1
	s_cbranch_vccnz .LBB0_311

; #define LAS __attribute__((address_space(3)))
; __device__ __forceinline__ unsigned pk2(float lo, float hi) { return f2bf(lo) | (f2bf(hi) << 16); }
; __device__ __forceinline__ void transpose_item(const float* W, int K, int N, bf16* WT, const float* gain, bool swiglu, LAS float* scr, int item, int lane) {
;     ...
;     for (int i = 0; i < 32; ++i) scr[(2 * i + (lane >> 5)) * 33 + (lane & 31)] = v[i];
;     asm volatile("s_waitcnt lgkmcnt(0)" ::: "memory");
;     const int r = lane & 15, ck = lane >> 4;
;     const int pnT = dr >> 8, rl = dr & 255;
;     char* blk = (char*)WT + ((size_t)((pnT * (K >> 6) + kb) * 2 + (rl >> 7)) * 16384);
; #pragma unroll
;     for (int rb = 0; rb < 2; ++rb)
; #pragma unroll
;         for (int ch = 0; ch < 2; ++ch) { const int s = 16 * rb + r, v = pg8::perm32(s);
;             const LAS float* sp = scr + (32 * ch + 8 * ck) * 33 + v;
;             u32x4 o; o.x = pk2(sp[0 * 33], sp[1 * 33]); o.y = pk2(sp[2 * 33], sp[3 * 33]); o.z = pk2(sp[4 * 33], sp[5 * 33]); o.w = pk2(sp[6 * 33], sp[7 * 33]);
;             *(u32x4*)(blk + pg8::lds_byte((rl & 127) + s, 32 * ch + 8 * ck)) = o; }
;     asm volatile("s_waitcnt lgkmcnt(0)" ::: "memory");
.LBB0_413:
	s_ashr_i32 s6, s41, 4
	s_and_b32 s6, s6, 0x7ffffff0
	s_add_i32 s6, s6, s2
	s_lshl_b32 s2, s6, 1
	s_bfe_u32 s6, s41, 0x10007
	s_or_b32 s6, s2, s6
	s_waitcnt vmcnt(30)
	ds_write2_b32 v45, v10, v11 offset1:66
	s_waitcnt vmcnt(28)
	ds_write2_b32 v45, v12, v13 offset0:132 offset1:198
	s_waitcnt vmcnt(26)
	ds_write2_b32 v50, v14, v15 offset0:8 offset1:74
	s_waitcnt vmcnt(24)
	ds_write2_b32 v50, v16, v17 offset0:140 offset1:206
	s_waitcnt vmcnt(22)
	ds_write2_b32 v51, v18, v19 offset0:16 offset1:82
	s_waitcnt vmcnt(20)
	ds_write2_b32 v51, v20, v21 offset0:148 offset1:214
	s_waitcnt vmcnt(18)
	ds_write2_b32 v52, v22, v23 offset0:24 offset1:90
	s_waitcnt vmcnt(16)
	ds_write2_b32 v52, v24, v25 offset0:156 offset1:222
	s_waitcnt vmcnt(14)
	ds_write2_b32 v53, v26, v27 offset0:32 offset1:98
	s_waitcnt vmcnt(12)
	ds_write2_b32 v53, v28, v29 offset0:164 offset1:230
	s_waitcnt vmcnt(10)
	ds_write2_b32 v54, v30, v31 offset0:40 offset1:106
	s_waitcnt vmcnt(8)
	ds_write2_b32 v54, v32, v33 offset0:172 offset1:238
	s_waitcnt vmcnt(6)
	ds_write2_b32 v55, v34, v35 offset0:48 offset1:114
	s_waitcnt vmcnt(4)
	ds_write2_b32 v55, v36, v37 offset0:180 offset1:246
	s_waitcnt vmcnt(2)
	ds_write2_b32 v56, v40, v41 offset0:56 offset1:122
	s_waitcnt vmcnt(0)
	ds_write2_b32 v56, v38, v39 offset0:188 offset1:254
	s_ashr_i32 s7, s6, 31
	s_waitcnt lgkmcnt(0)
	s_lshl_b64 s[6:7], s[6:7], 14
	s_add_u32 s6, s33, s6
	ds_read2_b32 v[14:15], v48 offset1:4
	s_addc_u32 s7, s83, s7
	s_and_b32 s2, s41, 0x7f
	ds_read2_b32 v[16:17], v48 offset0:33 offset1:37
	v_add_u32_e32 v0, s2, v154
	v_lshlrev_b32_e32 v10, 6, v0
	v_lshlrev_b32_e32 v11, 2, v0
	ds_read2_b32 v[18:19], v48 offset0:66 offset1:70
	v_and_b32_e32 v10, 0x3c0, v10
	v_and_b32_e32 v11, 32, v11
	ds_read2_b32 v[20:21], v48 offset0:99 offset1:103
	v_bitop3_b32 v32, v10, v11, v46 bitop3:0x36
	s_waitcnt lgkmcnt(3)
	v_bfe_u32 v10, v14, 16, 1
	v_add3_u32 v10, v14, v10, s37
	s_waitcnt lgkmcnt(2)
	v_bfe_u32 v11, v16, 16, 1
	ds_read2_b32 v[22:23], v48 offset0:132 offset1:136
	v_lshrrev_b32_e32 v10, 16, v10
	v_add3_u32 v11, v16, v11, s37
	ds_read2_b32 v[24:25], v48 offset0:165 offset1:169
	v_and_or_b32 v10, v11, s38, v10
	s_waitcnt lgkmcnt(3)
	v_bfe_u32 v11, v18, 16, 1
	v_add3_u32 v11, v18, v11, s37
	s_waitcnt lgkmcnt(2)
	v_bfe_u32 v12, v20, 16, 1
	ds_read2_b32 v[26:27], v48 offset0:198 offset1:202
	v_lshrrev_b32_e32 v11, 16, v11
	v_add3_u32 v12, v20, v12, s37
	ds_read2_b32 v[28:29], v48 offset0:231 offset1:235
	v_and_or_b32 v11, v12, s38, v11
	s_waitcnt lgkmcnt(3)
	v_bfe_u32 v12, v22, 16, 1
	v_add3_u32 v12, v22, v12, s37
	s_waitcnt lgkmcnt(2)
	v_bfe_u32 v13, v24, 16, 1
	v_lshrrev_b32_e32 v12, 16, v12
	v_add3_u32 v13, v24, v13, s37
	v_and_or_b32 v12, v13, s38, v12
	s_waitcnt lgkmcnt(1)
	v_bfe_u32 v13, v26, 16, 1
	v_add3_u32 v13, v26, v13, s37
	s_waitcnt lgkmcnt(0)
	v_bfe_u32 v14, v28, 16, 1
	v_lshrrev_b32_e32 v13, 16, v13
	v_add3_u32 v14, v28, v14, s37
	v_and_or_b32 v13, v14, s38, v13
	ds_read2_b32 v[30:31], v57 offset0:32 offset1:36
	v_lshlrev_b32_e32 v14, 7, v0
	v_and_or_b32 v14, v14, s40, v32
	ds_read2_b32 v[32:33], v57 offset0:65 offset1:69
	ds_read2_b32 v[34:35], v57 offset0:98 offset1:102
	ds_read2_b32 v[36:37], v57 offset0:131 offset1:135
	global_store_dwordx4 v14, v[10:13], s[6:7] sc1
	ds_read2_b32 v[38:39], v57 offset0:164 offset1:168
	ds_read2_b32 v[40:41], v57 offset0:197 offset1:201
	s_waitcnt lgkmcnt(5)
	v_bfe_u32 v10, v30, 16, 1
	v_add3_u32 v10, v30, v10, s37
	s_waitcnt lgkmcnt(4)
	v_bfe_u32 v11, v32, 16, 1
	v_lshrrev_b32_e32 v10, 16, v10
	v_add3_u32 v11, v32, v11, s37
	v_and_or_b32 v10, v11, s38, v10
	s_waitcnt lgkmcnt(3)
	v_bfe_u32 v11, v34, 16, 1
	v_add3_u32 v11, v34, v11, s37
	s_waitcnt lgkmcnt(2)
	v_bfe_u32 v12, v36, 16, 1
	ds_read2_b32 v[42:43], v57 offset0:230 offset1:234
	v_lshrrev_b32_e32 v11, 16, v11
	v_add3_u32 v12, v36, v12, s37
	ds_read2_b32 v[60:61], v58 offset0:7 offset1:11
	v_and_or_b32 v11, v12, s38, v11
	s_waitcnt lgkmcnt(3)
	v_bfe_u32 v12, v38, 16, 1
	v_add3_u32 v12, v38, v12, s37
	s_waitcnt lgkmcnt(2)
	v_bfe_u32 v13, v40, 16, 1
	v_lshrrev_b32_e32 v12, 16, v12
	v_add3_u32 v13, v40, v13, s37
	v_and_or_b32 v12, v13, s38, v12
	s_waitcnt lgkmcnt(1)
	v_bfe_u32 v13, v42, 16, 1
	v_add3_u32 v13, v42, v13, s37
	s_waitcnt lgkmcnt(0)
	v_bfe_u32 v16, v60, 16, 1
	v_lshrrev_b32_e32 v13, 16, v13
	v_add3_u32 v16, v60, v16, s37
	v_and_or_b32 v13, v16, s38, v13
	v_add_u32_e32 v0, 16, v0
	global_store_dwordx4 v14, v[10:13], s[6:7] offset:1024 sc1
	s_nop 1
	v_lshlrev_b32_e32 v10, 6, v0
	v_lshlrev_b32_e32 v11, 2, v0
	v_and_b32_e32 v10, 0x3c0, v10
	v_and_b32_e32 v11, 32, v11
	v_bitop3_b32 v14, v10, v11, v46 bitop3:0x36
	v_bfe_u32 v10, v15, 16, 1
	v_add3_u32 v10, v15, v10, s37
	v_bfe_u32 v11, v17, 16, 1
	v_lshrrev_b32_e32 v10, 16, v10
	v_add3_u32 v11, v17, v11, s37
	v_and_or_b32 v10, v11, s38, v10
	v_bfe_u32 v11, v19, 16, 1
	v_add3_u32 v11, v19, v11, s37
	v_bfe_u32 v12, v21, 16, 1
	v_lshrrev_b32_e32 v11, 16, v11
	v_add3_u32 v12, v21, v12, s37
	v_and_or_b32 v11, v12, s38, v11
	v_bfe_u32 v12, v23, 16, 1
	v_add3_u32 v12, v23, v12, s37
	v_bfe_u32 v13, v25, 16, 1
	v_lshrrev_b32_e32 v12, 16, v12
	v_add3_u32 v13, v25, v13, s37
	v_and_or_b32 v12, v13, s38, v12
	v_bfe_u32 v13, v27, 16, 1
	v_add3_u32 v13, v27, v13, s37
	v_bfe_u32 v15, v29, 16, 1
	v_lshrrev_b32_e32 v13, 16, v13
	v_add3_u32 v15, v29, v15, s37
	v_lshlrev_b32_e32 v0, 7, v0
	v_and_or_b32 v13, v15, s38, v13
	v_and_or_b32 v0, v0, s40, v14
	global_store_dwordx4 v0, v[10:13], s[6:7] sc1
	v_bfe_u32 v14, v61, 16, 1
	v_add3_u32 v14, v61, v14, s37
	v_bfe_u32 v10, v31, 16, 1
	v_add3_u32 v10, v31, v10, s37
	v_bfe_u32 v11, v33, 16, 1
	v_lshrrev_b32_e32 v10, 16, v10
	v_add3_u32 v11, v33, v11, s37
	v_and_or_b32 v10, v11, s38, v10
	v_bfe_u32 v11, v35, 16, 1
	v_add3_u32 v11, v35, v11, s37
	v_bfe_u32 v12, v37, 16, 1
	v_lshrrev_b32_e32 v11, 16, v11
	v_add3_u32 v12, v37, v12, s37
	v_and_or_b32 v11, v12, s38, v11
	v_bfe_u32 v12, v39, 16, 1
	v_add3_u32 v12, v39, v12, s37
	v_bfe_u32 v13, v41, 16, 1
	v_lshrrev_b32_e32 v12, 16, v12
	v_add3_u32 v13, v41, v13, s37
	v_and_or_b32 v12, v13, s38, v12
	v_bfe_u32 v13, v43, 16, 1
	v_add3_u32 v13, v43, v13, s37
	v_lshrrev_b32_e32 v13, 16, v13
	v_and_or_b32 v13, v14, s38, v13
	global_store_dwordx4 v0, v[10:13], s[6:7] offset:1024 sc1
	s_waitcnt lgkmcnt(0)

; __device__ __forceinline__ void transpose_item(const float* W, int K, int N, bf16* WT, const float* gain, bool swiglu, LAS float* scr, int item, int lane) {
;     const int nblk = N / 32, kb = item / nblk, nb = item % nblk, k0 = 64 * kb, n0 = 32 * nb;
;     int dr = n0;
;     if (swiglu) { if (n0 < DFF) dr = 256 * (n0 / 128) + (n0 % 128); else { const int j = n0 - DFF; dr = 256 * (j / 128) + 128 + (j % 128); } }
;     float v[32];
; #pragma unroll
;     for (int i = 0; i < 32; ++i) v[i] = W[(size_t)(k0 + 2 * i + (lane >> 5)) * N + n0 + (lane & 31)];
;     if (gain) {
; #pragma unroll
;         for (int i = 0; i < 32; ++i) v[i] *= gain[k0 + 2 * i + (lane >> 5)]; }
; #pragma unroll
;     for (int i = 0; i < 32; ++i) scr[(2 * i + (lane >> 5)) * 33 + (lane & 31)] = v[i];
; __global__ void __launch_bounds__(NTHR, 2) mk_fwd(Args args) {
;     ...
;               for (int it = me * NWAVES + wave; it < NDEF; it += nidle * NWAVES) { int r = it;
;                   if (r < I_UP) { transpose_item(args.in[13], D, NUP, Wup2, args.in[12], true, scr, r, lane); continue; } r -= I_UP;
;                   if (r < I_DN) { transpose_item(args.in[14], DFF, D, Wdn2, nullptr, false, scr, r, lane); continue; } r -= I_DN;
;                   if (r < I_SQ) { transpose_item(args.in[7], D, D, Watt, nullptr, false, scr, r, lane); continue; } r -= I_SQ;
;                   transpose_item(args.in[11], D, D, Wout, nullptr, false, scr, r, lane); } } } }
.LBB0_415:
	s_cmpk_gt_i32 s14, 0xaff
	s_mov_b64 s[6:7], -1
	s_cbranch_scc0 .LBB0_425
	s_cmpk_gt_u32 s14, 0x107f
	s_cbranch_scc0 .LBB0_422
	s_and_b32 s10, s17, 0x3e0
	s_cmpk_gt_u32 s14, 0x127f
	s_cbranch_scc0 .LBB0_419
	s_add_i32 s2, s14, 0xed80
	s_bfe_u32 s6, s2, 0xb0005
	s_lshl_b32 s2, s10, 2
	v_lshl_add_u64 v[10:11], v[2:3], 0, s[2:3]
	v_lshl_or_b32 v0, s6, 18, v49
	v_lshl_add_u64 v[10:11], v[10:11], 0, v[0:1]
	v_add_co_u32_e32 v12, vcc, 0x2000, v10
	s_and_b32 s2, s31, 48
	s_nop 0
	v_addc_co_u32_e32 v13, vcc, 0, v11, vcc
	v_add_co_u32_e32 v14, vcc, 0x4000, v10
	s_add_i32 s2, s2, s6
	s_nop 0
	v_addc_co_u32_e32 v15, vcc, 0, v11, vcc
	v_add_co_u32_e32 v16, vcc, 0x6000, v10
	s_lshl_b32 s2, s2, 15
	s_nop 0
	v_addc_co_u32_e32 v17, vcc, 0, v11, vcc
	v_add_co_u32_e32 v18, vcc, 0x8000, v10
	s_and_b32 s6, s35, 0x4000
	s_nop 0
	v_addc_co_u32_e32 v19, vcc, 0, v11, vcc
	v_add_co_u32_e32 v20, vcc, 0xa000, v10
	s_or_b32 s2, s2, s6
	s_nop 0
	v_addc_co_u32_e32 v21, vcc, 0, v11, vcc
	v_add_co_u32_e32 v22, vcc, 0xc000, v10
	s_add_u32 s6, s93, s2
	s_nop 0
	v_addc_co_u32_e32 v23, vcc, 0, v11, vcc
	v_add_co_u32_e32 v24, vcc, 0xe000, v10
	s_addc_u32 s7, s84, 0
	s_nop 0
	v_addc_co_u32_e32 v25, vcc, 0, v11, vcc
	global_load_dword v0, v[10:11], off
	global_load_dword v28, v[12:13], off
	global_load_dword v29, v[14:15], off
	global_load_dword v30, v[16:17], off
	global_load_dword v31, v[18:19], off
	global_load_dword v32, v[20:21], off
	global_load_dword v33, v[22:23], off
	global_load_dword v34, v[24:25], off
	v_add_co_u32_e32 v12, vcc, 0x10000, v10
	s_and_b32 s2, s35, 0x3000
	s_nop 0
	v_addc_co_u32_e32 v13, vcc, 0, v11, vcc
	v_add_co_u32_e32 v14, vcc, 0x12000, v10
	s_nop 1
	v_addc_co_u32_e32 v15, vcc, 0, v11, vcc
	v_add_co_u32_e32 v16, vcc, 0x14000, v10
	s_nop 1
	v_addc_co_u32_e32 v17, vcc, 0, v11, vcc
	v_add_co_u32_e32 v18, vcc, 0x16000, v10
	s_nop 1
	v_addc_co_u32_e32 v19, vcc, 0, v11, vcc
	v_add_co_u32_e32 v20, vcc, 0x18000, v10
	s_nop 1
	v_addc_co_u32_e32 v21, vcc, 0, v11, vcc
	v_add_co_u32_e32 v22, vcc, 0x1a000, v10
	s_nop 1
	v_addc_co_u32_e32 v23, vcc, 0, v11, vcc
	v_add_co_u32_e32 v24, vcc, 0x1c000, v10
	s_nop 1
	v_addc_co_u32_e32 v25, vcc, 0, v11, vcc
	v_add_co_u32_e32 v26, vcc, 0x1e000, v10
	s_nop 1
	v_addc_co_u32_e32 v27, vcc, 0, v11, vcc
	global_load_dword v35, v[12:13], off
	global_load_dword v36, v[14:15], off
	global_load_dword v37, v[16:17], off
	global_load_dword v38, v[18:19], off
	global_load_dword v39, v[20:21], off
	global_load_dword v40, v[22:23], off
	global_load_dword v41, v[24:25], off
	global_load_dword v42, v[26:27], off
	v_add_co_u32_e32 v12, vcc, 0x20000, v10
	s_nop 1
	v_addc_co_u32_e32 v13, vcc, 0, v11, vcc
	v_add_co_u32_e32 v14, vcc, 0x22000, v10
	s_nop 1
	v_addc_co_u32_e32 v15, vcc, 0, v11, vcc
	v_add_co_u32_e32 v16, vcc, 0x24000, v10
	s_nop 1
	v_addc_co_u32_e32 v17, vcc, 0, v11, vcc
	v_add_co_u32_e32 v18, vcc, 0x26000, v10
	s_nop 1
	v_addc_co_u32_e32 v19, vcc, 0, v11, vcc
	v_add_co_u32_e32 v20, vcc, 0x28000, v10
	s_nop 1
	v_addc_co_u32_e32 v21, vcc, 0, v11, vcc
	v_add_co_u32_e32 v22, vcc, 0x2a000, v10
	s_nop 1
	v_addc_co_u32_e32 v23, vcc, 0, v11, vcc
	v_add_co_u32_e32 v24, vcc, 0x2c000, v10
	s_nop 1
	v_addc_co_u32_e32 v25, vcc, 0, v11, vcc
	v_add_co_u32_e32 v26, vcc, 0x2e000, v10
	s_nop 1
	v_addc_co_u32_e32 v27, vcc, 0, v11, vcc
	global_load_dword v43, v[12:13], off
	global_load_dword v59, v[14:15], off
	global_load_dword v60, v[16:17], off
	global_load_dword v61, v[18:19], off
	global_load_dword v62, v[20:21], off
	global_load_dword v63, v[22:23], off
	global_load_dword v64, v[24:25], off
	s_nop 0
	global_load_dword v26, v[26:27], off
	v_add_co_u32_e32 v12, vcc, 0x30000, v10
	s_nop 1
	v_addc_co_u32_e32 v13, vcc, 0, v11, vcc
	v_add_co_u32_e32 v14, vcc, 0x32000, v10
	s_nop 1
	v_addc_co_u32_e32 v15, vcc, 0, v11, vcc
	v_add_co_u32_e32 v16, vcc, 0x34000, v10
	s_nop 1
	v_addc_co_u32_e32 v17, vcc, 0, v11, vcc
	v_add_co_u32_e32 v18, vcc, 0x36000, v10
	s_nop 1
	v_addc_co_u32_e32 v19, vcc, 0, v11, vcc
	v_add_co_u32_e32 v20, vcc, 0x38000, v10
	s_nop 1
	v_addc_co_u32_e32 v21, vcc, 0, v11, vcc
	v_add_co_u32_e32 v22, vcc, 0x3a000, v10
	s_nop 1
	v_addc_co_u32_e32 v23, vcc, 0, v11, vcc
	v_add_co_u32_e32 v24, vcc, 0x3c000, v10
	s_nop 1
	v_addc_co_u32_e32 v25, vcc, 0, v11, vcc
	v_add_co_u32_e32 v10, vcc, 0x3e000, v10
	s_nop 1
	v_addc_co_u32_e32 v11, vcc, 0, v11, vcc
	global_load_dword v12, v[12:13], off
	s_nop 0
	global_load_dword v13, v[14:15], off
	s_nop 0
	global_load_dword v14, v[16:17], off
	global_load_dword v15, v[18:19], off
	s_nop 0
	global_load_dword v16, v[20:21], off
	global_load_dword v17, v[22:23], off
	global_load_dword v18, v[24:25], off
	s_nop 0
	global_load_dword v10, v[10:11], off
	s_waitcnt vmcnt(30)
	ds_write2_b32 v45, v0, v28 offset1:66
	s_waitcnt vmcnt(28)
	ds_write2_b32 v45, v29, v30 offset0:132 offset1:198
	s_waitcnt vmcnt(26)
	ds_write2_b32 v50, v31, v32 offset0:8 offset1:74
	s_waitcnt vmcnt(24)
	ds_write2_b32 v50, v33, v34 offset0:140 offset1:206
	s_waitcnt vmcnt(22)
	ds_write2_b32 v51, v35, v36 offset0:16 offset1:82
	s_waitcnt vmcnt(20)
	ds_write2_b32 v51, v37, v38 offset0:148 offset1:214
	s_waitcnt vmcnt(18)
	ds_write2_b32 v52, v39, v40 offset0:24 offset1:90
	s_waitcnt vmcnt(16)
	ds_write2_b32 v52, v41, v42 offset0:156 offset1:222
	s_waitcnt vmcnt(14)
	ds_write2_b32 v53, v43, v59 offset0:32 offset1:98
	s_waitcnt vmcnt(12)
	ds_write2_b32 v53, v60, v61 offset0:164 offset1:230
	s_waitcnt vmcnt(10)
	ds_write2_b32 v54, v62, v63 offset0:40 offset1:106
	s_waitcnt vmcnt(8)
	ds_write2_b32 v54, v64, v26 offset0:172 offset1:238
	s_waitcnt vmcnt(6)
	ds_write2_b32 v55, v12, v13 offset0:48 offset1:114
	s_waitcnt vmcnt(4)
; #define LAS __attribute__((address_space(3)))
; __device__ __forceinline__ unsigned pk2(float lo, float hi) { return f2bf(lo) | (f2bf(hi) << 16); }
; __device__ __forceinline__ void transpose_item(const float* W, int K, int N, bf16* WT, const float* gain, bool swiglu, LAS float* scr, int item, int lane) {
;     ...
;     for (int i = 0; i < 32; ++i) scr[(2 * i + (lane >> 5)) * 33 + (lane & 31)] = v[i];
;     asm volatile("s_waitcnt lgkmcnt(0)" ::: "memory");
;     const int r = lane & 15, ck = lane >> 4;
;     const int pnT = dr >> 8, rl = dr & 255;
;     char* blk = (char*)WT + ((size_t)((pnT * (K >> 6) + kb) * 2 + (rl >> 7)) * 16384);
; #pragma unroll
;     for (int rb = 0; rb < 2; ++rb)
; #pragma unroll
;         for (int ch = 0; ch < 2; ++ch) { const int s = 16 * rb + r, v = pg8::perm32(s);
;             const LAS float* sp = scr + (32 * ch + 8 * ck) * 33 + v;
;             u32x4 o; o.x = pk2(sp[0 * 33], sp[1 * 33]); o.y = pk2(sp[2 * 33], sp[3 * 33]); o.z = pk2(sp[4 * 33], sp[5 * 33]); o.w = pk2(sp[6 * 33], sp[7 * 33]);
;             *(u32x4*)(blk + pg8::lds_byte((rl & 127) + s, 32 * ch + 8 * ck)) = o; }
;     asm volatile("s_waitcnt lgkmcnt(0)" ::: "memory");
	ds_write2_b32 v55, v14, v15 offset0:180 offset1:246
	s_waitcnt vmcnt(2)
	ds_write2_b32 v56, v16, v17 offset0:56 offset1:122
	s_waitcnt vmcnt(0)
	ds_write2_b32 v56, v18, v10 offset0:188 offset1:254
	s_waitcnt lgkmcnt(0)
	ds_read2_b32 v[14:15], v48 offset1:4
	ds_read2_b32 v[16:17], v48 offset0:33 offset1:37
	ds_read2_b32 v[18:19], v48 offset0:66 offset1:70
	ds_read2_b32 v[20:21], v48 offset0:99 offset1:103
	ds_read2_b32 v[22:23], v48 offset0:132 offset1:136
	s_waitcnt lgkmcnt(4)
	v_bfe_u32 v0, v14, 16, 1
	v_add3_u32 v0, v14, v0, s37
	s_waitcnt lgkmcnt(3)
	v_bfe_u32 v10, v16, 16, 1
	v_lshrrev_b32_e32 v0, 16, v0
	v_add3_u32 v10, v16, v10, s37
	ds_read2_b32 v[24:25], v48 offset0:165 offset1:169
	v_and_or_b32 v10, v10, s38, v0
	s_waitcnt lgkmcnt(3)
	v_bfe_u32 v0, v18, 16, 1
	v_add3_u32 v0, v18, v0, s37
	s_waitcnt lgkmcnt(2)
	v_bfe_u32 v11, v20, 16, 1
	ds_read2_b32 v[26:27], v48 offset0:198 offset1:202
	v_lshrrev_b32_e32 v0, 16, v0
	v_add3_u32 v11, v20, v11, s37
	ds_read2_b32 v[28:29], v48 offset0:231 offset1:235
	v_and_or_b32 v11, v11, s38, v0
	s_waitcnt lgkmcnt(3)
	v_bfe_u32 v0, v22, 16, 1
	v_add3_u32 v0, v22, v0, s37
	s_waitcnt lgkmcnt(2)
	v_bfe_u32 v12, v24, 16, 1
	v_lshrrev_b32_e32 v0, 16, v0
	v_add3_u32 v12, v24, v12, s37
	ds_read2_b32 v[30:31], v57 offset0:32 offset1:36
	v_and_or_b32 v12, v12, s38, v0
	s_waitcnt lgkmcnt(2)
	v_bfe_u32 v0, v26, 16, 1
	ds_read2_b32 v[32:33], v57 offset0:65 offset1:69
	v_add3_u32 v0, v26, v0, s37
	s_waitcnt lgkmcnt(2)
	v_bfe_u32 v13, v28, 16, 1
	v_lshrrev_b32_e32 v0, 16, v0
	v_add3_u32 v13, v28, v13, s37
	ds_read2_b32 v[34:35], v57 offset0:98 offset1:102
	v_and_or_b32 v13, v13, s38, v0
	v_or_b32_e32 v0, s2, v47
	ds_read2_b32 v[36:37], v57 offset0:131 offset1:135
	global_store_dwordx4 v0, v[10:13], s[6:7] sc1
	ds_read2_b32 v[38:39], v57 offset0:164 offset1:168
	ds_read2_b32 v[40:41], v57 offset0:197 offset1:201
	s_waitcnt lgkmcnt(5)
	v_bfe_u32 v10, v30, 16, 1
	v_add3_u32 v10, v30, v10, s37
	s_waitcnt lgkmcnt(4)
	v_bfe_u32 v11, v32, 16, 1
	v_lshrrev_b32_e32 v10, 16, v10
	v_add3_u32 v11, v32, v11, s37
	v_and_or_b32 v10, v11, s38, v10
	s_waitcnt lgkmcnt(3)
	v_bfe_u32 v11, v34, 16, 1
	v_add3_u32 v11, v34, v11, s37
	s_waitcnt lgkmcnt(2)
	v_bfe_u32 v12, v36, 16, 1
	ds_read2_b32 v[42:43], v57 offset0:230 offset1:234
	v_lshrrev_b32_e32 v11, 16, v11
	v_add3_u32 v12, v36, v12, s37
	ds_read2_b32 v[60:61], v58 offset0:7 offset1:11
	v_and_or_b32 v11, v12, s38, v11
	s_waitcnt lgkmcnt(3)
	v_bfe_u32 v12, v38, 16, 1
	v_add3_u32 v12, v38, v12, s37
	s_waitcnt lgkmcnt(2)
	v_bfe_u32 v13, v40, 16, 1
	v_lshrrev_b32_e32 v12, 16, v12
	v_add3_u32 v13, v40, v13, s37
	v_and_or_b32 v12, v13, s38, v12
	s_waitcnt lgkmcnt(1)
	v_bfe_u32 v13, v42, 16, 1
	v_add3_u32 v13, v42, v13, s37
	s_waitcnt lgkmcnt(0)
	v_bfe_u32 v14, v60, 16, 1
	v_lshrrev_b32_e32 v13, 16, v13
	v_add3_u32 v14, v60, v14, s37
	v_and_or_b32 v13, v14, s38, v13
	global_store_dwordx4 v0, v[10:13], s[6:7] offset:1024 sc1
	v_bfe_u32 v14, v29, 16, 1
	v_add3_u32 v14, v29, v14, s37
	v_bfe_u32 v10, v15, 16, 1
	v_add3_u32 v10, v15, v10, s37
	v_bfe_u32 v11, v17, 16, 1
	v_lshrrev_b32_e32 v10, 16, v10
	v_add3_u32 v11, v17, v11, s37
	v_and_or_b32 v10, v11, s38, v10
	v_bfe_u32 v11, v19, 16, 1
	v_add3_u32 v11, v19, v11, s37
	v_bfe_u32 v12, v21, 16, 1
	v_lshrrev_b32_e32 v11, 16, v11
	v_add3_u32 v12, v21, v12, s37
	v_and_or_b32 v11, v12, s38, v11
	v_bfe_u32 v12, v23, 16, 1
	v_add3_u32 v12, v23, v12, s37
	v_bfe_u32 v13, v25, 16, 1
	v_lshrrev_b32_e32 v12, 16, v12
	v_add3_u32 v13, v25, v13, s37
	v_and_or_b32 v12, v13, s38, v12
	v_bfe_u32 v13, v27, 16, 1
	v_add3_u32 v13, v27, v13, s37
	v_lshrrev_b32_e32 v13, 16, v13
	v_and_or_b32 v13, v14, s38, v13
	global_store_dwordx4 v0, v[10:13], s[6:7] offset:2048 sc1
	v_bfe_u32 v14, v61, 16, 1
	v_add3_u32 v14, v61, v14, s37
	v_bfe_u32 v10, v31, 16, 1
	v_add3_u32 v10, v31, v10, s37
	v_bfe_u32 v11, v33, 16, 1
	v_lshrrev_b32_e32 v10, 16, v10
	v_add3_u32 v11, v33, v11, s37
	v_and_or_b32 v10, v11, s38, v10
	v_bfe_u32 v11, v35, 16, 1
	v_add3_u32 v11, v35, v11, s37
	v_bfe_u32 v12, v37, 16, 1
	v_lshrrev_b32_e32 v11, 16, v11
	v_add3_u32 v12, v37, v12, s37
	v_and_or_b32 v11, v12, s38, v11
	v_bfe_u32 v12, v39, 16, 1
	v_add3_u32 v12, v39, v12, s37
	v_bfe_u32 v13, v41, 16, 1
	v_lshrrev_b32_e32 v12, 16, v12
	v_add3_u32 v13, v41, v13, s37
	v_and_or_b32 v12, v13, s38, v12
	v_bfe_u32 v13, v43, 16, 1
	v_add3_u32 v13, v43, v13, s37
	v_lshrrev_b32_e32 v13, 16, v13
	v_and_or_b32 v13, v14, s38, v13
	global_store_dwordx4 v0, v[10:13], s[6:7] offset:3072 sc1
	s_waitcnt lgkmcnt(0)
	s_mov_b64 s[6:7], 0
; __device__ __forceinline__ void transpose_item(const float* W, int K, int N, bf16* WT, const float* gain, bool swiglu, LAS float* scr, int item, int lane) {
;     const int nblk = N / 32, kb = item / nblk, nb = item % nblk, k0 = 64 * kb, n0 = 32 * nb;
;     int dr = n0;
;     if (swiglu) { if (n0 < DFF) dr = 256 * (n0 / 128) + (n0 % 128); else { const int j = n0 - DFF; dr = 256 * (j / 128) + 128 + (j % 128); } }
;     float v[32];
; #pragma unroll
;     for (int i = 0; i < 32; ++i) v[i] = W[(size_t)(k0 + 2 * i + (lane >> 5)) * N + n0 + (lane & 31)];
;     if (gain) {
; #pragma unroll
;         for (int i = 0; i < 32; ++i) v[i] *= gain[k0 + 2 * i + (lane >> 5)]; }
; #pragma unroll
;     for (int i = 0; i < 32; ++i) scr[(2 * i + (lane >> 5)) * 33 + (lane & 31)] = v[i];
; __global__ void __launch_bounds__(NTHR, 2) mk_fwd(Args args) {
;     ...
;               for (int it = me * NWAVES + wave; it < NDEF; it += nidle * NWAVES) { int r = it;
;                   if (r < I_UP) { transpose_item(args.in[13], D, NUP, Wup2, args.in[12], true, scr, r, lane); continue; } r -= I_UP;
;                   if (r < I_DN) { transpose_item(args.in[14], DFF, D, Wdn2, nullptr, false, scr, r, lane); continue; } r -= I_DN;
;                   if (r < I_SQ) { transpose_item(args.in[7], D, D, Watt, nullptr, false, scr, r, lane); continue; } r -= I_SQ;
;                   transpose_item(args.in[11], D, D, Wout, nullptr, false, scr, r, lane); } } } }
.LBB0_419:
	s_andn2_b64 vcc, exec, s[6:7]
	s_cbranch_vccnz .LBB0_421
	s_add_i32 s2, s14, 0xef80
	s_bfe_u32 s6, s2, 0xb0005
	s_lshl_b32 s2, s10, 2
	v_lshl_add_u64 v[10:11], v[4:5], 0, s[2:3]
	v_lshl_or_b32 v0, s6, 18, v49
	v_lshl_add_u64 v[10:11], v[10:11], 0, v[0:1]
	v_add_co_u32_e32 v12, vcc, 0x2000, v10
	s_and_b32 s2, s31, 48
	s_nop 0
	v_addc_co_u32_e32 v13, vcc, 0, v11, vcc
	v_add_co_u32_e32 v14, vcc, 0x4000, v10
	s_add_i32 s6, s6, s2
	s_nop 0
	v_addc_co_u32_e32 v15, vcc, 0, v11, vcc
	v_add_co_u32_e32 v16, vcc, 0x6000, v10
	s_lshl_b32 s2, s6, 15
	s_nop 0
	v_addc_co_u32_e32 v17, vcc, 0, v11, vcc
	v_add_co_u32_e32 v18, vcc, 0x8000, v10
	s_and_b32 s6, s35, 0x4000
	s_nop 0
	v_addc_co_u32_e32 v19, vcc, 0, v11, vcc
	v_add_co_u32_e32 v20, vcc, 0xa000, v10
	s_or_b32 s2, s2, s6
	s_nop 0
	v_addc_co_u32_e32 v21, vcc, 0, v11, vcc
	v_add_co_u32_e32 v22, vcc, 0xc000, v10
	s_add_u32 s6, s85, s2
	s_nop 0
	v_addc_co_u32_e32 v23, vcc, 0, v11, vcc
	v_add_co_u32_e32 v24, vcc, 0xe000, v10
	s_addc_u32 s7, s86, 0
	s_nop 0
	v_addc_co_u32_e32 v25, vcc, 0, v11, vcc
	global_load_dword v0, v[10:11], off
	global_load_dword v28, v[12:13], off
	global_load_dword v29, v[14:15], off
	global_load_dword v30, v[16:17], off
	global_load_dword v31, v[18:19], off
	global_load_dword v32, v[20:21], off
	global_load_dword v33, v[22:23], off
	global_load_dword v34, v[24:25], off
	v_add_co_u32_e32 v12, vcc, 0x10000, v10
	s_and_b32 s2, s35, 0x3000
	s_nop 0
	v_addc_co_u32_e32 v13, vcc, 0, v11, vcc
	v_add_co_u32_e32 v14, vcc, 0x12000, v10
	s_nop 1
	v_addc_co_u32_e32 v15, vcc, 0, v11, vcc
	v_add_co_u32_e32 v16, vcc, 0x14000, v10
	s_nop 1
	v_addc_co_u32_e32 v17, vcc, 0, v11, vcc
	v_add_co_u32_e32 v18, vcc, 0x16000, v10
	s_nop 1
	v_addc_co_u32_e32 v19, vcc, 0, v11, vcc
	v_add_co_u32_e32 v20, vcc, 0x18000, v10
	s_nop 1
	v_addc_co_u32_e32 v21, vcc, 0, v11, vcc
	v_add_co_u32_e32 v22, vcc, 0x1a000, v10
	s_nop 1
	v_addc_co_u32_e32 v23, vcc, 0, v11, vcc
	v_add_co_u32_e32 v24, vcc, 0x1c000, v10
	s_nop 1
	v_addc_co_u32_e32 v25, vcc, 0, v11, vcc
	v_add_co_u32_e32 v26, vcc, 0x1e000, v10
	s_nop 1
	v_addc_co_u32_e32 v27, vcc, 0, v11, vcc
	global_load_dword v35, v[12:13], off
	global_load_dword v36, v[14:15], off
	global_load_dword v37, v[16:17], off
	global_load_dword v38, v[18:19], off
	global_load_dword v39, v[20:21], off
	global_load_dword v40, v[22:23], off
	global_load_dword v41, v[24:25], off
	global_load_dword v42, v[26:27], off
	v_add_co_u32_e32 v12, vcc, 0x20000, v10
	s_nop 1
	v_addc_co_u32_e32 v13, vcc, 0, v11, vcc
	v_add_co_u32_e32 v14, vcc, 0x22000, v10
	s_nop 1
	v_addc_co_u32_e32 v15, vcc, 0, v11, vcc
	v_add_co_u32_e32 v16, vcc, 0x24000, v10
	s_nop 1
	v_addc_co_u32_e32 v17, vcc, 0, v11, vcc
	v_add_co_u32_e32 v18, vcc, 0x26000, v10
	s_nop 1
	v_addc_co_u32_e32 v19, vcc, 0, v11, vcc
	v_add_co_u32_e32 v20, vcc, 0x28000, v10
	s_nop 1
	v_addc_co_u32_e32 v21, vcc, 0, v11, vcc
	v_add_co_u32_e32 v22, vcc, 0x2a000, v10
	s_nop 1
	v_addc_co_u32_e32 v23, vcc, 0, v11, vcc
	v_add_co_u32_e32 v24, vcc, 0x2c000, v10
	s_nop 1
	v_addc_co_u32_e32 v25, vcc, 0, v11, vcc
	v_add_co_u32_e32 v26, vcc, 0x2e000, v10
	s_nop 1
	v_addc_co_u32_e32 v27, vcc, 0, v11, vcc
	global_load_dword v43, v[12:13], off
	global_load_dword v59, v[14:15], off
	global_load_dword v60, v[16:17], off
	global_load_dword v61, v[18:19], off
	global_load_dword v62, v[20:21], off
	global_load_dword v63, v[22:23], off
	global_load_dword v64, v[24:25], off
	s_nop 0
	global_load_dword v26, v[26:27], off
	v_add_co_u32_e32 v12, vcc, 0x30000, v10
	s_nop 1
	v_addc_co_u32_e32 v13, vcc, 0, v11, vcc
	v_add_co_u32_e32 v14, vcc, 0x32000, v10
	s_nop 1
	v_addc_co_u32_e32 v15, vcc, 0, v11, vcc
	v_add_co_u32_e32 v16, vcc, 0x34000, v10
	s_nop 1
	v_addc_co_u32_e32 v17, vcc, 0, v11, vcc
	v_add_co_u32_e32 v18, vcc, 0x36000, v10
	s_nop 1
	v_addc_co_u32_e32 v19, vcc, 0, v11, vcc
	v_add_co_u32_e32 v20, vcc, 0x38000, v10
	s_nop 1
	v_addc_co_u32_e32 v21, vcc, 0, v11, vcc
	v_add_co_u32_e32 v22, vcc, 0x3a000, v10
	s_nop 1
	v_addc_co_u32_e32 v23, vcc, 0, v11, vcc
	v_add_co_u32_e32 v24, vcc, 0x3c000, v10
	s_nop 1
	v_addc_co_u32_e32 v25, vcc, 0, v11, vcc
	v_add_co_u32_e32 v10, vcc, 0x3e000, v10
	s_nop 1
	v_addc_co_u32_e32 v11, vcc, 0, v11, vcc
	global_load_dword v12, v[12:13], off
	s_nop 0
	global_load_dword v13, v[14:15], off
	s_nop 0
	global_load_dword v14, v[16:17], off
	global_load_dword v15, v[18:19], off
	s_nop 0
	global_load_dword v16, v[20:21], off
	global_load_dword v17, v[22:23], off
	global_load_dword v18, v[24:25], off
	s_nop 0
	global_load_dword v10, v[10:11], off
	s_waitcnt vmcnt(30)
	ds_write2_b32 v45, v0, v28 offset1:66
	s_waitcnt vmcnt(28)
	ds_write2_b32 v45, v29, v30 offset0:132 offset1:198
	s_waitcnt vmcnt(26)
	ds_write2_b32 v50, v31, v32 offset0:8 offset1:74
	s_waitcnt vmcnt(24)
	ds_write2_b32 v50, v33, v34 offset0:140 offset1:206
	s_waitcnt vmcnt(22)
	ds_write2_b32 v51, v35, v36 offset0:16 offset1:82
	s_waitcnt vmcnt(20)
	ds_write2_b32 v51, v37, v38 offset0:148 offset1:214
	s_waitcnt vmcnt(18)
; #define LAS __attribute__((address_space(3)))
; __device__ __forceinline__ unsigned pk2(float lo, float hi) { return f2bf(lo) | (f2bf(hi) << 16); }
; __device__ __forceinline__ void transpose_item(const float* W, int K, int N, bf16* WT, const float* gain, bool swiglu, LAS float* scr, int item, int lane) {
;     ...
;     for (int i = 0; i < 32; ++i) scr[(2 * i + (lane >> 5)) * 33 + (lane & 31)] = v[i];
;     asm volatile("s_waitcnt lgkmcnt(0)" ::: "memory");
;     const int r = lane & 15, ck = lane >> 4;
;     const int pnT = dr >> 8, rl = dr & 255;
;     char* blk = (char*)WT + ((size_t)((pnT * (K >> 6) + kb) * 2 + (rl >> 7)) * 16384);
; #pragma unroll
;     for (int rb = 0; rb < 2; ++rb)
; #pragma unroll
;         for (int ch = 0; ch < 2; ++ch) { const int s = 16 * rb + r, v = pg8::perm32(s);
;             const LAS float* sp = scr + (32 * ch + 8 * ck) * 33 + v;
;             u32x4 o; o.x = pk2(sp[0 * 33], sp[1 * 33]); o.y = pk2(sp[2 * 33], sp[3 * 33]); o.z = pk2(sp[4 * 33], sp[5 * 33]); o.w = pk2(sp[6 * 33], sp[7 * 33]);
;             *(u32x4*)(blk + pg8::lds_byte((rl & 127) + s, 32 * ch + 8 * ck)) = o; }
;     asm volatile("s_waitcnt lgkmcnt(0)" ::: "memory");
	ds_write2_b32 v52, v39, v40 offset0:24 offset1:90
	s_waitcnt vmcnt(16)
	ds_write2_b32 v52, v41, v42 offset0:156 offset1:222
	s_waitcnt vmcnt(14)
	ds_write2_b32 v53, v43, v59 offset0:32 offset1:98
	s_waitcnt vmcnt(12)
	ds_write2_b32 v53, v60, v61 offset0:164 offset1:230
	s_waitcnt vmcnt(10)
	ds_write2_b32 v54, v62, v63 offset0:40 offset1:106
	s_waitcnt vmcnt(8)
	ds_write2_b32 v54, v64, v26 offset0:172 offset1:238
	s_waitcnt vmcnt(6)
	ds_write2_b32 v55, v12, v13 offset0:48 offset1:114
	s_waitcnt vmcnt(4)
	ds_write2_b32 v55, v14, v15 offset0:180 offset1:246
	s_waitcnt vmcnt(2)
	ds_write2_b32 v56, v16, v17 offset0:56 offset1:122
	s_waitcnt vmcnt(0)
	ds_write2_b32 v56, v18, v10 offset0:188 offset1:254
	s_waitcnt lgkmcnt(0)
	ds_read2_b32 v[14:15], v48 offset1:4
	ds_read2_b32 v[16:17], v48 offset0:33 offset1:37
	ds_read2_b32 v[18:19], v48 offset0:66 offset1:70
	ds_read2_b32 v[20:21], v48 offset0:99 offset1:103
	ds_read2_b32 v[22:23], v48 offset0:132 offset1:136
	s_waitcnt lgkmcnt(4)
	v_bfe_u32 v0, v14, 16, 1
	v_add3_u32 v0, v14, v0, s37
	s_waitcnt lgkmcnt(3)
	v_bfe_u32 v10, v16, 16, 1
	v_lshrrev_b32_e32 v0, 16, v0
	v_add3_u32 v10, v16, v10, s37
	ds_read2_b32 v[24:25], v48 offset0:165 offset1:169
	v_and_or_b32 v10, v10, s38, v0
	s_waitcnt lgkmcnt(3)
	v_bfe_u32 v0, v18, 16, 1
	v_add3_u32 v0, v18, v0, s37
	s_waitcnt lgkmcnt(2)
	v_bfe_u32 v11, v20, 16, 1
	ds_read2_b32 v[26:27], v48 offset0:198 offset1:202
	v_lshrrev_b32_e32 v0, 16, v0
	v_add3_u32 v11, v20, v11, s37
	ds_read2_b32 v[28:29], v48 offset0:231 offset1:235
	v_and_or_b32 v11, v11, s38, v0
	s_waitcnt lgkmcnt(3)
	v_bfe_u32 v0, v22, 16, 1
	v_add3_u32 v0, v22, v0, s37
	s_waitcnt lgkmcnt(2)
	v_bfe_u32 v12, v24, 16, 1
	v_lshrrev_b32_e32 v0, 16, v0
	v_add3_u32 v12, v24, v12, s37
	ds_read2_b32 v[30:31], v57 offset0:32 offset1:36
	v_and_or_b32 v12, v12, s38, v0
	s_waitcnt lgkmcnt(2)
	v_bfe_u32 v0, v26, 16, 1
	ds_read2_b32 v[32:33], v57 offset0:65 offset1:69
	v_add3_u32 v0, v26, v0, s37
	s_waitcnt lgkmcnt(2)
	v_bfe_u32 v13, v28, 16, 1
	v_lshrrev_b32_e32 v0, 16, v0
	v_add3_u32 v13, v28, v13, s37
	ds_read2_b32 v[34:35], v57 offset0:98 offset1:102
	v_and_or_b32 v13, v13, s38, v0
	v_or_b32_e32 v0, s2, v47
	ds_read2_b32 v[36:37], v57 offset0:131 offset1:135
	global_store_dwordx4 v0, v[10:13], s[6:7] sc1
	ds_read2_b32 v[38:39], v57 offset0:164 offset1:168
	ds_read2_b32 v[40:41], v57 offset0:197 offset1:201
	s_waitcnt lgkmcnt(5)
	v_bfe_u32 v10, v30, 16, 1
	v_add3_u32 v10, v30, v10, s37
	s_waitcnt lgkmcnt(4)
	v_bfe_u32 v11, v32, 16, 1
	v_lshrrev_b32_e32 v10, 16, v10
	v_add3_u32 v11, v32, v11, s37
	v_and_or_b32 v10, v11, s38, v10
	s_waitcnt lgkmcnt(3)
	v_bfe_u32 v11, v34, 16, 1
	v_add3_u32 v11, v34, v11, s37
	s_waitcnt lgkmcnt(2)
	v_bfe_u32 v12, v36, 16, 1
	ds_read2_b32 v[42:43], v57 offset0:230 offset1:234
	v_lshrrev_b32_e32 v11, 16, v11
	v_add3_u32 v12, v36, v12, s37
	ds_read2_b32 v[60:61], v58 offset0:7 offset1:11
	v_and_or_b32 v11, v12, s38, v11
	s_waitcnt lgkmcnt(3)
	v_bfe_u32 v12, v38, 16, 1
	v_add3_u32 v12, v38, v12, s37
	s_waitcnt lgkmcnt(2)
	v_bfe_u32 v13, v40, 16, 1
	v_lshrrev_b32_e32 v12, 16, v12
	v_add3_u32 v13, v40, v13, s37
	v_and_or_b32 v12, v13, s38, v12
	s_waitcnt lgkmcnt(1)
	v_bfe_u32 v13, v42, 16, 1
	v_add3_u32 v13, v42, v13, s37
	s_waitcnt lgkmcnt(0)
	v_bfe_u32 v14, v60, 16, 1
	v_lshrrev_b32_e32 v13, 16, v13
	v_add3_u32 v14, v60, v14, s37
	v_and_or_b32 v13, v14, s38, v13
	global_store_dwordx4 v0, v[10:13], s[6:7] offset:1024 sc1
	v_bfe_u32 v14, v29, 16, 1
	v_add3_u32 v14, v29, v14, s37
	v_bfe_u32 v10, v15, 16, 1
	v_add3_u32 v10, v15, v10, s37
	v_bfe_u32 v11, v17, 16, 1
	v_lshrrev_b32_e32 v10, 16, v10
	v_add3_u32 v11, v17, v11, s37
	v_and_or_b32 v10, v11, s38, v10
	v_bfe_u32 v11, v19, 16, 1
	v_add3_u32 v11, v19, v11, s37
	v_bfe_u32 v12, v21, 16, 1
	v_lshrrev_b32_e32 v11, 16, v11
	v_add3_u32 v12, v21, v12, s37
	v_and_or_b32 v11, v12, s38, v11
	v_bfe_u32 v12, v23, 16, 1
	v_add3_u32 v12, v23, v12, s37
	v_bfe_u32 v13, v25, 16, 1
	v_lshrrev_b32_e32 v12, 16, v12
	v_add3_u32 v13, v25, v13, s37
	v_and_or_b32 v12, v13, s38, v12
	v_bfe_u32 v13, v27, 16, 1
	v_add3_u32 v13, v27, v13, s37
	v_lshrrev_b32_e32 v13, 16, v13
	v_and_or_b32 v13, v14, s38, v13
	global_store_dwordx4 v0, v[10:13], s[6:7] offset:2048 sc1
	v_bfe_u32 v14, v61, 16, 1
	v_add3_u32 v14, v61, v14, s37
	v_bfe_u32 v10, v31, 16, 1
	v_add3_u32 v10, v31, v10, s37
	v_bfe_u32 v11, v33, 16, 1
	v_lshrrev_b32_e32 v10, 16, v10
	v_add3_u32 v11, v33, v11, s37
	v_and_or_b32 v10, v11, s38, v10
	v_bfe_u32 v11, v35, 16, 1
	v_add3_u32 v11, v35, v11, s37
	v_bfe_u32 v12, v37, 16, 1
	v_lshrrev_b32_e32 v11, 16, v11
	v_add3_u32 v12, v37, v12, s37
	v_and_or_b32 v11, v12, s38, v11
	v_bfe_u32 v12, v39, 16, 1
	v_add3_u32 v12, v39, v12, s37
	v_bfe_u32 v13, v41, 16, 1
	v_lshrrev_b32_e32 v12, 16, v12
	v_add3_u32 v13, v41, v13, s37
	v_and_or_b32 v12, v13, s38, v12
	v_bfe_u32 v13, v43, 16, 1
	v_add3_u32 v13, v43, v13, s37
	v_lshrrev_b32_e32 v13, 16, v13
	v_and_or_b32 v13, v14, s38, v13
	global_store_dwordx4 v0, v[10:13], s[6:7] offset:3072 sc1
	s_waitcnt lgkmcnt(0)

; __device__ __forceinline__ void transpose_item(const float* W, int K, int N, bf16* WT, const float* gain, bool swiglu, LAS float* scr, int item, int lane) {
;     const int nblk = N / 32, kb = item / nblk, nb = item % nblk, k0 = 64 * kb, n0 = 32 * nb;
;     int dr = n0;
;     if (swiglu) { if (n0 < DFF) dr = 256 * (n0 / 128) + (n0 % 128); else { const int j = n0 - DFF; dr = 256 * (j / 128) + 128 + (j % 128); } }
;     float v[32];
; #pragma unroll
;     for (int i = 0; i < 32; ++i) v[i] = W[(size_t)(k0 + 2 * i + (lane >> 5)) * N + n0 + (lane & 31)];
;     if (gain) {
; #pragma unroll
;         for (int i = 0; i < 32; ++i) v[i] *= gain[k0 + 2 * i + (lane >> 5)]; }
; #pragma unroll
;     for (int i = 0; i < 32; ++i) scr[(2 * i + (lane >> 5)) * 33 + (lane & 31)] = v[i];
; __global__ void __launch_bounds__(NTHR, 2) mk_fwd(Args args) {
;     ...
;               for (int it = me * NWAVES + wave; it < NDEF; it += nidle * NWAVES) { int r = it;
;                   if (r < I_UP) { transpose_item(args.in[13], D, NUP, Wup2, args.in[12], true, scr, r, lane); continue; } r -= I_UP;
;                   if (r < I_DN) { transpose_item(args.in[14], DFF, D, Wdn2, nullptr, false, scr, r, lane); continue; } r -= I_DN;
;                   if (r < I_SQ) { transpose_item(args.in[7], D, D, Watt, nullptr, false, scr, r, lane); continue; } r -= I_SQ;
;                   transpose_item(args.in[11], D, D, Wout, nullptr, false, scr, r, lane); } } } }
.LBB0_422:
	s_andn2_b64 vcc, exec, s[6:7]
	s_cbranch_vccnz .LBB0_424
	s_add_i32 s2, s14, 0xf500
	s_bfe_u32 s6, s2, 0xb0005
	s_and_b32 s2, s17, 0x3e0
	s_lshl_b32 s2, s2, 2
	v_lshl_add_u64 v[10:11], v[6:7], 0, s[2:3]
	v_lshl_or_b32 v0, s6, 18, v49
	v_lshl_add_u64 v[10:11], v[10:11], 0, v[0:1]
	v_add_co_u32_e32 v12, vcc, 0x2000, v10
	s_bfe_u32 s2, s17, 0x20008
	s_nop 0
	v_addc_co_u32_e32 v13, vcc, 0, v11, vcc
	v_add_co_u32_e32 v14, vcc, 0x4000, v10
	s_mul_i32 s2, s2, 44
	s_nop 0
	v_addc_co_u32_e32 v15, vcc, 0, v11, vcc
	v_add_co_u32_e32 v16, vcc, 0x6000, v10
	s_add_i32 s2, s2, s6
	s_nop 0
	v_addc_co_u32_e32 v17, vcc, 0, v11, vcc
	v_add_co_u32_e32 v18, vcc, 0x8000, v10
	s_lshl_b32 s2, s2, 15
	s_nop 0
	v_addc_co_u32_e32 v19, vcc, 0, v11, vcc
	v_add_co_u32_e32 v20, vcc, 0xa000, v10
	s_and_b32 s6, s35, 0x4000
	s_nop 0
	v_addc_co_u32_e32 v21, vcc, 0, v11, vcc
	v_add_co_u32_e32 v22, vcc, 0xc000, v10
	s_or_b32 s2, s2, s6
	s_nop 0
	v_addc_co_u32_e32 v23, vcc, 0, v11, vcc
	v_add_co_u32_e32 v24, vcc, 0xe000, v10
	s_add_u32 s6, s94, s2
	s_nop 0
	v_addc_co_u32_e32 v25, vcc, 0, v11, vcc
	global_load_dword v0, v[10:11], off
	global_load_dword v28, v[12:13], off
	global_load_dword v29, v[14:15], off
	global_load_dword v30, v[16:17], off
	global_load_dword v31, v[18:19], off
	global_load_dword v32, v[20:21], off
	global_load_dword v33, v[22:23], off
	global_load_dword v34, v[24:25], off
	v_add_co_u32_e32 v12, vcc, 0x10000, v10
	s_addc_u32 s7, s95, 0
	s_nop 0
	v_addc_co_u32_e32 v13, vcc, 0, v11, vcc
	v_add_co_u32_e32 v14, vcc, 0x12000, v10
	s_and_b32 s2, s35, 0x3000
	s_nop 0
	v_addc_co_u32_e32 v15, vcc, 0, v11, vcc
	v_add_co_u32_e32 v16, vcc, 0x14000, v10
	s_nop 1
	v_addc_co_u32_e32 v17, vcc, 0, v11, vcc
	v_add_co_u32_e32 v18, vcc, 0x16000, v10
	s_nop 1
	v_addc_co_u32_e32 v19, vcc, 0, v11, vcc
	v_add_co_u32_e32 v20, vcc, 0x18000, v10
	s_nop 1
	v_addc_co_u32_e32 v21, vcc, 0, v11, vcc
	v_add_co_u32_e32 v22, vcc, 0x1a000, v10
	s_nop 1
	v_addc_co_u32_e32 v23, vcc, 0, v11, vcc
	v_add_co_u32_e32 v24, vcc, 0x1c000, v10
	s_nop 1
	v_addc_co_u32_e32 v25, vcc, 0, v11, vcc
	v_add_co_u32_e32 v26, vcc, 0x1e000, v10
	s_nop 1
	v_addc_co_u32_e32 v27, vcc, 0, v11, vcc
	global_load_dword v35, v[12:13], off
	global_load_dword v36, v[14:15], off
	global_load_dword v37, v[16:17], off
	global_load_dword v38, v[18:19], off
	global_load_dword v39, v[20:21], off
	global_load_dword v40, v[22:23], off
	global_load_dword v41, v[24:25], off
	global_load_dword v42, v[26:27], off
	v_add_co_u32_e32 v12, vcc, 0x20000, v10
	s_nop 1
	v_addc_co_u32_e32 v13, vcc, 0, v11, vcc
	v_add_co_u32_e32 v14, vcc, 0x22000, v10
	s_nop 1
	v_addc_co_u32_e32 v15, vcc, 0, v11, vcc
	v_add_co_u32_e32 v16, vcc, 0x24000, v10
	s_nop 1
	v_addc_co_u32_e32 v17, vcc, 0, v11, vcc
	v_add_co_u32_e32 v18, vcc, 0x26000, v10
	s_nop 1
	v_addc_co_u32_e32 v19, vcc, 0, v11, vcc
	v_add_co_u32_e32 v20, vcc, 0x28000, v10
	s_nop 1
	v_addc_co_u32_e32 v21, vcc, 0, v11, vcc
	v_add_co_u32_e32 v22, vcc, 0x2a000, v10
	s_nop 1
	v_addc_co_u32_e32 v23, vcc, 0, v11, vcc
	v_add_co_u32_e32 v24, vcc, 0x2c000, v10
	s_nop 1
	v_addc_co_u32_e32 v25, vcc, 0, v11, vcc
	v_add_co_u32_e32 v26, vcc, 0x2e000, v10
	s_nop 1
	v_addc_co_u32_e32 v27, vcc, 0, v11, vcc
	global_load_dword v43, v[12:13], off
	global_load_dword v59, v[14:15], off
	global_load_dword v60, v[16:17], off
	global_load_dword v61, v[18:19], off
	global_load_dword v62, v[20:21], off
	global_load_dword v63, v[22:23], off
	global_load_dword v64, v[24:25], off
	s_nop 0
	global_load_dword v26, v[26:27], off
	v_add_co_u32_e32 v12, vcc, 0x30000, v10
	s_nop 1
	v_addc_co_u32_e32 v13, vcc, 0, v11, vcc
	v_add_co_u32_e32 v14, vcc, 0x32000, v10
	s_nop 1
	v_addc_co_u32_e32 v15, vcc, 0, v11, vcc
	v_add_co_u32_e32 v16, vcc, 0x34000, v10
	s_nop 1
	v_addc_co_u32_e32 v17, vcc, 0, v11, vcc
	v_add_co_u32_e32 v18, vcc, 0x36000, v10
	s_nop 1
	v_addc_co_u32_e32 v19, vcc, 0, v11, vcc
	v_add_co_u32_e32 v20, vcc, 0x38000, v10
	s_nop 1
	v_addc_co_u32_e32 v21, vcc, 0, v11, vcc
	v_add_co_u32_e32 v22, vcc, 0x3a000, v10
	s_nop 1
	v_addc_co_u32_e32 v23, vcc, 0, v11, vcc
	v_add_co_u32_e32 v24, vcc, 0x3c000, v10
	s_nop 1
	v_addc_co_u32_e32 v25, vcc, 0, v11, vcc
	v_add_co_u32_e32 v10, vcc, 0x3e000, v10
	s_nop 1
	v_addc_co_u32_e32 v11, vcc, 0, v11, vcc
	global_load_dword v12, v[12:13], off
	s_nop 0
	global_load_dword v13, v[14:15], off
	s_nop 0
	global_load_dword v14, v[16:17], off
	global_load_dword v15, v[18:19], off
	s_nop 0
	global_load_dword v16, v[20:21], off
	global_load_dword v17, v[22:23], off
	global_load_dword v18, v[24:25], off
	s_nop 0
	global_load_dword v10, v[10:11], off
	s_waitcnt vmcnt(30)
	ds_write2_b32 v45, v0, v28 offset1:66
	s_waitcnt vmcnt(28)
	ds_write2_b32 v45, v29, v30 offset0:132 offset1:198
	s_waitcnt vmcnt(26)
	ds_write2_b32 v50, v31, v32 offset0:8 offset1:74
	s_waitcnt vmcnt(24)
	ds_write2_b32 v50, v33, v34 offset0:140 offset1:206
	s_waitcnt vmcnt(22)
	ds_write2_b32 v51, v35, v36 offset0:16 offset1:82
	s_waitcnt vmcnt(20)
	ds_write2_b32 v51, v37, v38 offset0:148 offset1:214
	s_waitcnt vmcnt(18)
; #define LAS __attribute__((address_space(3)))
; __device__ __forceinline__ unsigned pk2(float lo, float hi) { return f2bf(lo) | (f2bf(hi) << 16); }
; __device__ __forceinline__ void transpose_item(const float* W, int K, int N, bf16* WT, const float* gain, bool swiglu, LAS float* scr, int item, int lane) {
;     ...
;     for (int i = 0; i < 32; ++i) scr[(2 * i + (lane >> 5)) * 33 + (lane & 31)] = v[i];
;     asm volatile("s_waitcnt lgkmcnt(0)" ::: "memory");
;     const int r = lane & 15, ck = lane >> 4;
;     const int pnT = dr >> 8, rl = dr & 255;
;     char* blk = (char*)WT + ((size_t)((pnT * (K >> 6) + kb) * 2 + (rl >> 7)) * 16384);
; #pragma unroll
;     for (int rb = 0; rb < 2; ++rb)
; #pragma unroll
;         for (int ch = 0; ch < 2; ++ch) { const int s = 16 * rb + r, v = pg8::perm32(s);
;             const LAS float* sp = scr + (32 * ch + 8 * ck) * 33 + v;
;             u32x4 o; o.x = pk2(sp[0 * 33], sp[1 * 33]); o.y = pk2(sp[2 * 33], sp[3 * 33]); o.z = pk2(sp[4 * 33], sp[5 * 33]); o.w = pk2(sp[6 * 33], sp[7 * 33]);
;             *(u32x4*)(blk + pg8::lds_byte((rl & 127) + s, 32 * ch + 8 * ck)) = o; }
;     asm volatile("s_waitcnt lgkmcnt(0)" ::: "memory");
	ds_write2_b32 v52, v39, v40 offset0:24 offset1:90
	s_waitcnt vmcnt(16)
	ds_write2_b32 v52, v41, v42 offset0:156 offset1:222
	s_waitcnt vmcnt(14)
	ds_write2_b32 v53, v43, v59 offset0:32 offset1:98
	s_waitcnt vmcnt(12)
	ds_write2_b32 v53, v60, v61 offset0:164 offset1:230
	s_waitcnt vmcnt(10)
	ds_write2_b32 v54, v62, v63 offset0:40 offset1:106
	s_waitcnt vmcnt(8)
	ds_write2_b32 v54, v64, v26 offset0:172 offset1:238
	s_waitcnt vmcnt(6)
	ds_write2_b32 v55, v12, v13 offset0:48 offset1:114
	s_waitcnt vmcnt(4)
	ds_write2_b32 v55, v14, v15 offset0:180 offset1:246
	s_waitcnt vmcnt(2)
	ds_write2_b32 v56, v16, v17 offset0:56 offset1:122
	s_waitcnt vmcnt(0)
	ds_write2_b32 v56, v18, v10 offset0:188 offset1:254
	s_waitcnt lgkmcnt(0)
	ds_read2_b32 v[14:15], v48 offset1:4
	ds_read2_b32 v[16:17], v48 offset0:33 offset1:37
	ds_read2_b32 v[18:19], v48 offset0:66 offset1:70
	ds_read2_b32 v[20:21], v48 offset0:99 offset1:103
	ds_read2_b32 v[22:23], v48 offset0:132 offset1:136
	s_waitcnt lgkmcnt(4)
	v_bfe_u32 v0, v14, 16, 1
	v_add3_u32 v0, v14, v0, s37
	s_waitcnt lgkmcnt(3)
	v_bfe_u32 v10, v16, 16, 1
	v_lshrrev_b32_e32 v0, 16, v0
	v_add3_u32 v10, v16, v10, s37
	ds_read2_b32 v[24:25], v48 offset0:165 offset1:169
	v_and_or_b32 v10, v10, s38, v0
	s_waitcnt lgkmcnt(3)
	v_bfe_u32 v0, v18, 16, 1
	v_add3_u32 v0, v18, v0, s37
	s_waitcnt lgkmcnt(2)
	v_bfe_u32 v11, v20, 16, 1
	ds_read2_b32 v[26:27], v48 offset0:198 offset1:202
	v_lshrrev_b32_e32 v0, 16, v0
	v_add3_u32 v11, v20, v11, s37
	ds_read2_b32 v[28:29], v48 offset0:231 offset1:235
	v_and_or_b32 v11, v11, s38, v0
	s_waitcnt lgkmcnt(3)
	v_bfe_u32 v0, v22, 16, 1
	v_add3_u32 v0, v22, v0, s37
	s_waitcnt lgkmcnt(2)
	v_bfe_u32 v12, v24, 16, 1
	v_lshrrev_b32_e32 v0, 16, v0
	v_add3_u32 v12, v24, v12, s37
	ds_read2_b32 v[30:31], v57 offset0:32 offset1:36
	v_and_or_b32 v12, v12, s38, v0
	s_waitcnt lgkmcnt(2)
	v_bfe_u32 v0, v26, 16, 1
	ds_read2_b32 v[32:33], v57 offset0:65 offset1:69
	v_add3_u32 v0, v26, v0, s37
	s_waitcnt lgkmcnt(2)
	v_bfe_u32 v13, v28, 16, 1
	v_lshrrev_b32_e32 v0, 16, v0
	v_add3_u32 v13, v28, v13, s37
	ds_read2_b32 v[34:35], v57 offset0:98 offset1:102
	v_and_or_b32 v13, v13, s38, v0
	v_or_b32_e32 v0, s2, v47
	ds_read2_b32 v[36:37], v57 offset0:131 offset1:135
	global_store_dwordx4 v0, v[10:13], s[6:7] sc1
	ds_read2_b32 v[38:39], v57 offset0:164 offset1:168
	ds_read2_b32 v[40:41], v57 offset0:197 offset1:201
	s_waitcnt lgkmcnt(5)
	v_bfe_u32 v10, v30, 16, 1
	v_add3_u32 v10, v30, v10, s37
	s_waitcnt lgkmcnt(4)
	v_bfe_u32 v11, v32, 16, 1
	v_lshrrev_b32_e32 v10, 16, v10
	v_add3_u32 v11, v32, v11, s37
	v_and_or_b32 v10, v11, s38, v10
	s_waitcnt lgkmcnt(3)
	v_bfe_u32 v11, v34, 16, 1
	v_add3_u32 v11, v34, v11, s37
	s_waitcnt lgkmcnt(2)
	v_bfe_u32 v12, v36, 16, 1
	ds_read2_b32 v[42:43], v57 offset0:230 offset1:234
	v_lshrrev_b32_e32 v11, 16, v11
	v_add3_u32 v12, v36, v12, s37
	ds_read2_b32 v[60:61], v58 offset0:7 offset1:11
	v_and_or_b32 v11, v12, s38, v11
	s_waitcnt lgkmcnt(3)
	v_bfe_u32 v12, v38, 16, 1
	v_add3_u32 v12, v38, v12, s37
	s_waitcnt lgkmcnt(2)
	v_bfe_u32 v13, v40, 16, 1
	v_lshrrev_b32_e32 v12, 16, v12
	v_add3_u32 v13, v40, v13, s37
	v_and_or_b32 v12, v13, s38, v12
	s_waitcnt lgkmcnt(1)
	v_bfe_u32 v13, v42, 16, 1
	v_add3_u32 v13, v42, v13, s37
	s_waitcnt lgkmcnt(0)
	v_bfe_u32 v14, v60, 16, 1
	v_lshrrev_b32_e32 v13, 16, v13
	v_add3_u32 v14, v60, v14, s37
	v_and_or_b32 v13, v14, s38, v13
	global_store_dwordx4 v0, v[10:13], s[6:7] offset:1024 sc1
	v_bfe_u32 v14, v29, 16, 1
	v_add3_u32 v14, v29, v14, s37
	v_bfe_u32 v10, v15, 16, 1
	v_add3_u32 v10, v15, v10, s37
	v_bfe_u32 v11, v17, 16, 1
	v_lshrrev_b32_e32 v10, 16, v10
	v_add3_u32 v11, v17, v11, s37
	v_and_or_b32 v10, v11, s38, v10
	v_bfe_u32 v11, v19, 16, 1
	v_add3_u32 v11, v19, v11, s37
	v_bfe_u32 v12, v21, 16, 1
	v_lshrrev_b32_e32 v11, 16, v11
	v_add3_u32 v12, v21, v12, s37
	v_and_or_b32 v11, v12, s38, v11
	v_bfe_u32 v12, v23, 16, 1
	v_add3_u32 v12, v23, v12, s37
	v_bfe_u32 v13, v25, 16, 1
	v_lshrrev_b32_e32 v12, 16, v12
	v_add3_u32 v13, v25, v13, s37
	v_and_or_b32 v12, v13, s38, v12
	v_bfe_u32 v13, v27, 16, 1
	v_add3_u32 v13, v27, v13, s37
	v_lshrrev_b32_e32 v13, 16, v13
	v_and_or_b32 v13, v14, s38, v13
	global_store_dwordx4 v0, v[10:13], s[6:7] offset:2048 sc1
	v_bfe_u32 v14, v61, 16, 1
	v_add3_u32 v14, v61, v14, s37
	v_bfe_u32 v10, v31, 16, 1
	v_add3_u32 v10, v31, v10, s37
	v_bfe_u32 v11, v33, 16, 1
	v_lshrrev_b32_e32 v10, 16, v10
	v_add3_u32 v11, v33, v11, s37
	v_and_or_b32 v10, v11, s38, v10
	v_bfe_u32 v11, v35, 16, 1
	v_add3_u32 v11, v35, v11, s37
	v_bfe_u32 v12, v37, 16, 1
	v_lshrrev_b32_e32 v11, 16, v11
	v_add3_u32 v12, v37, v12, s37
	v_and_or_b32 v11, v12, s38, v11
	v_bfe_u32 v12, v39, 16, 1
	v_add3_u32 v12, v39, v12, s37
	v_bfe_u32 v13, v41, 16, 1
	v_lshrrev_b32_e32 v12, 16, v12
	v_add3_u32 v13, v41, v13, s37
	v_and_or_b32 v12, v13, s38, v12
	v_bfe_u32 v13, v43, 16, 1
	v_add3_u32 v13, v43, v13, s37
	v_lshrrev_b32_e32 v13, 16, v13
	v_and_or_b32 v13, v14, s38, v13
	global_store_dwordx4 v0, v[10:13], s[6:7] offset:3072 sc1
	s_waitcnt lgkmcnt(0)

; #define LAS __attribute__((address_space(3)))
; __device__ __forceinline__ void attn_pool_phase(LAS unsigned char* lds, bf16* QKV, bf16* PL, const float* sinks, int G, int bid) {
;     ...
;             f32x16 S[5];
; #pragma unroll
;             for (int j = 0; j < 5; ++j) { const LAS unsigned char* kp = lds + (32 * (i + j) + q) * KROWB + hi * 16;
;                 f32x16 a = {};
; #pragma unroll
;                 for (int d0 = 0; d0 < 4; ++d0) a = __builtin_amdgcn_mfma_f32_32x32x16_bf16(*(const LAS bf16x8*)(kp + d0 * 32), qf[d0], a, 0, 0, 0);
;                 S[j] = a; }
;             float mx = sink2;
;             int qo = q - 4 * hi; asm volatile("" : "+v"(qo));
;             const float lb = -slopeL * (float)(128 + qo);
; #pragma unroll
;             for (int j = 0; j < 5; ++j) { const bool tile_ok = !(n == 0 && i + j < 4); const float lbj = lb + slopeL * (32.0f * (float)j);
; #pragma unroll
;                 for (int r = 0; r < 16; ++r) { const int crc = (r & 3) + 8 * (r >> 2);
;                     float s = S[j][r] + (lbj + slopeL * (float)crc);
;                     if (j == 0) s = (crc > qo) ? s : -INFINITY;
;                     if (j == 4) s = (crc <= qo) ? s : -INFINITY;
;                     if (!tile_ok) s = -INFINITY;
;                     S[j][r] = s; mx = fmaxf(mx, s); } }
.LBB0_503:
	ds_read_b128 v[0:3], v210
	ds_read_b128 v[16:19], v210 offset:32
	v_mov_b32_e32 v222, v174
	s_add_i32 s2, s36, 1
	s_waitcnt lgkmcnt(1)
	v_mfma_f32_32x32x16_bf16 v[0:15], v[0:3], v[32:35], 0
	s_waitcnt lgkmcnt(0)
	v_mfma_f32_32x32x16_bf16 v[0:15], v[16:19], v[140:143], v[0:15]
	ds_read_b128 v[16:19], v210 offset:64
	ds_read_b128 v[20:23], v210 offset:96
	s_waitcnt lgkmcnt(1)
	v_mfma_f32_32x32x16_bf16 v[0:15], v[16:19], v[136:139], v[0:15]
	ds_read_b128 v[16:19], v210 offset:18432
	ds_read_b128 v[64:67], v210 offset:4608
	ds_read_b128 v[60:63], v210 offset:4640
	ds_read_b128 v[36:39], v210 offset:18464
	ds_read_b128 v[56:59], v210 offset:4672
	ds_read_b128 v[52:55], v210 offset:4704
	ds_read_b128 v[48:51], v210 offset:9216
	ds_read_b128 v[156:159], v210 offset:9248
	ds_read_b128 v[44:47], v210 offset:9280
	ds_read_b128 v[40:43], v210 offset:9312
	ds_read_b128 v[72:75], v210 offset:18496
	s_waitcnt lgkmcnt(11)
	v_mfma_f32_32x32x16_bf16 v[0:15], v[20:23], v[132:135], v[0:15]
	s_waitcnt lgkmcnt(10)
	v_mfma_f32_32x32x16_bf16 v[16:31], v[16:19], v[32:35], 0
	s_waitcnt lgkmcnt(7)
	v_mfma_f32_32x32x16_bf16 v[16:31], v[36:39], v[140:143], v[16:31]
	ds_read_b128 v[36:39], v210 offset:13824
	ds_read_b128 v[152:155], v210 offset:13856
	ds_read_b128 v[148:151], v210 offset:13888
	ds_read_b128 v[144:147], v210 offset:13920
	ds_read_b128 v[68:71], v210 offset:18528
	v_add_u32_e32 v210, 0x1200, v210
	v_add_u32_e32 v76, 0x80, v222
	v_cvt_f32_i32_e32 v221, v76
	v_cmp_gt_i32_e32 vcc, 0, v222
	v_fma_f32 v223, -v161, v221, v190
	s_waitcnt lgkmcnt(5)
	v_mfma_f32_32x32x16_bf16 v[16:31], v[72:75], v[136:139], v[16:31]
	v_add_f32_e32 v72, v190, v223
	v_fma_f32 v224, -v161, v221, v208
	v_add_f32_e32 v0, v0, v72
	v_add_f32_e32 v72, v190, v224
	s_waitcnt lgkmcnt(0)
	v_mfma_f32_32x32x16_bf16 v[16:31], v[68:71], v[132:135], v[16:31]
	s_nop 11
	v_add_f32_e32 v16, v16, v72
	v_mfma_f32_32x32x16_bf16 v[64:79], v[64:67], v[32:35], 0
	v_cndmask_b32_e32 v219, v16, v189, vcc
	v_add_f32_e32 v16, v161, v223
	s_and_b64 vcc, s[10:11], vcc
	v_add_f32_e32 v1, v1, v16
	v_add_f32_e32 v16, v161, v224
	v_cndmask_b32_e32 v0, v189, v0, vcc
	v_add_f32_e32 v16, v17, v16
	v_mfma_f32_32x32x16_bf16 v[64:79], v[60:63], v[140:143], v[64:79]
	v_cmp_gt_i32_e32 vcc, 1, v222
	v_add_f32_e32 v17, v191, v223
	v_add_f32_e32 v2, v2, v17
	v_cndmask_b32_e32 v220, v16, v189, vcc
	s_and_b64 vcc, s[10:11], vcc
	v_add_f32_e32 v17, v191, v224
	v_cndmask_b32_e32 v1, v189, v1, vcc
	v_mfma_f32_32x32x16_bf16 v[64:79], v[56:59], v[136:139], v[64:79]
	v_add_f32_e32 v17, v18, v17
	v_cmp_gt_i32_e32 vcc, 2, v222
	v_max3_f32 v16, v209, v0, v1
	s_nop 0
	v_cndmask_b32_e32 v217, v17, v189, vcc
	v_add_f32_e32 v17, v192, v223
	s_and_b64 vcc, s[10:11], vcc
	v_mfma_f32_32x32x16_bf16 v[64:79], v[52:55], v[132:135], v[64:79]
	v_add_f32_e32 v3, v3, v17
	v_add_f32_e32 v17, v192, v224
	v_cndmask_b32_e32 v2, v189, v2, vcc
	v_add_f32_e32 v17, v19, v17
	v_cmp_gt_i32_e32 vcc, 3, v222
	v_mfma_f32_32x32x16_bf16 v[48:63], v[48:51], v[32:35], 0
	s_nop 0
	v_cndmask_b32_e32 v216, v17, v189, vcc
	v_add_f32_e32 v17, v193, v223
	s_and_b64 vcc, s[10:11], vcc
	v_add_f32_e32 v4, v4, v17
	v_add_f32_e32 v17, v193, v224
	v_cndmask_b32_e32 v3, v189, v3, vcc
	v_add_f32_e32 v17, v20, v17
	v_mfma_f32_32x32x16_bf16 v[48:63], v[156:159], v[140:143], v[48:63]
	v_cmp_gt_i32_e32 vcc, 8, v222
	v_max3_f32 v16, v16, v2, v3
	s_nop 0
	v_cndmask_b32_e32 v214, v17, v189, vcc
	v_add_f32_e32 v17, v194, v223
	s_and_b64 vcc, s[10:11], vcc
	v_add_f32_e32 v5, v5, v17
	v_mfma_f32_32x32x16_bf16 v[48:63], v[44:47], v[136:139], v[48:63]
	v_add_f32_e32 v17, v194, v224
	v_cndmask_b32_e32 v4, v189, v4, vcc
	v_add_f32_e32 v17, v21, v17
	v_cmp_gt_i32_e32 vcc, 9, v222
	s_nop 1
	v_cndmask_b32_e32 v213, v17, v189, vcc
	v_add_f32_e32 v17, v195, v223
	v_mfma_f32_32x32x16_bf16 v[48:63], v[40:43], v[132:135], v[48:63]
	s_and_b64 vcc, s[10:11], vcc
	v_add_f32_e32 v6, v6, v17
	v_add_f32_e32 v17, v195, v224
	v_cndmask_b32_e32 v5, v189, v5, vcc
	v_add_f32_e32 v17, v22, v17
	v_cmp_gt_i32_e32 vcc, 10, v222
	v_max3_f32 v16, v16, v4, v5
	v_mfma_f32_32x32x16_bf16 v[32:47], v[36:39], v[32:35], 0
	v_cndmask_b32_e32 v215, v17, v189, vcc
	v_add_f32_e32 v17, v196, v223
	s_and_b64 vcc, s[10:11], vcc
	v_add_f32_e32 v7, v7, v17
	v_add_f32_e32 v17, v196, v224
	v_cndmask_b32_e32 v6, v189, v6, vcc
	v_add_f32_e32 v17, v23, v17
	v_cmp_gt_i32_e32 vcc, 11, v222
	v_mfma_f32_32x32x16_bf16 v[32:47], v[152:155], v[140:143], v[32:47]
	s_nop 0
	v_cndmask_b32_e32 v212, v17, v189, vcc
	v_add_f32_e32 v17, v197, v223
	s_and_b64 vcc, s[10:11], vcc
	v_add_f32_e32 v8, v8, v17
	v_add_f32_e32 v17, v197, v224
	v_cndmask_b32_e32 v7, v189, v7, vcc
	v_add_f32_e32 v17, v24, v17
	v_cmp_gt_i32_e32 vcc, 16, v222
	v_mfma_f32_32x32x16_bf16 v[32:47], v[148:151], v[136:139], v[32:47]
	v_max3_f32 v16, v16, v6, v7
	v_cndmask_b32_e32 v156, v17, v189, vcc
	v_add_f32_e32 v17, v198, v223
	s_and_b64 vcc, s[10:11], vcc
	v_add_f32_e32 v9, v9, v17
	v_add_f32_e32 v17, v198, v224
	v_cndmask_b32_e32 v8, v189, v8, vcc
	v_add_f32_e32 v17, v25, v17
	v_cmp_gt_i32_e32 vcc, 17, v222
	v_mfma_f32_32x32x16_bf16 v[32:47], v[144:147], v[132:135], v[32:47]
	s_nop 0
	v_cndmask_b32_e32 v158, v17, v189, vcc
	v_add_f32_e32 v17, v199, v223
	s_and_b64 vcc, s[10:11], vcc
	v_add_f32_e32 v10, v10, v17
	v_add_f32_e32 v17, v199, v224
	v_cndmask_b32_e32 v9, v189, v9, vcc
	v_add_f32_e32 v17, v26, v17
	v_cmp_gt_i32_e32 vcc, 18, v222
	v_max3_f32 v16, v16, v8, v9
	s_nop 0
	v_cndmask_b32_e32 v157, v17, v189, vcc
	v_add_f32_e32 v17, v200, v223
	s_and_b64 vcc, s[10:11], vcc
	v_add_f32_e32 v11, v11, v17
	v_add_f32_e32 v17, v200, v224
	v_cndmask_b32_e32 v10, v189, v10, vcc
; #define LAS __attribute__((address_space(3)))
; __device__ __forceinline__ void attn_pool_phase(LAS unsigned char* lds, bf16* QKV, bf16* PL, const float* sinks, int G, int bid) {
;     ...
;             f32x16 S[5];
; #pragma unroll
;             for (int j = 0; j < 5; ++j) { const LAS unsigned char* kp = lds + (32 * (i + j) + q) * KROWB + hi * 16;
;                 f32x16 a = {};
; #pragma unroll
;                 for (int d0 = 0; d0 < 4; ++d0) a = __builtin_amdgcn_mfma_f32_32x32x16_bf16(*(const LAS bf16x8*)(kp + d0 * 32), qf[d0], a, 0, 0, 0);
;                 S[j] = a; }
;             float mx = sink2;
;             int qo = q - 4 * hi; asm volatile("" : "+v"(qo));
;             const float lb = -slopeL * (float)(128 + qo);
; #pragma unroll
;             for (int j = 0; j < 5; ++j) { const bool tile_ok = !(n == 0 && i + j < 4); const float lbj = lb + slopeL * (32.0f * (float)j);
; #pragma unroll
;                 for (int r = 0; r < 16; ++r) { const int crc = (r & 3) + 8 * (r >> 2);
;                     float s = S[j][r] + (lbj + slopeL * (float)crc);
;                     if (j == 0) s = (crc > qo) ? s : -INFINITY;
;                     if (j == 4) s = (crc <= qo) ? s : -INFINITY;
;                     if (!tile_ok) s = -INFINITY;
;                     S[j][r] = s; mx = fmaxf(mx, s); } }
	v_add_f32_e32 v17, v27, v17
	v_cmp_gt_i32_e32 vcc, 19, v222
	s_nop 1
	v_cndmask_b32_e32 v140, v17, v189, vcc
	v_add_f32_e32 v17, v201, v223
	s_and_b64 vcc, s[10:11], vcc
	v_add_f32_e32 v12, v12, v17
	v_add_f32_e32 v17, v201, v224
	v_cndmask_b32_e32 v11, v189, v11, vcc
	v_add_f32_e32 v17, v28, v17
	v_cmp_gt_i32_e32 vcc, 24, v222
	v_max3_f32 v16, v16, v10, v11
	s_nop 0
	v_cndmask_b32_e32 v136, v17, v189, vcc
	v_add_f32_e32 v17, v202, v223
	s_and_b64 vcc, s[10:11], vcc
	v_add_f32_e32 v13, v13, v17
	v_add_f32_e32 v17, v202, v224
	v_cndmask_b32_e32 v12, v189, v12, vcc
	v_add_f32_e32 v17, v29, v17
	v_cmp_gt_i32_e32 vcc, 25, v222
	s_nop 1
	v_cndmask_b32_e32 v133, v17, v189, vcc
	v_add_f32_e32 v17, v203, v223
	s_and_b64 vcc, s[10:11], vcc
	v_add_f32_e32 v14, v14, v17
	v_add_f32_e32 v17, v203, v224
	v_cndmask_b32_e32 v13, v189, v13, vcc
	v_add_f32_e32 v17, v30, v17
	v_cmp_gt_i32_e32 vcc, 26, v222
	v_max3_f32 v16, v16, v12, v13
	s_nop 0
	v_cndmask_b32_e32 v134, v17, v189, vcc
	v_add_f32_e32 v17, v204, v223
	s_and_b64 vcc, s[10:11], vcc
	v_add_f32_e32 v15, v15, v17
	v_add_f32_e32 v17, v204, v224
	v_cndmask_b32_e32 v14, v189, v14, vcc
	v_add_f32_e32 v17, v31, v17
	v_cmp_gt_i32_e32 vcc, 27, v222
	s_nop 1
	v_cndmask_b32_e32 v132, v17, v189, vcc
	v_fma_f32 v17, -v161, v221, v205
	v_add_f32_e32 v19, v161, v17
	v_add_f32_e32 v19, v65, v19
	v_add_f32_e32 v20, v191, v17
	v_fma_f32 v65, -v161, v221, v206
	v_add_f32_e32 v20, v66, v20
	v_add_f32_e32 v66, v190, v65
	v_add_f32_e32 v48, v48, v66
	v_add_f32_e32 v66, v161, v65
	v_add_f32_e32 v49, v49, v66
	v_add_f32_e32 v66, v191, v65
	v_add_f32_e32 v50, v50, v66
	v_add_f32_e32 v66, v192, v65
	v_add_f32_e32 v51, v51, v66
	v_add_f32_e32 v66, v193, v65
	v_add_f32_e32 v52, v52, v66
	v_add_f32_e32 v66, v194, v65
	v_add_f32_e32 v53, v53, v66
	v_add_f32_e32 v66, v195, v65
	v_add_f32_e32 v54, v54, v66
	v_add_f32_e32 v66, v196, v65
	v_add_f32_e32 v55, v55, v66
	v_add_f32_e32 v66, v197, v65
	s_and_b64 vcc, s[10:11], vcc
	v_add_f32_e32 v56, v56, v66
	v_add_f32_e32 v66, v198, v65
	s_cmp_gt_u32 s36, 2
	v_add_f32_e32 v57, v57, v66
	v_add_f32_e32 v66, v199, v65
	s_cselect_b64 s[8:9], -1, 0
	v_add_f32_e32 v58, v58, v66
	v_add_f32_e32 v66, v200, v65
	v_cndmask_b32_e32 v15, v189, v15, vcc
	v_add_f32_e32 v18, v190, v17
	s_or_b64 vcc, s[10:11], s[8:9]
	v_add_f32_e32 v59, v59, v66
	v_add_f32_e32 v66, v201, v65
	v_add_f32_e32 v18, v64, v18
	v_add_f32_e32 v21, v192, v17
	v_add_f32_e32 v22, v193, v17
	v_add_f32_e32 v23, v194, v17
	v_add_f32_e32 v24, v195, v17
	v_add_f32_e32 v25, v196, v17
	v_add_f32_e32 v26, v197, v17
	v_add_f32_e32 v27, v198, v17
	v_add_f32_e32 v28, v199, v17
	v_add_f32_e32 v29, v200, v17
	v_add_f32_e32 v30, v201, v17
	v_add_f32_e32 v31, v202, v17
	v_add_f32_e32 v64, v203, v17
	v_add_f32_e32 v17, v204, v17
	s_cmp_gt_u32 s36, 1
	v_add_f32_e32 v60, v60, v66
	v_add_f32_e32 v66, v202, v65
	v_add_f32_e32 v21, v67, v21
	v_add_f32_e32 v22, v68, v22
	v_add_f32_e32 v23, v69, v23
	v_add_f32_e32 v24, v70, v24
	v_add_f32_e32 v25, v71, v25
	v_add_f32_e32 v26, v72, v26
	v_add_f32_e32 v27, v73, v27
	v_add_f32_e32 v28, v74, v28
	v_add_f32_e32 v29, v75, v29
	v_add_f32_e32 v30, v76, v30
	v_add_f32_e32 v31, v77, v31
	v_add_f32_e32 v64, v78, v64
	v_add_f32_e32 v17, v79, v17
	s_cselect_b64 s[8:9], -1, 0
	v_add_f32_e32 v61, v61, v66
	v_add_f32_e32 v66, v203, v65
	v_add_f32_e32 v65, v204, v65
	v_cndmask_b32_e32 v18, v189, v18, vcc
	v_cndmask_b32_e32 v19, v189, v19, vcc
	v_cndmask_b32_e32 v20, v189, v20, vcc
	v_cndmask_b32_e32 v21, v189, v21, vcc
	v_cndmask_b32_e32 v22, v189, v22, vcc
	v_cndmask_b32_e32 v23, v189, v23, vcc
	v_cndmask_b32_e32 v24, v189, v24, vcc
	v_cndmask_b32_e32 v25, v189, v25, vcc
	v_cndmask_b32_e32 v26, v189, v26, vcc
	v_cndmask_b32_e32 v27, v189, v27, vcc
	v_cndmask_b32_e32 v28, v189, v28, vcc
	v_cndmask_b32_e32 v29, v189, v29, vcc
	v_cndmask_b32_e32 v30, v189, v30, vcc
	v_cndmask_b32_e32 v31, v189, v31, vcc
	v_cndmask_b32_e32 v64, v189, v64, vcc
	v_cndmask_b32_e32 v17, v189, v17, vcc
	s_or_b64 vcc, s[10:11], s[8:9]
	v_add_f32_e32 v63, v63, v65
	s_or_b32 s8, s36, s42
	v_fma_f32 v65, -v161, v221, v207
	v_add_f32_e32 v62, v62, v66
	s_cmp_eq_u32 s8, 0
	v_add_f32_e32 v66, v190, v65
	v_cndmask_b32_e32 v48, v189, v48, vcc
	v_cndmask_b32_e32 v49, v189, v49, vcc
	v_cndmask_b32_e32 v50, v189, v50, vcc
	v_cndmask_b32_e32 v51, v189, v51, vcc
	v_cndmask_b32_e32 v52, v189, v52, vcc
	v_cndmask_b32_e32 v53, v189, v53, vcc
	v_cndmask_b32_e32 v54, v189, v54, vcc
	v_cndmask_b32_e32 v55, v189, v55, vcc
	v_cndmask_b32_e32 v56, v189, v56, vcc
	v_cndmask_b32_e32 v57, v189, v57, vcc
	v_cndmask_b32_e32 v58, v189, v58, vcc
	v_cndmask_b32_e32 v59, v189, v59, vcc
	v_cndmask_b32_e32 v60, v189, v60, vcc
	v_cndmask_b32_e32 v61, v189, v61, vcc
	v_cndmask_b32_e32 v62, v189, v62, vcc
	v_cndmask_b32_e32 v63, v189, v63, vcc
	v_add_f32_e32 v32, v32, v66
	s_cselect_b64 vcc, -1, 0
	v_cndmask_b32_e32 v66, v32, v189, vcc
	v_add_f32_e32 v32, v161, v65
	v_add_f32_e32 v32, v33, v32
	v_cndmask_b32_e32 v67, v32, v189, vcc
	v_add_f32_e32 v32, v191, v65
	v_add_f32_e32 v32, v34, v32
	v_cndmask_b32_e32 v34, v32, v189, vcc
	v_add_f32_e32 v32, v192, v65
	v_add_f32_e32 v32, v35, v32
	v_cndmask_b32_e32 v35, v32, v189, vcc
	v_add_f32_e32 v32, v193, v65
	v_max3_f32 v16, v16, v14, v15
	v_add_f32_e32 v32, v36, v32
	v_max3_f32 v16, v16, v18, v19
	v_cndmask_b32_e32 v36, v32, v189, vcc
	v_add_f32_e32 v32, v194, v65
	v_max3_f32 v16, v16, v20, v21
	v_add_f32_e32 v32, v37, v32
	v_max3_f32 v16, v16, v22, v23
	v_cndmask_b32_e32 v37, v32, v189, vcc
	v_add_f32_e32 v32, v195, v65
	v_max3_f32 v16, v16, v24, v25
	v_add_f32_e32 v32, v38, v32
	v_max3_f32 v16, v16, v26, v27
; __device__ __forceinline__ void attn_pool_phase(LAS unsigned char* lds, bf16* QKV, bf16* PL, const float* sinks, int G, int bid) {
;     ...
;             float mx = sink2;
;             int qo = q - 4 * hi; asm volatile("" : "+v"(qo));
;             const float lb = -slopeL * (float)(128 + qo);
; #pragma unroll
;             for (int j = 0; j < 5; ++j) { const bool tile_ok = !(n == 0 && i + j < 4); const float lbj = lb + slopeL * (32.0f * (float)j);
; #pragma unroll
;                 for (int r = 0; r < 16; ++r) { const int crc = (r & 3) + 8 * (r >> 2);
;                     float s = S[j][r] + (lbj + slopeL * (float)crc);
;                     if (j == 0) s = (crc > qo) ? s : -INFINITY;
;                     if (j == 4) s = (crc <= qo) ? s : -INFINITY;
;                     if (!tile_ok) s = -INFINITY;
;                     S[j][r] = s; mx = fmaxf(mx, s); } }
;             mx = fmaxf(mx, __shfl_xor(mx, 32));
;             float l = 0.f;
; #pragma unroll
;             for (int j = 0; j < 5; ++j)
; #pragma unroll
;                 for (int r = 0; r < 16; ++r) { const float p = __builtin_amdgcn_exp2f(S[j][r] - mx); S[j][r] = p; l += p; }
	v_cndmask_b32_e32 v38, v32, v189, vcc
	v_add_f32_e32 v32, v196, v65
	v_max3_f32 v16, v16, v28, v29
	v_add_f32_e32 v32, v39, v32
	v_max3_f32 v16, v16, v30, v31
	v_cndmask_b32_e32 v39, v32, v189, vcc
	v_add_f32_e32 v32, v197, v65
	v_max3_f32 v16, v16, v64, v17
	v_add_f32_e32 v32, v40, v32
	v_max3_f32 v16, v16, v48, v49
	v_cndmask_b32_e32 v40, v32, v189, vcc
	v_add_f32_e32 v32, v198, v65
	v_max3_f32 v16, v16, v50, v51
	v_add_f32_e32 v32, v41, v32
	v_max3_f32 v16, v16, v52, v53
	v_cndmask_b32_e32 v41, v32, v189, vcc
	v_add_f32_e32 v32, v199, v65
	v_max3_f32 v16, v16, v54, v55
	v_add_f32_e32 v32, v42, v32
	v_max3_f32 v16, v16, v56, v57
	v_cndmask_b32_e32 v42, v32, v189, vcc
	v_add_f32_e32 v32, v200, v65
	v_max3_f32 v16, v16, v58, v59
	v_add_f32_e32 v32, v43, v32
	v_max3_f32 v16, v16, v60, v61
	v_cndmask_b32_e32 v43, v32, v189, vcc
	v_add_f32_e32 v32, v201, v65
	v_max3_f32 v16, v16, v62, v63
	v_add_f32_e32 v32, v44, v32
	v_max3_f32 v16, v16, v66, v67
	v_cndmask_b32_e32 v68, v32, v189, vcc
	v_add_f32_e32 v32, v202, v65
	v_max3_f32 v16, v16, v34, v35
	v_add_f32_e32 v32, v45, v32
	v_max3_f32 v16, v16, v36, v37
	v_cndmask_b32_e32 v69, v32, v189, vcc
	v_add_f32_e32 v32, v203, v65
	v_max3_f32 v16, v16, v38, v39
	v_add_f32_e32 v32, v46, v32
	v_max3_f32 v16, v16, v40, v41
	v_cndmask_b32_e32 v70, v32, v189, vcc
	v_add_f32_e32 v32, v204, v65
	v_max3_f32 v16, v16, v42, v43
	v_add_f32_e32 v32, v47, v32
	v_max3_f32 v16, v16, v68, v69
	v_cndmask_b32_e32 v65, v32, v189, vcc
	v_max3_f32 v16, v16, v70, v65
	v_max3_f32 v16, v16, v219, v220
	v_max3_f32 v16, v16, v217, v216
	v_max3_f32 v16, v16, v214, v213
	v_max3_f32 v16, v16, v215, v212
	v_and_b32_e32 v33, 64, v183
	v_max3_f32 v16, v16, v156, v158
	v_xor_b32_e32 v32, 32, v183
	v_add_u32_e32 v33, 64, v33
	v_max3_f32 v16, v16, v157, v140
	v_cmp_lt_i32_e32 vcc, v32, v33
	v_max3_f32 v16, v16, v136, v133
	v_max3_f32 v16, v16, v134, v132
	v_cndmask_b32_e32 v32, v183, v32, vcc
	v_lshlrev_b32_e32 v32, 2, v32
	ds_bpermute_b32 v33, v32, v16
	v_add_u32_e32 v221, 0x4000, v211
	s_mov_b32 s36, s2
	s_waitcnt lgkmcnt(0)
	v_max_f32_e32 v33, v33, v33
	v_max_f32_e32 v33, v16, v33
	v_sub_f32_e32 v0, v0, v33
	v_exp_f32_e32 v0, v0
	v_sub_f32_e32 v1, v1, v33
	v_exp_f32_e32 v1, v1
	v_sub_f32_e32 v2, v2, v33
	v_exp_f32_e32 v2, v2
	v_sub_f32_e32 v3, v3, v33
	v_exp_f32_e32 v3, v3
	v_sub_f32_e32 v4, v4, v33
	v_add_f32_e32 v16, 0, v0
	v_exp_f32_e32 v4, v4
	v_sub_f32_e32 v5, v5, v33
	v_add_f32_e32 v16, v1, v16
	v_exp_f32_e32 v5, v5
	v_sub_f32_e32 v6, v6, v33
	v_add_f32_e32 v16, v2, v16
	v_exp_f32_e32 v6, v6
	v_sub_f32_e32 v7, v7, v33
	v_add_f32_e32 v16, v3, v16
	v_exp_f32_e32 v7, v7
	v_sub_f32_e32 v8, v8, v33
	v_add_f32_e32 v16, v4, v16
	v_exp_f32_e32 v44, v8
	v_sub_f32_e32 v8, v9, v33
	v_add_f32_e32 v16, v5, v16
	v_exp_f32_e32 v45, v8
	v_sub_f32_e32 v8, v10, v33
	v_add_f32_e32 v16, v6, v16
	v_exp_f32_e32 v46, v8
	v_sub_f32_e32 v9, v11, v33
	v_add_f32_e32 v8, v7, v16
	v_exp_f32_e32 v47, v9
	v_sub_f32_e32 v9, v12, v33
	v_add_f32_e32 v8, v44, v8
	v_exp_f32_e32 v71, v9
	v_sub_f32_e32 v9, v13, v33
	v_add_f32_e32 v8, v45, v8
	v_exp_f32_e32 v72, v9
	v_sub_f32_e32 v9, v14, v33
	v_add_f32_e32 v8, v46, v8
	v_exp_f32_e32 v73, v9
	v_sub_f32_e32 v9, v15, v33
	v_add_f32_e32 v8, v47, v8
	v_exp_f32_e32 v74, v9
	v_sub_f32_e32 v9, v18, v33
	v_add_f32_e32 v8, v71, v8
	v_exp_f32_e32 v75, v9
	v_sub_f32_e32 v9, v19, v33
	v_add_f32_e32 v8, v72, v8
	v_exp_f32_e32 v76, v9
	v_sub_f32_e32 v9, v20, v33
	v_add_f32_e32 v8, v73, v8
	v_exp_f32_e32 v77, v9
	v_sub_f32_e32 v9, v21, v33
	v_add_f32_e32 v8, v74, v8
	v_exp_f32_e32 v78, v9
	v_sub_f32_e32 v9, v22, v33
	v_add_f32_e32 v8, v75, v8
	v_exp_f32_e32 v79, v9
	v_sub_f32_e32 v9, v23, v33
	v_add_f32_e32 v8, v76, v8
	v_exp_f32_e32 v135, v9
	v_sub_f32_e32 v9, v24, v33
	v_add_f32_e32 v8, v77, v8
	v_exp_f32_e32 v137, v9
	v_sub_f32_e32 v9, v25, v33
	v_add_f32_e32 v8, v78, v8
	v_exp_f32_e32 v138, v9
	v_sub_f32_e32 v9, v26, v33
	v_add_f32_e32 v8, v79, v8
	v_exp_f32_e32 v139, v9
	v_sub_f32_e32 v9, v27, v33
	v_add_f32_e32 v8, v135, v8
	v_exp_f32_e32 v141, v9
	v_sub_f32_e32 v9, v28, v33
	v_add_f32_e32 v8, v137, v8
	v_exp_f32_e32 v142, v9
	v_sub_f32_e32 v9, v29, v33
	v_add_f32_e32 v8, v138, v8
	v_exp_f32_e32 v143, v9
	v_sub_f32_e32 v9, v30, v33
	v_add_f32_e32 v8, v139, v8
	v_exp_f32_e32 v144, v9
	v_sub_f32_e32 v9, v31, v33
	v_add_f32_e32 v8, v141, v8
	v_exp_f32_e32 v145, v9
	v_sub_f32_e32 v9, v64, v33
	v_add_f32_e32 v8, v142, v8
	v_exp_f32_e32 v64, v9
	v_sub_f32_e32 v9, v17, v33
	v_add_f32_e32 v8, v143, v8
	v_exp_f32_e32 v146, v9
	v_sub_f32_e32 v9, v48, v33
	v_add_f32_e32 v8, v144, v8
	v_exp_f32_e32 v147, v9
	v_sub_f32_e32 v9, v49, v33
	v_add_f32_e32 v8, v145, v8
	v_exp_f32_e32 v148, v9
	v_sub_f32_e32 v9, v50, v33
	v_add_f32_e32 v8, v64, v8
	v_exp_f32_e32 v50, v9
	v_sub_f32_e32 v9, v51, v33
	v_add_f32_e32 v8, v146, v8
	v_exp_f32_e32 v51, v9
	v_sub_f32_e32 v9, v52, v33
	v_add_f32_e32 v8, v147, v8
	v_exp_f32_e32 v52, v9
	v_sub_f32_e32 v9, v53, v33
	v_add_f32_e32 v8, v148, v8
	v_exp_f32_e32 v53, v9
	v_sub_f32_e32 v9, v54, v33
	v_add_f32_e32 v8, v50, v8
	v_exp_f32_e32 v54, v9
	v_sub_f32_e32 v9, v55, v33
	v_add_f32_e32 v8, v51, v8
	v_exp_f32_e32 v55, v9
	v_sub_f32_e32 v9, v56, v33
	v_add_f32_e32 v8, v52, v8
	v_exp_f32_e32 v56, v9
	v_sub_f32_e32 v9, v57, v33
	v_add_f32_e32 v8, v53, v8
	v_exp_f32_e32 v57, v9
	v_sub_f32_e32 v9, v58, v33
	v_add_f32_e32 v8, v54, v8
	v_exp_f32_e32 v58, v9
	v_sub_f32_e32 v9, v59, v33
	v_add_f32_e32 v8, v55, v8
	v_exp_f32_e32 v59, v9
	v_sub_f32_e32 v9, v60, v33
	v_add_f32_e32 v8, v56, v8
	v_exp_f32_e32 v60, v9
	v_sub_f32_e32 v9, v61, v33
	v_add_f32_e32 v8, v57, v8
	v_exp_f32_e32 v61, v9
	v_sub_f32_e32 v9, v62, v33
; __device__ __forceinline__ unsigned cvt_pk_bf16(float lo, float hi) { unsigned r; asm volatile("v_cvt_pk_bf16_f32 %0, %1, %2" : "=v"(r) : "v"(lo), "v"(hi)); return r; }
; #define LAS __attribute__((address_space(3)))
; __device__ __forceinline__ void attn_pool_phase(LAS unsigned char* lds, bf16* QKV, bf16* PL, const float* sinks, int G, int bid) {
;     ...
;             float l = 0.f;
; #pragma unroll
;             for (int j = 0; j < 5; ++j)
; #pragma unroll
;                 for (int r = 0; r < 16; ++r) { const float p = __builtin_amdgcn_exp2f(S[j][r] - mx); S[j][r] = p; l += p; }
;             l += __shfl_xor(l, 32); l += __builtin_amdgcn_exp2f(sink2 - mx);
;             f32x16 o0 = {}, o1 = {};
; #pragma unroll
;             for (int j = 0; j < 5; ++j)
; #pragma unroll
;                 for (int c = 0; c < 2; ++c) {
;                     u32x4 pw; pw.x = pg8::cvt_pk_bf16(S[j][8 * c + 0], S[j][8 * c + 1]); pw.y = pg8::cvt_pk_bf16(S[j][8 * c + 2], S[j][8 * c + 3]);
;                     pw.z = pg8::cvt_pk_bf16(S[j][8 * c + 4], S[j][8 * c + 5]); pw.w = pg8::cvt_pk_bf16(S[j][8 * c + 6], S[j][8 * c + 7]);
;                     const bf16x8 pb = __builtin_bit_cast(bf16x8, pw);
;                     const LAS unsigned char* vp = lds + LDS_VT + q * VROWB + (32 * (i + j) + 16 * c + 4 * hi) * 2;
;                     const u32x2 a0 = *(const LAS u32x2*)vp, a1 = *(const LAS u32x2*)(vp + 16), b0 = *(const LAS u32x2*)(vp + 32 * VROWB), b1 = *(const LAS u32x2*)(vp + 32 * VROWB + 16);
;                     const bf16x8 va = __builtin_bit_cast(bf16x8, (u32x4){a0.x, a0.y, a1.x, a1.y}), vb = __builtin_bit_cast(bf16x8, (u32x4){b0.x, b0.y, b1.x, b1.y});
;                     o0 = __builtin_amdgcn_mfma_f32_32x32x16_bf16(va, pb, o0, 0, 0, 0);
;                     o1 = __builtin_amdgcn_mfma_f32_32x32x16_bf16(vb, pb, o1, 0, 0, 0); }
	v_add_f32_e32 v8, v58, v8
	v_exp_f32_e32 v62, v9
	v_sub_f32_e32 v9, v63, v33
	v_add_f32_e32 v8, v59, v8
	v_exp_f32_e32 v63, v9
	v_sub_f32_e32 v9, v66, v33
	v_add_f32_e32 v8, v60, v8
	v_exp_f32_e32 v66, v9
	v_sub_f32_e32 v9, v67, v33
	v_add_f32_e32 v8, v61, v8
	v_exp_f32_e32 v67, v9
	v_sub_f32_e32 v9, v34, v33
	v_add_f32_e32 v8, v62, v8
	v_exp_f32_e32 v149, v9
	v_sub_f32_e32 v9, v35, v33
	v_add_f32_e32 v8, v63, v8
	v_exp_f32_e32 v150, v9
	v_sub_f32_e32 v9, v36, v33
	v_cvt_pk_bf16_f32 v16, v0, v1
	v_cvt_pk_bf16_f32 v17, v2, v3
	v_cvt_pk_bf16_f32 v18, v4, v5
	v_cvt_pk_bf16_f32 v19, v6, v7
	ds_read2_b64 v[0:3], v211 offset1:2
	v_add_f32_e32 v8, v66, v8
	v_exp_f32_e32 v151, v9
	v_sub_f32_e32 v9, v37, v33
	v_add_f32_e32 v8, v67, v8
	v_exp_f32_e32 v152, v9
	v_sub_f32_e32 v9, v38, v33
	v_add_f32_e32 v8, v149, v8
	v_exp_f32_e32 v153, v9
	v_sub_f32_e32 v4, v39, v33
	v_add_f32_e32 v8, v150, v8
	v_exp_f32_e32 v154, v4
	v_sub_f32_e32 v4, v40, v33
	ds_read2_b64 v[20:23], v221 offset0:32 offset1:34
	v_add_f32_e32 v8, v151, v8
	v_exp_f32_e32 v155, v4
	v_sub_f32_e32 v4, v41, v33
	v_add_f32_e32 v8, v152, v8
	v_exp_f32_e32 v159, v4
	v_sub_f32_e32 v24, v42, v33
	v_add_f32_e32 v48, v153, v8
	v_exp_f32_e32 v222, v24
	v_cvt_pk_bf16_f32 v34, v44, v45
	v_cvt_pk_bf16_f32 v35, v46, v47
	v_cvt_pk_bf16_f32 v36, v71, v72
	v_cvt_pk_bf16_f32 v37, v73, v74
	ds_read2_b64 v[38:41], v211 offset0:4 offset1:6
	v_add_f32_e32 v42, v154, v48
	s_waitcnt lgkmcnt(2)
	v_mfma_f32_32x32x16_bf16 v[0:15], v[0:3], v[16:19], 0
	v_add_f32_e32 v42, v155, v42
	v_add_f32_e32 v42, v159, v42
	v_add_f32_e32 v71, v222, v42
	v_sub_f32_e32 v42, v43, v33
	v_exp_f32_e32 v72, v42
	ds_read2_b64 v[42:45], v221 offset0:36 offset1:38
	s_waitcnt lgkmcnt(2)
	v_mfma_f32_32x32x16_bf16 v[16:31], v[20:23], v[16:19], 0
	s_waitcnt lgkmcnt(1)
	v_mfma_f32_32x32x16_bf16 v[0:15], v[38:41], v[34:37], v[0:15]
	v_sub_f32_e32 v38, v68, v33
	v_exp_f32_e32 v68, v38
	v_cvt_pk_bf16_f32 v38, v75, v76
	v_cvt_pk_bf16_f32 v39, v77, v78
	v_cvt_pk_bf16_f32 v40, v79, v135
	v_cvt_pk_bf16_f32 v41, v137, v138
	ds_read2_b64 v[46:49], v211 offset0:8 offset1:10
	s_waitcnt lgkmcnt(1)
	v_mfma_f32_32x32x16_bf16 v[16:31], v[42:45], v[34:37], v[16:31]
	v_add_f32_e32 v34, v72, v71
	v_add_f32_e32 v42, v68, v34
	v_sub_f32_e32 v34, v69, v33
	v_exp_f32_e32 v69, v34
	v_sub_f32_e32 v34, v70, v33
	v_exp_f32_e32 v70, v34
	ds_read2_b64 v[34:37], v221 offset0:40 offset1:42
	v_add_f32_e32 v42, v69, v42
	s_waitcnt lgkmcnt(0)
	v_mfma_f32_32x32x16_bf16 v[16:31], v[34:37], v[38:41], v[16:31]
	v_sub_f32_e32 v34, v65, v33
	v_add_f32_e32 v71, v70, v42
	v_cvt_pk_bf16_f32 v42, v139, v141
	v_cvt_pk_bf16_f32 v43, v142, v143
	v_cvt_pk_bf16_f32 v44, v144, v145
	v_cvt_pk_bf16_f32 v45, v64, v146
	v_exp_f32_e32 v64, v34
	v_sub_f32_e32 v34, v219, v33
	v_exp_f32_e32 v65, v34
	v_sub_f32_e32 v34, v220, v33
	v_exp_f32_e32 v73, v34
	ds_read2_b64 v[34:37], v221 offset0:44 offset1:46
	v_mfma_f32_32x32x16_bf16 v[0:15], v[46:49], v[38:41], v[0:15]
	ds_read2_b64 v[46:49], v211 offset0:12 offset1:14
	v_sub_f32_e32 v38, v217, v33
	v_exp_f32_e32 v74, v38
	v_cvt_pk_bf16_f32 v38, v147, v148
	v_cvt_pk_bf16_f32 v39, v50, v51
	v_cvt_pk_bf16_f32 v40, v52, v53
	v_cvt_pk_bf16_f32 v41, v54, v55
	s_waitcnt lgkmcnt(1)
	v_mfma_f32_32x32x16_bf16 v[16:31], v[34:37], v[42:45], v[16:31]
	v_add_f32_e32 v34, v64, v71
	v_add_f32_e32 v34, v65, v34
	v_add_f32_e32 v34, v73, v34
	v_add_f32_e32 v50, v74, v34
	v_sub_f32_e32 v34, v216, v33
	v_exp_f32_e32 v51, v34
	ds_read2_b64 v[34:37], v221 offset0:48 offset1:50
	s_waitcnt lgkmcnt(1)
	v_mfma_f32_32x32x16_bf16 v[0:15], v[46:49], v[42:45], v[0:15]
	ds_read2_b64 v[46:49], v211 offset0:16 offset1:18
	v_sub_f32_e32 v42, v214, v33
	v_exp_f32_e32 v52, v42
	v_cvt_pk_bf16_f32 v42, v56, v57
	v_cvt_pk_bf16_f32 v43, v58, v59
	v_cvt_pk_bf16_f32 v44, v60, v61
	v_cvt_pk_bf16_f32 v45, v62, v63
	s_waitcnt lgkmcnt(1)
	v_mfma_f32_32x32x16_bf16 v[16:31], v[34:37], v[38:41], v[16:31]
	v_add_f32_e32 v34, v51, v50
	s_waitcnt lgkmcnt(0)
	v_mfma_f32_32x32x16_bf16 v[0:15], v[46:49], v[38:41], v[0:15]
	v_add_f32_e32 v38, v52, v34
	v_sub_f32_e32 v34, v213, v33
	v_exp_f32_e32 v50, v34
	v_sub_f32_e32 v34, v215, v33
	v_exp_f32_e32 v53, v34
	ds_read2_b64 v[34:37], v221 offset0:52 offset1:54
	ds_read2_b64 v[46:49], v211 offset0:20 offset1:22
	s_waitcnt lgkmcnt(1)
	v_mfma_f32_32x32x16_bf16 v[16:31], v[34:37], v[42:45], v[16:31]
	v_sub_f32_e32 v34, v212, v33
	v_exp_f32_e32 v55, v34
	v_sub_f32_e32 v34, v156, v33
	v_add_f32_e32 v38, v50, v38
	v_exp_f32_e32 v56, v34
	v_sub_f32_e32 v34, v158, v33
	v_add_f32_e32 v54, v53, v38
	v_cvt_pk_bf16_f32 v38, v66, v67
	v_cvt_pk_bf16_f32 v39, v149, v150
	v_cvt_pk_bf16_f32 v40, v151, v152
	v_cvt_pk_bf16_f32 v41, v153, v154
	v_exp_f32_e32 v57, v34
	ds_read2_b64 v[34:37], v221 offset0:56 offset1:58
	s_waitcnt lgkmcnt(1)
	v_mfma_f32_32x32x16_bf16 v[0:15], v[46:49], v[42:45], v[0:15]
	v_sub_f32_e32 v42, v157, v33
	v_exp_f32_e32 v58, v42
	ds_read2_b64 v[46:49], v211 offset0:24 offset1:26
	v_cvt_pk_bf16_f32 v42, v155, v159
	v_cvt_pk_bf16_f32 v43, v222, v72
	v_cvt_pk_bf16_f32 v44, v68, v69
	v_cvt_pk_bf16_f32 v45, v70, v64
	s_waitcnt lgkmcnt(1)
; #define LAS __attribute__((address_space(3)))
; __device__ __forceinline__ void attn_pool_phase(LAS unsigned char* lds, bf16* QKV, bf16* PL, const float* sinks, int G, int bid) {
;     ...
;             l += __shfl_xor(l, 32); l += __builtin_amdgcn_exp2f(sink2 - mx);
;             f32x16 o0 = {}, o1 = {};
; #pragma unroll
;             for (int j = 0; j < 5; ++j)
; #pragma unroll
;                 for (int c = 0; c < 2; ++c) {
;                     u32x4 pw; pw.x = pg8::cvt_pk_bf16(S[j][8 * c + 0], S[j][8 * c + 1]); pw.y = pg8::cvt_pk_bf16(S[j][8 * c + 2], S[j][8 * c + 3]);
;                     pw.z = pg8::cvt_pk_bf16(S[j][8 * c + 4], S[j][8 * c + 5]); pw.w = pg8::cvt_pk_bf16(S[j][8 * c + 6], S[j][8 * c + 7]);
;                     const bf16x8 pb = __builtin_bit_cast(bf16x8, pw);
;                     const LAS unsigned char* vp = lds + LDS_VT + q * VROWB + (32 * (i + j) + 16 * c + 4 * hi) * 2;
;                     const u32x2 a0 = *(const LAS u32x2*)vp, a1 = *(const LAS u32x2*)(vp + 16), b0 = *(const LAS u32x2*)(vp + 32 * VROWB), b1 = *(const LAS u32x2*)(vp + 32 * VROWB + 16);
;                     const bf16x8 va = __builtin_bit_cast(bf16x8, (u32x4){a0.x, a0.y, a1.x, a1.y}), vb = __builtin_bit_cast(bf16x8, (u32x4){b0.x, b0.y, b1.x, b1.y});
;                     o0 = __builtin_amdgcn_mfma_f32_32x32x16_bf16(va, pb, o0, 0, 0, 0);
;                     o1 = __builtin_amdgcn_mfma_f32_32x32x16_bf16(vb, pb, o1, 0, 0, 0); }
;             const float inv = 1.0f / l;
; #pragma unroll
;             for (int rg = 0; rg < 4; ++rg) { const int d = 8 * rg + 4 * hi;
;                 u32x2 w0, w1; w0.x = pg8::cvt_pk_bf16(o0[4 * rg] * inv, o0[4 * rg + 1] * inv); w0.y = pg8::cvt_pk_bf16(o0[4 * rg + 2] * inv, o0[4 * rg + 3] * inv);
;                 w1.x = pg8::cvt_pk_bf16(o1[4 * rg] * inv, o1[4 * rg + 1] * inv); w1.y = pg8::cvt_pk_bf16(o1[4 * rg + 2] * inv, o1[4 * rg + 3] * inv);
;                 *(LAS u32x2*)(ost + q * OROWB + d * 2) = w0; *(LAS u32x2*)(ost + q * OROWB + (32 + d) * 2) = w1; }
;             asm volatile("s_waitcnt lgkmcnt(0)" ::: "memory");
; #pragma unroll
;             for (int k = 0; k < 4; ++k) { const int r = 8 * k + (lane >> 3), ch = lane & 7;
;                 const u32x4 v = *(const LAS u32x4*)(ost + r * OROWB + ch * 16);
;                 *(u32x4*)(orow + (size_t)r * NIN + ch * 8) = v; }
;             asm volatile("s_waitcnt lgkmcnt(0)" ::: "memory");
	v_mfma_f32_32x32x16_bf16 v[16:31], v[34:37], v[38:41], v[16:31]
	v_add_f32_e32 v34, v55, v54
	v_add_f32_e32 v34, v56, v34
	v_add_f32_e32 v34, v57, v34
	v_add_f32_e32 v54, v58, v34
	v_sub_f32_e32 v34, v140, v33
	v_exp_f32_e32 v59, v34
	ds_read2_b64 v[34:37], v221 offset0:60 offset1:62
	s_waitcnt lgkmcnt(1)
	v_mfma_f32_32x32x16_bf16 v[0:15], v[46:49], v[38:41], v[0:15]
	v_sub_f32_e32 v38, v136, v33
	v_exp_f32_e32 v60, v38
	ds_read2_b64 v[46:49], v211 offset0:28 offset1:30
	v_cvt_pk_bf16_f32 v38, v65, v73
	v_cvt_pk_bf16_f32 v39, v74, v51
	v_cvt_pk_bf16_f32 v40, v52, v50
	v_cvt_pk_bf16_f32 v41, v53, v55
	s_waitcnt lgkmcnt(1)
	v_mfma_f32_32x32x16_bf16 v[16:31], v[34:37], v[42:45], v[16:31]
	v_add_f32_e32 v34, v59, v54
	v_add_f32_e32 v50, v60, v34
	v_sub_f32_e32 v34, v133, v33
	v_exp_f32_e32 v51, v34
	v_sub_f32_e32 v34, v134, v33
	v_exp_f32_e32 v52, v34
	ds_read2_b64 v[34:37], v221 offset0:64 offset1:66
	s_waitcnt lgkmcnt(1)
	v_mfma_f32_32x32x16_bf16 v[0:15], v[46:49], v[42:45], v[0:15]
	ds_read2_b64 v[46:49], v211 offset0:32 offset1:34
	v_sub_f32_e32 v42, v132, v33
	v_exp_f32_e32 v53, v42
	v_cvt_pk_bf16_f32 v42, v56, v57
	v_cvt_pk_bf16_f32 v43, v58, v59
	v_cvt_pk_bf16_f32 v44, v60, v51
	v_cvt_pk_bf16_f32 v45, v52, v53
	s_waitcnt lgkmcnt(1)
	v_mfma_f32_32x32x16_bf16 v[16:31], v[34:37], v[38:41], v[16:31]
	v_add_f32_e32 v34, v51, v50
	v_add_f32_e32 v34, v52, v34
	v_add_f32_e32 v36, v53, v34
	ds_bpermute_b32 v37, v32, v36
	v_sub_f32_e32 v32, v209, v33
	s_waitcnt vmcnt(0)
	v_mov_b64_e32 v[134:135], v[118:119]
	v_mov_b64_e32 v[138:139], v[122:123]
	s_waitcnt lgkmcnt(1)
	v_mfma_f32_32x32x16_bf16 v[0:15], v[46:49], v[38:41], v[0:15]
	v_exp_f32_e32 v38, v32
	ds_read2_b64 v[46:49], v211 offset0:36 offset1:38
	ds_read2_b64 v[32:35], v221 offset0:68 offset1:70
	s_waitcnt lgkmcnt(2)
	v_add_f32_e32 v36, v36, v37
	v_add_f32_e32 v36, v38, v36
	v_div_scale_f32 v37, s[8:9], v36, v36, 1.0
	v_rcp_f32_e32 v38, v37
	s_waitcnt lgkmcnt(1)
	v_mfma_f32_32x32x16_bf16 v[0:15], v[46:49], v[42:45], v[0:15]
	v_mov_b64_e32 v[142:143], v[126:127]
	v_add_u32_e32 v211, 64, v211
	v_mov_b64_e32 v[132:133], v[116:117]
	v_mov_b64_e32 v[136:137], v[120:121]
	v_mov_b64_e32 v[140:141], v[124:125]
	s_waitcnt lgkmcnt(0)
	v_mfma_f32_32x32x16_bf16 v[16:31], v[32:35], v[42:45], v[16:31]
	v_fma_f32 v32, -v37, v38, 1.0
	v_fmac_f32_e32 v38, v32, v38
	v_div_scale_f32 v32, vcc, 1.0, v36, 1.0
	v_mul_f32_e32 v33, v32, v38
	v_fma_f32 v34, -v37, v33, v32
	v_fmac_f32_e32 v33, v34, v38
	v_fma_f32 v32, -v37, v33, v32
	v_div_fmas_f32 v32, v32, v38, v33
	v_div_fixup_f32 v32, v32, v36, 1.0
	v_mul_f32_e32 v0, v0, v32
	v_mul_f32_e32 v1, v1, v32
	v_cvt_pk_bf16_f32 v0, v0, v1
	v_mul_f32_e32 v1, v2, v32
	v_mul_f32_e32 v2, v3, v32
	v_cvt_pk_bf16_f32 v1, v1, v2
	v_mul_f32_e32 v2, v16, v32
	v_mul_f32_e32 v3, v17, v32
	v_cvt_pk_bf16_f32 v2, v2, v3
	v_mul_f32_e32 v3, v18, v32
	v_mul_f32_e32 v16, v19, v32
	v_cvt_pk_bf16_f32 v3, v3, v16
	ds_write2_b64 v184, v[0:1], v[2:3] offset1:8
	v_mul_f32_e32 v0, v4, v32
	v_mul_f32_e32 v1, v5, v32
	v_cvt_pk_bf16_f32 v0, v0, v1
	v_mul_f32_e32 v1, v6, v32
	v_mul_f32_e32 v2, v7, v32
	v_cvt_pk_bf16_f32 v1, v1, v2
	v_mul_f32_e32 v2, v20, v32
	v_mul_f32_e32 v3, v21, v32
	v_cvt_pk_bf16_f32 v2, v2, v3
	v_mul_f32_e32 v3, v22, v32
	v_mul_f32_e32 v4, v23, v32
	v_cvt_pk_bf16_f32 v3, v3, v4
	ds_write2_b64 v184, v[0:1], v[2:3] offset0:2 offset1:10
	v_mul_f32_e32 v0, v8, v32
	v_mul_f32_e32 v1, v9, v32
	v_cvt_pk_bf16_f32 v0, v0, v1
	v_mul_f32_e32 v1, v10, v32
	v_mul_f32_e32 v2, v11, v32
	v_cvt_pk_bf16_f32 v1, v1, v2
	v_mul_f32_e32 v2, v24, v32
	v_mul_f32_e32 v3, v25, v32
	v_cvt_pk_bf16_f32 v2, v2, v3
	v_mul_f32_e32 v3, v26, v32
	v_mul_f32_e32 v4, v27, v32
	v_cvt_pk_bf16_f32 v3, v3, v4
	ds_write2_b64 v184, v[0:1], v[2:3] offset0:4 offset1:12
	v_mul_f32_e32 v0, v12, v32
	v_mul_f32_e32 v1, v13, v32
	v_cvt_pk_bf16_f32 v0, v0, v1
	v_mul_f32_e32 v1, v14, v32
	v_mul_f32_e32 v2, v15, v32
	v_cvt_pk_bf16_f32 v1, v1, v2
	v_mul_f32_e32 v2, v28, v32
	v_mul_f32_e32 v3, v29, v32
	v_cvt_pk_bf16_f32 v2, v2, v3
	v_mul_f32_e32 v3, v30, v32
	v_mul_f32_e32 v4, v31, v32
	v_cvt_pk_bf16_f32 v3, v3, v4
	ds_write2_b64 v184, v[0:1], v[2:3] offset0:6 offset1:14
	s_waitcnt lgkmcnt(0)
	ds_read_b128 v[0:3], v185
	ds_read_b128 v[4:7], v185 offset:1152
	v_lshl_add_u64 v[8:9], v[166:167], 0, s[6:7]
	v_add_co_u32_e32 v10, vcc, s39, v8
	s_add_u32 s6, s6, 0x3c000
	s_nop 0
	v_addc_co_u32_e32 v11, vcc, 0, v9, vcc
	s_waitcnt lgkmcnt(1)
	global_store_dwordx4 v[10:11], v[0:3], off sc1
	s_addc_u32 s7, s7, 0
	v_mov_b64_e32 v[32:33], v[128:129]
	v_add_co_u32_e32 v0, vcc, s40, v8
	s_cmp_eq_u32 s6, 0xf0000
	s_nop 0
	v_addc_co_u32_e32 v1, vcc, 0, v9, vcc
	s_waitcnt lgkmcnt(0)
	global_store_dwordx4 v[0:1], v[4:7], off sc1
	ds_read_b128 v[0:3], v185 offset:2304
	ds_read_b128 v[4:7], v185 offset:3456
	v_add_co_u32_e32 v10, vcc, s41, v8
	v_mov_b64_e32 v[34:35], v[130:131]
	s_nop 0
	v_addc_co_u32_e32 v11, vcc, 0, v9, vcc
	s_waitcnt lgkmcnt(1)
	global_store_dwordx4 v[10:11], v[0:3], off sc1
	s_nop 1
	v_add_co_u32_e32 v0, vcc, 0x702d000, v8
	s_nop 1
	v_addc_co_u32_e32 v1, vcc, 0, v9, vcc
	s_waitcnt lgkmcnt(0)
	global_store_dwordx4 v[0:1], v[4:7], off sc1
	s_waitcnt lgkmcnt(0)
	s_cbranch_scc1 .LBB0_494

;     __device__ static __forceinline__ float ub(unsigned w, int k) { return (float)((w >> (8 * k)) & 0xffu); }
;     __device__ __forceinline__ void operator()(f32x4 (&acc)[2][2][4][2], const Unit& u, int wr, int wc, int fr, int fq) const {
;     ...
;         u32x4 gw[2][4];
; #pragma unroll
;         for (int ai = 0; ai < 2; ++ai)
; #pragma unroll
;             for (int m = 0; m < 4; ++m) gw[ai][m] = *(const u32x4*)(G8 + ((size_t)(((u.pm * 8 + gsel + u.pn) * 8 + (wr * 4 + wc)) * 8 + (ai * 4 + m)) * 1024) + (fq * 16 + fr) * 16);
;     ...
;             for (int ai = 0; ai < 2; ++ai)
; #pragma unroll
;                 for (int m = 0; m < 4; ++m)
; #pragma unroll
;                     for (int bj = 0; bj < 2; ++bj) { const u32x4 gq = gw[ai][m]; u32x2 g; g.x = bj ? gq.z : gq.x; g.y = bj ? gq.w : gq.y; f32x4& a0 = acc[ai][bj][m][0]; f32x4& a1 = acc[ai][bj][m][1];
;                         a0[0] *= ub(g.x, 0) * q; a0[1] *= ub(g.x, 1) * q; a0[2] *= ub(g.x, 2) * q; a0[3] *= ub(g.x, 3) * q; a1[0] *= ub(g.y, 0) * q; a1[1] *= ub(g.y, 1) * q; a1[2] *= ub(g.y, 2) * q; a1[3] *= ub(g.y, 3) * q;
;                         asm volatile("" : "+v"(a0), "+v"(a1)); }
.LBB0_649:
	s_lshl_b32 s1, s89, 6
	s_lshl_b32 s0, s88, 9
	s_add_i32 s1, s76, s1
	s_add_i32 s0, s1, s0
	s_ashr_i32 s1, s0, 31
	s_lshl_b64 s[8:9], s[0:1], 10
	v_lshl_add_u64 v[128:129], v[172:173], 0, s[8:9]
	global_load_dwordx4 v[156:159], v[128:129], off
	s_or_b32 s8, s0, 1
	s_ashr_i32 s9, s8, 31
	s_lshl_b64 s[8:9], s[8:9], 10
	v_lshl_add_u64 v[128:129], v[172:173], 0, s[8:9]
	global_load_dwordx4 v[152:155], v[128:129], off
	s_or_b32 s8, s0, 2
	s_ashr_i32 s9, s8, 31
	s_lshl_b64 s[8:9], s[8:9], 10
	v_lshl_add_u64 v[128:129], v[172:173], 0, s[8:9]
	global_load_dwordx4 v[148:151], v[128:129], off
	s_or_b32 s8, s0, 3
	s_ashr_i32 s9, s8, 31
	s_lshl_b64 s[8:9], s[8:9], 10
	v_lshl_add_u64 v[128:129], v[172:173], 0, s[8:9]
	global_load_dwordx4 v[144:147], v[128:129], off
	s_or_b32 s8, s0, 4
	s_ashr_i32 s9, s8, 31
	s_lshl_b64 s[8:9], s[8:9], 10
	v_lshl_add_u64 v[128:129], v[172:173], 0, s[8:9]
	global_load_dwordx4 v[140:143], v[128:129], off
	s_or_b32 s8, s0, 5
	s_ashr_i32 s9, s8, 31
	s_lshl_b64 s[8:9], s[8:9], 10
	v_lshl_add_u64 v[128:129], v[172:173], 0, s[8:9]
	global_load_dwordx4 v[136:139], v[128:129], off
	s_or_b32 s8, s0, 6
	s_or_b32 s0, s0, 7
	s_ashr_i32 s1, s0, 31
	s_ashr_i32 s9, s8, 31
	s_lshl_b64 s[0:1], s[0:1], 10
	s_lshl_b64 s[8:9], s[8:9], 10
	v_lshl_add_u64 v[132:133], v[172:173], 0, s[0:1]
	global_load_dwordx4 v[132:135], v[132:133], off
	v_lshl_add_u64 v[128:129], v[172:173], 0, s[8:9]
	global_load_dwordx4 v[128:131], v[128:129], off
	s_lshl_b32 s0, s89, 3
	s_lshl_b32 s1, s88, 5
	s_add_i32 s1, s1, s0
	s_or_b32 s0, s1, s73
	s_ashr_i32 s1, s0, 31
	s_lshl_b64 s[8:9], s[0:1], 14
	s_add_u32 s66, s6, s8
	s_addc_u32 s67, s7, s9
	s_or_b32 s8, s0, 4
	s_ashr_i32 s9, s8, 31
	s_lshl_b64 s[8:9], s[8:9], 14
	s_add_u32 s68, s6, s8
	s_addc_u32 s69, s7, s9
	s_or_b32 s8, s0, 1
	s_ashr_i32 s9, s8, 31
	s_lshl_b64 s[8:9], s[8:9], 14
	s_waitcnt vmcnt(0)
	v_cvt_f32_ubyte3_e32 v203, v156
	v_cvt_f32_ubyte2_e32 v202, v156
	v_cvt_f32_ubyte1_e32 v205, v156
	v_cvt_f32_ubyte0_e32 v204, v156
	v_pk_mul_f32 v[204:205], v[204:205], s[58:59] op_sel_hi:[1,0]
	v_pk_mul_f32 v[202:203], v[202:203], s[58:59] op_sel_hi:[1,0]
	v_pk_mul_f32 v[124:125], v[124:125], v[204:205]
	v_pk_mul_f32 v[126:127], v[126:127], v[202:203]
	v_cvt_f32_ubyte3_e32 v203, v157
	v_cvt_f32_ubyte2_e32 v202, v157
	v_cvt_f32_ubyte1_e32 v205, v157
	v_cvt_f32_ubyte0_e32 v204, v157
	v_pk_mul_f32 v[156:157], v[204:205], s[58:59] op_sel_hi:[1,0]
	v_pk_mul_f32 v[202:203], v[202:203], s[58:59] op_sel_hi:[1,0]
	v_pk_mul_f32 v[120:121], v[120:121], v[156:157]
	v_pk_mul_f32 v[122:123], v[122:123], v[202:203]
	v_cvt_f32_ubyte3_e32 v157, v158
	v_cvt_f32_ubyte2_e32 v156, v158
	v_cvt_f32_ubyte1_e32 v203, v158
	v_cvt_f32_ubyte0_e32 v202, v158
	v_pk_mul_f32 v[202:203], v[202:203], s[58:59] op_sel_hi:[1,0]
	v_pk_mul_f32 v[156:157], v[156:157], s[58:59] op_sel_hi:[1,0]
	v_pk_mul_f32 v[116:117], v[116:117], v[202:203]
	v_pk_mul_f32 v[118:119], v[118:119], v[156:157]
	v_cvt_f32_ubyte3_e32 v157, v159
	v_cvt_f32_ubyte2_e32 v156, v159
	v_cvt_f32_ubyte1_e32 v203, v159
	v_cvt_f32_ubyte0_e32 v202, v159
	v_pk_mul_f32 v[158:159], v[202:203], s[58:59] op_sel_hi:[1,0]
	v_pk_mul_f32 v[156:157], v[156:157], s[58:59] op_sel_hi:[1,0]
	v_pk_mul_f32 v[112:113], v[112:113], v[158:159]
	v_pk_mul_f32 v[114:115], v[114:115], v[156:157]
	v_cvt_f32_ubyte3_e32 v157, v152
	v_cvt_f32_ubyte2_e32 v156, v152
	v_cvt_f32_ubyte1_e32 v159, v152
	v_cvt_f32_ubyte0_e32 v158, v152
	v_pk_mul_f32 v[158:159], v[158:159], s[58:59] op_sel_hi:[1,0]
	v_pk_mul_f32 v[156:157], v[156:157], s[58:59] op_sel_hi:[1,0]
	v_pk_mul_f32 v[108:109], v[108:109], v[158:159]
	v_pk_mul_f32 v[110:111], v[110:111], v[156:157]
	v_cvt_f32_ubyte3_e32 v157, v153
	v_cvt_f32_ubyte2_e32 v156, v153
	v_cvt_f32_ubyte1_e32 v159, v153
	v_cvt_f32_ubyte0_e32 v158, v153
	v_pk_mul_f32 v[152:153], v[158:159], s[58:59] op_sel_hi:[1,0]
	v_pk_mul_f32 v[156:157], v[156:157], s[58:59] op_sel_hi:[1,0]
	v_pk_mul_f32 v[104:105], v[104:105], v[152:153]
	v_pk_mul_f32 v[106:107], v[106:107], v[156:157]
	v_cvt_f32_ubyte3_e32 v153, v154
	v_cvt_f32_ubyte2_e32 v152, v154
	v_cvt_f32_ubyte1_e32 v157, v154
	v_cvt_f32_ubyte0_e32 v156, v154
	v_pk_mul_f32 v[156:157], v[156:157], s[58:59] op_sel_hi:[1,0]
	v_pk_mul_f32 v[152:153], v[152:153], s[58:59] op_sel_hi:[1,0]
	v_pk_mul_f32 v[100:101], v[100:101], v[156:157]
	v_pk_mul_f32 v[102:103], v[102:103], v[152:153]
	v_cvt_f32_ubyte3_e32 v153, v155
	v_cvt_f32_ubyte2_e32 v152, v155
	v_cvt_f32_ubyte1_e32 v157, v155
	v_cvt_f32_ubyte0_e32 v156, v155
	v_pk_mul_f32 v[154:155], v[156:157], s[58:59] op_sel_hi:[1,0]
	v_pk_mul_f32 v[152:153], v[152:153], s[58:59] op_sel_hi:[1,0]
	v_pk_mul_f32 v[92:93], v[92:93], v[154:155]
	v_pk_mul_f32 v[94:95], v[94:95], v[152:153]
	v_cvt_f32_ubyte3_e32 v153, v148
	v_cvt_f32_ubyte2_e32 v152, v148
	v_cvt_f32_ubyte1_e32 v155, v148
	v_cvt_f32_ubyte0_e32 v154, v148
	v_pk_mul_f32 v[154:155], v[154:155], s[58:59] op_sel_hi:[1,0]
	v_pk_mul_f32 v[152:153], v[152:153], s[58:59] op_sel_hi:[1,0]
	v_pk_mul_f32 v[96:97], v[96:97], v[154:155]
	v_pk_mul_f32 v[98:99], v[98:99], v[152:153]
	v_cvt_f32_ubyte3_e32 v153, v149
	v_cvt_f32_ubyte2_e32 v152, v149
	v_cvt_f32_ubyte1_e32 v155, v149
	v_cvt_f32_ubyte0_e32 v154, v149
	v_pk_mul_f32 v[148:149], v[154:155], s[58:59] op_sel_hi:[1,0]
	v_pk_mul_f32 v[152:153], v[152:153], s[58:59] op_sel_hi:[1,0]
	v_pk_mul_f32 v[88:89], v[88:89], v[148:149]
	v_pk_mul_f32 v[90:91], v[90:91], v[152:153]
	v_cvt_f32_ubyte3_e32 v149, v150
	v_cvt_f32_ubyte2_e32 v148, v150
	v_cvt_f32_ubyte1_e32 v153, v150
	v_cvt_f32_ubyte0_e32 v152, v150
	v_pk_mul_f32 v[152:153], v[152:153], s[58:59] op_sel_hi:[1,0]
	v_pk_mul_f32 v[148:149], v[148:149], s[58:59] op_sel_hi:[1,0]
;     __device__ static __forceinline__ float ub(unsigned w, int k) { return (float)((w >> (8 * k)) & 0xffu); }
;     __device__ __forceinline__ void operator()(f32x4 (&acc)[2][2][4][2], const Unit& u, int wr, int wc, int fr, int fq) const {
;     ...
;             for (int ai = 0; ai < 2; ++ai)
; #pragma unroll
;                 for (int m = 0; m < 4; ++m)
; #pragma unroll
;                     for (int bj = 0; bj < 2; ++bj) { const u32x4 gq = gw[ai][m]; u32x2 g; g.x = bj ? gq.z : gq.x; g.y = bj ? gq.w : gq.y; f32x4& a0 = acc[ai][bj][m][0]; f32x4& a1 = acc[ai][bj][m][1];
;                         a0[0] *= ub(g.x, 0) * q; a0[1] *= ub(g.x, 1) * q; a0[2] *= ub(g.x, 2) * q; a0[3] *= ub(g.x, 3) * q; a1[0] *= ub(g.y, 0) * q; a1[1] *= ub(g.y, 1) * q; a1[2] *= ub(g.y, 2) * q; a1[3] *= ub(g.y, 3) * q;
;                         asm volatile("" : "+v"(a0), "+v"(a1)); }
	v_pk_mul_f32 v[84:85], v[84:85], v[152:153]
	v_pk_mul_f32 v[86:87], v[86:87], v[148:149]
	v_cvt_f32_ubyte3_e32 v149, v151
	v_cvt_f32_ubyte2_e32 v148, v151
	v_cvt_f32_ubyte1_e32 v153, v151
	v_cvt_f32_ubyte0_e32 v152, v151
	v_pk_mul_f32 v[150:151], v[152:153], s[58:59] op_sel_hi:[1,0]
	v_pk_mul_f32 v[148:149], v[148:149], s[58:59] op_sel_hi:[1,0]
	v_pk_mul_f32 v[76:77], v[76:77], v[150:151]
	v_pk_mul_f32 v[78:79], v[78:79], v[148:149]
	v_cvt_f32_ubyte3_e32 v149, v144
	v_cvt_f32_ubyte2_e32 v148, v144
	v_cvt_f32_ubyte1_e32 v151, v144
	v_cvt_f32_ubyte0_e32 v150, v144
	v_pk_mul_f32 v[150:151], v[150:151], s[58:59] op_sel_hi:[1,0]
	v_pk_mul_f32 v[148:149], v[148:149], s[58:59] op_sel_hi:[1,0]
	v_pk_mul_f32 v[80:81], v[80:81], v[150:151]
	v_pk_mul_f32 v[82:83], v[82:83], v[148:149]
	v_cvt_f32_ubyte3_e32 v149, v145
	v_cvt_f32_ubyte2_e32 v148, v145
	v_cvt_f32_ubyte1_e32 v151, v145
	v_cvt_f32_ubyte0_e32 v150, v145
	v_pk_mul_f32 v[144:145], v[150:151], s[58:59] op_sel_hi:[1,0]
	v_pk_mul_f32 v[148:149], v[148:149], s[58:59] op_sel_hi:[1,0]
	v_pk_mul_f32 v[72:73], v[72:73], v[144:145]
	v_pk_mul_f32 v[74:75], v[74:75], v[148:149]
	v_cvt_f32_ubyte3_e32 v145, v146
	v_cvt_f32_ubyte2_e32 v144, v146
	v_cvt_f32_ubyte1_e32 v149, v146
	v_cvt_f32_ubyte0_e32 v148, v146
	v_pk_mul_f32 v[148:149], v[148:149], s[58:59] op_sel_hi:[1,0]
	v_pk_mul_f32 v[144:145], v[144:145], s[58:59] op_sel_hi:[1,0]
	v_pk_mul_f32 v[68:69], v[68:69], v[148:149]
	v_pk_mul_f32 v[70:71], v[70:71], v[144:145]
	v_cvt_f32_ubyte3_e32 v145, v147
	v_cvt_f32_ubyte2_e32 v144, v147
	v_cvt_f32_ubyte1_e32 v149, v147
	v_cvt_f32_ubyte0_e32 v148, v147
	v_pk_mul_f32 v[146:147], v[148:149], s[58:59] op_sel_hi:[1,0]
	v_pk_mul_f32 v[144:145], v[144:145], s[58:59] op_sel_hi:[1,0]
	v_pk_mul_f32 v[64:65], v[64:65], v[146:147]
	v_pk_mul_f32 v[66:67], v[66:67], v[144:145]
	v_cvt_f32_ubyte3_e32 v145, v140
	v_cvt_f32_ubyte2_e32 v144, v140
	v_cvt_f32_ubyte1_e32 v147, v140
	v_cvt_f32_ubyte0_e32 v146, v140
	v_pk_mul_f32 v[146:147], v[146:147], s[58:59] op_sel_hi:[1,0]
	v_pk_mul_f32 v[144:145], v[144:145], s[58:59] op_sel_hi:[1,0]
	v_pk_mul_f32 v[60:61], v[60:61], v[146:147]
	v_pk_mul_f32 v[62:63], v[62:63], v[144:145]
	v_cvt_f32_ubyte3_e32 v145, v141
	v_cvt_f32_ubyte2_e32 v144, v141
	v_cvt_f32_ubyte1_e32 v147, v141
	v_cvt_f32_ubyte0_e32 v146, v141
	v_pk_mul_f32 v[140:141], v[146:147], s[58:59] op_sel_hi:[1,0]
	v_pk_mul_f32 v[144:145], v[144:145], s[58:59] op_sel_hi:[1,0]
	v_pk_mul_f32 v[56:57], v[56:57], v[140:141]
	v_pk_mul_f32 v[58:59], v[58:59], v[144:145]
	v_cvt_f32_ubyte3_e32 v141, v142
	v_cvt_f32_ubyte2_e32 v140, v142
	v_cvt_f32_ubyte1_e32 v145, v142
	v_cvt_f32_ubyte0_e32 v144, v142
	v_pk_mul_f32 v[144:145], v[144:145], s[58:59] op_sel_hi:[1,0]
	v_pk_mul_f32 v[140:141], v[140:141], s[58:59] op_sel_hi:[1,0]
	v_pk_mul_f32 v[52:53], v[52:53], v[144:145]
	v_pk_mul_f32 v[54:55], v[54:55], v[140:141]
	v_cvt_f32_ubyte3_e32 v141, v143
	v_cvt_f32_ubyte2_e32 v140, v143
	v_cvt_f32_ubyte1_e32 v145, v143
	v_cvt_f32_ubyte0_e32 v144, v143
	v_pk_mul_f32 v[142:143], v[144:145], s[58:59] op_sel_hi:[1,0]
	v_pk_mul_f32 v[140:141], v[140:141], s[58:59] op_sel_hi:[1,0]
	v_pk_mul_f32 v[44:45], v[44:45], v[142:143]
	v_pk_mul_f32 v[46:47], v[46:47], v[140:141]
	v_cvt_f32_ubyte3_e32 v141, v136
	v_cvt_f32_ubyte2_e32 v140, v136
	v_cvt_f32_ubyte1_e32 v143, v136
	v_cvt_f32_ubyte0_e32 v142, v136
	v_pk_mul_f32 v[142:143], v[142:143], s[58:59] op_sel_hi:[1,0]
	v_pk_mul_f32 v[140:141], v[140:141], s[58:59] op_sel_hi:[1,0]
	v_pk_mul_f32 v[48:49], v[48:49], v[142:143]
	v_pk_mul_f32 v[50:51], v[50:51], v[140:141]
	v_cvt_f32_ubyte3_e32 v141, v137
	v_cvt_f32_ubyte2_e32 v140, v137
	v_cvt_f32_ubyte1_e32 v143, v137
	v_cvt_f32_ubyte0_e32 v142, v137
	v_pk_mul_f32 v[136:137], v[142:143], s[58:59] op_sel_hi:[1,0]
	v_pk_mul_f32 v[140:141], v[140:141], s[58:59] op_sel_hi:[1,0]
	v_pk_mul_f32 v[40:41], v[40:41], v[136:137]
	v_pk_mul_f32 v[42:43], v[42:43], v[140:141]
	v_cvt_f32_ubyte3_e32 v137, v138
	v_cvt_f32_ubyte2_e32 v136, v138
	v_cvt_f32_ubyte1_e32 v141, v138
	v_cvt_f32_ubyte0_e32 v140, v138
	v_pk_mul_f32 v[140:141], v[140:141], s[58:59] op_sel_hi:[1,0]
	v_pk_mul_f32 v[136:137], v[136:137], s[58:59] op_sel_hi:[1,0]
	v_pk_mul_f32 v[36:37], v[36:37], v[140:141]
	v_pk_mul_f32 v[38:39], v[38:39], v[136:137]
	v_cvt_f32_ubyte3_e32 v137, v139
	v_cvt_f32_ubyte2_e32 v136, v139
	v_cvt_f32_ubyte1_e32 v141, v139
	v_cvt_f32_ubyte0_e32 v140, v139
	v_pk_mul_f32 v[138:139], v[140:141], s[58:59] op_sel_hi:[1,0]
	v_pk_mul_f32 v[136:137], v[136:137], s[58:59] op_sel_hi:[1,0]
	v_pk_mul_f32 v[28:29], v[28:29], v[138:139]
	v_pk_mul_f32 v[30:31], v[30:31], v[136:137]
	v_cvt_f32_ubyte3_e32 v137, v128
	v_cvt_f32_ubyte2_e32 v136, v128
	v_cvt_f32_ubyte1_e32 v139, v128
	v_cvt_f32_ubyte0_e32 v138, v128
	v_pk_mul_f32 v[138:139], v[138:139], s[58:59] op_sel_hi:[1,0]
	v_pk_mul_f32 v[136:137], v[136:137], s[58:59] op_sel_hi:[1,0]
	v_pk_mul_f32 v[32:33], v[32:33], v[138:139]
	v_pk_mul_f32 v[34:35], v[34:35], v[136:137]
	v_cvt_f32_ubyte3_e32 v137, v129
	v_cvt_f32_ubyte2_e32 v136, v129
	v_cvt_f32_ubyte1_e32 v139, v129
	v_cvt_f32_ubyte0_e32 v138, v129
	v_pk_mul_f32 v[128:129], v[138:139], s[58:59] op_sel_hi:[1,0]
	v_pk_mul_f32 v[136:137], v[136:137], s[58:59] op_sel_hi:[1,0]
	v_pk_mul_f32 v[24:25], v[24:25], v[128:129]
	v_pk_mul_f32 v[26:27], v[26:27], v[136:137]
	v_cvt_f32_ubyte3_e32 v129, v130
	v_cvt_f32_ubyte2_e32 v128, v130
	v_cvt_f32_ubyte1_e32 v137, v130
	v_cvt_f32_ubyte0_e32 v136, v130
	v_pk_mul_f32 v[136:137], v[136:137], s[58:59] op_sel_hi:[1,0]
	v_pk_mul_f32 v[128:129], v[128:129], s[58:59] op_sel_hi:[1,0]
	v_pk_mul_f32 v[20:21], v[20:21], v[136:137]
	v_pk_mul_f32 v[22:23], v[22:23], v[128:129]
; __device__ __forceinline__ unsigned cvt_pk_bf16(float lo, float hi) { unsigned r; asm volatile("v_cvt_pk_bf16_f32 %0, %1, %2" : "=v"(r) : "v"(lo), "v"(hi)); return r; }
;     __device__ static __forceinline__ float ub(unsigned w, int k) { return (float)((w >> (8 * k)) & 0xffu); }
;     __device__ __forceinline__ void operator()(f32x4 (&acc)[2][2][4][2], const Unit& u, int wr, int wc, int fr, int fq) const {
;     ...
;             for (int ai = 0; ai < 2; ++ai)
; #pragma unroll
;                 for (int m = 0; m < 4; ++m)
; #pragma unroll
;                     for (int bj = 0; bj < 2; ++bj) { const u32x4 gq = gw[ai][m]; u32x2 g; g.x = bj ? gq.z : gq.x; g.y = bj ? gq.w : gq.y; f32x4& a0 = acc[ai][bj][m][0]; f32x4& a1 = acc[ai][bj][m][1];
;                         a0[0] *= ub(g.x, 0) * q; a0[1] *= ub(g.x, 1) * q; a0[2] *= ub(g.x, 2) * q; a0[3] *= ub(g.x, 3) * q; a1[0] *= ub(g.y, 0) * q; a1[1] *= ub(g.y, 1) * q; a1[2] *= ub(g.y, 2) * q; a1[3] *= ub(g.y, 3) * q;
;                         asm volatile("" : "+v"(a0), "+v"(a1)); }
;         }
; #pragma unroll
;         for (int ai = 0; ai < 2; ++ai)
; #pragma unroll
;             for (int m = 0; m < 4; ++m)
; #pragma unroll
;                 for (int bj = 0; bj < 2; ++bj) { const f32x4 a0 = acc[ai][bj][m][0], a1 = acc[ai][bj][m][1];
;                     u32x4 w; w.x = cvt_pk_bf16(a0[0], a0[1]); w.y = cvt_pk_bf16(a0[2], a0[3]); w.z = cvt_pk_bf16(a1[0], a1[1]); w.w = cvt_pk_bf16(a1[2], a1[3]);
;                     *(u32x4*)mg_at(u, ai, m, bj, wr, wc, fr, fq) = w; }
	v_cvt_f32_ubyte3_e32 v129, v131
	v_cvt_f32_ubyte2_e32 v128, v131
	v_cvt_f32_ubyte1_e32 v137, v131
	v_cvt_f32_ubyte0_e32 v136, v131
	v_pk_mul_f32 v[130:131], v[136:137], s[58:59] op_sel_hi:[1,0]
	v_pk_mul_f32 v[128:129], v[128:129], s[58:59] op_sel_hi:[1,0]
	v_pk_mul_f32 v[12:13], v[12:13], v[130:131]
	v_pk_mul_f32 v[14:15], v[14:15], v[128:129]
	v_cvt_f32_ubyte3_e32 v129, v132
	v_cvt_f32_ubyte2_e32 v128, v132
	v_cvt_f32_ubyte1_e32 v131, v132
	v_cvt_f32_ubyte0_e32 v130, v132
	v_pk_mul_f32 v[130:131], v[130:131], s[58:59] op_sel_hi:[1,0]
	v_pk_mul_f32 v[128:129], v[128:129], s[58:59] op_sel_hi:[1,0]
	v_pk_mul_f32 v[16:17], v[16:17], v[130:131]
	v_pk_mul_f32 v[18:19], v[18:19], v[128:129]
	v_cvt_f32_ubyte3_e32 v129, v133
	v_cvt_f32_ubyte2_e32 v128, v133
	v_cvt_f32_ubyte1_e32 v131, v133
	v_cvt_f32_ubyte0_e32 v130, v133
	v_pk_mul_f32 v[130:131], v[130:131], s[58:59] op_sel_hi:[1,0]
	v_pk_mul_f32 v[128:129], v[128:129], s[58:59] op_sel_hi:[1,0]
	v_pk_mul_f32 v[8:9], v[8:9], v[130:131]
	v_pk_mul_f32 v[10:11], v[10:11], v[128:129]
	v_cvt_f32_ubyte3_e32 v129, v134
	v_cvt_f32_ubyte2_e32 v128, v134
	v_cvt_f32_ubyte1_e32 v131, v134
	v_cvt_f32_ubyte0_e32 v130, v134
	v_pk_mul_f32 v[130:131], v[130:131], s[58:59] op_sel_hi:[1,0]
	v_pk_mul_f32 v[128:129], v[128:129], s[58:59] op_sel_hi:[1,0]
	v_pk_mul_f32 v[4:5], v[4:5], v[130:131]
	v_pk_mul_f32 v[6:7], v[6:7], v[128:129]
	v_cvt_f32_ubyte3_e32 v129, v135
	v_cvt_f32_ubyte2_e32 v128, v135
	v_cvt_f32_ubyte1_e32 v131, v135
	v_cvt_f32_ubyte0_e32 v130, v135
	v_pk_mul_f32 v[130:131], v[130:131], s[58:59] op_sel_hi:[1,0]
	v_pk_mul_f32 v[128:129], v[128:129], s[58:59] op_sel_hi:[1,0]
	v_pk_mul_f32 v[0:1], v[0:1], v[130:131]
	v_pk_mul_f32 v[2:3], v[2:3], v[128:129]
	s_nop 0
	v_cvt_pk_bf16_f32 v124, v124, v125
	v_cvt_pk_bf16_f32 v125, v126, v127
	v_cvt_pk_bf16_f32 v126, v120, v121
	v_lshl_add_u64 v[120:121], s[66:67], 0, v[164:165]
	v_cvt_pk_bf16_f32 v127, v122, v123
	global_store_dwordx4 v[120:121], v[124:127], off sc1
	v_cvt_pk_bf16_f32 v116, v116, v117
	v_cvt_pk_bf16_f32 v117, v118, v119
	v_cvt_pk_bf16_f32 v118, v112, v113
	v_lshl_add_u64 v[112:113], s[68:69], 0, v[164:165]
	v_cvt_pk_bf16_f32 v119, v114, v115
	global_store_dwordx4 v[112:113], v[116:119], off sc1
	v_cvt_pk_bf16_f32 v108, v108, v109
	v_cvt_pk_bf16_f32 v109, v110, v111
	v_cvt_pk_bf16_f32 v110, v104, v105
	v_lshl_add_u64 v[104:105], s[66:67], 0, v[166:167]
	v_cvt_pk_bf16_f32 v111, v106, v107
	global_store_dwordx4 v[104:105], v[108:111], off sc1
	v_cvt_pk_bf16_f32 v100, v100, v101
	v_cvt_pk_bf16_f32 v101, v102, v103
	v_cvt_pk_bf16_f32 v102, v92, v93
	v_lshl_add_u64 v[92:93], s[68:69], 0, v[166:167]
	v_cvt_pk_bf16_f32 v103, v94, v95
	global_store_dwordx4 v[92:93], v[100:103], off sc1
	v_cvt_pk_bf16_f32 v92, v96, v97
	v_cvt_pk_bf16_f32 v93, v98, v99
	v_cvt_pk_bf16_f32 v94, v88, v89
	v_lshl_add_u64 v[88:89], s[66:67], 0, v[168:169]
	v_cvt_pk_bf16_f32 v95, v90, v91
	global_store_dwordx4 v[88:89], v[92:95], off sc1
	v_cvt_pk_bf16_f32 v84, v84, v85
	v_cvt_pk_bf16_f32 v85, v86, v87
	v_cvt_pk_bf16_f32 v86, v76, v77
	v_lshl_add_u64 v[76:77], s[68:69], 0, v[168:169]
	v_cvt_pk_bf16_f32 v87, v78, v79
	global_store_dwordx4 v[76:77], v[84:87], off sc1
	v_cvt_pk_bf16_f32 v76, v80, v81
	v_cvt_pk_bf16_f32 v77, v82, v83
	v_cvt_pk_bf16_f32 v78, v72, v73
	v_lshl_add_u64 v[72:73], s[66:67], 0, v[170:171]
	s_add_u32 s66, s6, s8
	s_addc_u32 s67, s7, s9
	s_or_b32 s0, s0, 5
	s_ashr_i32 s1, s0, 31
	s_lshl_b64 s[0:1], s[0:1], 14
	v_cvt_pk_bf16_f32 v79, v74, v75
	global_store_dwordx4 v[72:73], v[76:79], off sc1
	v_cvt_pk_bf16_f32 v68, v68, v69
	v_cvt_pk_bf16_f32 v69, v70, v71
	v_cvt_pk_bf16_f32 v70, v64, v65
	v_lshl_add_u64 v[64:65], s[68:69], 0, v[170:171]
	s_add_u32 s0, s6, s0
	v_cvt_pk_bf16_f32 v71, v66, v67
	global_store_dwordx4 v[64:65], v[68:71], off sc1
	v_cvt_pk_bf16_f32 v60, v60, v61
	v_cvt_pk_bf16_f32 v61, v62, v63
	v_cvt_pk_bf16_f32 v62, v56, v57
	v_lshl_add_u64 v[56:57], s[66:67], 0, v[164:165]
	s_addc_u32 s1, s7, s1
	v_cvt_pk_bf16_f32 v63, v58, v59
	global_store_dwordx4 v[56:57], v[60:63], off sc1
	v_cvt_pk_bf16_f32 v52, v52, v53
	v_cvt_pk_bf16_f32 v53, v54, v55
	v_cvt_pk_bf16_f32 v54, v44, v45
	v_lshl_add_u64 v[44:45], s[0:1], 0, v[164:165]
	v_cvt_pk_bf16_f32 v55, v46, v47
	global_store_dwordx4 v[44:45], v[52:55], off sc1
	v_cvt_pk_bf16_f32 v44, v48, v49
	v_cvt_pk_bf16_f32 v45, v50, v51
	v_cvt_pk_bf16_f32 v46, v40, v41
	v_lshl_add_u64 v[40:41], s[66:67], 0, v[166:167]
	v_cvt_pk_bf16_f32 v47, v42, v43
	global_store_dwordx4 v[40:41], v[44:47], off sc1
	v_cvt_pk_bf16_f32 v36, v36, v37
	v_cvt_pk_bf16_f32 v37, v38, v39
	v_cvt_pk_bf16_f32 v38, v28, v29
	v_lshl_add_u64 v[28:29], s[0:1], 0, v[166:167]
	v_cvt_pk_bf16_f32 v39, v30, v31
	global_store_dwordx4 v[28:29], v[36:39], off sc1
	v_cvt_pk_bf16_f32 v28, v32, v33
	v_cvt_pk_bf16_f32 v29, v34, v35
	v_cvt_pk_bf16_f32 v30, v24, v25
	v_lshl_add_u64 v[24:25], s[66:67], 0, v[168:169]
	v_cvt_pk_bf16_f32 v31, v26, v27
	global_store_dwordx4 v[24:25], v[28:31], off sc1
	v_cvt_pk_bf16_f32 v20, v20, v21
	v_cvt_pk_bf16_f32 v21, v22, v23
	v_cvt_pk_bf16_f32 v22, v12, v13
	v_lshl_add_u64 v[12:13], s[0:1], 0, v[168:169]
	v_cvt_pk_bf16_f32 v23, v14, v15
	global_store_dwordx4 v[12:13], v[20:23], off sc1
	v_cvt_pk_bf16_f32 v12, v16, v17
	v_cvt_pk_bf16_f32 v13, v18, v19
	v_cvt_pk_bf16_f32 v14, v8, v9
	v_lshl_add_u64 v[8:9], s[66:67], 0, v[170:171]
	v_cvt_pk_bf16_f32 v15, v10, v11
	global_store_dwordx4 v[8:9], v[12:15], off sc1
	v_cvt_pk_bf16_f32 v4, v4, v5
	v_cvt_pk_bf16_f32 v5, v6, v7
	v_cvt_pk_bf16_f32 v6, v0, v1
	v_lshl_add_u64 v[0:1], s[0:1], 0, v[170:171]
	s_mov_b64 s[0:1], -1
	s_and_b64 vcc, exec, s[2:3]
	v_cvt_pk_bf16_f32 v7, v2, v3
	global_store_dwordx4 v[0:1], v[4:7], off sc1
	s_cbranch_vccnz .LBB0_636
	s_andn2_b64 vcc, exec, s[54:55]
	s_cbranch_vccnz .LBB0_635
	s_barrier
	s_branch .LBB0_635

; __device__ __forceinline__ float bf_lo(unsigned w) { return __uint_as_float(w << 16); }
; __device__ __forceinline__ float bf_hi(unsigned w) { return __uint_as_float(w & 0xffff0000u); }
;     __device__ static __forceinline__ float ub(unsigned w, int k) { return (float)((w >> (8 * k)) & 0xffu); }
;     __device__ __forceinline__ void operator()(f32x4 (&acc)[2][2][4][2], const Unit& u, int wr, int wc, int fr, int fq) const {
;     ...
;             for (int m = 0; m < 4; ++m) gw[ai][m] = *(const u32x4*)(G8 + ((size_t)(((u.pm * 8 + gsel + u.pn) * 8 + (wr * 4 + wc)) * 8 + (ai * 4 + m)) * 1024) + (fq * 16 + fr) * 16);
;         if (ACCUM) {
;             int chain = row0; float dep = acc[0][0][0][0][0];
; #pragma unroll
;             for (int ai = 0; ai < 2; ++ai) { u32x4 ow[4][2];
;                 asm volatile("" : "+v"(chain) : "v"(dep));
; #pragma unroll
;                 for (int m = 0; m < 4; ++m)
; #pragma unroll
;                     for (int bj = 0; bj < 2; ++bj) ow[m][bj] = *(const u32x4*)(mg_at(u, ai, m, bj, wr, wc, fr, fq) + (chain - row0));
; #pragma unroll
;                 for (int m = 0; m < 4; ++m)
; #pragma unroll
;                     for (int bj = 0; bj < 2; ++bj) { const u32x4 gq = gw[ai][m]; u32x2 g; g.x = bj ? gq.z : gq.x; g.y = bj ? gq.w : gq.y; const u32x4 o = ow[m][bj]; f32x4& a0 = acc[ai][bj][m][0]; f32x4& a1 = acc[ai][bj][m][1];
;                         a0[0] = a0[0] * (ub(g.x, 0) * q) + bf_lo(o.x); a0[1] = a0[1] * (ub(g.x, 1) * q) + bf_hi(o.x); a0[2] = a0[2] * (ub(g.x, 2) * q) + bf_lo(o.y); a0[3] = a0[3] * (ub(g.x, 3) * q) + bf_hi(o.y);
;                         a1[0] = a1[0] * (ub(g.y, 0) * q) + bf_lo(o.z); a1[1] = a1[1] * (ub(g.y, 1) * q) + bf_hi(o.z); a1[2] = a1[2] * (ub(g.y, 2) * q) + bf_lo(o.w); a1[3] = a1[3] * (ub(g.y, 3) * q) + bf_hi(o.w);
.LBB0_673:
	s_lshl_b32 s9, s63, 6
	s_lshl_b32 s8, s62, 9
	s_add_i32 s9, s77, s9
	s_add_i32 s8, s9, s8
	s_ashr_i32 s9, s8, 31
	s_lshl_b64 s[64:65], s[8:9], 10
	v_lshl_add_u64 v[108:109], v[184:185], 0, s[64:65]
	s_or_b32 s64, s8, 1
	s_ashr_i32 s65, s64, 31
	s_lshl_b64 s[64:65], s[64:65], 10
	v_lshl_add_u64 v[110:111], v[184:185], 0, s[64:65]
	s_or_b32 s64, s8, 2
	s_ashr_i32 s65, s64, 31
	s_lshl_b64 s[64:65], s[64:65], 10
	global_load_dwordx4 v[204:207], v[108:109], off
	global_load_dwordx4 v[164:167], v[110:111], off
	v_lshl_add_u64 v[108:109], v[184:185], 0, s[64:65]
	s_or_b32 s64, s8, 3
	s_ashr_i32 s65, s64, 31
	s_lshl_b64 s[64:65], s[64:65], 10
	v_lshl_add_u64 v[110:111], v[184:185], 0, s[64:65]
	s_or_b32 s64, s8, 4
	s_ashr_i32 s65, s64, 31
	s_lshl_b64 s[64:65], s[64:65], 10
	global_load_dwordx4 v[152:155], v[108:109], off
	global_load_dwordx4 v[144:147], v[110:111], off
	v_lshl_add_u64 v[108:109], v[184:185], 0, s[64:65]
	s_or_b32 s64, s8, 5
	s_ashr_i32 s65, s64, 31
	s_lshl_b64 s[64:65], s[64:65], 10
	v_lshl_add_u64 v[110:111], v[184:185], 0, s[64:65]
	s_or_b32 s64, s8, 6
	s_or_b32 s8, s8, 7
	s_ashr_i32 s65, s64, 31
	s_ashr_i32 s9, s8, 31
	s_lshl_b64 s[64:65], s[64:65], 10
	s_lshl_b64 s[8:9], s[8:9], 10
	v_lshl_add_u32 v219, s62, 8, v198
	global_load_dwordx4 v[140:143], v[108:109], off
	global_load_dwordx4 v[136:139], v[110:111], off
	v_lshl_add_u64 v[108:109], v[184:185], 0, s[64:65]
	v_lshl_add_u64 v[110:111], v[184:185], 0, s[8:9]
	s_lshl_b32 s8, s63, 3
	s_lshl_b32 s9, s62, 5
	v_mov_b32_e32 v236, v219
	global_load_dwordx4 v[132:135], v[108:109], off
	s_nop 0
	global_load_dwordx4 v[108:111], v[110:111], off
	s_add_i32 s9, s9, s8
	s_or_b32 s66, s9, s74
	v_sub_u32_e32 v148, v236, v219
	v_ashrrev_i32_e32 v149, 31, v148
	v_lshl_add_u64 v[148:149], s[6:7], 0, v[148:149]
	s_ashr_i32 s67, s66, 31
	s_lshl_b64 s[64:65], s[66:67], 14
	v_lshl_add_u64 v[150:151], v[148:149], 0, v[176:177]
	v_lshl_add_u64 v[156:157], v[150:151], 0, s[64:65]
	global_load_dwordx4 v[208:211], v[156:157], off
	s_or_b32 s8, s66, 4
	s_ashr_i32 s9, s8, 31
	s_lshl_b64 s[62:63], s[8:9], 14
	v_lshl_add_u64 v[150:151], v[150:151], 0, s[62:63]
	global_load_dwordx4 v[212:215], v[150:151], off
	v_lshl_add_u64 v[150:151], v[148:149], 0, v[178:179]
	v_lshl_add_u64 v[156:157], v[150:151], 0, s[64:65]
	global_load_dwordx4 v[220:223], v[156:157], off
	v_lshl_add_u64 v[156:157], v[148:149], 0, v[180:181]
	v_lshl_add_u64 v[148:149], v[148:149], 0, v[182:183]
	v_lshl_add_u64 v[150:151], v[150:151], 0, s[62:63]
	v_lshl_add_u64 v[158:159], v[156:157], 0, s[64:65]
	v_lshl_add_u64 v[156:157], v[156:157], 0, s[62:63]
	v_lshl_add_u64 v[216:217], v[148:149], 0, s[64:65]
	v_lshl_add_u64 v[148:149], v[148:149], 0, s[62:63]
	global_load_dwordx4 v[224:227], v[150:151], off
	global_load_dwordx4 v[168:171], v[158:159], off
	global_load_dwordx4 v[160:163], v[156:157], off
	s_nop 0
	global_load_dwordx4 v[156:159], v[216:217], off
	s_nop 0
	global_load_dwordx4 v[148:151], v[148:149], off
	s_or_b32 s8, s66, 1
	s_ashr_i32 s9, s8, 31
	s_lshl_b64 s[68:69], s[8:9], 14
	s_or_b32 s8, s66, 5
	s_ashr_i32 s9, s8, 31
	s_lshl_b64 s[66:67], s[8:9], 14
	s_add_u32 s64, s6, s64
	s_addc_u32 s65, s7, s65
	s_add_u32 s62, s6, s62
	s_addc_u32 s63, s7, s63
	s_waitcnt vmcnt(0)
	v_cvt_f32_ubyte3_e32 v229, v204
	v_cvt_f32_ubyte2_e32 v228, v204
	v_pk_mul_f32 v[228:229], v[228:229], s[10:11] op_sel_hi:[1,0]
	v_cvt_f32_ubyte1_e32 v217, v204
	v_cvt_f32_ubyte0_e32 v216, v204
	v_cvt_f32_ubyte1_e32 v231, v205
	v_cvt_f32_ubyte0_e32 v230, v205
	v_pk_mul_f32 v[216:217], v[216:217], s[10:11] op_sel_hi:[1,0]
	v_pk_mul_f32 v[230:231], v[230:231], s[10:11] op_sel_hi:[1,0]
	v_lshlrev_b32_e32 v232, 16, v208
	v_and_b32_e32 v233, 0xffff0000, v208
	v_lshlrev_b32_e32 v208, 16, v209
	v_and_b32_e32 v209, 0xffff0000, v209
	v_pk_fma_f32 v[130:131], v[130:131], v[228:229], v[208:209]
	v_cvt_f32_ubyte3_e32 v209, v205
	v_cvt_f32_ubyte2_e32 v208, v205
	v_pk_mul_f32 v[204:205], v[208:209], s[10:11] op_sel_hi:[1,0]
	v_lshlrev_b32_e32 v208, 16, v211
	v_and_b32_e32 v209, 0xffff0000, v211
	v_pk_fma_f32 v[126:127], v[126:127], v[204:205], v[208:209]
	v_cvt_f32_ubyte1_e32 v205, v206
	v_cvt_f32_ubyte0_e32 v204, v206
	v_pk_mul_f32 v[204:205], v[204:205], s[10:11] op_sel_hi:[1,0]
	v_lshlrev_b32_e32 v208, 16, v212
	v_and_b32_e32 v209, 0xffff0000, v212
	v_pk_fma_f32 v[120:121], v[120:121], v[204:205], v[208:209]
	v_cvt_f32_ubyte3_e32 v205, v206
	v_cvt_f32_ubyte2_e32 v204, v206
	v_pk_mul_f32 v[204:205], v[204:205], s[10:11] op_sel_hi:[1,0]
	v_lshlrev_b32_e32 v208, 16, v213
	v_and_b32_e32 v209, 0xffff0000, v213
	v_pk_fma_f32 v[122:123], v[122:123], v[204:205], v[208:209]
	v_cvt_f32_ubyte1_e32 v205, v207
	v_cvt_f32_ubyte0_e32 v204, v207
	v_pk_mul_f32 v[204:205], v[204:205], s[10:11] op_sel_hi:[1,0]
	v_lshlrev_b32_e32 v208, 16, v214
	v_and_b32_e32 v209, 0xffff0000, v214
	v_pk_fma_f32 v[116:117], v[116:117], v[204:205], v[208:209]
	v_cvt_f32_ubyte3_e32 v205, v207
	v_cvt_f32_ubyte2_e32 v204, v207
	v_pk_mul_f32 v[204:205], v[204:205], s[10:11] op_sel_hi:[1,0]
	v_lshlrev_b32_e32 v206, 16, v215
	v_and_b32_e32 v207, 0xffff0000, v215
	v_pk_fma_f32 v[118:119], v[118:119], v[204:205], v[206:207]
	v_cvt_f32_ubyte1_e32 v205, v164
	v_cvt_f32_ubyte0_e32 v204, v164
	v_pk_mul_f32 v[204:205], v[204:205], s[10:11] op_sel_hi:[1,0]
	v_lshlrev_b32_e32 v206, 16, v220
	v_and_b32_e32 v207, 0xffff0000, v220
	v_pk_fma_f32 v[112:113], v[112:113], v[204:205], v[206:207]
	v_cvt_f32_ubyte3_e32 v205, v164
	v_cvt_f32_ubyte2_e32 v204, v164
	v_pk_mul_f32 v[204:205], v[204:205], s[10:11] op_sel_hi:[1,0]
	v_lshlrev_b32_e32 v206, 16, v221
	v_and_b32_e32 v207, 0xffff0000, v221
; __device__ __forceinline__ float bf_lo(unsigned w) { return __uint_as_float(w << 16); }
; __device__ __forceinline__ float bf_hi(unsigned w) { return __uint_as_float(w & 0xffff0000u); }
;     __device__ static __forceinline__ float ub(unsigned w, int k) { return (float)((w >> (8 * k)) & 0xffu); }
;     __device__ __forceinline__ void operator()(f32x4 (&acc)[2][2][4][2], const Unit& u, int wr, int wc, int fr, int fq) const {
;     ...
;                 for (int m = 0; m < 4; ++m)
; #pragma unroll
;                     for (int bj = 0; bj < 2; ++bj) { const u32x4 gq = gw[ai][m]; u32x2 g; g.x = bj ? gq.z : gq.x; g.y = bj ? gq.w : gq.y; const u32x4 o = ow[m][bj]; f32x4& a0 = acc[ai][bj][m][0]; f32x4& a1 = acc[ai][bj][m][1];
;                         a0[0] = a0[0] * (ub(g.x, 0) * q) + bf_lo(o.x); a0[1] = a0[1] * (ub(g.x, 1) * q) + bf_hi(o.x); a0[2] = a0[2] * (ub(g.x, 2) * q) + bf_lo(o.y); a0[3] = a0[3] * (ub(g.x, 3) * q) + bf_hi(o.y);
;                         a1[0] = a1[0] * (ub(g.y, 0) * q) + bf_lo(o.z); a1[1] = a1[1] * (ub(g.y, 1) * q) + bf_hi(o.z); a1[2] = a1[2] * (ub(g.y, 2) * q) + bf_lo(o.w); a1[3] = a1[3] * (ub(g.y, 3) * q) + bf_hi(o.w);
;                         asm volatile("" : "+v"(a0), "+v"(a1)); }
	v_pk_fma_f32 v[114:115], v[114:115], v[204:205], v[206:207]
	v_cvt_f32_ubyte1_e32 v205, v165
	v_cvt_f32_ubyte0_e32 v204, v165
	v_pk_mul_f32 v[204:205], v[204:205], s[10:11] op_sel_hi:[1,0]
	v_lshlrev_b32_e32 v206, 16, v222
	v_and_b32_e32 v207, 0xffff0000, v222
	v_pk_fma_f32 v[104:105], v[104:105], v[204:205], v[206:207]
	v_cvt_f32_ubyte3_e32 v205, v165
	v_cvt_f32_ubyte2_e32 v204, v165
	v_pk_mul_f32 v[164:165], v[204:205], s[10:11] op_sel_hi:[1,0]
	v_lshlrev_b32_e32 v204, 16, v223
	v_and_b32_e32 v205, 0xffff0000, v223
	v_pk_fma_f32 v[106:107], v[106:107], v[164:165], v[204:205]
	v_cvt_f32_ubyte1_e32 v165, v166
	v_cvt_f32_ubyte0_e32 v164, v166
	v_pk_mul_f32 v[164:165], v[164:165], s[10:11] op_sel_hi:[1,0]
	v_lshlrev_b32_e32 v204, 16, v224
	v_and_b32_e32 v205, 0xffff0000, v224
	v_pk_fma_f32 v[100:101], v[100:101], v[164:165], v[204:205]
	v_cvt_f32_ubyte3_e32 v165, v166
	v_cvt_f32_ubyte2_e32 v164, v166
	v_pk_mul_f32 v[164:165], v[164:165], s[10:11] op_sel_hi:[1,0]
	v_lshlrev_b32_e32 v204, 16, v225
	v_and_b32_e32 v205, 0xffff0000, v225
	v_pk_fma_f32 v[102:103], v[102:103], v[164:165], v[204:205]
	v_cvt_f32_ubyte1_e32 v165, v167
	v_cvt_f32_ubyte0_e32 v164, v167
	v_pk_mul_f32 v[164:165], v[164:165], s[10:11] op_sel_hi:[1,0]
	v_lshlrev_b32_e32 v204, 16, v226
	v_and_b32_e32 v205, 0xffff0000, v226
	v_pk_fma_f32 v[96:97], v[96:97], v[164:165], v[204:205]
	v_cvt_f32_ubyte3_e32 v165, v167
	v_cvt_f32_ubyte2_e32 v164, v167
	v_pk_mul_f32 v[164:165], v[164:165], s[10:11] op_sel_hi:[1,0]
	v_lshlrev_b32_e32 v166, 16, v227
	v_and_b32_e32 v167, 0xffff0000, v227
	v_pk_fma_f32 v[98:99], v[98:99], v[164:165], v[166:167]
	v_cvt_f32_ubyte1_e32 v165, v152
	v_cvt_f32_ubyte0_e32 v164, v152
	v_pk_mul_f32 v[164:165], v[164:165], s[10:11] op_sel_hi:[1,0]
	v_lshlrev_b32_e32 v166, 16, v168
	v_and_b32_e32 v167, 0xffff0000, v168
	v_pk_fma_f32 v[92:93], v[92:93], v[164:165], v[166:167]
	v_cvt_f32_ubyte3_e32 v165, v152
	v_cvt_f32_ubyte2_e32 v164, v152
	v_pk_mul_f32 v[164:165], v[164:165], s[10:11] op_sel_hi:[1,0]
	v_lshlrev_b32_e32 v166, 16, v169
	v_and_b32_e32 v167, 0xffff0000, v169
	v_pk_fma_f32 v[94:95], v[94:95], v[164:165], v[166:167]
	v_cvt_f32_ubyte1_e32 v165, v153
	v_cvt_f32_ubyte0_e32 v164, v153
	v_pk_mul_f32 v[164:165], v[164:165], s[10:11] op_sel_hi:[1,0]
	v_lshlrev_b32_e32 v166, 16, v170
	v_and_b32_e32 v167, 0xffff0000, v170
	v_pk_fma_f32 v[88:89], v[88:89], v[164:165], v[166:167]
	v_cvt_f32_ubyte3_e32 v165, v153
	v_cvt_f32_ubyte2_e32 v164, v153
	v_pk_mul_f32 v[152:153], v[164:165], s[10:11] op_sel_hi:[1,0]
	v_lshlrev_b32_e32 v164, 16, v171
	v_and_b32_e32 v165, 0xffff0000, v171
	v_pk_fma_f32 v[90:91], v[90:91], v[152:153], v[164:165]
	v_cvt_f32_ubyte1_e32 v153, v154
	v_cvt_f32_ubyte0_e32 v152, v154
	v_pk_mul_f32 v[152:153], v[152:153], s[10:11] op_sel_hi:[1,0]
	v_lshlrev_b32_e32 v164, 16, v160
	v_and_b32_e32 v165, 0xffff0000, v160
	v_pk_fma_f32 v[84:85], v[84:85], v[152:153], v[164:165]
	v_cvt_f32_ubyte3_e32 v153, v154
	v_cvt_f32_ubyte2_e32 v152, v154
	v_pk_mul_f32 v[152:153], v[152:153], s[10:11] op_sel_hi:[1,0]
	v_lshlrev_b32_e32 v160, 16, v161
	v_and_b32_e32 v161, 0xffff0000, v161
	v_pk_fma_f32 v[86:87], v[86:87], v[152:153], v[160:161]
	v_cvt_f32_ubyte1_e32 v153, v155
	v_cvt_f32_ubyte0_e32 v152, v155
	v_pk_mul_f32 v[152:153], v[152:153], s[10:11] op_sel_hi:[1,0]
	v_lshlrev_b32_e32 v160, 16, v162
	v_and_b32_e32 v161, 0xffff0000, v162
	v_pk_fma_f32 v[80:81], v[80:81], v[152:153], v[160:161]
	v_cvt_f32_ubyte3_e32 v153, v155
	v_cvt_f32_ubyte2_e32 v152, v155
	v_pk_mul_f32 v[152:153], v[152:153], s[10:11] op_sel_hi:[1,0]
	v_lshlrev_b32_e32 v154, 16, v163
	v_and_b32_e32 v155, 0xffff0000, v163
	v_pk_fma_f32 v[82:83], v[82:83], v[152:153], v[154:155]
	v_cvt_f32_ubyte1_e32 v153, v144
	v_cvt_f32_ubyte0_e32 v152, v144
	v_pk_mul_f32 v[152:153], v[152:153], s[10:11] op_sel_hi:[1,0]
	v_lshlrev_b32_e32 v154, 16, v156
	v_and_b32_e32 v155, 0xffff0000, v156
	v_pk_fma_f32 v[76:77], v[76:77], v[152:153], v[154:155]
	v_cvt_f32_ubyte3_e32 v153, v144
	v_cvt_f32_ubyte2_e32 v152, v144
	v_pk_mul_f32 v[152:153], v[152:153], s[10:11] op_sel_hi:[1,0]
	v_lshlrev_b32_e32 v154, 16, v157
	v_and_b32_e32 v155, 0xffff0000, v157
	v_pk_fma_f32 v[78:79], v[78:79], v[152:153], v[154:155]
	v_cvt_f32_ubyte1_e32 v153, v145
	v_cvt_f32_ubyte0_e32 v152, v145
	v_pk_mul_f32 v[152:153], v[152:153], s[10:11] op_sel_hi:[1,0]
	v_lshlrev_b32_e32 v154, 16, v158
	v_and_b32_e32 v155, 0xffff0000, v158
	v_pk_fma_f32 v[72:73], v[72:73], v[152:153], v[154:155]
	v_cvt_f32_ubyte3_e32 v153, v145
	v_cvt_f32_ubyte2_e32 v152, v145
	v_pk_mul_f32 v[144:145], v[152:153], s[10:11] op_sel_hi:[1,0]
	v_lshlrev_b32_e32 v152, 16, v159
	v_and_b32_e32 v153, 0xffff0000, v159
	v_pk_fma_f32 v[74:75], v[74:75], v[144:145], v[152:153]
	v_cvt_f32_ubyte1_e32 v145, v146
	v_cvt_f32_ubyte0_e32 v144, v146
	v_pk_mul_f32 v[144:145], v[144:145], s[10:11] op_sel_hi:[1,0]
	v_lshlrev_b32_e32 v152, 16, v148
	v_and_b32_e32 v153, 0xffff0000, v148
	v_pk_fma_f32 v[68:69], v[68:69], v[144:145], v[152:153]
	v_cvt_f32_ubyte3_e32 v145, v146
	v_cvt_f32_ubyte2_e32 v144, v146
	v_pk_mul_f32 v[144:145], v[144:145], s[10:11] op_sel_hi:[1,0]
	v_lshlrev_b32_e32 v148, 16, v149
	v_and_b32_e32 v149, 0xffff0000, v149
	v_pk_fma_f32 v[70:71], v[70:71], v[144:145], v[148:149]
	v_cvt_f32_ubyte1_e32 v145, v147
	v_cvt_f32_ubyte0_e32 v144, v147
	v_pk_mul_f32 v[144:145], v[144:145], s[10:11] op_sel_hi:[1,0]
	v_lshlrev_b32_e32 v148, 16, v150
	v_and_b32_e32 v149, 0xffff0000, v150
	v_pk_fma_f32 v[64:65], v[64:65], v[144:145], v[148:149]
	v_cvt_f32_ubyte3_e32 v145, v147
	v_cvt_f32_ubyte2_e32 v144, v147
	v_lshlrev_b32_e32 v234, 16, v210
	v_and_b32_e32 v235, 0xffff0000, v210
; __device__ __forceinline__ float bf_lo(unsigned w) { return __uint_as_float(w << 16); }
; __device__ __forceinline__ float bf_hi(unsigned w) { return __uint_as_float(w & 0xffff0000u); }
;     __device__ static __forceinline__ float ub(unsigned w, int k) { return (float)((w >> (8 * k)) & 0xffu); }
;     __device__ __forceinline__ void operator()(f32x4 (&acc)[2][2][4][2], const Unit& u, int wr, int wc, int fr, int fq) const {
;     ...
;             int chain = row0; float dep = acc[0][0][0][0][0];
; #pragma unroll
;             for (int ai = 0; ai < 2; ++ai) { u32x4 ow[4][2];
;                 asm volatile("" : "+v"(chain) : "v"(dep));
; #pragma unroll
;                 for (int m = 0; m < 4; ++m)
; #pragma unroll
;                     for (int bj = 0; bj < 2; ++bj) ow[m][bj] = *(const u32x4*)(mg_at(u, ai, m, bj, wr, wc, fr, fq) + (chain - row0));
; #pragma unroll
;                 for (int m = 0; m < 4; ++m)
; #pragma unroll
;                     for (int bj = 0; bj < 2; ++bj) { const u32x4 gq = gw[ai][m]; u32x2 g; g.x = bj ? gq.z : gq.x; g.y = bj ? gq.w : gq.y; const u32x4 o = ow[m][bj]; f32x4& a0 = acc[ai][bj][m][0]; f32x4& a1 = acc[ai][bj][m][1];
;                         a0[0] = a0[0] * (ub(g.x, 0) * q) + bf_lo(o.x); a0[1] = a0[1] * (ub(g.x, 1) * q) + bf_hi(o.x); a0[2] = a0[2] * (ub(g.x, 2) * q) + bf_lo(o.y); a0[3] = a0[3] * (ub(g.x, 3) * q) + bf_hi(o.y);
;                         a1[0] = a1[0] * (ub(g.y, 0) * q) + bf_lo(o.z); a1[1] = a1[1] * (ub(g.y, 1) * q) + bf_hi(o.z); a1[2] = a1[2] * (ub(g.y, 2) * q) + bf_lo(o.w); a1[3] = a1[3] * (ub(g.y, 3) * q) + bf_hi(o.w);
;                         asm volatile("" : "+v"(a0), "+v"(a1)); }
	v_pk_mul_f32 v[144:145], v[144:145], s[10:11] op_sel_hi:[1,0]
	v_lshlrev_b32_e32 v146, 16, v151
	v_and_b32_e32 v147, 0xffff0000, v151
	v_pk_fma_f32 v[128:129], v[128:129], v[216:217], v[232:233]
	v_pk_fma_f32 v[124:125], v[124:125], v[230:231], v[234:235]
	v_pk_fma_f32 v[66:67], v[66:67], v[144:145], v[146:147]
	s_nop 0
	v_cvt_f32_ubyte1_e32 v209, v140
	v_cvt_f32_ubyte0_e32 v208, v140
	v_sub_u32_e32 v144, v236, v219
	v_ashrrev_i32_e32 v145, 31, v144
	v_lshl_add_u64 v[144:145], s[6:7], 0, v[144:145]
	v_lshl_add_u64 v[146:147], v[144:145], 0, v[176:177]
	v_lshl_add_u64 v[148:149], v[146:147], 0, s[68:69]
	global_load_dwordx4 v[160:163], v[148:149], off
	v_lshl_add_u64 v[146:147], v[146:147], 0, s[66:67]
	global_load_dwordx4 v[164:167], v[146:147], off
	v_lshl_add_u64 v[146:147], v[144:145], 0, v[178:179]
	v_lshl_add_u64 v[148:149], v[146:147], 0, s[68:69]
	global_load_dwordx4 v[168:171], v[148:149], off
	v_lshl_add_u64 v[146:147], v[146:147], 0, s[66:67]
	global_load_dwordx4 v[204:207], v[146:147], off
	v_lshl_add_u64 v[146:147], v[144:145], 0, v[180:181]
	v_lshl_add_u64 v[148:149], v[146:147], 0, s[68:69]
	v_lshl_add_u64 v[146:147], v[146:147], 0, s[66:67]
	global_load_dwordx4 v[156:159], v[148:149], off
	global_load_dwordx4 v[152:155], v[146:147], off
	v_lshl_add_u64 v[144:145], v[144:145], 0, v[182:183]
	v_lshl_add_u64 v[146:147], v[144:145], 0, s[68:69]
	v_lshl_add_u64 v[144:145], v[144:145], 0, s[66:67]
	global_load_dwordx4 v[148:151], v[146:147], off
	s_nop 0
	global_load_dwordx4 v[144:147], v[144:145], off
	v_pk_mul_f32 v[208:209], v[208:209], s[10:11] op_sel_hi:[1,0]
	s_waitcnt vmcnt(7)
	v_lshlrev_b32_e32 v210, 16, v160
	v_and_b32_e32 v211, 0xffff0000, v160
	v_pk_fma_f32 v[60:61], v[60:61], v[208:209], v[210:211]
	v_cvt_f32_ubyte3_e32 v209, v140
	v_cvt_f32_ubyte2_e32 v208, v140
	v_pk_mul_f32 v[208:209], v[208:209], s[10:11] op_sel_hi:[1,0]
	v_lshlrev_b32_e32 v160, 16, v161
	v_and_b32_e32 v161, 0xffff0000, v161
	v_pk_fma_f32 v[62:63], v[62:63], v[208:209], v[160:161]
	v_cvt_f32_ubyte1_e32 v161, v141
	v_cvt_f32_ubyte0_e32 v160, v141
	v_pk_mul_f32 v[160:161], v[160:161], s[10:11] op_sel_hi:[1,0]
	v_lshlrev_b32_e32 v208, 16, v162
	v_and_b32_e32 v209, 0xffff0000, v162
	v_pk_fma_f32 v[56:57], v[56:57], v[160:161], v[208:209]
	v_cvt_f32_ubyte3_e32 v161, v141
	v_cvt_f32_ubyte2_e32 v160, v141
	v_pk_mul_f32 v[140:141], v[160:161], s[10:11] op_sel_hi:[1,0]
	v_lshlrev_b32_e32 v160, 16, v163
	v_and_b32_e32 v161, 0xffff0000, v163
	v_pk_fma_f32 v[58:59], v[58:59], v[140:141], v[160:161]
	v_cvt_f32_ubyte1_e32 v141, v142
	v_cvt_f32_ubyte0_e32 v140, v142
	v_pk_mul_f32 v[140:141], v[140:141], s[10:11] op_sel_hi:[1,0]
	s_waitcnt vmcnt(6)
	v_lshlrev_b32_e32 v160, 16, v164
	v_and_b32_e32 v161, 0xffff0000, v164
	v_pk_fma_f32 v[52:53], v[52:53], v[140:141], v[160:161]
	v_cvt_f32_ubyte3_e32 v141, v142
	v_cvt_f32_ubyte2_e32 v140, v142
	v_pk_mul_f32 v[140:141], v[140:141], s[10:11] op_sel_hi:[1,0]
	v_lshlrev_b32_e32 v160, 16, v165
	v_and_b32_e32 v161, 0xffff0000, v165
	v_pk_fma_f32 v[54:55], v[54:55], v[140:141], v[160:161]
	v_cvt_f32_ubyte1_e32 v141, v143
	v_cvt_f32_ubyte0_e32 v140, v143
	v_pk_mul_f32 v[140:141], v[140:141], s[10:11] op_sel_hi:[1,0]
	v_lshlrev_b32_e32 v160, 16, v166
	v_and_b32_e32 v161, 0xffff0000, v166
	v_pk_fma_f32 v[48:49], v[48:49], v[140:141], v[160:161]
	v_cvt_f32_ubyte3_e32 v141, v143
	v_cvt_f32_ubyte2_e32 v140, v143
	v_pk_mul_f32 v[140:141], v[140:141], s[10:11] op_sel_hi:[1,0]
	v_lshlrev_b32_e32 v142, 16, v167
	v_and_b32_e32 v143, 0xffff0000, v167
	v_pk_fma_f32 v[50:51], v[50:51], v[140:141], v[142:143]
	v_cvt_f32_ubyte1_e32 v141, v136
	v_cvt_f32_ubyte0_e32 v140, v136
	v_pk_mul_f32 v[140:141], v[140:141], s[10:11] op_sel_hi:[1,0]
	s_waitcnt vmcnt(5)
	v_lshlrev_b32_e32 v142, 16, v168
	v_and_b32_e32 v143, 0xffff0000, v168
	v_pk_fma_f32 v[44:45], v[44:45], v[140:141], v[142:143]
	v_cvt_f32_ubyte3_e32 v141, v136
	v_cvt_f32_ubyte2_e32 v140, v136
	v_pk_mul_f32 v[140:141], v[140:141], s[10:11] op_sel_hi:[1,0]
	v_lshlrev_b32_e32 v142, 16, v169
	v_and_b32_e32 v143, 0xffff0000, v169
	v_pk_fma_f32 v[46:47], v[46:47], v[140:141], v[142:143]
	v_cvt_f32_ubyte1_e32 v141, v137
	v_cvt_f32_ubyte0_e32 v140, v137
	v_pk_mul_f32 v[140:141], v[140:141], s[10:11] op_sel_hi:[1,0]
	v_lshlrev_b32_e32 v142, 16, v170
	v_and_b32_e32 v143, 0xffff0000, v170
	v_pk_fma_f32 v[40:41], v[40:41], v[140:141], v[142:143]
	v_cvt_f32_ubyte3_e32 v141, v137
	v_cvt_f32_ubyte2_e32 v140, v137
	v_pk_mul_f32 v[136:137], v[140:141], s[10:11] op_sel_hi:[1,0]
	v_lshlrev_b32_e32 v140, 16, v171
	v_and_b32_e32 v141, 0xffff0000, v171
	v_pk_fma_f32 v[42:43], v[42:43], v[136:137], v[140:141]
	v_cvt_f32_ubyte1_e32 v137, v138
	v_cvt_f32_ubyte0_e32 v136, v138
	v_pk_mul_f32 v[136:137], v[136:137], s[10:11] op_sel_hi:[1,0]
	s_waitcnt vmcnt(4)
	v_lshlrev_b32_e32 v140, 16, v204
	v_and_b32_e32 v141, 0xffff0000, v204
	v_pk_fma_f32 v[36:37], v[36:37], v[136:137], v[140:141]
	v_cvt_f32_ubyte3_e32 v137, v138
	v_cvt_f32_ubyte2_e32 v136, v138
	v_pk_mul_f32 v[136:137], v[136:137], s[10:11] op_sel_hi:[1,0]
	v_lshlrev_b32_e32 v140, 16, v205
	v_and_b32_e32 v141, 0xffff0000, v205
	v_pk_fma_f32 v[38:39], v[38:39], v[136:137], v[140:141]
	v_cvt_f32_ubyte1_e32 v137, v139
	v_cvt_f32_ubyte0_e32 v136, v139
	v_pk_mul_f32 v[136:137], v[136:137], s[10:11] op_sel_hi:[1,0]
	v_lshlrev_b32_e32 v140, 16, v206
	v_and_b32_e32 v141, 0xffff0000, v206
	v_pk_fma_f32 v[32:33], v[32:33], v[136:137], v[140:141]
	v_cvt_f32_ubyte3_e32 v137, v139
	v_cvt_f32_ubyte2_e32 v136, v139
	v_pk_mul_f32 v[136:137], v[136:137], s[10:11] op_sel_hi:[1,0]
	v_lshlrev_b32_e32 v138, 16, v207
	v_and_b32_e32 v139, 0xffff0000, v207
	v_pk_fma_f32 v[34:35], v[34:35], v[136:137], v[138:139]
	v_cvt_f32_ubyte1_e32 v137, v132
	v_cvt_f32_ubyte0_e32 v136, v132
	v_pk_mul_f32 v[136:137], v[136:137], s[10:11] op_sel_hi:[1,0]
	s_waitcnt vmcnt(3)
; __device__ __forceinline__ float bf_lo(unsigned w) { return __uint_as_float(w << 16); }
; __device__ __forceinline__ float bf_hi(unsigned w) { return __uint_as_float(w & 0xffff0000u); }
;     __device__ static __forceinline__ float ub(unsigned w, int k) { return (float)((w >> (8 * k)) & 0xffu); }
;     __device__ __forceinline__ void operator()(f32x4 (&acc)[2][2][4][2], const Unit& u, int wr, int wc, int fr, int fq) const {
;     ...
;                 for (int m = 0; m < 4; ++m)
; #pragma unroll
;                     for (int bj = 0; bj < 2; ++bj) { const u32x4 gq = gw[ai][m]; u32x2 g; g.x = bj ? gq.z : gq.x; g.y = bj ? gq.w : gq.y; const u32x4 o = ow[m][bj]; f32x4& a0 = acc[ai][bj][m][0]; f32x4& a1 = acc[ai][bj][m][1];
;                         a0[0] = a0[0] * (ub(g.x, 0) * q) + bf_lo(o.x); a0[1] = a0[1] * (ub(g.x, 1) * q) + bf_hi(o.x); a0[2] = a0[2] * (ub(g.x, 2) * q) + bf_lo(o.y); a0[3] = a0[3] * (ub(g.x, 3) * q) + bf_hi(o.y);
;                         a1[0] = a1[0] * (ub(g.y, 0) * q) + bf_lo(o.z); a1[1] = a1[1] * (ub(g.y, 1) * q) + bf_hi(o.z); a1[2] = a1[2] * (ub(g.y, 2) * q) + bf_lo(o.w); a1[3] = a1[3] * (ub(g.y, 3) * q) + bf_hi(o.w);
;                         asm volatile("" : "+v"(a0), "+v"(a1)); }
	v_lshlrev_b32_e32 v138, 16, v156
	v_and_b32_e32 v139, 0xffff0000, v156
	v_pk_fma_f32 v[28:29], v[28:29], v[136:137], v[138:139]
	v_cvt_f32_ubyte3_e32 v137, v132
	v_cvt_f32_ubyte2_e32 v136, v132
	v_pk_mul_f32 v[136:137], v[136:137], s[10:11] op_sel_hi:[1,0]
	v_lshlrev_b32_e32 v138, 16, v157
	v_and_b32_e32 v139, 0xffff0000, v157
	v_pk_fma_f32 v[30:31], v[30:31], v[136:137], v[138:139]
	v_cvt_f32_ubyte1_e32 v137, v133
	v_cvt_f32_ubyte0_e32 v136, v133
	v_pk_mul_f32 v[136:137], v[136:137], s[10:11] op_sel_hi:[1,0]
	v_lshlrev_b32_e32 v138, 16, v158
	v_and_b32_e32 v139, 0xffff0000, v158
	v_pk_fma_f32 v[24:25], v[24:25], v[136:137], v[138:139]
	v_cvt_f32_ubyte3_e32 v137, v133
	v_cvt_f32_ubyte2_e32 v136, v133
	v_pk_mul_f32 v[132:133], v[136:137], s[10:11] op_sel_hi:[1,0]
	v_lshlrev_b32_e32 v136, 16, v159
	v_and_b32_e32 v137, 0xffff0000, v159
	v_pk_fma_f32 v[26:27], v[26:27], v[132:133], v[136:137]
	v_cvt_f32_ubyte1_e32 v133, v134
	v_cvt_f32_ubyte0_e32 v132, v134
	v_pk_mul_f32 v[132:133], v[132:133], s[10:11] op_sel_hi:[1,0]
	s_waitcnt vmcnt(2)
	v_lshlrev_b32_e32 v136, 16, v152
	v_and_b32_e32 v137, 0xffff0000, v152
	v_pk_fma_f32 v[20:21], v[20:21], v[132:133], v[136:137]
	v_cvt_f32_ubyte3_e32 v133, v134
	v_cvt_f32_ubyte2_e32 v132, v134
	v_pk_mul_f32 v[132:133], v[132:133], s[10:11] op_sel_hi:[1,0]
	v_lshlrev_b32_e32 v136, 16, v153
	v_and_b32_e32 v137, 0xffff0000, v153
	v_pk_fma_f32 v[22:23], v[22:23], v[132:133], v[136:137]
	v_cvt_f32_ubyte1_e32 v133, v135
	v_cvt_f32_ubyte0_e32 v132, v135
	v_pk_mul_f32 v[132:133], v[132:133], s[10:11] op_sel_hi:[1,0]
	v_lshlrev_b32_e32 v136, 16, v154
	v_and_b32_e32 v137, 0xffff0000, v154
	v_pk_fma_f32 v[16:17], v[16:17], v[132:133], v[136:137]
	v_cvt_f32_ubyte3_e32 v133, v135
	v_cvt_f32_ubyte2_e32 v132, v135
	v_pk_mul_f32 v[132:133], v[132:133], s[10:11] op_sel_hi:[1,0]
	v_lshlrev_b32_e32 v134, 16, v155
	v_and_b32_e32 v135, 0xffff0000, v155
	v_pk_fma_f32 v[18:19], v[18:19], v[132:133], v[134:135]
	v_cvt_f32_ubyte1_e32 v133, v108
	v_cvt_f32_ubyte0_e32 v132, v108
	v_pk_mul_f32 v[132:133], v[132:133], s[10:11] op_sel_hi:[1,0]
	s_waitcnt vmcnt(1)
	v_lshlrev_b32_e32 v134, 16, v148
	v_and_b32_e32 v135, 0xffff0000, v148
	v_pk_fma_f32 v[12:13], v[12:13], v[132:133], v[134:135]
	v_cvt_f32_ubyte3_e32 v133, v108
	v_cvt_f32_ubyte2_e32 v132, v108
	v_pk_mul_f32 v[132:133], v[132:133], s[10:11] op_sel_hi:[1,0]
	v_lshlrev_b32_e32 v134, 16, v149
	v_and_b32_e32 v135, 0xffff0000, v149
	v_pk_fma_f32 v[14:15], v[14:15], v[132:133], v[134:135]
	v_cvt_f32_ubyte1_e32 v133, v109
	v_cvt_f32_ubyte0_e32 v132, v109
	v_pk_mul_f32 v[132:133], v[132:133], s[10:11] op_sel_hi:[1,0]
	v_lshlrev_b32_e32 v134, 16, v150
	v_and_b32_e32 v135, 0xffff0000, v150
	v_pk_fma_f32 v[8:9], v[8:9], v[132:133], v[134:135]
	v_cvt_f32_ubyte3_e32 v133, v109
	v_cvt_f32_ubyte2_e32 v132, v109
	v_pk_mul_f32 v[108:109], v[132:133], s[10:11] op_sel_hi:[1,0]
	v_lshlrev_b32_e32 v132, 16, v151
	v_and_b32_e32 v133, 0xffff0000, v151
	v_pk_fma_f32 v[10:11], v[10:11], v[108:109], v[132:133]
	v_cvt_f32_ubyte1_e32 v109, v110
	v_cvt_f32_ubyte0_e32 v108, v110
	v_pk_mul_f32 v[108:109], v[108:109], s[10:11] op_sel_hi:[1,0]
	s_waitcnt vmcnt(0)
; __device__ __forceinline__ unsigned cvt_pk_bf16(float lo, float hi) { unsigned r; asm volatile("v_cvt_pk_bf16_f32 %0, %1, %2" : "=v"(r) : "v"(lo), "v"(hi)); return r; }
; __device__ __forceinline__ float bf_lo(unsigned w) { return __uint_as_float(w << 16); }
;     __device__ __forceinline__ void operator()(f32x4 (&acc)[2][2][4][2], const Unit& u, int wr, int wc, int fr, int fq) const {
;     ...
;                 for (int m = 0; m < 4; ++m)
; #pragma unroll
;                     for (int bj = 0; bj < 2; ++bj) { const u32x4 gq = gw[ai][m]; u32x2 g; g.x = bj ? gq.z : gq.x; g.y = bj ? gq.w : gq.y; const u32x4 o = ow[m][bj]; f32x4& a0 = acc[ai][bj][m][0]; f32x4& a1 = acc[ai][bj][m][1];
;                         a0[0] = a0[0] * (ub(g.x, 0) * q) + bf_lo(o.x); a0[1] = a0[1] * (ub(g.x, 1) * q) + bf_hi(o.x); a0[2] = a0[2] * (ub(g.x, 2) * q) + bf_lo(o.y); a0[3] = a0[3] * (ub(g.x, 3) * q) + bf_hi(o.y);
;                         a1[0] = a1[0] * (ub(g.y, 0) * q) + bf_lo(o.z); a1[1] = a1[1] * (ub(g.y, 1) * q) + bf_hi(o.z); a1[2] = a1[2] * (ub(g.y, 2) * q) + bf_lo(o.w); a1[3] = a1[3] * (ub(g.y, 3) * q) + bf_hi(o.w);
;                         asm volatile("" : "+v"(a0), "+v"(a1)); }
;                 dep = acc[ai][1][3][1][3]; }
;         } else {
; #pragma unroll
;             for (int ai = 0; ai < 2; ++ai)
; #pragma unroll
;                 for (int m = 0; m < 4; ++m)
; #pragma unroll
;                     for (int bj = 0; bj < 2; ++bj) { const u32x4 gq = gw[ai][m]; u32x2 g; g.x = bj ? gq.z : gq.x; g.y = bj ? gq.w : gq.y; f32x4& a0 = acc[ai][bj][m][0]; f32x4& a1 = acc[ai][bj][m][1];
;                         a0[0] *= ub(g.x, 0) * q; a0[1] *= ub(g.x, 1) * q; a0[2] *= ub(g.x, 2) * q; a0[3] *= ub(g.x, 3) * q; a1[0] *= ub(g.y, 0) * q; a1[1] *= ub(g.y, 1) * q; a1[2] *= ub(g.y, 2) * q; a1[3] *= ub(g.y, 3) * q;
;                         asm volatile("" : "+v"(a0), "+v"(a1)); }
;         }
; #pragma unroll
;         for (int ai = 0; ai < 2; ++ai)
; #pragma unroll
;             for (int m = 0; m < 4; ++m)
; #pragma unroll
;                 for (int bj = 0; bj < 2; ++bj) { const f32x4 a0 = acc[ai][bj][m][0], a1 = acc[ai][bj][m][1];
;                     u32x4 w; w.x = cvt_pk_bf16(a0[0], a0[1]); w.y = cvt_pk_bf16(a0[2], a0[3]); w.z = cvt_pk_bf16(a1[0], a1[1]); w.w = cvt_pk_bf16(a1[2], a1[3]);
;                     *(u32x4*)mg_at(u, ai, m, bj, wr, wc, fr, fq) = w; }
	v_lshlrev_b32_e32 v132, 16, v144
	v_and_b32_e32 v133, 0xffff0000, v144
	v_pk_fma_f32 v[4:5], v[4:5], v[108:109], v[132:133]
	v_cvt_f32_ubyte3_e32 v109, v110
	v_cvt_f32_ubyte2_e32 v108, v110
	v_pk_mul_f32 v[108:109], v[108:109], s[10:11] op_sel_hi:[1,0]
	v_lshlrev_b32_e32 v132, 16, v145
	v_and_b32_e32 v133, 0xffff0000, v145
	v_pk_fma_f32 v[6:7], v[6:7], v[108:109], v[132:133]
	v_cvt_f32_ubyte1_e32 v109, v111
	v_cvt_f32_ubyte0_e32 v108, v111
	v_pk_mul_f32 v[108:109], v[108:109], s[10:11] op_sel_hi:[1,0]
	v_lshlrev_b32_e32 v132, 16, v146
	v_and_b32_e32 v133, 0xffff0000, v146
	v_pk_fma_f32 v[0:1], v[0:1], v[108:109], v[132:133]
	v_cvt_f32_ubyte3_e32 v109, v111
	v_cvt_f32_ubyte2_e32 v108, v111
	v_pk_mul_f32 v[108:109], v[108:109], s[10:11] op_sel_hi:[1,0]
	v_lshlrev_b32_e32 v110, 16, v147
	v_and_b32_e32 v111, 0xffff0000, v147
	v_pk_fma_f32 v[2:3], v[2:3], v[108:109], v[110:111]
	s_nop 0
	v_cvt_pk_bf16_f32 v108, v128, v129
	v_cvt_pk_bf16_f32 v109, v130, v131
	v_cvt_pk_bf16_f32 v110, v124, v125
	v_lshl_add_u64 v[124:125], s[64:65], 0, v[176:177]
	v_cvt_pk_bf16_f32 v111, v126, v127
	global_store_dwordx4 v[124:125], v[108:111], off sc1
	s_nop 1
	v_cvt_pk_bf16_f32 v108, v120, v121
	v_cvt_pk_bf16_f32 v109, v122, v123
	v_cvt_pk_bf16_f32 v110, v116, v117
	v_lshl_add_u64 v[116:117], s[62:63], 0, v[176:177]
	v_cvt_pk_bf16_f32 v111, v118, v119
	global_store_dwordx4 v[116:117], v[108:111], off sc1
	s_nop 1
	v_cvt_pk_bf16_f32 v108, v112, v113
	v_cvt_pk_bf16_f32 v109, v114, v115
	v_cvt_pk_bf16_f32 v110, v104, v105
	v_lshl_add_u64 v[104:105], s[64:65], 0, v[178:179]
	v_cvt_pk_bf16_f32 v111, v106, v107
	global_store_dwordx4 v[104:105], v[108:111], off sc1
	v_cvt_pk_bf16_f32 v100, v100, v101
	v_cvt_pk_bf16_f32 v101, v102, v103
	v_cvt_pk_bf16_f32 v102, v96, v97
	v_lshl_add_u64 v[96:97], s[62:63], 0, v[178:179]
	v_cvt_pk_bf16_f32 v103, v98, v99
	global_store_dwordx4 v[96:97], v[100:103], off sc1
	v_cvt_pk_bf16_f32 v92, v92, v93
	v_cvt_pk_bf16_f32 v93, v94, v95
	v_cvt_pk_bf16_f32 v94, v88, v89
	v_lshl_add_u64 v[88:89], s[64:65], 0, v[180:181]
	v_cvt_pk_bf16_f32 v95, v90, v91
	global_store_dwordx4 v[88:89], v[92:95], off sc1
	v_cvt_pk_bf16_f32 v84, v84, v85
	v_cvt_pk_bf16_f32 v85, v86, v87
	v_cvt_pk_bf16_f32 v86, v80, v81
	v_lshl_add_u64 v[80:81], s[62:63], 0, v[180:181]
	v_cvt_pk_bf16_f32 v87, v82, v83
	global_store_dwordx4 v[80:81], v[84:87], off sc1
	v_cvt_pk_bf16_f32 v76, v76, v77
	v_cvt_pk_bf16_f32 v77, v78, v79
	v_cvt_pk_bf16_f32 v78, v72, v73
	v_lshl_add_u64 v[72:73], s[64:65], 0, v[182:183]
	v_cvt_pk_bf16_f32 v79, v74, v75
	global_store_dwordx4 v[72:73], v[76:79], off sc1
	v_cvt_pk_bf16_f32 v68, v68, v69
	v_cvt_pk_bf16_f32 v69, v70, v71
	v_cvt_pk_bf16_f32 v70, v64, v65
	v_lshl_add_u64 v[64:65], s[62:63], 0, v[182:183]
	s_add_u32 s62, s6, s68
	s_addc_u32 s63, s7, s69
	s_add_u32 s64, s6, s66
	v_cvt_pk_bf16_f32 v71, v66, v67
	global_store_dwordx4 v[64:65], v[68:71], off sc1
	v_cvt_pk_bf16_f32 v60, v60, v61
	v_cvt_pk_bf16_f32 v61, v62, v63
	v_cvt_pk_bf16_f32 v62, v56, v57
	v_lshl_add_u64 v[56:57], s[62:63], 0, v[176:177]
	s_addc_u32 s65, s7, s67
	v_cvt_pk_bf16_f32 v63, v58, v59
	global_store_dwordx4 v[56:57], v[60:63], off sc1
	v_cvt_pk_bf16_f32 v52, v52, v53
	v_cvt_pk_bf16_f32 v53, v54, v55
	v_cvt_pk_bf16_f32 v54, v48, v49
	v_lshl_add_u64 v[48:49], s[64:65], 0, v[176:177]
	v_cvt_pk_bf16_f32 v55, v50, v51
	global_store_dwordx4 v[48:49], v[52:55], off sc1
	v_cvt_pk_bf16_f32 v44, v44, v45
	v_cvt_pk_bf16_f32 v45, v46, v47
	v_cvt_pk_bf16_f32 v46, v40, v41
	v_lshl_add_u64 v[40:41], s[62:63], 0, v[178:179]
	v_cvt_pk_bf16_f32 v47, v42, v43
	global_store_dwordx4 v[40:41], v[44:47], off sc1
	v_cvt_pk_bf16_f32 v36, v36, v37
	v_cvt_pk_bf16_f32 v37, v38, v39
	v_cvt_pk_bf16_f32 v38, v32, v33
	v_lshl_add_u64 v[32:33], s[64:65], 0, v[178:179]
	v_cvt_pk_bf16_f32 v39, v34, v35
	global_store_dwordx4 v[32:33], v[36:39], off sc1
	v_cvt_pk_bf16_f32 v28, v28, v29
	v_cvt_pk_bf16_f32 v29, v30, v31
	v_cvt_pk_bf16_f32 v30, v24, v25
	v_lshl_add_u64 v[24:25], s[62:63], 0, v[180:181]
	v_cvt_pk_bf16_f32 v31, v26, v27
	global_store_dwordx4 v[24:25], v[28:31], off sc1
	v_cvt_pk_bf16_f32 v20, v20, v21
	v_cvt_pk_bf16_f32 v21, v22, v23
	v_cvt_pk_bf16_f32 v22, v16, v17
	v_lshl_add_u64 v[16:17], s[64:65], 0, v[180:181]
	v_cvt_pk_bf16_f32 v23, v18, v19
	global_store_dwordx4 v[16:17], v[20:23], off sc1
	v_cvt_pk_bf16_f32 v12, v12, v13
	v_cvt_pk_bf16_f32 v13, v14, v15
	v_cvt_pk_bf16_f32 v14, v8, v9
	v_lshl_add_u64 v[8:9], s[62:63], 0, v[182:183]
	v_cvt_pk_bf16_f32 v15, v10, v11
	global_store_dwordx4 v[8:9], v[12:15], off sc1
	v_cvt_pk_bf16_f32 v4, v4, v5
	v_cvt_pk_bf16_f32 v5, v6, v7
	v_cvt_pk_bf16_f32 v6, v0, v1
	v_lshl_add_u64 v[0:1], s[64:65], 0, v[182:183]
	s_andn2_b64 vcc, exec, s[2:3]
	s_mov_b64 s[2:3], -1
	v_cvt_pk_bf16_f32 v7, v2, v3
	global_store_dwordx4 v[0:1], v[4:7], off sc1
	s_cbranch_vccnz .LBB0_662
	s_andn2_b64 vcc, exec, s[48:49]
	s_cbranch_vccnz .LBB0_661
	s_barrier
	s_branch .LBB0_661

; __device__ __forceinline__ unsigned cvt_pk_bf16(float lo, float hi) { unsigned r; asm volatile("v_cvt_pk_bf16_f32 %0, %1, %2" : "=v"(r) : "v"(lo), "v"(hi)); return r; }
; __device__ __forceinline__ float bf_lo(unsigned w) { return __uint_as_float(w << 16); }
; __device__ __forceinline__ float bf_hi(unsigned w) { return __uint_as_float(w & 0xffff0000u); }
;     __device__ __forceinline__ void operator()(f32x4 (&acc)[2][2][4][2], const Unit& u, int wr, int wc, int fr, int fq) const {
;     ...
;                 for (int bj = 0; bj < 2; ++bj) pre[ai][m][bj] = *(const u32x4*)hb_at(u, ai, m, bj, wr, wc, fr, fq);
; #pragma unroll
;         for (int ai = 0; ai < 2; ++ai)
; #pragma unroll
;             for (int m = 0; m < 4; ++m) { const int row = row0 + ai * HALF + m * 16; float s = 0.f;
; #pragma unroll
;                 for (int bj = 0; bj < 2; ++bj) { const size_t o2 = (size_t)row * 1024 + col0 + bj * HALF; const u32x4 p = pre[ai][m][bj]; const f32x4 a0 = acc[ai][bj][m][0], a1 = acc[ai][bj][m][1];
;                     f32x4 o0, o1; o0[0] = bf_lo(p.x) + a0[0] * alpha; o0[1] = bf_hi(p.x) + a0[1] * alpha; o0[2] = bf_lo(p.y) + a0[2] * alpha; o0[3] = bf_hi(p.y) + a0[3] * alpha;
;                     o1[0] = bf_lo(p.z) + a1[0] * alpha; o1[1] = bf_hi(p.z) + a1[1] * alpha; o1[2] = bf_lo(p.w) + a1[2] * alpha; o1[3] = bf_hi(p.w) + a1[3] * alpha;
;                     s += ((o0[0] * o0[0] + o0[1] * o0[1]) + (o0[2] * o0[2] + o0[3] * o0[3])) + ((o1[0] * o1[0] + o1[1] * o1[1]) + (o1[2] * o1[2] + o1[3] * o1[3]));
;                     u32x4 w; w.x = cvt_pk_bf16(o0[0], o0[1]); w.y = cvt_pk_bf16(o0[2], o0[3]); w.z = cvt_pk_bf16(o1[0], o1[1]); w.w = cvt_pk_bf16(o1[2], o1[3]);
;                     *(u32x4*)hb_at(u, ai, m, bj, wr, wc, fr, fq) = w;
;                     if (out) { *(f32x4*)(out + o2) = o0; *(f32x4*)(out + o2 + 4) = o1; } }
;                 s += __shfl_xor(s, 16); s += __shfl_xor(s, 32);
;                 if (ssq && fq == 0) atomicAdd(ssq + row, s); }
.LBB0_754:
	s_lshl_b32 s57, s66, 3
	s_lshl_b32 s59, s64, 5
	s_add_i32 s59, s59, s57
	s_or_b32 s66, s59, s77
	s_ashr_i32 s67, s66, 31
	s_lshl_b64 s[68:69], s[66:67], 14
	s_or_b32 s70, s66, 4
	v_lshl_add_u64 v[128:129], v[198:199], 0, s[68:69]
	s_ashr_i32 s71, s70, 31
	global_load_dwordx4 v[220:223], v[128:129], off
	s_lshl_b64 s[70:71], s[70:71], 14
	v_lshl_add_u64 v[128:129], v[198:199], 0, s[70:71]
	global_load_dwordx4 v[224:227], v[128:129], off
	v_lshl_add_u32 v208, s64, 8, v210
	s_or_b32 s64, s66, 1
	s_or_b32 s72, s66, 5
	s_ashr_i32 s65, s64, 31
	s_ashr_i32 s73, s72, 31
	s_lshl_b64 s[66:67], s[64:65], 14
	s_lshl_b64 s[64:65], s[72:73], 14
	v_lshl_add_u64 v[128:129], v[200:201], 0, s[68:69]
	v_lshl_add_u64 v[130:131], v[202:203], 0, s[68:69]
	v_lshl_add_u64 v[132:133], v[196:197], 0, s[68:69]
	v_lshl_add_u64 v[134:135], v[200:201], 0, s[70:71]
	v_lshl_add_u64 v[136:137], v[202:203], 0, s[70:71]
	v_lshl_add_u64 v[138:139], v[196:197], 0, s[70:71]
	v_lshl_add_u64 v[140:141], v[198:199], 0, s[66:67]
	v_lshl_add_u64 v[142:143], v[198:199], 0, s[64:65]
	v_lshl_add_u64 v[144:145], v[200:201], 0, s[66:67]
	v_lshl_add_u64 v[146:147], v[200:201], 0, s[64:65]
	v_lshl_add_u64 v[228:229], v[202:203], 0, s[66:67]
	v_lshl_add_u64 v[230:231], v[202:203], 0, s[64:65]
	v_lshl_add_u64 v[232:233], v[196:197], 0, s[66:67]
	v_lshl_add_u64 v[234:235], v[196:197], 0, s[64:65]
	global_load_dwordx4 v[180:183], v[128:129], off
	global_load_dwordx4 v[176:179], v[134:135], off
	global_load_dwordx4 v[172:175], v[130:131], off
	global_load_dwordx4 v[168:171], v[136:137], off
	global_load_dwordx4 v[164:167], v[132:133], off
	global_load_dwordx4 v[160:163], v[138:139], off
	global_load_dwordx4 v[156:159], v[140:141], off
	global_load_dwordx4 v[152:155], v[142:143], off
	global_load_dwordx4 v[148:151], v[144:145], off
	s_nop 0
	global_load_dwordx4 v[144:147], v[146:147], off
	s_nop 0
	global_load_dwordx4 v[140:143], v[228:229], off
	global_load_dwordx4 v[136:139], v[230:231], off
	global_load_dwordx4 v[132:135], v[232:233], off
	global_load_dwordx4 v[128:131], v[234:235], off
	s_add_u32 s68, s12, s68
	s_addc_u32 s69, s13, s69
	v_lshl_add_u64 v[228:229], s[68:69], 0, v[186:187]
	s_add_u32 s70, s12, s70
	s_addc_u32 s71, s13, s71
	s_waitcnt vmcnt(0)
	v_lshlrev_b32_e32 v209, 16, v220
	v_and_b32_e32 v217, 0xffff0000, v220
	v_lshlrev_b32_e32 v219, 16, v221
	v_and_b32_e32 v220, 0xffff0000, v221
	v_lshlrev_b32_e32 v221, 16, v222
	v_and_b32_e32 v222, 0xffff0000, v222
	v_lshlrev_b32_e32 v230, 16, v223
	v_and_b32_e32 v223, 0xffff0000, v223
	v_add_f32_e32 v125, v125, v217
	v_add_f32_e32 v127, v127, v220
	v_add_f32_e32 v217, v121, v222
	v_add_f32_e32 v123, v123, v223
	v_add_f32_e32 v124, v124, v209
	v_add_f32_e32 v126, v126, v219
	v_add_f32_e32 v209, v120, v221
	v_add_f32_e32 v219, v122, v230
	v_lshlrev_b32_e32 v222, 16, v225
	v_and_b32_e32 v223, 0xffff0000, v225
	v_mul_f32_e32 v225, v125, v125
	v_mul_f32_e32 v230, v127, v127
	v_mul_f32_e32 v231, v217, v217
	v_mul_f32_e32 v232, v123, v123
	v_cvt_pk_bf16_f32 v120, v124, v125
	v_cvt_pk_bf16_f32 v121, v126, v127
	v_fmac_f32_e32 v225, v124, v124
	v_fmac_f32_e32 v230, v126, v126
	v_fmac_f32_e32 v231, v209, v209
	v_fmac_f32_e32 v232, v219, v219
	v_lshlrev_b32_e32 v220, 16, v224
	v_and_b32_e32 v221, 0xffff0000, v224
	v_lshlrev_b32_e32 v224, 16, v226
	v_cvt_pk_bf16_f32 v122, v209, v217
	v_cvt_pk_bf16_f32 v123, v219, v123
	global_store_dwordx4 v[228:229], v[120:123], off sc1
	v_add_f32_e32 v117, v117, v221
	v_add_f32_e32 v119, v119, v223
	v_add_f32_e32 v120, v225, v230
	v_add_f32_e32 v121, v231, v232
	v_add_f32_e32 v120, v120, v121
	v_add_f32_e32 v121, v112, v224
	v_and_b32_e32 v112, 0xffff0000, v226
	v_add_f32_e32 v113, v113, v112
	v_lshlrev_b32_e32 v112, 16, v227
	v_add_f32_e32 v114, v114, v112
	v_and_b32_e32 v112, 0xffff0000, v227
	v_add_f32_e32 v116, v116, v220
	v_add_f32_e32 v118, v118, v222
	v_add_f32_e32 v115, v115, v112
	v_mul_f32_e32 v112, v117, v117
	v_mul_f32_e32 v122, v119, v119
	v_fmac_f32_e32 v112, v116, v116
	v_fmac_f32_e32 v122, v118, v118
	v_add_f32_e32 v112, v112, v122
	v_mul_f32_e32 v122, v113, v113
	v_mul_f32_e32 v123, v115, v115
	v_fmac_f32_e32 v122, v121, v121
	v_fmac_f32_e32 v123, v114, v114
	v_add_f32_e32 v122, v122, v123
	v_add_f32_e32 v112, v112, v122
	v_cvt_pk_bf16_f32 v116, v116, v117
	v_and_b32_e32 v117, 64, v216
	v_add_f32_e32 v120, v120, v112
	v_xor_b32_e32 v112, 16, v216
	v_add_u32_e32 v122, 64, v117
	v_cmp_lt_i32_e32 vcc, v112, v122
	v_cvt_pk_bf16_f32 v117, v118, v119
	v_cvt_pk_bf16_f32 v118, v121, v113
	v_xor_b32_e32 v113, 32, v216
	v_cvt_pk_bf16_f32 v119, v114, v115
	v_ashrrev_i32_e32 v209, 31, v208
	v_cndmask_b32_e32 v112, v216, v112, vcc
	v_lshlrev_b32_e32 v112, 2, v112
	ds_bpermute_b32 v123, v112, v120
	v_cmp_lt_i32_e32 vcc, v113, v122
	s_waitcnt lgkmcnt(0)
	v_add_f32_e32 v114, v120, v123
	v_cndmask_b32_e32 v113, v216, v113, vcc
	v_lshlrev_b32_e32 v113, 2, v113
	ds_bpermute_b32 v115, v113, v114
	v_lshl_add_u64 v[120:121], s[70:71], 0, v[186:187]
	global_store_dwordx4 v[120:121], v[116:119], off sc1
	s_and_saveexec_b64 s[72:73], s[2:3]
	s_cbranch_execz .LBB0_756
	v_lshl_add_u64 v[116:117], v[208:209], 2, s[0:1]
	s_waitcnt lgkmcnt(0)
	v_add_f32_e32 v114, v114, v115
	global_atomic_add_f32 v[116:117], v114, off
; __device__ __forceinline__ unsigned cvt_pk_bf16(float lo, float hi) { unsigned r; asm volatile("v_cvt_pk_bf16_f32 %0, %1, %2" : "=v"(r) : "v"(lo), "v"(hi)); return r; }
; __device__ __forceinline__ float bf_lo(unsigned w) { return __uint_as_float(w << 16); }
; __device__ __forceinline__ float bf_hi(unsigned w) { return __uint_as_float(w & 0xffff0000u); }
;     __device__ __forceinline__ void operator()(f32x4 (&acc)[2][2][4][2], const Unit& u, int wr, int wc, int fr, int fq) const {
;     ...
;             for (int m = 0; m < 4; ++m) { const int row = row0 + ai * HALF + m * 16; float s = 0.f;
; #pragma unroll
;                 for (int bj = 0; bj < 2; ++bj) { const size_t o2 = (size_t)row * 1024 + col0 + bj * HALF; const u32x4 p = pre[ai][m][bj]; const f32x4 a0 = acc[ai][bj][m][0], a1 = acc[ai][bj][m][1];
;                     f32x4 o0, o1; o0[0] = bf_lo(p.x) + a0[0] * alpha; o0[1] = bf_hi(p.x) + a0[1] * alpha; o0[2] = bf_lo(p.y) + a0[2] * alpha; o0[3] = bf_hi(p.y) + a0[3] * alpha;
;                     o1[0] = bf_lo(p.z) + a1[0] * alpha; o1[1] = bf_hi(p.z) + a1[1] * alpha; o1[2] = bf_lo(p.w) + a1[2] * alpha; o1[3] = bf_hi(p.w) + a1[3] * alpha;
;                     s += ((o0[0] * o0[0] + o0[1] * o0[1]) + (o0[2] * o0[2] + o0[3] * o0[3])) + ((o1[0] * o1[0] + o1[1] * o1[1]) + (o1[2] * o1[2] + o1[3] * o1[3]));
;                     u32x4 w; w.x = cvt_pk_bf16(o0[0], o0[1]); w.y = cvt_pk_bf16(o0[2], o0[3]); w.z = cvt_pk_bf16(o1[0], o1[1]); w.w = cvt_pk_bf16(o1[2], o1[3]);
;                     *(u32x4*)hb_at(u, ai, m, bj, wr, wc, fr, fq) = w;
;                     if (out) { *(f32x4*)(out + o2) = o0; *(f32x4*)(out + o2 + 4) = o1; } }
;                 s += __shfl_xor(s, 16); s += __shfl_xor(s, 32);
;                 if (ssq && fq == 0) atomicAdd(ssq + row, s); }
.LBB0_756:
	s_or_b64 exec, exec, s[72:73]
	v_lshlrev_b32_e32 v114, 16, v180
	v_add_f32_e32 v108, v108, v114
	v_and_b32_e32 v114, 0xffff0000, v180
	v_add_f32_e32 v109, v109, v114
	v_lshlrev_b32_e32 v114, 16, v181
	v_add_f32_e32 v110, v110, v114
	v_and_b32_e32 v114, 0xffff0000, v181
	v_add_f32_e32 v111, v111, v114
	v_lshlrev_b32_e32 v114, 16, v182
	v_add_f32_e32 v114, v104, v114
	v_and_b32_e32 v104, 0xffff0000, v182
	s_waitcnt lgkmcnt(0)
	v_add_f32_e32 v115, v105, v104
	v_lshlrev_b32_e32 v104, 16, v183
	v_add_f32_e32 v116, v106, v104
	v_and_b32_e32 v104, 0xffff0000, v183
	v_add_f32_e32 v107, v107, v104
	v_mul_f32_e32 v104, v109, v109
	v_mul_f32_e32 v105, v111, v111
	v_fmac_f32_e32 v104, v108, v108
	v_fmac_f32_e32 v105, v110, v110
	v_add_f32_e32 v104, v104, v105
	v_mul_f32_e32 v105, v115, v115
	v_mul_f32_e32 v106, v107, v107
	v_fmac_f32_e32 v105, v114, v114
	v_fmac_f32_e32 v106, v116, v116
	v_add_f32_e32 v105, v105, v106
	v_add_f32_e32 v117, v104, v105
	v_cvt_pk_bf16_f32 v104, v108, v109
	v_lshlrev_b32_e32 v108, 16, v176
	v_add_f32_e32 v100, v100, v108
	v_and_b32_e32 v108, 0xffff0000, v176
	v_add_f32_e32 v101, v101, v108
	v_lshlrev_b32_e32 v108, 16, v177
	v_add_f32_e32 v102, v102, v108
	v_and_b32_e32 v108, 0xffff0000, v177
	v_add_f32_e32 v103, v103, v108
	v_lshlrev_b32_e32 v108, 16, v178
	v_add_f32_e32 v108, v96, v108
	v_and_b32_e32 v96, 0xffff0000, v178
	v_add_f32_e32 v109, v97, v96
	v_lshlrev_b32_e32 v96, 16, v179
	v_cvt_pk_bf16_f32 v105, v110, v111
	v_add_f32_e32 v110, v98, v96
	v_and_b32_e32 v96, 0xffff0000, v179
	v_add_f32_e32 v111, v99, v96
	v_mul_f32_e32 v96, v101, v101
	v_mul_f32_e32 v97, v103, v103
	v_fmac_f32_e32 v96, v100, v100
	v_fmac_f32_e32 v97, v102, v102
	v_add_f32_e32 v96, v96, v97
	v_mul_f32_e32 v97, v109, v109
	v_mul_f32_e32 v98, v111, v111
	v_fmac_f32_e32 v97, v108, v108
	v_fmac_f32_e32 v98, v110, v110
	v_add_f32_e32 v97, v97, v98
	v_add_f32_e32 v96, v96, v97
	v_cvt_pk_bf16_f32 v106, v114, v115
	v_add_f32_e32 v114, v117, v96
	ds_bpermute_b32 v115, v112, v114
	v_lshl_add_u64 v[96:97], s[68:69], 0, v[192:193]
	v_cvt_pk_bf16_f32 v107, v116, v107
	global_store_dwordx4 v[96:97], v[104:107], off sc1
	v_cvt_pk_bf16_f32 v98, v100, v101
	s_waitcnt lgkmcnt(0)
	v_add_f32_e32 v96, v114, v115
	ds_bpermute_b32 v97, v113, v96
	v_cvt_pk_bf16_f32 v99, v102, v103
	v_lshl_add_u64 v[102:103], s[70:71], 0, v[192:193]
	v_cvt_pk_bf16_f32 v100, v108, v109
	v_cvt_pk_bf16_f32 v101, v110, v111
	global_store_dwordx4 v[102:103], v[98:101], off sc1
	s_and_saveexec_b64 s[72:73], s[2:3]
	s_cbranch_execz .LBB0_758
	v_lshl_add_u64 v[98:99], v[208:209], 2, s[0:1]
	s_waitcnt lgkmcnt(0)
	v_add_f32_e32 v96, v96, v97
	global_atomic_add_f32 v[98:99], v96, off offset:64
.LBB0_758:
	s_or_b64 exec, exec, s[72:73]
	v_lshlrev_b32_e32 v96, 16, v172
	v_add_f32_e32 v92, v92, v96
	v_and_b32_e32 v96, 0xffff0000, v172
	v_add_f32_e32 v93, v93, v96
	v_lshlrev_b32_e32 v96, 16, v173
	v_add_f32_e32 v94, v94, v96
	v_and_b32_e32 v96, 0xffff0000, v173
	v_add_f32_e32 v95, v95, v96
	v_lshlrev_b32_e32 v96, 16, v174
	v_add_f32_e32 v96, v88, v96
	v_and_b32_e32 v88, 0xffff0000, v174
	s_waitcnt lgkmcnt(0)
	v_add_f32_e32 v97, v89, v88
	v_lshlrev_b32_e32 v88, 16, v175
	v_add_f32_e32 v98, v90, v88
	v_and_b32_e32 v88, 0xffff0000, v175
	v_add_f32_e32 v91, v91, v88
	v_mul_f32_e32 v88, v93, v93
	v_mul_f32_e32 v89, v95, v95
	v_fmac_f32_e32 v88, v92, v92
	v_fmac_f32_e32 v89, v94, v94
	v_add_f32_e32 v88, v88, v89
	v_mul_f32_e32 v89, v97, v97
	v_mul_f32_e32 v90, v91, v91
	v_fmac_f32_e32 v89, v96, v96
	v_fmac_f32_e32 v90, v98, v98
	v_add_f32_e32 v89, v89, v90
	v_add_f32_e32 v99, v88, v89
	v_cvt_pk_bf16_f32 v88, v92, v93
	v_lshlrev_b32_e32 v92, 16, v168
	v_add_f32_e32 v84, v84, v92
	v_and_b32_e32 v92, 0xffff0000, v168
	v_add_f32_e32 v85, v85, v92
	v_lshlrev_b32_e32 v92, 16, v169
	v_add_f32_e32 v86, v86, v92
	v_and_b32_e32 v92, 0xffff0000, v169
	v_add_f32_e32 v87, v87, v92
	v_lshlrev_b32_e32 v92, 16, v170
	v_add_f32_e32 v92, v80, v92
	v_and_b32_e32 v80, 0xffff0000, v170
	v_add_f32_e32 v93, v81, v80
	v_lshlrev_b32_e32 v80, 16, v171
	v_cvt_pk_bf16_f32 v89, v94, v95
	v_add_f32_e32 v94, v82, v80
	v_and_b32_e32 v80, 0xffff0000, v171
	v_add_f32_e32 v95, v83, v80
	v_mul_f32_e32 v80, v85, v85
	v_mul_f32_e32 v81, v87, v87
	v_fmac_f32_e32 v80, v84, v84
	v_fmac_f32_e32 v81, v86, v86
	v_add_f32_e32 v80, v80, v81
	v_mul_f32_e32 v81, v93, v93
	v_mul_f32_e32 v82, v95, v95
	v_fmac_f32_e32 v81, v92, v92
	v_fmac_f32_e32 v82, v94, v94
	v_add_f32_e32 v81, v81, v82
	v_add_f32_e32 v80, v80, v81
	v_cvt_pk_bf16_f32 v90, v96, v97
	v_add_f32_e32 v96, v99, v80
	ds_bpermute_b32 v97, v112, v96
	v_lshl_add_u64 v[80:81], s[68:69], 0, v[194:195]
	v_cvt_pk_bf16_f32 v91, v98, v91
	global_store_dwordx4 v[80:81], v[88:91], off sc1
	v_cvt_pk_bf16_f32 v82, v84, v85
	s_waitcnt lgkmcnt(0)
	v_add_f32_e32 v80, v96, v97
	ds_bpermute_b32 v81, v113, v80
	v_cvt_pk_bf16_f32 v83, v86, v87
	v_lshl_add_u64 v[86:87], s[70:71], 0, v[194:195]
	v_cvt_pk_bf16_f32 v84, v92, v93
	v_cvt_pk_bf16_f32 v85, v94, v95
	global_store_dwordx4 v[86:87], v[82:85], off sc1
	s_and_saveexec_b64 s[72:73], s[2:3]
	s_cbranch_execz .LBB0_760
	v_lshl_add_u64 v[82:83], v[208:209], 2, s[0:1]
	s_waitcnt lgkmcnt(0)
	v_add_f32_e32 v80, v80, v81
	global_atomic_add_f32 v[82:83], v80, off offset:128
; __device__ __forceinline__ unsigned cvt_pk_bf16(float lo, float hi) { unsigned r; asm volatile("v_cvt_pk_bf16_f32 %0, %1, %2" : "=v"(r) : "v"(lo), "v"(hi)); return r; }
; __device__ __forceinline__ float bf_lo(unsigned w) { return __uint_as_float(w << 16); }
; __device__ __forceinline__ float bf_hi(unsigned w) { return __uint_as_float(w & 0xffff0000u); }
;     __device__ __forceinline__ void operator()(f32x4 (&acc)[2][2][4][2], const Unit& u, int wr, int wc, int fr, int fq) const {
;     ...
;             for (int m = 0; m < 4; ++m) { const int row = row0 + ai * HALF + m * 16; float s = 0.f;
; #pragma unroll
;                 for (int bj = 0; bj < 2; ++bj) { const size_t o2 = (size_t)row * 1024 + col0 + bj * HALF; const u32x4 p = pre[ai][m][bj]; const f32x4 a0 = acc[ai][bj][m][0], a1 = acc[ai][bj][m][1];
;                     f32x4 o0, o1; o0[0] = bf_lo(p.x) + a0[0] * alpha; o0[1] = bf_hi(p.x) + a0[1] * alpha; o0[2] = bf_lo(p.y) + a0[2] * alpha; o0[3] = bf_hi(p.y) + a0[3] * alpha;
;                     o1[0] = bf_lo(p.z) + a1[0] * alpha; o1[1] = bf_hi(p.z) + a1[1] * alpha; o1[2] = bf_lo(p.w) + a1[2] * alpha; o1[3] = bf_hi(p.w) + a1[3] * alpha;
;                     s += ((o0[0] * o0[0] + o0[1] * o0[1]) + (o0[2] * o0[2] + o0[3] * o0[3])) + ((o1[0] * o1[0] + o1[1] * o1[1]) + (o1[2] * o1[2] + o1[3] * o1[3]));
;                     u32x4 w; w.x = cvt_pk_bf16(o0[0], o0[1]); w.y = cvt_pk_bf16(o0[2], o0[3]); w.z = cvt_pk_bf16(o1[0], o1[1]); w.w = cvt_pk_bf16(o1[2], o1[3]);
;                     *(u32x4*)hb_at(u, ai, m, bj, wr, wc, fr, fq) = w;
;                     if (out) { *(f32x4*)(out + o2) = o0; *(f32x4*)(out + o2 + 4) = o1; } }
;                 s += __shfl_xor(s, 16); s += __shfl_xor(s, 32);
;                 if (ssq && fq == 0) atomicAdd(ssq + row, s); }
.LBB0_760:
	s_or_b64 exec, exec, s[72:73]
	v_lshlrev_b32_e32 v80, 16, v164
	v_add_f32_e32 v76, v76, v80
	v_and_b32_e32 v80, 0xffff0000, v164
	v_add_f32_e32 v77, v77, v80
	v_lshlrev_b32_e32 v80, 16, v165
	v_add_f32_e32 v78, v78, v80
	v_and_b32_e32 v80, 0xffff0000, v165
	v_add_f32_e32 v79, v79, v80
	v_lshlrev_b32_e32 v80, 16, v166
	v_add_f32_e32 v80, v72, v80
	v_and_b32_e32 v72, 0xffff0000, v166
	s_waitcnt lgkmcnt(0)
	v_add_f32_e32 v81, v73, v72
	v_lshlrev_b32_e32 v72, 16, v167
	v_add_f32_e32 v82, v74, v72
	v_and_b32_e32 v72, 0xffff0000, v167
	v_add_f32_e32 v75, v75, v72
	v_mul_f32_e32 v72, v77, v77
	v_mul_f32_e32 v73, v79, v79
	v_fmac_f32_e32 v72, v76, v76
	v_fmac_f32_e32 v73, v78, v78
	v_add_f32_e32 v72, v72, v73
	v_mul_f32_e32 v73, v81, v81
	v_mul_f32_e32 v74, v75, v75
	v_fmac_f32_e32 v73, v80, v80
	v_fmac_f32_e32 v74, v82, v82
	v_add_f32_e32 v73, v73, v74
	v_add_f32_e32 v83, v72, v73
	v_cvt_pk_bf16_f32 v72, v76, v77
	v_lshlrev_b32_e32 v76, 16, v160
	v_add_f32_e32 v68, v68, v76
	v_and_b32_e32 v76, 0xffff0000, v160
	v_add_f32_e32 v69, v69, v76
	v_lshlrev_b32_e32 v76, 16, v161
	v_add_f32_e32 v70, v70, v76
	v_and_b32_e32 v76, 0xffff0000, v161
	v_add_f32_e32 v71, v71, v76
	v_lshlrev_b32_e32 v76, 16, v162
	v_add_f32_e32 v76, v64, v76
	v_and_b32_e32 v64, 0xffff0000, v162
	v_add_f32_e32 v77, v65, v64
	v_lshlrev_b32_e32 v64, 16, v163
	v_cvt_pk_bf16_f32 v73, v78, v79
	v_add_f32_e32 v78, v66, v64
	v_and_b32_e32 v64, 0xffff0000, v163
	v_add_f32_e32 v79, v67, v64
	v_mul_f32_e32 v64, v69, v69
	v_mul_f32_e32 v65, v71, v71
	v_fmac_f32_e32 v64, v68, v68
	v_fmac_f32_e32 v65, v70, v70
	v_add_f32_e32 v64, v64, v65
	v_mul_f32_e32 v65, v77, v77
	v_mul_f32_e32 v66, v79, v79
	v_fmac_f32_e32 v65, v76, v76
	v_fmac_f32_e32 v66, v78, v78
	v_add_f32_e32 v65, v65, v66
	v_add_f32_e32 v64, v64, v65
	v_cvt_pk_bf16_f32 v74, v80, v81
	v_add_f32_e32 v80, v83, v64
	ds_bpermute_b32 v81, v112, v80
	v_lshl_add_u64 v[64:65], s[68:69], 0, v[184:185]
	v_cvt_pk_bf16_f32 v75, v82, v75
	global_store_dwordx4 v[64:65], v[72:75], off sc1
	v_cvt_pk_bf16_f32 v66, v68, v69
	s_waitcnt lgkmcnt(0)
	v_add_f32_e32 v64, v80, v81
	ds_bpermute_b32 v65, v113, v64
	v_cvt_pk_bf16_f32 v67, v70, v71
	v_lshl_add_u64 v[70:71], s[70:71], 0, v[184:185]
	v_cvt_pk_bf16_f32 v68, v76, v77
	v_cvt_pk_bf16_f32 v69, v78, v79
	global_store_dwordx4 v[70:71], v[66:69], off sc1
	s_and_saveexec_b64 s[68:69], s[2:3]
	s_cbranch_execz .LBB0_762
	v_lshl_add_u64 v[66:67], v[208:209], 2, s[0:1]
	s_waitcnt lgkmcnt(0)
	v_add_f32_e32 v64, v64, v65
	global_atomic_add_f32 v[66:67], v64, off offset:192
.LBB0_762:
	s_or_b64 exec, exec, s[68:69]
	v_lshlrev_b32_e32 v64, 16, v156
	v_add_f32_e32 v60, v60, v64
	v_and_b32_e32 v64, 0xffff0000, v156
	v_add_f32_e32 v61, v61, v64
	v_lshlrev_b32_e32 v64, 16, v157
	v_add_f32_e32 v62, v62, v64
	v_and_b32_e32 v64, 0xffff0000, v157
	v_add_f32_e32 v63, v63, v64
	v_lshlrev_b32_e32 v64, 16, v158
	v_add_f32_e32 v64, v56, v64
	v_and_b32_e32 v56, 0xffff0000, v158
	s_waitcnt lgkmcnt(0)
	v_add_f32_e32 v65, v57, v56
	v_lshlrev_b32_e32 v56, 16, v159
	v_add_f32_e32 v66, v58, v56
	v_and_b32_e32 v56, 0xffff0000, v159
	v_add_f32_e32 v59, v59, v56
	v_mul_f32_e32 v56, v61, v61
	v_mul_f32_e32 v57, v63, v63
	v_fmac_f32_e32 v56, v60, v60
	v_fmac_f32_e32 v57, v62, v62
	v_add_f32_e32 v56, v56, v57
	v_mul_f32_e32 v57, v65, v65
	v_mul_f32_e32 v58, v59, v59
	v_fmac_f32_e32 v57, v64, v64
	v_fmac_f32_e32 v58, v66, v66
	s_add_u32 s66, s12, s66
	v_add_f32_e32 v57, v57, v58
	s_addc_u32 s67, s13, s67
	v_add_f32_e32 v67, v56, v57
	v_cvt_pk_bf16_f32 v56, v60, v61
	v_lshl_add_u64 v[60:61], s[66:67], 0, v[186:187]
	v_cvt_pk_bf16_f32 v57, v62, v63
	v_cvt_pk_bf16_f32 v58, v64, v65
	v_cvt_pk_bf16_f32 v59, v66, v59
	global_store_dwordx4 v[60:61], v[56:59], off sc1
	s_add_u32 s64, s12, s64
	s_addc_u32 s65, s13, s65
	v_lshlrev_b32_e32 v56, 16, v152
	v_add_f32_e32 v52, v52, v56
	v_and_b32_e32 v56, 0xffff0000, v152
	v_add_f32_e32 v53, v53, v56
	v_lshlrev_b32_e32 v56, 16, v153
	v_add_f32_e32 v54, v54, v56
	v_and_b32_e32 v56, 0xffff0000, v153
	v_add_f32_e32 v55, v55, v56
	v_lshlrev_b32_e32 v56, 16, v154
	v_add_f32_e32 v48, v48, v56
	v_and_b32_e32 v56, 0xffff0000, v154
	v_add_f32_e32 v49, v49, v56
	v_lshlrev_b32_e32 v56, 16, v155
	v_add_f32_e32 v56, v50, v56
	v_and_b32_e32 v50, 0xffff0000, v155
	v_add_f32_e32 v57, v51, v50
	v_mul_f32_e32 v50, v53, v53
	v_mul_f32_e32 v51, v55, v55
	v_fmac_f32_e32 v50, v52, v52
	v_fmac_f32_e32 v51, v54, v54
	v_add_f32_e32 v50, v50, v51
	v_mul_f32_e32 v51, v49, v49
	v_mul_f32_e32 v58, v57, v57
	v_fmac_f32_e32 v51, v48, v48
	v_fmac_f32_e32 v58, v56, v56
	v_add_f32_e32 v51, v51, v58
	v_add_f32_e32 v50, v50, v51
	v_add_f32_e32 v58, v67, v50
	ds_bpermute_b32 v59, v112, v58
	v_cvt_pk_bf16_f32 v50, v52, v53
	v_cvt_pk_bf16_f32 v51, v54, v55
	v_cvt_pk_bf16_f32 v52, v48, v49
	v_lshl_add_u64 v[54:55], s[64:65], 0, v[186:187]
	s_waitcnt lgkmcnt(0)
	v_add_f32_e32 v48, v58, v59
	ds_bpermute_b32 v49, v113, v48
	v_cvt_pk_bf16_f32 v53, v56, v57
	global_store_dwordx4 v[54:55], v[50:53], off sc1
	s_and_saveexec_b64 s[68:69], s[2:3]
	s_cbranch_execz .LBB0_764
	v_lshl_add_u64 v[50:51], v[208:209], 2, s[0:1]
	s_waitcnt lgkmcnt(0)
	v_add_f32_e32 v48, v48, v49
	global_atomic_add_f32 v[50:51], v48, off offset:512
; __device__ __forceinline__ unsigned cvt_pk_bf16(float lo, float hi) { unsigned r; asm volatile("v_cvt_pk_bf16_f32 %0, %1, %2" : "=v"(r) : "v"(lo), "v"(hi)); return r; }
; __device__ __forceinline__ float bf_lo(unsigned w) { return __uint_as_float(w << 16); }
; __device__ __forceinline__ float bf_hi(unsigned w) { return __uint_as_float(w & 0xffff0000u); }
;     __device__ __forceinline__ void operator()(f32x4 (&acc)[2][2][4][2], const Unit& u, int wr, int wc, int fr, int fq) const {
;     ...
;             for (int m = 0; m < 4; ++m) { const int row = row0 + ai * HALF + m * 16; float s = 0.f;
; #pragma unroll
;                 for (int bj = 0; bj < 2; ++bj) { const size_t o2 = (size_t)row * 1024 + col0 + bj * HALF; const u32x4 p = pre[ai][m][bj]; const f32x4 a0 = acc[ai][bj][m][0], a1 = acc[ai][bj][m][1];
;                     f32x4 o0, o1; o0[0] = bf_lo(p.x) + a0[0] * alpha; o0[1] = bf_hi(p.x) + a0[1] * alpha; o0[2] = bf_lo(p.y) + a0[2] * alpha; o0[3] = bf_hi(p.y) + a0[3] * alpha;
;                     o1[0] = bf_lo(p.z) + a1[0] * alpha; o1[1] = bf_hi(p.z) + a1[1] * alpha; o1[2] = bf_lo(p.w) + a1[2] * alpha; o1[3] = bf_hi(p.w) + a1[3] * alpha;
;                     s += ((o0[0] * o0[0] + o0[1] * o0[1]) + (o0[2] * o0[2] + o0[3] * o0[3])) + ((o1[0] * o1[0] + o1[1] * o1[1]) + (o1[2] * o1[2] + o1[3] * o1[3]));
;                     u32x4 w; w.x = cvt_pk_bf16(o0[0], o0[1]); w.y = cvt_pk_bf16(o0[2], o0[3]); w.z = cvt_pk_bf16(o1[0], o1[1]); w.w = cvt_pk_bf16(o1[2], o1[3]);
;                     *(u32x4*)hb_at(u, ai, m, bj, wr, wc, fr, fq) = w;
;                     if (out) { *(f32x4*)(out + o2) = o0; *(f32x4*)(out + o2 + 4) = o1; } }
;                 s += __shfl_xor(s, 16); s += __shfl_xor(s, 32);
;                 if (ssq && fq == 0) atomicAdd(ssq + row, s); }
.LBB0_764:
	s_or_b64 exec, exec, s[68:69]
	v_lshlrev_b32_e32 v48, 16, v148
	v_add_f32_e32 v44, v44, v48
	v_and_b32_e32 v48, 0xffff0000, v148
	v_add_f32_e32 v45, v45, v48
	v_lshlrev_b32_e32 v48, 16, v149
	v_add_f32_e32 v46, v46, v48
	v_and_b32_e32 v48, 0xffff0000, v149
	v_add_f32_e32 v47, v47, v48
	v_lshlrev_b32_e32 v48, 16, v150
	v_add_f32_e32 v48, v40, v48
	v_and_b32_e32 v40, 0xffff0000, v150
	s_waitcnt lgkmcnt(0)
	v_add_f32_e32 v49, v41, v40
	v_lshlrev_b32_e32 v40, 16, v151
	v_add_f32_e32 v50, v42, v40
	v_and_b32_e32 v40, 0xffff0000, v151
	v_add_f32_e32 v43, v43, v40
	v_mul_f32_e32 v40, v45, v45
	v_mul_f32_e32 v41, v47, v47
	v_fmac_f32_e32 v40, v44, v44
	v_fmac_f32_e32 v41, v46, v46
	v_add_f32_e32 v40, v40, v41
	v_mul_f32_e32 v41, v49, v49
	v_mul_f32_e32 v42, v43, v43
	v_fmac_f32_e32 v41, v48, v48
	v_fmac_f32_e32 v42, v50, v50
	v_add_f32_e32 v41, v41, v42
	v_add_f32_e32 v51, v40, v41
	v_cvt_pk_bf16_f32 v40, v44, v45
	v_lshlrev_b32_e32 v44, 16, v144
	v_add_f32_e32 v36, v36, v44
	v_and_b32_e32 v44, 0xffff0000, v144
	v_add_f32_e32 v37, v37, v44
	v_lshlrev_b32_e32 v44, 16, v145
	v_add_f32_e32 v38, v38, v44
	v_and_b32_e32 v44, 0xffff0000, v145
	v_add_f32_e32 v39, v39, v44
	v_lshlrev_b32_e32 v44, 16, v146
	v_add_f32_e32 v44, v32, v44
	v_and_b32_e32 v32, 0xffff0000, v146
	v_add_f32_e32 v45, v33, v32
	v_lshlrev_b32_e32 v32, 16, v147
	v_cvt_pk_bf16_f32 v41, v46, v47
	v_add_f32_e32 v46, v34, v32
	v_and_b32_e32 v32, 0xffff0000, v147
	v_add_f32_e32 v47, v35, v32
	v_mul_f32_e32 v32, v37, v37
	v_mul_f32_e32 v33, v39, v39
	v_fmac_f32_e32 v32, v36, v36
	v_fmac_f32_e32 v33, v38, v38
	v_add_f32_e32 v32, v32, v33
	v_mul_f32_e32 v33, v45, v45
	v_mul_f32_e32 v34, v47, v47
	v_fmac_f32_e32 v33, v44, v44
	v_fmac_f32_e32 v34, v46, v46
	v_add_f32_e32 v33, v33, v34
	v_add_f32_e32 v32, v32, v33
	v_cvt_pk_bf16_f32 v42, v48, v49
	v_add_f32_e32 v48, v51, v32
	ds_bpermute_b32 v49, v112, v48
	v_lshl_add_u64 v[32:33], s[66:67], 0, v[192:193]
	v_cvt_pk_bf16_f32 v43, v50, v43
	global_store_dwordx4 v[32:33], v[40:43], off sc1
	v_cvt_pk_bf16_f32 v34, v36, v37
	s_waitcnt lgkmcnt(0)
	v_add_f32_e32 v32, v48, v49
	ds_bpermute_b32 v33, v113, v32
	v_cvt_pk_bf16_f32 v35, v38, v39
	v_lshl_add_u64 v[38:39], s[64:65], 0, v[192:193]
	v_cvt_pk_bf16_f32 v36, v44, v45
	v_cvt_pk_bf16_f32 v37, v46, v47
	global_store_dwordx4 v[38:39], v[34:37], off sc1
	s_and_saveexec_b64 s[68:69], s[2:3]
	s_cbranch_execz .LBB0_766
	v_lshl_add_u64 v[34:35], v[208:209], 2, s[0:1]
	s_waitcnt lgkmcnt(0)
	v_add_f32_e32 v32, v32, v33
	global_atomic_add_f32 v[34:35], v32, off offset:576
; __device__ __forceinline__ unsigned cvt_pk_bf16(float lo, float hi) { unsigned r; asm volatile("v_cvt_pk_bf16_f32 %0, %1, %2" : "=v"(r) : "v"(lo), "v"(hi)); return r; }
; __device__ __forceinline__ float bf_lo(unsigned w) { return __uint_as_float(w << 16); }
; __device__ __forceinline__ float bf_hi(unsigned w) { return __uint_as_float(w & 0xffff0000u); }
;     __device__ __forceinline__ void operator()(f32x4 (&acc)[2][2][4][2], const Unit& u, int wr, int wc, int fr, int fq) const {
;     ...
;             for (int m = 0; m < 4; ++m) { const int row = row0 + ai * HALF + m * 16; float s = 0.f;
; #pragma unroll
;                 for (int bj = 0; bj < 2; ++bj) { const size_t o2 = (size_t)row * 1024 + col0 + bj * HALF; const u32x4 p = pre[ai][m][bj]; const f32x4 a0 = acc[ai][bj][m][0], a1 = acc[ai][bj][m][1];
;                     f32x4 o0, o1; o0[0] = bf_lo(p.x) + a0[0] * alpha; o0[1] = bf_hi(p.x) + a0[1] * alpha; o0[2] = bf_lo(p.y) + a0[2] * alpha; o0[3] = bf_hi(p.y) + a0[3] * alpha;
;                     o1[0] = bf_lo(p.z) + a1[0] * alpha; o1[1] = bf_hi(p.z) + a1[1] * alpha; o1[2] = bf_lo(p.w) + a1[2] * alpha; o1[3] = bf_hi(p.w) + a1[3] * alpha;
;                     s += ((o0[0] * o0[0] + o0[1] * o0[1]) + (o0[2] * o0[2] + o0[3] * o0[3])) + ((o1[0] * o1[0] + o1[1] * o1[1]) + (o1[2] * o1[2] + o1[3] * o1[3]));
;                     u32x4 w; w.x = cvt_pk_bf16(o0[0], o0[1]); w.y = cvt_pk_bf16(o0[2], o0[3]); w.z = cvt_pk_bf16(o1[0], o1[1]); w.w = cvt_pk_bf16(o1[2], o1[3]);
;                     *(u32x4*)hb_at(u, ai, m, bj, wr, wc, fr, fq) = w;
;                     if (out) { *(f32x4*)(out + o2) = o0; *(f32x4*)(out + o2 + 4) = o1; } }
;                 s += __shfl_xor(s, 16); s += __shfl_xor(s, 32);
;                 if (ssq && fq == 0) atomicAdd(ssq + row, s); }
.LBB0_766:
	s_or_b64 exec, exec, s[68:69]
	v_lshlrev_b32_e32 v32, 16, v140
	v_add_f32_e32 v28, v28, v32
	v_and_b32_e32 v32, 0xffff0000, v140
	v_add_f32_e32 v29, v29, v32
	v_lshlrev_b32_e32 v32, 16, v141
	v_add_f32_e32 v30, v30, v32
	v_and_b32_e32 v32, 0xffff0000, v141
	v_add_f32_e32 v31, v31, v32
	v_lshlrev_b32_e32 v32, 16, v142
	v_add_f32_e32 v32, v24, v32
	v_and_b32_e32 v24, 0xffff0000, v142
	s_waitcnt lgkmcnt(0)
	v_add_f32_e32 v33, v25, v24
	v_lshlrev_b32_e32 v24, 16, v143
	v_add_f32_e32 v34, v26, v24
	v_and_b32_e32 v24, 0xffff0000, v143
	v_add_f32_e32 v27, v27, v24
	v_mul_f32_e32 v24, v29, v29
	v_mul_f32_e32 v25, v31, v31
	v_fmac_f32_e32 v24, v28, v28
	v_fmac_f32_e32 v25, v30, v30
	v_add_f32_e32 v24, v24, v25
	v_mul_f32_e32 v25, v33, v33
	v_mul_f32_e32 v26, v27, v27
	v_fmac_f32_e32 v25, v32, v32
	v_fmac_f32_e32 v26, v34, v34
	v_add_f32_e32 v25, v25, v26
	v_add_f32_e32 v35, v24, v25
	v_cvt_pk_bf16_f32 v24, v28, v29
	v_lshlrev_b32_e32 v28, 16, v136
	v_add_f32_e32 v20, v20, v28
	v_and_b32_e32 v28, 0xffff0000, v136
	v_add_f32_e32 v21, v21, v28
	v_lshlrev_b32_e32 v28, 16, v137
	v_add_f32_e32 v22, v22, v28
	v_and_b32_e32 v28, 0xffff0000, v137
	v_add_f32_e32 v23, v23, v28
	v_lshlrev_b32_e32 v28, 16, v138
	v_add_f32_e32 v28, v16, v28
	v_and_b32_e32 v16, 0xffff0000, v138
	v_add_f32_e32 v29, v17, v16
	v_lshlrev_b32_e32 v16, 16, v139
	v_cvt_pk_bf16_f32 v25, v30, v31
	v_add_f32_e32 v30, v18, v16
	v_and_b32_e32 v16, 0xffff0000, v139
	v_add_f32_e32 v31, v19, v16
	v_mul_f32_e32 v16, v21, v21
	v_mul_f32_e32 v17, v23, v23
	v_fmac_f32_e32 v16, v20, v20
	v_fmac_f32_e32 v17, v22, v22
	v_add_f32_e32 v16, v16, v17
	v_mul_f32_e32 v17, v29, v29
	v_mul_f32_e32 v18, v31, v31
	v_fmac_f32_e32 v17, v28, v28
	v_fmac_f32_e32 v18, v30, v30
	v_add_f32_e32 v17, v17, v18
	v_add_f32_e32 v16, v16, v17
	v_cvt_pk_bf16_f32 v26, v32, v33
	v_add_f32_e32 v32, v35, v16
	ds_bpermute_b32 v33, v112, v32
	v_lshl_add_u64 v[16:17], s[66:67], 0, v[194:195]
	v_cvt_pk_bf16_f32 v27, v34, v27
	global_store_dwordx4 v[16:17], v[24:27], off sc1
	v_cvt_pk_bf16_f32 v18, v20, v21
	s_waitcnt lgkmcnt(0)
	v_add_f32_e32 v16, v32, v33
	ds_bpermute_b32 v17, v113, v16
	v_cvt_pk_bf16_f32 v19, v22, v23
	v_lshl_add_u64 v[22:23], s[64:65], 0, v[194:195]
	v_cvt_pk_bf16_f32 v20, v28, v29
	v_cvt_pk_bf16_f32 v21, v30, v31
	global_store_dwordx4 v[22:23], v[18:21], off sc1
	s_and_saveexec_b64 s[68:69], s[2:3]
	s_cbranch_execz .LBB0_768
	v_lshl_add_u64 v[18:19], v[208:209], 2, s[0:1]
	s_waitcnt lgkmcnt(0)
	v_add_f32_e32 v16, v16, v17
	global_atomic_add_f32 v[18:19], v16, off offset:640
.LBB0_768:
	s_or_b64 exec, exec, s[68:69]
	v_lshlrev_b32_e32 v16, 16, v132
	v_add_f32_e32 v12, v12, v16
	v_and_b32_e32 v16, 0xffff0000, v132
	v_add_f32_e32 v13, v13, v16
	v_lshlrev_b32_e32 v16, 16, v133
	v_add_f32_e32 v14, v14, v16
	v_and_b32_e32 v16, 0xffff0000, v133
	v_add_f32_e32 v15, v15, v16
	v_lshlrev_b32_e32 v16, 16, v134
	v_add_f32_e32 v16, v8, v16
	v_and_b32_e32 v8, 0xffff0000, v134
	s_waitcnt lgkmcnt(0)
	v_add_f32_e32 v17, v9, v8
	v_lshlrev_b32_e32 v8, 16, v135
	v_add_f32_e32 v18, v10, v8
	v_and_b32_e32 v8, 0xffff0000, v135
	v_add_f32_e32 v11, v11, v8
	v_mul_f32_e32 v8, v13, v13
	v_mul_f32_e32 v9, v15, v15
	v_fmac_f32_e32 v8, v12, v12
	v_fmac_f32_e32 v9, v14, v14
	v_add_f32_e32 v8, v8, v9
	v_mul_f32_e32 v9, v17, v17
	v_mul_f32_e32 v10, v11, v11
	v_fmac_f32_e32 v9, v16, v16
	v_fmac_f32_e32 v10, v18, v18
	v_add_f32_e32 v9, v9, v10
	v_add_f32_e32 v19, v8, v9
	v_cvt_pk_bf16_f32 v8, v12, v13
	v_lshlrev_b32_e32 v12, 16, v128
	v_add_f32_e32 v4, v4, v12
	v_and_b32_e32 v12, 0xffff0000, v128
	v_add_f32_e32 v5, v5, v12
	v_lshlrev_b32_e32 v12, 16, v129
	v_add_f32_e32 v6, v6, v12
	v_and_b32_e32 v12, 0xffff0000, v129
	v_add_f32_e32 v7, v7, v12
	v_lshlrev_b32_e32 v12, 16, v130
	v_add_f32_e32 v12, v0, v12
	v_and_b32_e32 v0, 0xffff0000, v130
	v_add_f32_e32 v13, v1, v0
	v_lshlrev_b32_e32 v0, 16, v131
	v_cvt_pk_bf16_f32 v9, v14, v15
	v_add_f32_e32 v14, v2, v0
	v_and_b32_e32 v0, 0xffff0000, v131
	v_add_f32_e32 v15, v3, v0
	v_mul_f32_e32 v0, v5, v5
	v_mul_f32_e32 v1, v7, v7
	v_fmac_f32_e32 v0, v4, v4
	v_fmac_f32_e32 v1, v6, v6
	v_add_f32_e32 v0, v0, v1
	v_mul_f32_e32 v1, v13, v13
	v_mul_f32_e32 v2, v15, v15
	v_fmac_f32_e32 v1, v12, v12
	v_fmac_f32_e32 v2, v14, v14
	v_add_f32_e32 v1, v1, v2
	v_add_f32_e32 v0, v0, v1
	v_cvt_pk_bf16_f32 v10, v16, v17
	v_add_f32_e32 v16, v19, v0
	ds_bpermute_b32 v17, v112, v16
	v_lshl_add_u64 v[0:1], s[66:67], 0, v[184:185]
	v_cvt_pk_bf16_f32 v11, v18, v11
	global_store_dwordx4 v[0:1], v[8:11], off sc1
	v_cvt_pk_bf16_f32 v2, v4, v5
	s_waitcnt lgkmcnt(0)
	v_add_f32_e32 v0, v16, v17
	ds_bpermute_b32 v1, v113, v0
	v_cvt_pk_bf16_f32 v3, v6, v7
	v_lshl_add_u64 v[6:7], s[64:65], 0, v[184:185]
	v_cvt_pk_bf16_f32 v4, v12, v13
	v_cvt_pk_bf16_f32 v5, v14, v15
	global_store_dwordx4 v[6:7], v[2:5], off sc1
	s_and_saveexec_b64 s[64:65], s[2:3]
	s_cbranch_execz .LBB0_770
	v_lshl_add_u64 v[2:3], v[208:209], 2, s[0:1]
	s_waitcnt lgkmcnt(0)
	v_add_f32_e32 v0, v0, v1
	global_atomic_add_f32 v[2:3], v0, off offset:704

; __device__ __forceinline__ unsigned cvt_pk_bf16(float lo, float hi) { unsigned r; asm volatile("v_cvt_pk_bf16_f32 %0, %1, %2" : "=v"(r) : "v"(lo), "v"(hi)); return r; }
;     __device__ __forceinline__ void operator()(f32x4 (&acc)[2][2][4][2], const Unit& u, int wr, int wc, int fr, int fq) const {
;         const int row0 = u.pm * BM + wr * 64 + fr, col0 = u.pn * HALF + wc * 32 + 8 * fq;
;         bf16_t* Ob = O + ((size_t)(u.pm * ldc + (col0 >> 6)) * BM) * 64;
;         float sq[2][4];
; #pragma unroll
;         for (int ai = 0; ai < 2; ++ai)
; #pragma unroll
;             for (int m = 0; m < 4; ++m) sq[ai][m] = ssq[row0 + ai * HALF + m * 16];
; #pragma unroll
;         for (int ai = 0; ai < 2; ++ai)
; #pragma unroll
;             for (int m = 0; m < 4; ++m) { const float ms = sq[ai][m] * (1.0f / 1024.0f) + 1e-6f, nrl = -__builtin_amdgcn_rsqf(ms) * LOG2E;
;                 float o[8];
; #pragma unroll
;                 for (int n = 0; n < 2; ++n)
; #pragma unroll
;                     for (int e = 0; e < 4; ++e) { const float a = acc[ai][0][m][n][e], bb = acc[ai][1][m][n][e];
;                         o[4 * n + e] = (a * bb) * __builtin_amdgcn_rcpf(__builtin_fmaf(__builtin_amdgcn_exp2f(a * nrl), ms, ms)); }
;                 u32x4 w; w.x = cvt_pk_bf16(o[0], o[1]); w.y = cvt_pk_bf16(o[2], o[3]); w.z = cvt_pk_bf16(o[4], o[5]); w.w = cvt_pk_bf16(o[6], o[7]);
;                 *(u32x4*)((char*)Ob + ai * HTB + lds_byte(wr * 64 + m * 16 + fr, (col0 & 63))) = w; }
.LBB0_841:
	v_lshl_add_u32 v148, s60, 8, v140
	v_ashrrev_i32_e32 v149, 31, v148
	v_lshl_add_u64 v[148:149], v[148:149], 2, s[0:1]
	global_load_dword v147, v[148:149], off
	global_load_dword v150, v[148:149], off offset:64
	v_mul_f32_e32 v153, v108, v104
	global_load_dword v154, v[148:149], off offset:128
	global_load_dword v155, v[148:149], off offset:192
	global_load_dword v156, v[148:149], off offset:512
	global_load_dword v157, v[148:149], off offset:576
	global_load_dword v158, v[148:149], off offset:640
	global_load_dword v104, v[148:149], off offset:704
	v_mul_f32_e32 v105, v109, v105
	v_mul_f32_e32 v106, v110, v106
	v_mul_f32_e32 v96, v100, v96
	v_mul_f32_e32 v124, v116, v124
	v_mul_f32_e32 v125, v117, v125
	v_mul_f32_e32 v126, v118, v126
	v_mul_f32_e32 v127, v119, v127
	v_mul_f32_e32 v151, v112, v120
	v_mul_f32_e32 v152, v113, v121
	v_mul_f32_e32 v122, v114, v122
	v_mul_f32_e32 v123, v115, v123
	s_lshl_b32 s53, s61, 7
	s_or_b32 s53, s53, s71
	s_mul_i32 s55, s60, 44
	s_ashr_i32 s53, s53, 6
	s_add_i32 s60, s53, s55
	v_mul_f32_e32 v98, v102, v98
	s_ashr_i32 s61, s60, 31
	s_lshl_b64 s[60:61], s[60:61], 15
	s_add_u32 s60, s28, s60
	s_addc_u32 s61, s29, s61
	v_lshl_add_u64 v[120:121], s[60:61], 0, v[128:129]
	v_mul_f32_e32 v107, v111, v107
	v_mul_f32_e32 v88, v92, v88
	v_mul_f32_e32 v89, v93, v89
	v_mul_f32_e32 v90, v94, v90
	v_mul_f32_e32 v91, v95, v91
	v_mul_f32_e32 v80, v84, v80
	v_mul_f32_e32 v82, v86, v82
	v_mul_f32_e32 v72, v76, v72
	v_mul_f32_e32 v73, v77, v73
	v_mul_f32_e32 v74, v78, v74
	v_mul_f32_e32 v75, v79, v75
	v_mul_f32_e32 v64, v68, v64
	v_mul_f32_e32 v66, v70, v66
	v_mul_f32_e32 v56, v60, v56
	v_mul_f32_e32 v57, v61, v57
	v_mul_f32_e32 v58, v62, v58
	v_mul_f32_e32 v59, v63, v59
	v_mul_f32_e32 v48, v52, v48
	v_mul_f32_e32 v50, v54, v50
	v_mul_f32_e32 v40, v44, v40
	v_mul_f32_e32 v41, v45, v41
	v_mul_f32_e32 v42, v46, v42
	v_mul_f32_e32 v43, v47, v43
	v_mul_f32_e32 v32, v36, v32
	v_mul_f32_e32 v34, v38, v34
	v_mul_f32_e32 v24, v28, v24
	v_mul_f32_e32 v25, v29, v25
	v_mul_f32_e32 v26, v30, v26
	v_mul_f32_e32 v27, v31, v27
	v_mul_f32_e32 v16, v20, v16
	v_mul_f32_e32 v18, v22, v18
	v_mul_f32_e32 v8, v12, v8
	v_mul_f32_e32 v9, v13, v9
	v_mul_f32_e32 v10, v14, v10
	v_mul_f32_e32 v11, v15, v11
	v_mul_f32_e32 v0, v4, v0
	v_mul_f32_e32 v2, v6, v2
	s_waitcnt vmcnt(0)
	v_fmamk_f32 v147, v147, 0x3a800000, v146
	v_fmamk_f32 v148, v150, 0x3a800000, v146
	v_rsq_f32_e32 v150, v148
	v_rsq_f32_e32 v149, v147
	v_mul_f32_e32 v150, 0xbfb8aa3b, v150
	v_mul_f32_e32 v109, v109, v150
	v_exp_f32_e32 v109, v109
	v_mul_f32_e32 v110, v110, v150
	v_exp_f32_e32 v110, v110
	v_mul_f32_e32 v159, v100, v150
	v_fma_f32 v109, v109, v148, v148
	v_rcp_f32_e32 v109, v109
	v_fma_f32 v110, v110, v148, v148
	v_rcp_f32_e32 v110, v110
	v_mul_f32_e32 v149, 0xbfb8aa3b, v149
	v_mul_f32_e32 v105, v105, v109
	v_exp_f32_e32 v109, v159
	v_mul_f32_e32 v106, v106, v110
	v_mul_f32_e32 v110, v101, v150
	v_exp_f32_e32 v110, v110
	v_fma_f32 v109, v109, v148, v148
	v_rcp_f32_e32 v109, v109
	v_mul_f32_e32 v116, v116, v149
	v_mul_f32_e32 v117, v117, v149
	v_mul_f32_e32 v118, v118, v149
	v_mul_f32_e32 v100, v96, v109
	v_mul_f32_e32 v96, v101, v97
	v_fma_f32 v97, v110, v148, v148
	v_mul_f32_e32 v101, v102, v150
	v_rcp_f32_e32 v97, v97
	v_exp_f32_e32 v101, v101
	v_mul_f32_e32 v119, v119, v149
	v_mul_f32_e32 v112, v112, v149
	v_mul_f32_e32 v113, v113, v149
	v_mul_f32_e32 v114, v114, v149
	v_mul_f32_e32 v115, v115, v149
	v_mul_f32_e32 v108, v108, v150
	v_mul_f32_e32 v149, v111, v150
	v_exp_f32_e32 v116, v116
	v_mul_f32_e32 v109, v103, v150
	v_mul_f32_e32 v110, v96, v97
	v_fma_f32 v96, v101, v148, v148
	v_exp_f32_e32 v117, v117
	v_exp_f32_e32 v118, v118
	v_exp_f32_e32 v119, v119
	v_exp_f32_e32 v112, v112
	v_exp_f32_e32 v113, v113
	v_exp_f32_e32 v114, v114
	v_exp_f32_e32 v115, v115
	v_exp_f32_e32 v108, v108
	v_exp_f32_e32 v149, v149
	v_exp_f32_e32 v109, v109
	v_rcp_f32_e32 v96, v96
	v_fma_f32 v116, v116, v147, v147
	v_fmamk_f32 v102, v154, 0x3a800000, v146
	v_fma_f32 v117, v117, v147, v147
	v_fma_f32 v118, v118, v147, v147
	v_fma_f32 v119, v119, v147, v147
	v_fma_f32 v112, v112, v147, v147
	v_fma_f32 v113, v113, v147, v147
	v_fma_f32 v114, v114, v147, v147
	v_fmac_f32_e32 v147, v115, v147
	v_fma_f32 v108, v108, v148, v148
	v_fma_f32 v115, v149, v148, v148
	v_rcp_f32_e32 v116, v116
	v_fmac_f32_e32 v148, v109, v148
	v_mul_f32_e32 v101, v98, v96
	v_mul_f32_e32 v96, v103, v99
	v_rsq_f32_e32 v103, v102
	v_rcp_f32_e32 v117, v117
	v_rcp_f32_e32 v118, v118
	v_rcp_f32_e32 v119, v119
	v_rcp_f32_e32 v112, v112
	v_rcp_f32_e32 v113, v113
	v_rcp_f32_e32 v114, v114
	v_rcp_f32_e32 v147, v147
	v_rcp_f32_e32 v108, v108
	v_rcp_f32_e32 v149, v115
	v_rcp_f32_e32 v97, v148
	v_mul_f32_e32 v115, v124, v116
	v_mul_f32_e32 v103, 0xbfb8aa3b, v103
	v_mul_f32_e32 v116, v125, v117
	v_mul_f32_e32 v117, v126, v118
	v_mul_f32_e32 v118, v127, v119
	v_mul_f32_e32 v119, v151, v112
	v_mul_f32_e32 v124, v152, v113
	v_mul_f32_e32 v122, v122, v114
	v_mul_f32_e32 v123, v123, v147
	v_mul_f32_e32 v108, v153, v108
	v_cvt_pk_bf16_f32 v112, v115, v116
	v_cvt_pk_bf16_f32 v113, v117, v118
	v_cvt_pk_bf16_f32 v114, v119, v124
	v_cvt_pk_bf16_f32 v115, v122, v123
	global_store_dwordx4 v[120:121], v[112:115], off sc1
	v_mul_f32_e32 v107, v107, v149
	v_mul_f32_e32 v99, v96, v97
	v_cvt_pk_bf16_f32 v96, v108, v105
	v_cvt_pk_bf16_f32 v97, v106, v107
	v_mul_f32_e32 v105, v92, v103
	v_mul_f32_e32 v106, v93, v103
	v_mul_f32_e32 v92, v94, v103
	v_mul_f32_e32 v93, v95, v103
	v_exp_f32_e32 v92, v92
	v_exp_f32_e32 v93, v93
	v_mul_f32_e32 v94, v84, v103
	v_exp_f32_e32 v94, v94
	v_fma_f32 v92, v92, v102, v102
	v_fma_f32 v93, v93, v102, v102
; __device__ __forceinline__ unsigned cvt_pk_bf16(float lo, float hi) { unsigned r; asm volatile("v_cvt_pk_bf16_f32 %0, %1, %2" : "=v"(r) : "v"(lo), "v"(hi)); return r; }
;     __device__ __forceinline__ void operator()(f32x4 (&acc)[2][2][4][2], const Unit& u, int wr, int wc, int fr, int fq) const {
;     ...
;             for (int m = 0; m < 4; ++m) { const float ms = sq[ai][m] * (1.0f / 1024.0f) + 1e-6f, nrl = -__builtin_amdgcn_rsqf(ms) * LOG2E;
;                 float o[8];
; #pragma unroll
;                 for (int n = 0; n < 2; ++n)
; #pragma unroll
;                     for (int e = 0; e < 4; ++e) { const float a = acc[ai][0][m][n][e], bb = acc[ai][1][m][n][e];
;                         o[4 * n + e] = (a * bb) * __builtin_amdgcn_rcpf(__builtin_fmaf(__builtin_amdgcn_exp2f(a * nrl), ms, ms)); }
;                 u32x4 w; w.x = cvt_pk_bf16(o[0], o[1]); w.y = cvt_pk_bf16(o[2], o[3]); w.z = cvt_pk_bf16(o[4], o[5]); w.w = cvt_pk_bf16(o[6], o[7]);
;                 *(u32x4*)((char*)Ob + ai * HTB + lds_byte(wr * 64 + m * 16 + fr, (col0 & 63))) = w; }
	v_rcp_f32_e32 v92, v92
	v_rcp_f32_e32 v93, v93
	v_exp_f32_e32 v105, v105
	v_exp_f32_e32 v106, v106
	v_mul_f32_e32 v90, v90, v92
	v_mul_f32_e32 v91, v91, v93
	v_fma_f32 v92, v94, v102, v102
	v_mul_f32_e32 v93, v85, v103
	v_rcp_f32_e32 v92, v92
	v_exp_f32_e32 v93, v93
	v_cvt_pk_bf16_f32 v98, v100, v110
	v_cvt_pk_bf16_f32 v99, v101, v99
	v_mul_f32_e32 v84, v80, v92
	v_mul_f32_e32 v80, v85, v81
	v_fma_f32 v81, v93, v102, v102
	v_mul_f32_e32 v85, v86, v103
	v_rcp_f32_e32 v81, v81
	v_exp_f32_e32 v85, v85
	v_mul_f32_e32 v92, v87, v103
	v_exp_f32_e32 v92, v92
	v_mul_f32_e32 v93, v80, v81
	v_fma_f32 v80, v85, v102, v102
	v_rcp_f32_e32 v80, v80
	v_lshl_add_u64 v[100:101], s[60:61], 0, v[130:131]
	global_store_dwordx4 v[100:101], v[96:99], off sc1
	v_fmamk_f32 v86, v155, 0x3a800000, v146
	v_mul_f32_e32 v85, v82, v80
	v_fma_f32 v96, v105, v102, v102
	v_fma_f32 v97, v106, v102, v102
	v_rcp_f32_e32 v96, v96
	v_rcp_f32_e32 v97, v97
	v_fmac_f32_e32 v102, v92, v102
	v_mul_f32_e32 v80, v87, v83
	v_rsq_f32_e32 v87, v86
	v_rcp_f32_e32 v81, v102
	v_mul_f32_e32 v88, v88, v96
	v_mul_f32_e32 v89, v89, v97
	v_mul_f32_e32 v87, 0xbfb8aa3b, v87
	v_mul_f32_e32 v83, v80, v81
	v_cvt_pk_bf16_f32 v80, v88, v89
	v_mul_f32_e32 v88, v76, v87
	v_mul_f32_e32 v89, v77, v87
	v_mul_f32_e32 v76, v78, v87
	v_mul_f32_e32 v77, v79, v87
	v_exp_f32_e32 v76, v76
	v_exp_f32_e32 v77, v77
	v_mul_f32_e32 v78, v68, v87
	v_exp_f32_e32 v78, v78
	v_fma_f32 v76, v76, v86, v86
	v_fma_f32 v77, v77, v86, v86
	v_rcp_f32_e32 v76, v76
	v_rcp_f32_e32 v77, v77
	v_exp_f32_e32 v88, v88
	v_exp_f32_e32 v89, v89
	v_mul_f32_e32 v74, v74, v76
	v_mul_f32_e32 v75, v75, v77
	v_fma_f32 v76, v78, v86, v86
	v_mul_f32_e32 v77, v69, v87
	v_rcp_f32_e32 v76, v76
	v_exp_f32_e32 v77, v77
	v_cvt_pk_bf16_f32 v81, v90, v91
	v_cvt_pk_bf16_f32 v82, v84, v93
	v_mul_f32_e32 v68, v64, v76
	v_mul_f32_e32 v64, v69, v65
	v_fma_f32 v65, v77, v86, v86
	v_mul_f32_e32 v69, v70, v87
	v_rcp_f32_e32 v65, v65
	v_exp_f32_e32 v69, v69
	v_mul_f32_e32 v76, v71, v87
	v_exp_f32_e32 v76, v76
	v_mul_f32_e32 v77, v64, v65
	v_fma_f32 v64, v69, v86, v86
	v_cvt_pk_bf16_f32 v83, v85, v83
	v_lshl_add_u64 v[84:85], s[60:61], 0, v[132:133]
	v_rcp_f32_e32 v64, v64
	global_store_dwordx4 v[84:85], v[80:83], off sc1
	v_fmamk_f32 v70, v156, 0x3a800000, v146
	v_mul_f32_e32 v69, v66, v64
	v_fma_f32 v80, v88, v86, v86
	v_fma_f32 v81, v89, v86, v86
	v_fmac_f32_e32 v86, v76, v86
	v_rcp_f32_e32 v65, v86
	v_rcp_f32_e32 v80, v80
	v_rcp_f32_e32 v81, v81
	v_mul_f32_e32 v64, v71, v67
	v_rsq_f32_e32 v71, v70
	v_mul_f32_e32 v67, v64, v65
	v_mul_f32_e32 v72, v72, v80
	v_mul_f32_e32 v73, v73, v81
	v_cvt_pk_bf16_f32 v64, v72, v73
	v_cvt_pk_bf16_f32 v65, v74, v75
	v_cvt_pk_bf16_f32 v66, v68, v77
	v_cvt_pk_bf16_f32 v67, v69, v67
	v_lshl_add_u64 v[68:69], s[60:61], 0, v[134:135]
	global_store_dwordx4 v[68:69], v[64:67], off sc1
	s_add_u32 s60, s60, 0x4000
	s_addc_u32 s61, s61, 0
	v_mul_f32_e32 v64, 0xbfb8aa3b, v71
	v_mul_f32_e32 v65, v60, v64
	v_mul_f32_e32 v66, v61, v64
	v_mul_f32_e32 v60, v62, v64
	v_mul_f32_e32 v61, v63, v64
	v_exp_f32_e32 v60, v60
	v_exp_f32_e32 v61, v61
	v_mul_f32_e32 v62, v52, v64
	v_exp_f32_e32 v62, v62
	v_fma_f32 v60, v60, v70, v70
	v_fma_f32 v61, v61, v70, v70
	v_rcp_f32_e32 v60, v60
	v_rcp_f32_e32 v61, v61
	v_exp_f32_e32 v65, v65
	v_exp_f32_e32 v66, v66
	v_mul_f32_e32 v58, v58, v60
	v_mul_f32_e32 v59, v59, v61
	v_fma_f32 v60, v62, v70, v70
	v_mul_f32_e32 v61, v53, v64
	v_rcp_f32_e32 v60, v60
	v_exp_f32_e32 v61, v61
	v_fma_f32 v65, v65, v70, v70
	v_fma_f32 v66, v66, v70, v70
	v_mul_f32_e32 v52, v48, v60
	v_mul_f32_e32 v48, v53, v49
	v_fma_f32 v49, v61, v70, v70
	v_mul_f32_e32 v53, v54, v64
	v_rcp_f32_e32 v49, v49
	v_exp_f32_e32 v53, v53
	v_mul_f32_e32 v60, v55, v64
	v_exp_f32_e32 v60, v60
	v_mul_f32_e32 v61, v48, v49
	v_fma_f32 v48, v53, v70, v70
	v_rcp_f32_e32 v48, v48
	v_fmamk_f32 v54, v157, 0x3a800000, v146
	v_rcp_f32_e32 v65, v65
	v_rcp_f32_e32 v66, v66
	v_fmac_f32_e32 v70, v60, v70
	v_mul_f32_e32 v53, v50, v48
	v_mul_f32_e32 v48, v55, v51
	v_rsq_f32_e32 v55, v54
	v_rcp_f32_e32 v49, v70
	v_mul_f32_e32 v56, v56, v65
	v_mul_f32_e32 v57, v57, v66
	v_mul_f32_e32 v55, 0xbfb8aa3b, v55
	v_mul_f32_e32 v51, v48, v49
	v_cvt_pk_bf16_f32 v48, v56, v57
	v_mul_f32_e32 v56, v44, v55
	v_mul_f32_e32 v57, v45, v55
	v_mul_f32_e32 v44, v46, v55
	v_mul_f32_e32 v45, v47, v55
	v_exp_f32_e32 v44, v44
	v_exp_f32_e32 v45, v45
	v_mul_f32_e32 v46, v36, v55
	v_exp_f32_e32 v46, v46
; __device__ __forceinline__ unsigned cvt_pk_bf16(float lo, float hi) { unsigned r; asm volatile("v_cvt_pk_bf16_f32 %0, %1, %2" : "=v"(r) : "v"(lo), "v"(hi)); return r; }
;     __device__ __forceinline__ void operator()(f32x4 (&acc)[2][2][4][2], const Unit& u, int wr, int wc, int fr, int fq) const {
;     ...
;             for (int m = 0; m < 4; ++m) { const float ms = sq[ai][m] * (1.0f / 1024.0f) + 1e-6f, nrl = -__builtin_amdgcn_rsqf(ms) * LOG2E;
;                 float o[8];
; #pragma unroll
;                 for (int n = 0; n < 2; ++n)
; #pragma unroll
;                     for (int e = 0; e < 4; ++e) { const float a = acc[ai][0][m][n][e], bb = acc[ai][1][m][n][e];
;                         o[4 * n + e] = (a * bb) * __builtin_amdgcn_rcpf(__builtin_fmaf(__builtin_amdgcn_exp2f(a * nrl), ms, ms)); }
;                 u32x4 w; w.x = cvt_pk_bf16(o[0], o[1]); w.y = cvt_pk_bf16(o[2], o[3]); w.z = cvt_pk_bf16(o[4], o[5]); w.w = cvt_pk_bf16(o[6], o[7]);
;                 *(u32x4*)((char*)Ob + ai * HTB + lds_byte(wr * 64 + m * 16 + fr, (col0 & 63))) = w; }
	v_fma_f32 v44, v44, v54, v54
	v_fma_f32 v45, v45, v54, v54
	v_rcp_f32_e32 v44, v44
	v_rcp_f32_e32 v45, v45
	v_exp_f32_e32 v56, v56
	v_exp_f32_e32 v57, v57
	v_mul_f32_e32 v42, v42, v44
	v_mul_f32_e32 v43, v43, v45
	v_fma_f32 v44, v46, v54, v54
	v_mul_f32_e32 v45, v37, v55
	v_rcp_f32_e32 v44, v44
	v_exp_f32_e32 v45, v45
	v_cvt_pk_bf16_f32 v49, v58, v59
	v_cvt_pk_bf16_f32 v50, v52, v61
	v_mul_f32_e32 v36, v32, v44
	v_mul_f32_e32 v32, v37, v33
	v_fma_f32 v33, v45, v54, v54
	v_mul_f32_e32 v37, v38, v55
	v_rcp_f32_e32 v33, v33
	v_exp_f32_e32 v37, v37
	v_mul_f32_e32 v44, v39, v55
	v_exp_f32_e32 v44, v44
	v_mul_f32_e32 v45, v32, v33
	v_fma_f32 v32, v37, v54, v54
	v_rcp_f32_e32 v32, v32
	v_cvt_pk_bf16_f32 v51, v53, v51
	v_lshl_add_u64 v[52:53], s[60:61], 0, v[128:129]
	global_store_dwordx4 v[52:53], v[48:51], off sc1
	v_fmamk_f32 v38, v158, 0x3a800000, v146
	v_mul_f32_e32 v37, v34, v32
	v_fma_f32 v48, v56, v54, v54
	v_fma_f32 v49, v57, v54, v54
	v_rcp_f32_e32 v48, v48
	v_rcp_f32_e32 v49, v49
	v_fmac_f32_e32 v54, v44, v54
	v_mul_f32_e32 v32, v39, v35
	v_rsq_f32_e32 v39, v38
	v_rcp_f32_e32 v33, v54
	v_mul_f32_e32 v40, v40, v48
	v_mul_f32_e32 v41, v41, v49
	v_mul_f32_e32 v39, 0xbfb8aa3b, v39
	v_mul_f32_e32 v35, v32, v33
	v_cvt_pk_bf16_f32 v32, v40, v41
	v_mul_f32_e32 v40, v28, v39
	v_mul_f32_e32 v41, v29, v39
	v_mul_f32_e32 v28, v30, v39
	v_mul_f32_e32 v29, v31, v39
	v_exp_f32_e32 v28, v28
	v_exp_f32_e32 v29, v29
	v_mul_f32_e32 v30, v20, v39
	v_exp_f32_e32 v30, v30
	v_fma_f32 v28, v28, v38, v38
	v_fma_f32 v29, v29, v38, v38
	v_rcp_f32_e32 v28, v28
	v_rcp_f32_e32 v29, v29
	v_exp_f32_e32 v40, v40
	v_exp_f32_e32 v41, v41
	v_mul_f32_e32 v26, v26, v28
	v_mul_f32_e32 v27, v27, v29
	v_fma_f32 v28, v30, v38, v38
	v_mul_f32_e32 v29, v21, v39
	v_rcp_f32_e32 v28, v28
	v_exp_f32_e32 v29, v29
	v_cvt_pk_bf16_f32 v33, v42, v43
	v_cvt_pk_bf16_f32 v34, v36, v45
	v_mul_f32_e32 v20, v16, v28
	v_mul_f32_e32 v16, v21, v17
	v_fma_f32 v17, v29, v38, v38
	v_mul_f32_e32 v21, v22, v39
	v_rcp_f32_e32 v17, v17
	v_exp_f32_e32 v21, v21
	v_mul_f32_e32 v28, v23, v39
	v_exp_f32_e32 v28, v28
	v_mul_f32_e32 v29, v16, v17
	v_fma_f32 v16, v21, v38, v38
	v_rcp_f32_e32 v16, v16
	v_cvt_pk_bf16_f32 v35, v37, v35
	v_lshl_add_u64 v[36:37], s[60:61], 0, v[130:131]
	global_store_dwordx4 v[36:37], v[32:35], off sc1
	v_fmamk_f32 v22, v104, 0x3a800000, v146
	v_mul_f32_e32 v21, v18, v16
	v_fma_f32 v32, v40, v38, v38
	v_fma_f32 v33, v41, v38, v38
	v_rcp_f32_e32 v32, v32
	v_rcp_f32_e32 v33, v33
	v_fmac_f32_e32 v38, v28, v38
	v_mul_f32_e32 v16, v23, v19
	v_rsq_f32_e32 v23, v22
	v_rcp_f32_e32 v17, v38
	v_mul_f32_e32 v24, v24, v32
	v_mul_f32_e32 v25, v25, v33
	v_mul_f32_e32 v23, 0xbfb8aa3b, v23
	v_mul_f32_e32 v19, v16, v17
	v_cvt_pk_bf16_f32 v16, v24, v25
	v_mul_f32_e32 v24, v12, v23
	v_mul_f32_e32 v25, v13, v23
	v_mul_f32_e32 v12, v14, v23
	v_mul_f32_e32 v13, v15, v23
	v_exp_f32_e32 v12, v12
	v_exp_f32_e32 v13, v13
	v_mul_f32_e32 v14, v4, v23
	v_exp_f32_e32 v14, v14
	v_fma_f32 v12, v12, v22, v22
	v_fma_f32 v13, v13, v22, v22
	v_rcp_f32_e32 v12, v12
	v_rcp_f32_e32 v13, v13
	v_exp_f32_e32 v24, v24
	v_exp_f32_e32 v25, v25
	v_mul_f32_e32 v10, v10, v12
	v_mul_f32_e32 v11, v11, v13
	v_fma_f32 v12, v14, v22, v22
	v_mul_f32_e32 v13, v5, v23
	v_rcp_f32_e32 v12, v12
	v_exp_f32_e32 v13, v13
	v_cvt_pk_bf16_f32 v17, v26, v27
	v_cvt_pk_bf16_f32 v18, v20, v29
	v_mul_f32_e32 v4, v0, v12
	v_mul_f32_e32 v0, v5, v1
	v_fma_f32 v1, v13, v22, v22
	v_mul_f32_e32 v5, v6, v23
	v_rcp_f32_e32 v1, v1
	v_exp_f32_e32 v5, v5
	v_mul_f32_e32 v12, v7, v23
	v_exp_f32_e32 v12, v12
	v_cvt_pk_bf16_f32 v19, v21, v19
	v_lshl_add_u64 v[20:21], s[60:61], 0, v[132:133]
	v_mul_f32_e32 v13, v0, v1
	v_fma_f32 v0, v5, v22, v22
	global_store_dwordx4 v[20:21], v[16:19], off sc1
	v_rcp_f32_e32 v0, v0
	s_andn2_b64 vcc, exec, s[2:3]
	v_fma_f32 v16, v24, v22, v22
	v_fma_f32 v17, v25, v22, v22
	v_fmac_f32_e32 v22, v12, v22
	v_rcp_f32_e32 v1, v22
	v_rcp_f32_e32 v16, v16
	v_rcp_f32_e32 v17, v17
	v_mul_f32_e32 v5, v2, v0
	v_mul_f32_e32 v0, v7, v3
	v_mul_f32_e32 v3, v0, v1
	v_mul_f32_e32 v8, v8, v16
	v_mul_f32_e32 v9, v9, v17
	v_cvt_pk_bf16_f32 v0, v8, v9
	v_cvt_pk_bf16_f32 v1, v10, v11
	v_cvt_pk_bf16_f32 v2, v4, v13
	v_cvt_pk_bf16_f32 v3, v5, v3
	v_lshl_add_u64 v[4:5], s[60:61], 0, v[134:135]
	s_mov_b64 s[2:3], -1
	global_store_dwordx4 v[4:5], v[0:3], off sc1
	s_cbranch_vccnz .LBB0_834
	s_andn2_b64 vcc, exec, s[42:43]
	s_cbranch_vccnz .LBB0_833
	s_barrier
	s_branch .LBB0_833
